# loop-edge edit 7.11: K-loop counter/pointer/exit-test SALU moved in front of the loop-back barrier (all 7 GEMM loops and peels)
# baseline (speedup 1.0000x reference)
; #define PG8_STAGE(bufoff, gbase, voff) do { _Pragma("unroll") for (int _i = 0; _i < 2; ++_i) \
;         __builtin_amdgcn_global_load_lds((const unsigned*)((const char*)(gbase) + (voff)[_i]), (PG8_LAS unsigned*)(lds + (bufoff) + ldsw + _i * 8192), 16, 0, 0); } while (0)
; #define PG8_LDA(dst, b, h) do { _Pragma("unroll") for (int m = 0; m < 4; ++m) _Pragma("unroll") for (int k = 0; k < 2; ++k) dst[m][k] = *(const PG8_LAS bf16x8*)(lds + PG8_SA(b, h) + aoff + m * 2048 + k * 1024); } while (0)
; #define PG8_LDB(dst, b, h) do { _Pragma("unroll") for (int n = 0; n < 2; ++n) _Pragma("unroll") for (int k = 0; k < 2; ++k) dst[n][k] = *(const PG8_LAS bf16x8*)(lds + PG8_SB(b, h) + boff + n * 2048 + k * 1024); } while (0)
; #define PG8_WAIT_V(n) asm volatile("s_waitcnt vmcnt(" #n ")" ::: "memory")
; #define PG8_WAIT_L(n) asm volatile("s_waitcnt lgkmcnt(" #n ")" ::: "memory")
; #define PG8_BAR __builtin_amdgcn_s_barrier()
; #define PG8_SCHED __builtin_amdgcn_sched_barrier(0)
; template <class Epi, class Sched, bool ALIGN_EPI = false, bool SP2 = false, bool I8 = false>
; __device__ __forceinline__ void gemm_phase(PG8_LAS unsigned char* lds, const Gemm g, const Sched& S, const Epi& E) {
;     ...
;         const char* nA = has_next ? (const char*)g.A + (size_t)nxt.pm * tstep : cA; const char* nB = has_next ? (const char*)g.Bt + (size_t)nxt.pn * tstep : cB;
;         for (int t = 0; t < nt; t += 2) {
;             const bool last = (t == nt - 2);
;             const char* a1 = cA + (size_t)(t + 1) * kstep;
;             const char* a2 = last ? nA : cA + (size_t)(t + 2) * kstep; const char* b2 = last ? nB : cB + (size_t)(t + 2) * kstep;
;             const char* a3 = a2 + kstep; const char* b3 = b2 + kstep;
;             if (last && has_next) S.a_ready(nxt);
;             if constexpr (SP2) {
;             PG8_LDB(B0, 0, 0); PG8_LDB(B1, 0, 1); PG8_SCHED; PG8_LDA(At, 0, 0); PG8_STAGE(PG8_SA(1, 1), a1 + hstep, voffA);
;             PG8_WAIT_V(8); PG8_WAIT_L(0); PG8_BAR; PG8_MMA(0, 0, At, B0); PG8_MMA(0, 1, At, B1); PG8_BAR; PG8_SCHED;
;             PG8_LDA(At, 0, 1); PG8_STAGE(PG8_SB(0, 0), b2, voffB); PG8_STAGE(PG8_SB(0, 1), b2 + hstep, voffB); PG8_STAGE(PG8_SA(0, 0), a2, voffA);
;             PG8_WAIT_V(8); PG8_WAIT_L(0); PG8_BAR; PG8_MMA(1, 0, At, B0); PG8_MMA(1, 1, At, B1); PG8_BAR; PG8_SCHED;
.LBB0_207:
	s_ashr_i32 s19, s18, 31
	s_lshl_b64 s[22:23], s[18:19], 20
	s_add_u32 s22, s28, s22
	s_addc_u32 s23, s34, s23
	s_and_b64 s[24:25], s[6:7], exec
	s_cselect_b32 s19, s23, s27
	s_cselect_b32 s64, s22, s26
	s_ashr_i32 s17, s16, 31
	s_lshl_b64 s[24:25], s[16:17], 20
	s_add_u32 s24, s35, s24
	s_addc_u32 s25, s42, s25
	s_and_b64 s[40:41], s[6:7], exec
	s_cselect_b32 s17, s25, s37
	s_cselect_b32 s65, s24, s36
	s_add_u32 s26, s26, 0x80080
	s_addc_u32 s27, s27, 0
	s_add_u32 s72, s36, 0x100
	s_addc_u32 s73, s37, 0
	s_mov_b32 s76, -2
	s_add_u32 s36, s26, 0xfff80080
	s_addc_u32 s37, s27, -1
	s_add_i32 s50, 0, 0x10000
	s_cmp_eq_u32 s76, 28
	s_cselect_b32 s41, s19, s37
	s_cselect_b32 s40, s64, s36
	s_cselect_b32 s37, s17, s73
	s_cselect_b32 s36, s65, s72
	s_add_i32 s56, 0, 0x14000
	v_add_u32_e32 v136, s50, v175
	v_add_u32_e32 v172, s56, v175
	ds_read_b128 v[116:119], v136
	ds_read_b128 v[124:127], v136 offset:1024
	ds_read_b128 v[132:135], v136 offset:2048
	ds_read_b128 v[136:139], v136 offset:3072
	ds_read_b128 v[160:163], v172
	ds_read_b128 v[164:167], v172 offset:1024
	ds_read_b128 v[168:171], v172 offset:2048
	ds_read_b128 v[178:181], v172 offset:3072
	v_lshl_add_u64 v[172:173], s[26:27], 0, v[156:157]
	s_add_i32 m0, s44, 0xc000
	ds_read_b128 v[182:185], v177
	ds_read_b128 v[186:189], v177 offset:1024
	ds_read_b128 v[204:207], v177 offset:2048
	ds_read_b128 v[208:211], v177 offset:3072
	ds_read_b128 v[212:215], v177 offset:4096
	ds_read_b128 v[216:219], v177 offset:5120
	ds_read_b128 v[220:223], v177 offset:6144
	ds_read_b128 v[224:227], v177 offset:7168
	global_load_lds_dwordx4 v[172:173], off
	v_lshl_add_u64 v[172:173], s[26:27], 0, v[158:159]
	s_add_i32 m0, s44, 0xe000
	s_nop 0
	global_load_lds_dwordx4 v[172:173], off
	s_waitcnt vmcnt(8)
	s_waitcnt lgkmcnt(0)
	s_barrier
	s_setprio 1
	s_waitcnt lgkmcnt(0)
	v_mfma_i32_16x16x64_i8 v[144:147], v[116:119], v[182:185], 0
	v_mfma_i32_16x16x64_i8 v[144:147], v[124:127], v[186:189], v[144:147]
	v_mfma_i32_16x16x64_i8 v[112:115], v[124:127], v[208:211], 0
	v_mfma_i32_16x16x64_i8 v[112:115], v[116:119], v[204:207], v[112:115]
	v_mfma_i32_16x16x64_i8 v[96:99], v[116:119], v[212:215], 0
	v_mfma_i32_16x16x64_i8 v[96:99], v[124:127], v[216:219], v[96:99]
	v_mfma_i32_16x16x64_i8 v[80:83], v[124:127], v[224:227], 0
	v_mfma_i32_16x16x64_i8 v[80:83], v[116:119], v[220:223], v[80:83]
	v_mfma_i32_16x16x64_i8 v[76:79], v[132:135], v[220:223], 0
	v_mfma_i32_16x16x64_i8 v[76:79], v[136:139], v[224:227], v[76:79]
	v_mfma_i32_16x16x64_i8 v[92:95], v[136:139], v[216:219], 0
	v_mfma_i32_16x16x64_i8 v[92:95], v[132:135], v[212:215], v[92:95]
	v_mfma_i32_16x16x64_i8 v[108:111], v[132:135], v[204:207], 0
	v_mfma_i32_16x16x64_i8 v[108:111], v[136:139], v[208:211], v[108:111]
	v_mfma_i32_16x16x64_i8 v[140:143], v[136:139], v[186:189], 0
	v_mfma_i32_16x16x64_i8 v[140:143], v[132:135], v[182:185], v[140:143]
	v_mfma_i32_16x16x64_i8 v[128:131], v[160:163], v[182:185], 0
	v_mfma_i32_16x16x64_i8 v[128:131], v[164:167], v[186:189], v[128:131]
	v_mfma_i32_16x16x64_i8 v[104:107], v[164:167], v[208:211], 0
	v_mfma_i32_16x16x64_i8 v[104:107], v[160:163], v[204:207], v[104:107]
	v_mfma_i32_16x16x64_i8 v[88:91], v[160:163], v[212:215], 0
	v_mfma_i32_16x16x64_i8 v[88:91], v[164:167], v[216:219], v[88:91]
	v_mfma_i32_16x16x64_i8 v[72:75], v[164:167], v[224:227], 0
	v_mfma_i32_16x16x64_i8 v[72:75], v[160:163], v[220:223], v[72:75]
	v_mfma_i32_16x16x64_i8 v[68:71], v[168:171], v[220:223], 0
	v_mfma_i32_16x16x64_i8 v[68:71], v[178:181], v[224:227], v[68:71]
	v_mfma_i32_16x16x64_i8 v[84:87], v[178:181], v[216:219], 0
	v_mfma_i32_16x16x64_i8 v[84:87], v[168:171], v[212:215], v[84:87]
	v_mfma_i32_16x16x64_i8 v[100:103], v[168:171], v[204:207], 0
	v_mfma_i32_16x16x64_i8 v[100:103], v[178:181], v[208:211], v[100:103]
	v_mfma_i32_16x16x64_i8 v[120:123], v[178:181], v[186:189], 0
	v_mfma_i32_16x16x64_i8 v[120:123], v[168:171], v[182:185], v[120:123]
	s_setprio 0
	s_barrier
	s_add_i32 s50, s50, s43
	v_lshl_add_u64 v[172:173], s[36:37], 0, v[2:3]
	s_mov_b32 m0, s50
	ds_read_b128 v[182:185], v177 offset:16384
	ds_read_b128 v[186:189], v177 offset:17408
	ds_read_b128 v[204:207], v177 offset:18432
	ds_read_b128 v[208:211], v177 offset:19456
	ds_read_b128 v[212:215], v177 offset:20480
	ds_read_b128 v[216:219], v177 offset:21504
	ds_read_b128 v[220:223], v177 offset:22528
	ds_read_b128 v[224:227], v177 offset:23552
	global_load_lds_dwordx4 v[172:173], off
	s_add_i32 m0, s50, 0x2000
	s_add_u32 s50, s36, 0x80000
	v_lshl_add_u64 v[190:191], s[36:37], 0, v[148:149]
	s_addc_u32 s51, s37, 0
	s_add_i32 s56, s56, s43
	global_load_lds_dwordx4 v[190:191], off
	v_lshl_add_u64 v[228:229], s[50:51], 0, v[2:3]
	s_mov_b32 m0, s56
	v_lshl_add_u64 v[240:241], s[40:41], 0, v[150:151]
	global_load_lds_dwordx4 v[228:229], off
	v_lshl_add_u64 v[228:229], s[50:51], 0, v[148:149]
	s_add_i32 m0, s56, 0x2000
	s_nop 0
	global_load_lds_dwordx4 v[228:229], off
	v_lshl_add_u64 v[228:229], s[40:41], 0, v[152:153]
	s_mov_b32 m0, s44
	s_nop 0
	global_load_lds_dwordx4 v[228:229], off
	s_mov_b32 m0, s45
	s_nop 0
	global_load_lds_dwordx4 v[240:241], off
	s_waitcnt vmcnt(8)
	s_waitcnt lgkmcnt(0)
	s_barrier
; #define PG8_STAGE(bufoff, gbase, voff) do { _Pragma("unroll") for (int _i = 0; _i < 2; ++_i) \
;         __builtin_amdgcn_global_load_lds((const unsigned*)((const char*)(gbase) + (voff)[_i]), (PG8_LAS unsigned*)(lds + (bufoff) + ldsw + _i * 8192), 16, 0, 0); } while (0)
; #define PG8_LDA(dst, b, h) do { _Pragma("unroll") for (int m = 0; m < 4; ++m) _Pragma("unroll") for (int k = 0; k < 2; ++k) dst[m][k] = *(const PG8_LAS bf16x8*)(lds + PG8_SA(b, h) + aoff + m * 2048 + k * 1024); } while (0)
; #define PG8_LDB(dst, b, h) do { _Pragma("unroll") for (int n = 0; n < 2; ++n) _Pragma("unroll") for (int k = 0; k < 2; ++k) dst[n][k] = *(const PG8_LAS bf16x8*)(lds + PG8_SB(b, h) + boff + n * 2048 + k * 1024); } while (0)
; #define PG8_WAIT_V(n) asm volatile("s_waitcnt vmcnt(" #n ")" ::: "memory")
; #define PG8_WAIT_L(n) asm volatile("s_waitcnt lgkmcnt(" #n ")" ::: "memory")
; #define PG8_BAR __builtin_amdgcn_s_barrier()
; #define PG8_SCHED __builtin_amdgcn_sched_barrier(0)
; template <class Epi, class Sched, bool ALIGN_EPI = false, bool SP2 = false, bool I8 = false>
; __device__ __forceinline__ void gemm_phase(PG8_LAS unsigned char* lds, const Gemm g, const Sched& S, const Epi& E) {
;     ...
;             PG8_WAIT_V(8); PG8_WAIT_L(0); PG8_BAR; PG8_MMA(1, 0, At, B0); PG8_MMA(1, 1, At, B1); PG8_BAR; PG8_SCHED;
;             PG8_LDB(B0, 1, 0); PG8_LDB(B1, 1, 1); PG8_SCHED; PG8_LDA(At, 1, 0); PG8_STAGE(PG8_SA(0, 1), a2 + hstep, voffA);
;             PG8_WAIT_V(8); PG8_WAIT_L(0); PG8_BAR; PG8_MMA(0, 0, At, B0); PG8_MMA(0, 1, At, B1); PG8_BAR; PG8_SCHED;
	s_setprio 1
	s_waitcnt lgkmcnt(0)
	v_mfma_i32_16x16x64_i8 v[64:67], v[116:119], v[182:185], 0
	v_mfma_i32_16x16x64_i8 v[64:67], v[124:127], v[186:189], v[64:67]
	v_mfma_i32_16x16x64_i8 v[48:51], v[124:127], v[208:211], 0
	v_mfma_i32_16x16x64_i8 v[48:51], v[116:119], v[204:207], v[48:51]
	v_mfma_i32_16x16x64_i8 v[32:35], v[116:119], v[212:215], 0
	v_mfma_i32_16x16x64_i8 v[32:35], v[124:127], v[216:219], v[32:35]
	v_mfma_i32_16x16x64_i8 v[16:19], v[124:127], v[224:227], 0
	v_mfma_i32_16x16x64_i8 v[16:19], v[116:119], v[220:223], v[16:19]
	v_mfma_i32_16x16x64_i8 v[12:15], v[132:135], v[220:223], 0
	v_mfma_i32_16x16x64_i8 v[12:15], v[136:139], v[224:227], v[12:15]
	v_mfma_i32_16x16x64_i8 v[28:31], v[136:139], v[216:219], 0
	v_mfma_i32_16x16x64_i8 v[28:31], v[132:135], v[212:215], v[28:31]
	v_mfma_i32_16x16x64_i8 v[44:47], v[132:135], v[204:207], 0
	v_mfma_i32_16x16x64_i8 v[44:47], v[136:139], v[208:211], v[44:47]
	v_mfma_i32_16x16x64_i8 v[60:63], v[136:139], v[186:189], 0
	v_mfma_i32_16x16x64_i8 v[60:63], v[132:135], v[182:185], v[60:63]
	v_mfma_i32_16x16x64_i8 v[56:59], v[160:163], v[182:185], 0
	v_mfma_i32_16x16x64_i8 v[56:59], v[164:167], v[186:189], v[56:59]
	v_mfma_i32_16x16x64_i8 v[40:43], v[164:167], v[208:211], 0
	v_mfma_i32_16x16x64_i8 v[40:43], v[160:163], v[204:207], v[40:43]
	v_mfma_i32_16x16x64_i8 v[24:27], v[160:163], v[212:215], 0
	v_mfma_i32_16x16x64_i8 v[24:27], v[164:167], v[216:219], v[24:27]
	v_mfma_i32_16x16x64_i8 v[8:11], v[164:167], v[224:227], 0
	v_mfma_i32_16x16x64_i8 v[8:11], v[160:163], v[220:223], v[8:11]
	v_mfma_i32_16x16x64_i8 v[4:7], v[168:171], v[220:223], 0
	v_mfma_i32_16x16x64_i8 v[4:7], v[178:181], v[224:227], v[4:7]
	v_mfma_i32_16x16x64_i8 v[20:23], v[178:181], v[216:219], 0
	v_mfma_i32_16x16x64_i8 v[20:23], v[168:171], v[212:215], v[20:23]
	v_mfma_i32_16x16x64_i8 v[36:39], v[168:171], v[204:207], 0
	v_mfma_i32_16x16x64_i8 v[36:39], v[178:181], v[208:211], v[36:39]
	v_mfma_i32_16x16x64_i8 v[52:55], v[178:181], v[186:189], 0
	v_mfma_i32_16x16x64_i8 v[52:55], v[168:171], v[182:185], v[52:55]
	s_setprio 0
	s_barrier
	s_add_i32 s50, 0, 0x18000
	s_add_i32 s51, 0, 0x1c000
	v_add_u32_e32 v136, s50, v175
	v_add_u32_e32 v178, s51, v175
	ds_read_b128 v[116:119], v136
	ds_read_b128 v[124:127], v136 offset:1024
	ds_read_b128 v[132:135], v136 offset:2048
	ds_read_b128 v[136:139], v136 offset:3072
	ds_read_b128 v[160:163], v178
	ds_read_b128 v[164:167], v178 offset:1024
	ds_read_b128 v[168:171], v178 offset:2048
	ds_read_b128 v[178:181], v178 offset:3072
	s_add_u32 s40, s40, 0x80000
	s_addc_u32 s41, s41, 0
	s_mov_b32 m0, s46
	v_lshl_add_u64 v[242:243], s[40:41], 0, v[152:153]
	ds_read_b128 v[182:185], v177 offset:32768
	ds_read_b128 v[186:189], v177 offset:33792
	ds_read_b128 v[204:207], v177 offset:34816
	ds_read_b128 v[208:211], v177 offset:35840
	ds_read_b128 v[212:215], v177 offset:36864
	ds_read_b128 v[216:219], v177 offset:37888
	ds_read_b128 v[220:223], v177 offset:38912
	ds_read_b128 v[224:227], v177 offset:39936
	global_load_lds_dwordx4 v[242:243], off
	v_lshl_add_u64 v[242:243], s[40:41], 0, v[150:151]
	s_mov_b32 m0, s47
	s_nop 0
	global_load_lds_dwordx4 v[242:243], off
	s_waitcnt vmcnt(8)
	s_waitcnt lgkmcnt(0)
	s_barrier
	s_setprio 1
	s_waitcnt lgkmcnt(0)
	v_mfma_i32_16x16x64_i8 v[144:147], v[116:119], v[182:185], v[144:147]
	v_mfma_i32_16x16x64_i8 v[144:147], v[124:127], v[186:189], v[144:147]
	v_mfma_i32_16x16x64_i8 v[112:115], v[124:127], v[208:211], v[112:115]
	v_mfma_i32_16x16x64_i8 v[112:115], v[116:119], v[204:207], v[112:115]
	v_mfma_i32_16x16x64_i8 v[96:99], v[116:119], v[212:215], v[96:99]
	v_mfma_i32_16x16x64_i8 v[96:99], v[124:127], v[216:219], v[96:99]
	v_mfma_i32_16x16x64_i8 v[80:83], v[124:127], v[224:227], v[80:83]
	v_mfma_i32_16x16x64_i8 v[80:83], v[116:119], v[220:223], v[80:83]
	v_mfma_i32_16x16x64_i8 v[76:79], v[132:135], v[220:223], v[76:79]
	v_mfma_i32_16x16x64_i8 v[76:79], v[136:139], v[224:227], v[76:79]
	v_mfma_i32_16x16x64_i8 v[92:95], v[136:139], v[216:219], v[92:95]
	v_mfma_i32_16x16x64_i8 v[92:95], v[132:135], v[212:215], v[92:95]
	v_mfma_i32_16x16x64_i8 v[108:111], v[132:135], v[204:207], v[108:111]
	v_mfma_i32_16x16x64_i8 v[108:111], v[136:139], v[208:211], v[108:111]
	v_mfma_i32_16x16x64_i8 v[140:143], v[136:139], v[186:189], v[140:143]
	v_mfma_i32_16x16x64_i8 v[140:143], v[132:135], v[182:185], v[140:143]
	v_mfma_i32_16x16x64_i8 v[128:131], v[160:163], v[182:185], v[128:131]
	v_mfma_i32_16x16x64_i8 v[128:131], v[164:167], v[186:189], v[128:131]
	v_mfma_i32_16x16x64_i8 v[104:107], v[164:167], v[208:211], v[104:107]
	v_mfma_i32_16x16x64_i8 v[104:107], v[160:163], v[204:207], v[104:107]
	v_mfma_i32_16x16x64_i8 v[88:91], v[160:163], v[212:215], v[88:91]
	v_mfma_i32_16x16x64_i8 v[88:91], v[164:167], v[216:219], v[88:91]
	v_mfma_i32_16x16x64_i8 v[72:75], v[164:167], v[224:227], v[72:75]
	v_mfma_i32_16x16x64_i8 v[72:75], v[160:163], v[220:223], v[72:75]
	v_mfma_i32_16x16x64_i8 v[68:71], v[168:171], v[220:223], v[68:71]
	v_mfma_i32_16x16x64_i8 v[68:71], v[178:181], v[224:227], v[68:71]
	v_mfma_i32_16x16x64_i8 v[84:87], v[178:181], v[216:219], v[84:87]
	v_mfma_i32_16x16x64_i8 v[84:87], v[168:171], v[212:215], v[84:87]
	v_mfma_i32_16x16x64_i8 v[100:103], v[168:171], v[204:207], v[100:103]
	v_mfma_i32_16x16x64_i8 v[100:103], v[178:181], v[208:211], v[100:103]
	v_mfma_i32_16x16x64_i8 v[120:123], v[178:181], v[186:189], v[120:123]
	v_mfma_i32_16x16x64_i8 v[120:123], v[168:171], v[182:185], v[120:123]
	s_setprio 0
	s_barrier
; #define PG8_STAGE(bufoff, gbase, voff) do { _Pragma("unroll") for (int _i = 0; _i < 2; ++_i) \
;         __builtin_amdgcn_global_load_lds((const unsigned*)((const char*)(gbase) + (voff)[_i]), (PG8_LAS unsigned*)(lds + (bufoff) + ldsw + _i * 8192), 16, 0, 0); } while (0)
; #define PG8_LDA(dst, b, h) do { _Pragma("unroll") for (int m = 0; m < 4; ++m) _Pragma("unroll") for (int k = 0; k < 2; ++k) dst[m][k] = *(const PG8_LAS bf16x8*)(lds + PG8_SA(b, h) + aoff + m * 2048 + k * 1024); } while (0)
; #define PG8_LDB(dst, b, h) do { _Pragma("unroll") for (int n = 0; n < 2; ++n) _Pragma("unroll") for (int k = 0; k < 2; ++k) dst[n][k] = *(const PG8_LAS bf16x8*)(lds + PG8_SB(b, h) + boff + n * 2048 + k * 1024); } while (0)
; #define PG8_WAIT_V(n) asm volatile("s_waitcnt vmcnt(" #n ")" ::: "memory")
; template <class Epi, class Sched, bool ALIGN_EPI = false, bool SP2 = false, bool I8 = false>
; __device__ __forceinline__ void gemm_phase(PG8_LAS unsigned char* lds, const Gemm g, const Sched& S, const Epi& E) {
;     ...
;             const char* a1 = cA + (size_t)(t + 1) * kstep;
;             const char* a2 = last ? nA : cA + (size_t)(t + 2) * kstep; const char* b2 = last ? nB : cB + (size_t)(t + 2) * kstep;
;             const char* a3 = a2 + kstep; const char* b3 = b2 + kstep;
;             if (last && has_next) S.a_ready(nxt);
;             if constexpr (SP2) {
;             PG8_LDB(B0, 0, 0); PG8_LDB(B1, 0, 1); PG8_SCHED; PG8_LDA(At, 0, 0); PG8_STAGE(PG8_SA(1, 1), a1 + hstep, voffA);
;             PG8_WAIT_V(8); PG8_WAIT_L(0); PG8_BAR; PG8_MMA(0, 0, At, B0); PG8_MMA(0, 1, At, B1); PG8_BAR; PG8_SCHED;
;             PG8_LDA(At, 0, 1); PG8_STAGE(PG8_SB(0, 0), b2, voffB); PG8_STAGE(PG8_SB(0, 1), b2 + hstep, voffB); PG8_STAGE(PG8_SA(0, 0), a2, voffA);
;             PG8_WAIT_V(8); PG8_WAIT_L(0); PG8_BAR; PG8_MMA(1, 0, At, B0); PG8_MMA(1, 1, At, B1); PG8_BAR; PG8_SCHED;
;             PG8_LDB(B0, 1, 0); PG8_LDB(B1, 1, 1); PG8_SCHED; PG8_LDA(At, 1, 0); PG8_STAGE(PG8_SA(0, 1), a2 + hstep, voffA);
;             PG8_WAIT_V(8); PG8_WAIT_L(0); PG8_BAR; PG8_MMA(0, 0, At, B0); PG8_MMA(0, 1, At, B1); PG8_BAR; PG8_SCHED;
;             PG8_LDA(At, 1, 1); PG8_STAGE(PG8_SB(1, 0), b3, voffB); PG8_STAGE(PG8_SB(1, 1), b3 + hstep, voffB); PG8_STAGE(PG8_SA(1, 0), a3, voffA);
;             PG8_WAIT_V(8); PG8_WAIT_L(0); PG8_BAR; PG8_MMA(1, 0, At, B0); PG8_MMA(1, 1, At, B1); PG8_BAR; PG8_SCHED;
	s_add_i32 s40, s50, s43
	v_lshl_add_u64 v[172:173], v[172:173], 0, s[84:85]
	s_mov_b32 m0, s40
	ds_read_b128 v[182:185], v177 offset:49152
	ds_read_b128 v[186:189], v177 offset:50176
	ds_read_b128 v[204:207], v177 offset:51200
	ds_read_b128 v[208:211], v177 offset:52224
	ds_read_b128 v[212:215], v177 offset:53248
	ds_read_b128 v[216:219], v177 offset:54272
	ds_read_b128 v[220:223], v177 offset:55296
	ds_read_b128 v[224:227], v177 offset:56320
	global_load_lds_dwordx4 v[172:173], off
	s_add_i32 m0, s40, 0x2000
	s_add_u32 s36, s36, 0x80080
	v_lshl_add_u64 v[172:173], v[190:191], 0, s[84:85]
	s_addc_u32 s37, s37, 0
	s_add_i32 s40, s51, s43
	global_load_lds_dwordx4 v[172:173], off
	v_lshl_add_u64 v[172:173], s[36:37], 0, v[2:3]
	s_mov_b32 m0, s40
	s_nop 0
	global_load_lds_dwordx4 v[172:173], off
	v_lshl_add_u64 v[172:173], s[36:37], 0, v[148:149]
	s_add_i32 m0, s40, 0x2000
	s_nop 0
	global_load_lds_dwordx4 v[172:173], off
	v_lshl_add_u64 v[172:173], v[228:229], 0, s[84:85]
	s_mov_b32 m0, s52
	s_nop 0
	global_load_lds_dwordx4 v[172:173], off
	v_lshl_add_u64 v[172:173], v[240:241], 0, s[84:85]
	s_mov_b32 m0, s53
	s_nop 0
	global_load_lds_dwordx4 v[172:173], off
	s_waitcnt vmcnt(8)
	s_waitcnt lgkmcnt(0)
	s_barrier
	s_setprio 1
	s_waitcnt lgkmcnt(0)
	v_mfma_i32_16x16x64_i8 v[64:67], v[116:119], v[182:185], v[64:67]
	v_mfma_i32_16x16x64_i8 v[64:67], v[124:127], v[186:189], v[64:67]
	v_mfma_i32_16x16x64_i8 v[48:51], v[124:127], v[208:211], v[48:51]
	v_mfma_i32_16x16x64_i8 v[48:51], v[116:119], v[204:207], v[48:51]
	v_mfma_i32_16x16x64_i8 v[32:35], v[116:119], v[212:215], v[32:35]
	v_mfma_i32_16x16x64_i8 v[32:35], v[124:127], v[216:219], v[32:35]
	v_mfma_i32_16x16x64_i8 v[16:19], v[124:127], v[224:227], v[16:19]
	v_mfma_i32_16x16x64_i8 v[16:19], v[116:119], v[220:223], v[16:19]
	v_mfma_i32_16x16x64_i8 v[12:15], v[132:135], v[220:223], v[12:15]
	v_mfma_i32_16x16x64_i8 v[12:15], v[136:139], v[224:227], v[12:15]
	v_mfma_i32_16x16x64_i8 v[28:31], v[136:139], v[216:219], v[28:31]
	v_mfma_i32_16x16x64_i8 v[28:31], v[132:135], v[212:215], v[28:31]
	v_mfma_i32_16x16x64_i8 v[44:47], v[132:135], v[204:207], v[44:47]
	v_mfma_i32_16x16x64_i8 v[44:47], v[136:139], v[208:211], v[44:47]
	v_mfma_i32_16x16x64_i8 v[60:63], v[136:139], v[186:189], v[60:63]
	v_mfma_i32_16x16x64_i8 v[60:63], v[132:135], v[182:185], v[60:63]
	v_mfma_i32_16x16x64_i8 v[56:59], v[160:163], v[182:185], v[56:59]
	v_mfma_i32_16x16x64_i8 v[56:59], v[164:167], v[186:189], v[56:59]
	v_mfma_i32_16x16x64_i8 v[40:43], v[164:167], v[208:211], v[40:43]
	v_mfma_i32_16x16x64_i8 v[40:43], v[160:163], v[204:207], v[40:43]
	v_mfma_i32_16x16x64_i8 v[24:27], v[160:163], v[212:215], v[24:27]
	v_mfma_i32_16x16x64_i8 v[24:27], v[164:167], v[216:219], v[24:27]
	v_mfma_i32_16x16x64_i8 v[8:11], v[164:167], v[224:227], v[8:11]
	v_mfma_i32_16x16x64_i8 v[8:11], v[160:163], v[220:223], v[8:11]
	v_mfma_i32_16x16x64_i8 v[4:7], v[168:171], v[220:223], v[4:7]
	v_mfma_i32_16x16x64_i8 v[4:7], v[178:181], v[224:227], v[4:7]
	v_mfma_i32_16x16x64_i8 v[20:23], v[178:181], v[216:219], v[20:23]
	v_mfma_i32_16x16x64_i8 v[20:23], v[168:171], v[212:215], v[20:23]
	v_mfma_i32_16x16x64_i8 v[36:39], v[168:171], v[204:207], v[36:39]
	v_mfma_i32_16x16x64_i8 v[36:39], v[178:181], v[208:211], v[36:39]
	v_mfma_i32_16x16x64_i8 v[52:55], v[178:181], v[186:189], v[52:55]
	v_mfma_i32_16x16x64_i8 v[52:55], v[168:171], v[182:185], v[52:55]
	s_setprio 0
	s_add_i32 s76, s76, 2
	s_add_u32 s26, s26, 0x100
	s_addc_u32 s27, s27, 0
	s_add_u32 s72, s72, 0x100
	s_addc_u32 s73, s73, 0
	s_cmp_gt_u32 s76, 29
	s_barrier
	s_cbranch_scc1 .Lkloop_exit_0
.LBB0_208:
	s_add_u32 s36, s26, 0xfff80080
	s_addc_u32 s37, s27, -1
	s_add_i32 s50, 0, 0x10000
	s_cmp_eq_u32 s76, 28
	s_cselect_b32 s41, s19, s37
	s_cselect_b32 s40, s64, s36
	s_cselect_b32 s37, s17, s73
	s_cselect_b32 s36, s65, s72
	s_add_i32 s56, 0, 0x14000
	v_add_u32_e32 v136, s50, v175
	v_add_u32_e32 v172, s56, v175
	ds_read_b128 v[116:119], v136
	ds_read_b128 v[124:127], v136 offset:1024
	ds_read_b128 v[132:135], v136 offset:2048
	ds_read_b128 v[136:139], v136 offset:3072
	ds_read_b128 v[160:163], v172
	ds_read_b128 v[164:167], v172 offset:1024
	ds_read_b128 v[168:171], v172 offset:2048
	ds_read_b128 v[178:181], v172 offset:3072
	v_lshl_add_u64 v[172:173], s[26:27], 0, v[156:157]
	s_add_i32 m0, s44, 0xc000
	ds_read_b128 v[182:185], v177
	ds_read_b128 v[186:189], v177 offset:1024
	ds_read_b128 v[204:207], v177 offset:2048
	ds_read_b128 v[208:211], v177 offset:3072
	ds_read_b128 v[212:215], v177 offset:4096
	ds_read_b128 v[216:219], v177 offset:5120
	ds_read_b128 v[220:223], v177 offset:6144
	ds_read_b128 v[224:227], v177 offset:7168
	global_load_lds_dwordx4 v[172:173], off
	v_lshl_add_u64 v[172:173], s[26:27], 0, v[158:159]
	s_add_i32 m0, s44, 0xe000
	s_nop 0
	global_load_lds_dwordx4 v[172:173], off
	s_waitcnt vmcnt(8)
	s_waitcnt lgkmcnt(0)
	s_barrier
; #define PG8_STAGE(bufoff, gbase, voff) do { _Pragma("unroll") for (int _i = 0; _i < 2; ++_i) \
;         __builtin_amdgcn_global_load_lds((const unsigned*)((const char*)(gbase) + (voff)[_i]), (PG8_LAS unsigned*)(lds + (bufoff) + ldsw + _i * 8192), 16, 0, 0); } while (0)
; #define PG8_LDA(dst, b, h) do { _Pragma("unroll") for (int m = 0; m < 4; ++m) _Pragma("unroll") for (int k = 0; k < 2; ++k) dst[m][k] = *(const PG8_LAS bf16x8*)(lds + PG8_SA(b, h) + aoff + m * 2048 + k * 1024); } while (0)
; #define PG8_LDB(dst, b, h) do { _Pragma("unroll") for (int n = 0; n < 2; ++n) _Pragma("unroll") for (int k = 0; k < 2; ++k) dst[n][k] = *(const PG8_LAS bf16x8*)(lds + PG8_SB(b, h) + boff + n * 2048 + k * 1024); } while (0)
; #define PG8_WAIT_V(n) asm volatile("s_waitcnt vmcnt(" #n ")" ::: "memory")
; #define PG8_WAIT_L(n) asm volatile("s_waitcnt lgkmcnt(" #n ")" ::: "memory")
; #define PG8_BAR __builtin_amdgcn_s_barrier()
; #define PG8_SCHED __builtin_amdgcn_sched_barrier(0)
; template <class Epi, class Sched, bool ALIGN_EPI = false, bool SP2 = false, bool I8 = false>
; __device__ __forceinline__ void gemm_phase(PG8_LAS unsigned char* lds, const Gemm g, const Sched& S, const Epi& E) {
;     ...
;             PG8_WAIT_V(8); PG8_WAIT_L(0); PG8_BAR; PG8_MMA(0, 0, At, B0); PG8_MMA(0, 1, At, B1); PG8_BAR; PG8_SCHED;
;             PG8_LDA(At, 0, 1); PG8_STAGE(PG8_SB(0, 0), b2, voffB); PG8_STAGE(PG8_SB(0, 1), b2 + hstep, voffB); PG8_STAGE(PG8_SA(0, 0), a2, voffA);
;             PG8_WAIT_V(8); PG8_WAIT_L(0); PG8_BAR; PG8_MMA(1, 0, At, B0); PG8_MMA(1, 1, At, B1); PG8_BAR; PG8_SCHED;
;             PG8_LDB(B0, 1, 0); PG8_LDB(B1, 1, 1); PG8_SCHED; PG8_LDA(At, 1, 0); PG8_STAGE(PG8_SA(0, 1), a2 + hstep, voffA);
;             PG8_WAIT_V(8); PG8_WAIT_L(0); PG8_BAR; PG8_MMA(0, 0, At, B0); PG8_MMA(0, 1, At, B1); PG8_BAR; PG8_SCHED;
	s_setprio 1
	s_waitcnt lgkmcnt(0)
	v_mfma_i32_16x16x64_i8 v[144:147], v[116:119], v[182:185], v[144:147]
	v_mfma_i32_16x16x64_i8 v[144:147], v[124:127], v[186:189], v[144:147]
	v_mfma_i32_16x16x64_i8 v[112:115], v[124:127], v[208:211], v[112:115]
	v_mfma_i32_16x16x64_i8 v[112:115], v[116:119], v[204:207], v[112:115]
	v_mfma_i32_16x16x64_i8 v[96:99], v[116:119], v[212:215], v[96:99]
	v_mfma_i32_16x16x64_i8 v[96:99], v[124:127], v[216:219], v[96:99]
	v_mfma_i32_16x16x64_i8 v[80:83], v[124:127], v[224:227], v[80:83]
	v_mfma_i32_16x16x64_i8 v[80:83], v[116:119], v[220:223], v[80:83]
	v_mfma_i32_16x16x64_i8 v[76:79], v[132:135], v[220:223], v[76:79]
	v_mfma_i32_16x16x64_i8 v[76:79], v[136:139], v[224:227], v[76:79]
	v_mfma_i32_16x16x64_i8 v[92:95], v[136:139], v[216:219], v[92:95]
	v_mfma_i32_16x16x64_i8 v[92:95], v[132:135], v[212:215], v[92:95]
	v_mfma_i32_16x16x64_i8 v[108:111], v[132:135], v[204:207], v[108:111]
	v_mfma_i32_16x16x64_i8 v[108:111], v[136:139], v[208:211], v[108:111]
	v_mfma_i32_16x16x64_i8 v[140:143], v[136:139], v[186:189], v[140:143]
	v_mfma_i32_16x16x64_i8 v[140:143], v[132:135], v[182:185], v[140:143]
	v_mfma_i32_16x16x64_i8 v[128:131], v[160:163], v[182:185], v[128:131]
	v_mfma_i32_16x16x64_i8 v[128:131], v[164:167], v[186:189], v[128:131]
	v_mfma_i32_16x16x64_i8 v[104:107], v[164:167], v[208:211], v[104:107]
	v_mfma_i32_16x16x64_i8 v[104:107], v[160:163], v[204:207], v[104:107]
	v_mfma_i32_16x16x64_i8 v[88:91], v[160:163], v[212:215], v[88:91]
	v_mfma_i32_16x16x64_i8 v[88:91], v[164:167], v[216:219], v[88:91]
	v_mfma_i32_16x16x64_i8 v[72:75], v[164:167], v[224:227], v[72:75]
	v_mfma_i32_16x16x64_i8 v[72:75], v[160:163], v[220:223], v[72:75]
	v_mfma_i32_16x16x64_i8 v[68:71], v[168:171], v[220:223], v[68:71]
	v_mfma_i32_16x16x64_i8 v[68:71], v[178:181], v[224:227], v[68:71]
	v_mfma_i32_16x16x64_i8 v[84:87], v[178:181], v[216:219], v[84:87]
	v_mfma_i32_16x16x64_i8 v[84:87], v[168:171], v[212:215], v[84:87]
	v_mfma_i32_16x16x64_i8 v[100:103], v[168:171], v[204:207], v[100:103]
	v_mfma_i32_16x16x64_i8 v[100:103], v[178:181], v[208:211], v[100:103]
	v_mfma_i32_16x16x64_i8 v[120:123], v[178:181], v[186:189], v[120:123]
	v_mfma_i32_16x16x64_i8 v[120:123], v[168:171], v[182:185], v[120:123]
	s_setprio 0
	s_barrier
	s_add_i32 s50, s50, s43
	v_lshl_add_u64 v[172:173], s[36:37], 0, v[2:3]
	s_mov_b32 m0, s50
	ds_read_b128 v[182:185], v177 offset:16384
	ds_read_b128 v[186:189], v177 offset:17408
	ds_read_b128 v[204:207], v177 offset:18432
	ds_read_b128 v[208:211], v177 offset:19456
	ds_read_b128 v[212:215], v177 offset:20480
	ds_read_b128 v[216:219], v177 offset:21504
	ds_read_b128 v[220:223], v177 offset:22528
	ds_read_b128 v[224:227], v177 offset:23552
	global_load_lds_dwordx4 v[172:173], off
	s_add_i32 m0, s50, 0x2000
	s_add_u32 s50, s36, 0x80000
	v_lshl_add_u64 v[190:191], s[36:37], 0, v[148:149]
	s_addc_u32 s51, s37, 0
	s_add_i32 s56, s56, s43
	global_load_lds_dwordx4 v[190:191], off
	v_lshl_add_u64 v[228:229], s[50:51], 0, v[2:3]
	s_mov_b32 m0, s56
	v_lshl_add_u64 v[240:241], s[40:41], 0, v[150:151]
	global_load_lds_dwordx4 v[228:229], off
	v_lshl_add_u64 v[228:229], s[50:51], 0, v[148:149]
	s_add_i32 m0, s56, 0x2000
	s_nop 0
	global_load_lds_dwordx4 v[228:229], off
	v_lshl_add_u64 v[228:229], s[40:41], 0, v[152:153]
	s_mov_b32 m0, s44
	s_nop 0
	global_load_lds_dwordx4 v[228:229], off
	s_mov_b32 m0, s45
	s_nop 0
	global_load_lds_dwordx4 v[240:241], off
	s_waitcnt vmcnt(8)
	s_waitcnt lgkmcnt(0)
	s_barrier
	s_setprio 1
	s_waitcnt lgkmcnt(0)
	v_mfma_i32_16x16x64_i8 v[64:67], v[116:119], v[182:185], v[64:67]
	v_mfma_i32_16x16x64_i8 v[64:67], v[124:127], v[186:189], v[64:67]
	v_mfma_i32_16x16x64_i8 v[48:51], v[124:127], v[208:211], v[48:51]
	v_mfma_i32_16x16x64_i8 v[48:51], v[116:119], v[204:207], v[48:51]
	v_mfma_i32_16x16x64_i8 v[32:35], v[116:119], v[212:215], v[32:35]
	v_mfma_i32_16x16x64_i8 v[32:35], v[124:127], v[216:219], v[32:35]
	v_mfma_i32_16x16x64_i8 v[16:19], v[124:127], v[224:227], v[16:19]
	v_mfma_i32_16x16x64_i8 v[16:19], v[116:119], v[220:223], v[16:19]
	v_mfma_i32_16x16x64_i8 v[12:15], v[132:135], v[220:223], v[12:15]
	v_mfma_i32_16x16x64_i8 v[12:15], v[136:139], v[224:227], v[12:15]
	v_mfma_i32_16x16x64_i8 v[28:31], v[136:139], v[216:219], v[28:31]
	v_mfma_i32_16x16x64_i8 v[28:31], v[132:135], v[212:215], v[28:31]
	v_mfma_i32_16x16x64_i8 v[44:47], v[132:135], v[204:207], v[44:47]
	v_mfma_i32_16x16x64_i8 v[44:47], v[136:139], v[208:211], v[44:47]
	v_mfma_i32_16x16x64_i8 v[60:63], v[136:139], v[186:189], v[60:63]
	v_mfma_i32_16x16x64_i8 v[60:63], v[132:135], v[182:185], v[60:63]
	v_mfma_i32_16x16x64_i8 v[56:59], v[160:163], v[182:185], v[56:59]
	v_mfma_i32_16x16x64_i8 v[56:59], v[164:167], v[186:189], v[56:59]
	v_mfma_i32_16x16x64_i8 v[40:43], v[164:167], v[208:211], v[40:43]
	v_mfma_i32_16x16x64_i8 v[40:43], v[160:163], v[204:207], v[40:43]
	v_mfma_i32_16x16x64_i8 v[24:27], v[160:163], v[212:215], v[24:27]
	v_mfma_i32_16x16x64_i8 v[24:27], v[164:167], v[216:219], v[24:27]
	v_mfma_i32_16x16x64_i8 v[8:11], v[164:167], v[224:227], v[8:11]
	v_mfma_i32_16x16x64_i8 v[8:11], v[160:163], v[220:223], v[8:11]
	v_mfma_i32_16x16x64_i8 v[4:7], v[168:171], v[220:223], v[4:7]
	v_mfma_i32_16x16x64_i8 v[4:7], v[178:181], v[224:227], v[4:7]
	v_mfma_i32_16x16x64_i8 v[20:23], v[178:181], v[216:219], v[20:23]
	v_mfma_i32_16x16x64_i8 v[20:23], v[168:171], v[212:215], v[20:23]
	v_mfma_i32_16x16x64_i8 v[36:39], v[168:171], v[204:207], v[36:39]
	v_mfma_i32_16x16x64_i8 v[36:39], v[178:181], v[208:211], v[36:39]
	v_mfma_i32_16x16x64_i8 v[52:55], v[178:181], v[186:189], v[52:55]
	v_mfma_i32_16x16x64_i8 v[52:55], v[168:171], v[182:185], v[52:55]
	s_setprio 0
	s_barrier
; #define PG8_STAGE(bufoff, gbase, voff) do { _Pragma("unroll") for (int _i = 0; _i < 2; ++_i) \
;         __builtin_amdgcn_global_load_lds((const unsigned*)((const char*)(gbase) + (voff)[_i]), (PG8_LAS unsigned*)(lds + (bufoff) + ldsw + _i * 8192), 16, 0, 0); } while (0)
; #define PG8_LDA(dst, b, h) do { _Pragma("unroll") for (int m = 0; m < 4; ++m) _Pragma("unroll") for (int k = 0; k < 2; ++k) dst[m][k] = *(const PG8_LAS bf16x8*)(lds + PG8_SA(b, h) + aoff + m * 2048 + k * 1024); } while (0)
; #define PG8_LDB(dst, b, h) do { _Pragma("unroll") for (int n = 0; n < 2; ++n) _Pragma("unroll") for (int k = 0; k < 2; ++k) dst[n][k] = *(const PG8_LAS bf16x8*)(lds + PG8_SB(b, h) + boff + n * 2048 + k * 1024); } while (0)
; #define PG8_WAIT_V(n) asm volatile("s_waitcnt vmcnt(" #n ")" ::: "memory")
; #define PG8_WAIT_L(n) asm volatile("s_waitcnt lgkmcnt(" #n ")" ::: "memory")
; #define PG8_BAR __builtin_amdgcn_s_barrier()
; #define PG8_SCHED __builtin_amdgcn_sched_barrier(0)
; template <class Epi, class Sched, bool ALIGN_EPI = false, bool SP2 = false, bool I8 = false>
; __device__ __forceinline__ void gemm_phase(PG8_LAS unsigned char* lds, const Gemm g, const Sched& S, const Epi& E) {
;     ...
;             PG8_LDB(B0, 1, 0); PG8_LDB(B1, 1, 1); PG8_SCHED; PG8_LDA(At, 1, 0); PG8_STAGE(PG8_SA(0, 1), a2 + hstep, voffA);
;             PG8_WAIT_V(8); PG8_WAIT_L(0); PG8_BAR; PG8_MMA(0, 0, At, B0); PG8_MMA(0, 1, At, B1); PG8_BAR; PG8_SCHED;
;             PG8_LDA(At, 1, 1); PG8_STAGE(PG8_SB(1, 0), b3, voffB); PG8_STAGE(PG8_SB(1, 1), b3 + hstep, voffB); PG8_STAGE(PG8_SA(1, 0), a3, voffA);
;             PG8_WAIT_V(8); PG8_WAIT_L(0); PG8_BAR; PG8_MMA(1, 0, At, B0); PG8_MMA(1, 1, At, B1); PG8_BAR; PG8_SCHED;
	s_add_i32 s50, 0, 0x18000
	s_add_i32 s51, 0, 0x1c000
	v_add_u32_e32 v136, s50, v175
	v_add_u32_e32 v178, s51, v175
	ds_read_b128 v[116:119], v136
	ds_read_b128 v[124:127], v136 offset:1024
	ds_read_b128 v[132:135], v136 offset:2048
	ds_read_b128 v[136:139], v136 offset:3072
	ds_read_b128 v[160:163], v178
	ds_read_b128 v[164:167], v178 offset:1024
	ds_read_b128 v[168:171], v178 offset:2048
	ds_read_b128 v[178:181], v178 offset:3072
	s_add_u32 s40, s40, 0x80000
	s_addc_u32 s41, s41, 0
	s_mov_b32 m0, s46
	v_lshl_add_u64 v[242:243], s[40:41], 0, v[152:153]
	ds_read_b128 v[182:185], v177 offset:32768
	ds_read_b128 v[186:189], v177 offset:33792
	ds_read_b128 v[204:207], v177 offset:34816
	ds_read_b128 v[208:211], v177 offset:35840
	ds_read_b128 v[212:215], v177 offset:36864
	ds_read_b128 v[216:219], v177 offset:37888
	ds_read_b128 v[220:223], v177 offset:38912
	ds_read_b128 v[224:227], v177 offset:39936
	global_load_lds_dwordx4 v[242:243], off
	v_lshl_add_u64 v[242:243], s[40:41], 0, v[150:151]
	s_mov_b32 m0, s47
	s_nop 0
	global_load_lds_dwordx4 v[242:243], off
	s_waitcnt vmcnt(8)
	s_waitcnt lgkmcnt(0)
	s_barrier
	s_setprio 1
	s_waitcnt lgkmcnt(0)
	v_mfma_i32_16x16x64_i8 v[144:147], v[116:119], v[182:185], v[144:147]
	v_mfma_i32_16x16x64_i8 v[144:147], v[124:127], v[186:189], v[144:147]
	v_mfma_i32_16x16x64_i8 v[112:115], v[124:127], v[208:211], v[112:115]
	v_mfma_i32_16x16x64_i8 v[112:115], v[116:119], v[204:207], v[112:115]
	v_mfma_i32_16x16x64_i8 v[96:99], v[116:119], v[212:215], v[96:99]
	v_mfma_i32_16x16x64_i8 v[96:99], v[124:127], v[216:219], v[96:99]
	v_mfma_i32_16x16x64_i8 v[80:83], v[124:127], v[224:227], v[80:83]
	v_mfma_i32_16x16x64_i8 v[80:83], v[116:119], v[220:223], v[80:83]
	v_mfma_i32_16x16x64_i8 v[76:79], v[132:135], v[220:223], v[76:79]
	v_mfma_i32_16x16x64_i8 v[76:79], v[136:139], v[224:227], v[76:79]
	v_mfma_i32_16x16x64_i8 v[92:95], v[136:139], v[216:219], v[92:95]
	v_mfma_i32_16x16x64_i8 v[92:95], v[132:135], v[212:215], v[92:95]
	v_mfma_i32_16x16x64_i8 v[108:111], v[132:135], v[204:207], v[108:111]
	v_mfma_i32_16x16x64_i8 v[108:111], v[136:139], v[208:211], v[108:111]
	v_mfma_i32_16x16x64_i8 v[140:143], v[136:139], v[186:189], v[140:143]
	v_mfma_i32_16x16x64_i8 v[140:143], v[132:135], v[182:185], v[140:143]
	v_mfma_i32_16x16x64_i8 v[128:131], v[160:163], v[182:185], v[128:131]
	v_mfma_i32_16x16x64_i8 v[128:131], v[164:167], v[186:189], v[128:131]
	v_mfma_i32_16x16x64_i8 v[104:107], v[164:167], v[208:211], v[104:107]
	v_mfma_i32_16x16x64_i8 v[104:107], v[160:163], v[204:207], v[104:107]
	v_mfma_i32_16x16x64_i8 v[88:91], v[160:163], v[212:215], v[88:91]
	v_mfma_i32_16x16x64_i8 v[88:91], v[164:167], v[216:219], v[88:91]
	v_mfma_i32_16x16x64_i8 v[72:75], v[164:167], v[224:227], v[72:75]
	v_mfma_i32_16x16x64_i8 v[72:75], v[160:163], v[220:223], v[72:75]
	v_mfma_i32_16x16x64_i8 v[68:71], v[168:171], v[220:223], v[68:71]
	v_mfma_i32_16x16x64_i8 v[68:71], v[178:181], v[224:227], v[68:71]
	v_mfma_i32_16x16x64_i8 v[84:87], v[178:181], v[216:219], v[84:87]
	v_mfma_i32_16x16x64_i8 v[84:87], v[168:171], v[212:215], v[84:87]
	v_mfma_i32_16x16x64_i8 v[100:103], v[168:171], v[204:207], v[100:103]
	v_mfma_i32_16x16x64_i8 v[100:103], v[178:181], v[208:211], v[100:103]
	v_mfma_i32_16x16x64_i8 v[120:123], v[178:181], v[186:189], v[120:123]
	v_mfma_i32_16x16x64_i8 v[120:123], v[168:171], v[182:185], v[120:123]
	s_setprio 0
	s_barrier
	s_add_i32 s40, s50, s43
	v_lshl_add_u64 v[172:173], v[172:173], 0, s[84:85]
	s_mov_b32 m0, s40
	ds_read_b128 v[182:185], v177 offset:49152
	ds_read_b128 v[186:189], v177 offset:50176
	ds_read_b128 v[204:207], v177 offset:51200
	ds_read_b128 v[208:211], v177 offset:52224
	ds_read_b128 v[212:215], v177 offset:53248
	ds_read_b128 v[216:219], v177 offset:54272
	ds_read_b128 v[220:223], v177 offset:55296
	ds_read_b128 v[224:227], v177 offset:56320
	global_load_lds_dwordx4 v[172:173], off
	s_add_i32 m0, s40, 0x2000
	s_add_u32 s36, s36, 0x80080
	v_lshl_add_u64 v[172:173], v[190:191], 0, s[84:85]
	s_addc_u32 s37, s37, 0
	s_add_i32 s40, s51, s43
	global_load_lds_dwordx4 v[172:173], off
	v_lshl_add_u64 v[172:173], s[36:37], 0, v[2:3]
	s_mov_b32 m0, s40
	s_nop 0
	global_load_lds_dwordx4 v[172:173], off
	v_lshl_add_u64 v[172:173], s[36:37], 0, v[148:149]
	s_add_i32 m0, s40, 0x2000
	s_nop 0
	global_load_lds_dwordx4 v[172:173], off
	v_lshl_add_u64 v[172:173], v[228:229], 0, s[84:85]
	s_mov_b32 m0, s52
	s_nop 0
	global_load_lds_dwordx4 v[172:173], off
	v_lshl_add_u64 v[172:173], v[240:241], 0, s[84:85]
	s_mov_b32 m0, s53
	s_nop 0
	global_load_lds_dwordx4 v[172:173], off
	s_waitcnt vmcnt(8)
	s_waitcnt lgkmcnt(0)
	s_barrier
	s_setprio 1
	s_waitcnt lgkmcnt(0)
	v_mfma_i32_16x16x64_i8 v[64:67], v[116:119], v[182:185], v[64:67]
	v_mfma_i32_16x16x64_i8 v[64:67], v[124:127], v[186:189], v[64:67]
	v_mfma_i32_16x16x64_i8 v[48:51], v[124:127], v[208:211], v[48:51]
	v_mfma_i32_16x16x64_i8 v[48:51], v[116:119], v[204:207], v[48:51]
	v_mfma_i32_16x16x64_i8 v[32:35], v[116:119], v[212:215], v[32:35]
	v_mfma_i32_16x16x64_i8 v[32:35], v[124:127], v[216:219], v[32:35]
	v_mfma_i32_16x16x64_i8 v[16:19], v[124:127], v[224:227], v[16:19]
	v_mfma_i32_16x16x64_i8 v[16:19], v[116:119], v[220:223], v[16:19]
	v_mfma_i32_16x16x64_i8 v[12:15], v[132:135], v[220:223], v[12:15]
	v_mfma_i32_16x16x64_i8 v[12:15], v[136:139], v[224:227], v[12:15]
	v_mfma_i32_16x16x64_i8 v[28:31], v[136:139], v[216:219], v[28:31]
	v_mfma_i32_16x16x64_i8 v[28:31], v[132:135], v[212:215], v[28:31]
	v_mfma_i32_16x16x64_i8 v[44:47], v[132:135], v[204:207], v[44:47]
	v_mfma_i32_16x16x64_i8 v[44:47], v[136:139], v[208:211], v[44:47]
	v_mfma_i32_16x16x64_i8 v[60:63], v[136:139], v[186:189], v[60:63]
	v_mfma_i32_16x16x64_i8 v[60:63], v[132:135], v[182:185], v[60:63]
	v_mfma_i32_16x16x64_i8 v[56:59], v[160:163], v[182:185], v[56:59]
	v_mfma_i32_16x16x64_i8 v[56:59], v[164:167], v[186:189], v[56:59]
	v_mfma_i32_16x16x64_i8 v[40:43], v[164:167], v[208:211], v[40:43]
	v_mfma_i32_16x16x64_i8 v[40:43], v[160:163], v[204:207], v[40:43]
	v_mfma_i32_16x16x64_i8 v[24:27], v[160:163], v[212:215], v[24:27]
	v_mfma_i32_16x16x64_i8 v[24:27], v[164:167], v[216:219], v[24:27]
	v_mfma_i32_16x16x64_i8 v[8:11], v[164:167], v[224:227], v[8:11]
	v_mfma_i32_16x16x64_i8 v[8:11], v[160:163], v[220:223], v[8:11]
	v_mfma_i32_16x16x64_i8 v[4:7], v[168:171], v[220:223], v[4:7]
	v_mfma_i32_16x16x64_i8 v[4:7], v[178:181], v[224:227], v[4:7]
	v_mfma_i32_16x16x64_i8 v[20:23], v[178:181], v[216:219], v[20:23]
	v_mfma_i32_16x16x64_i8 v[20:23], v[168:171], v[212:215], v[20:23]
	v_mfma_i32_16x16x64_i8 v[36:39], v[168:171], v[204:207], v[36:39]
	v_mfma_i32_16x16x64_i8 v[36:39], v[178:181], v[208:211], v[36:39]
	v_mfma_i32_16x16x64_i8 v[52:55], v[178:181], v[186:189], v[52:55]
	v_mfma_i32_16x16x64_i8 v[52:55], v[168:171], v[182:185], v[52:55]
	s_setprio 0
	s_add_i32 s76, s76, 2
	s_add_u32 s26, s26, 0x100
	s_addc_u32 s27, s27, 0
	s_add_u32 s72, s72, 0x100
	s_addc_u32 s73, s73, 0
	s_cmp_gt_u32 s76, 29
	s_barrier
	s_cbranch_scc0 .LBB0_208

; #define PG8_STAGE(bufoff, gbase, voff) do { _Pragma("unroll") for (int _i = 0; _i < 2; ++_i) \
;         __builtin_amdgcn_global_load_lds((const unsigned*)((const char*)(gbase) + (voff)[_i]), (PG8_LAS unsigned*)(lds + (bufoff) + ldsw + _i * 8192), 16, 0, 0); } while (0)
; #define PG8_LDA(dst, b, h) do { _Pragma("unroll") for (int m = 0; m < 4; ++m) _Pragma("unroll") for (int k = 0; k < 2; ++k) dst[m][k] = *(const PG8_LAS bf16x8*)(lds + PG8_SA(b, h) + aoff + m * 2048 + k * 1024); } while (0)
; #define PG8_LDB(dst, b, h) do { _Pragma("unroll") for (int n = 0; n < 2; ++n) _Pragma("unroll") for (int k = 0; k < 2; ++k) dst[n][k] = *(const PG8_LAS bf16x8*)(lds + PG8_SB(b, h) + boff + n * 2048 + k * 1024); } while (0)
; #define PG8_WAIT_V(n) asm volatile("s_waitcnt vmcnt(" #n ")" ::: "memory")
; #define PG8_WAIT_L(n) asm volatile("s_waitcnt lgkmcnt(" #n ")" ::: "memory")
; #define PG8_BAR __builtin_amdgcn_s_barrier()
; #define PG8_SCHED __builtin_amdgcn_sched_barrier(0)
; template <class Epi, class Sched, bool ALIGN_EPI = false, bool SP2 = false, bool I8 = false>
; __device__ __forceinline__ void gemm_phase(PG8_LAS unsigned char* lds, const Gemm g, const Sched& S, const Epi& E) {
;     ...
;         const char* nA = has_next ? (const char*)g.A + (size_t)nxt.pm * tstep : cA; const char* nB = has_next ? (const char*)g.Bt + (size_t)nxt.pn * tstep : cB;
;         for (int t = 0; t < nt; t += 2) {
;             const bool last = (t == nt - 2);
;             const char* a1 = cA + (size_t)(t + 1) * kstep;
;             const char* a2 = last ? nA : cA + (size_t)(t + 2) * kstep; const char* b2 = last ? nB : cB + (size_t)(t + 2) * kstep;
;             const char* a3 = a2 + kstep; const char* b3 = b2 + kstep;
;             if (last && has_next) S.a_ready(nxt);
;             if constexpr (SP2) {
;             PG8_LDB(B0, 0, 0); PG8_LDB(B1, 0, 1); PG8_SCHED; PG8_LDA(At, 0, 0); PG8_STAGE(PG8_SA(1, 1), a1 + hstep, voffA);
;             PG8_WAIT_V(8); PG8_WAIT_L(0); PG8_BAR; PG8_MMA(0, 0, At, B0); PG8_MMA(0, 1, At, B1); PG8_BAR; PG8_SCHED;
;             PG8_LDA(At, 0, 1); PG8_STAGE(PG8_SB(0, 0), b2, voffB); PG8_STAGE(PG8_SB(0, 1), b2 + hstep, voffB); PG8_STAGE(PG8_SA(0, 0), a2, voffA);
;             PG8_WAIT_V(8); PG8_WAIT_L(0); PG8_BAR; PG8_MMA(1, 0, At, B0); PG8_MMA(1, 1, At, B1); PG8_BAR; PG8_SCHED;
.LBB0_229:
	s_ashr_i32 s37, s36, 31
	s_lshl_b64 s[34:35], s[36:37], 21
	s_add_u32 s40, s42, s34
	s_addc_u32 s41, s43, s35
	s_and_b64 s[34:35], s[8:9], exec
	s_cselect_b32 s11, s41, s13
	s_cselect_b32 s34, s40, s12
	s_ashr_i32 s27, s26, 31
	s_lshl_b64 s[50:51], s[26:27], 21
	s_add_u32 s54, s44, s50
	s_addc_u32 s55, s45, s51
	s_and_b64 s[50:51], s[8:9], exec
	s_cselect_b32 s27, s55, s73
	s_cselect_b32 s35, s54, s72
	s_add_u32 s12, s12, 0x100080
	s_addc_u32 s13, s13, 0
	s_add_u32 s37, s72, 0x100
	s_addc_u32 s61, s73, 0
	s_mov_b32 s97, -2
	s_add_u32 s50, s12, 0xfff00080
	s_addc_u32 s51, s13, -1
	s_add_i32 s56, 0, 0x10000
	s_cmp_eq_u32 s97, 60
	s_cselect_b32 s77, s11, s51
	s_cselect_b32 s76, s34, s50
	s_cselect_b32 s73, s27, s61
	s_cselect_b32 s72, s35, s37
	s_add_i32 s57, 0, 0x14000
	v_add_u32_e32 v156, s56, v171
	v_add_u32_e32 v168, s57, v171
	s_waitcnt vmcnt(0)
	ds_read_b128 v[112:115], v156
	ds_read_b128 v[120:123], v156 offset:1024
	ds_read_b128 v[152:155], v156 offset:2048
	ds_read_b128 v[156:159], v156 offset:3072
	ds_read_b128 v[160:163], v168
	ds_read_b128 v[164:167], v168 offset:1024
	s_waitcnt lgkmcnt(0)
	ds_read_b128 v[176:179], v168 offset:2048
	ds_read_b128 v[180:183], v168 offset:3072
	v_lshl_add_u64 v[168:169], s[12:13], 0, v[148:149]
	s_add_i32 m0, s47, 0xc000
	ds_read_b128 v[184:187], v173
	ds_read_b128 v[188:191], v173 offset:1024
	ds_read_b128 v[204:207], v173 offset:2048
	ds_read_b128 v[208:211], v173 offset:3072
	ds_read_b128 v[212:215], v173 offset:4096
	ds_read_b128 v[216:219], v173 offset:5120
	ds_read_b128 v[220:223], v173 offset:6144
	ds_read_b128 v[224:227], v173 offset:7168
	global_load_lds_dwordx4 v[168:169], off
	v_lshl_add_u64 v[168:169], s[12:13], 0, v[150:151]
	s_add_i32 m0, s47, 0xe000
	s_nop 0
	global_load_lds_dwordx4 v[168:169], off
	s_waitcnt vmcnt(8)
	s_waitcnt lgkmcnt(0)
	s_barrier
	s_setprio 1
	s_waitcnt lgkmcnt(0)
	v_mfma_f32_16x16x32_bf16 v[136:139], v[112:115], v[184:187], 0
	v_mfma_f32_16x16x32_bf16 v[136:139], v[120:123], v[188:191], v[136:139]
	v_mfma_f32_16x16x32_bf16 v[116:119], v[120:123], v[208:211], 0
	v_mfma_f32_16x16x32_bf16 v[116:119], v[112:115], v[204:207], v[116:119]
	v_mfma_f32_16x16x32_bf16 v[96:99], v[112:115], v[212:215], 0
	v_mfma_f32_16x16x32_bf16 v[96:99], v[120:123], v[216:219], v[96:99]
	v_mfma_f32_16x16x32_bf16 v[80:83], v[120:123], v[224:227], 0
	v_mfma_f32_16x16x32_bf16 v[80:83], v[112:115], v[220:223], v[80:83]
	v_mfma_f32_16x16x32_bf16 v[76:79], v[152:155], v[220:223], 0
	v_mfma_f32_16x16x32_bf16 v[76:79], v[156:159], v[224:227], v[76:79]
	v_mfma_f32_16x16x32_bf16 v[92:95], v[156:159], v[216:219], 0
	v_mfma_f32_16x16x32_bf16 v[92:95], v[152:155], v[212:215], v[92:95]
	v_mfma_f32_16x16x32_bf16 v[108:111], v[152:155], v[204:207], 0
	v_mfma_f32_16x16x32_bf16 v[108:111], v[156:159], v[208:211], v[108:111]
	v_mfma_f32_16x16x32_bf16 v[132:135], v[156:159], v[188:191], 0
	v_mfma_f32_16x16x32_bf16 v[132:135], v[152:155], v[184:187], v[132:135]
	v_mfma_f32_16x16x32_bf16 v[128:131], v[160:163], v[184:187], 0
	v_mfma_f32_16x16x32_bf16 v[128:131], v[164:167], v[188:191], v[128:131]
	v_mfma_f32_16x16x32_bf16 v[104:107], v[164:167], v[208:211], 0
	v_mfma_f32_16x16x32_bf16 v[104:107], v[160:163], v[204:207], v[104:107]
	v_mfma_f32_16x16x32_bf16 v[88:91], v[160:163], v[212:215], 0
	v_mfma_f32_16x16x32_bf16 v[88:91], v[164:167], v[216:219], v[88:91]
	v_mfma_f32_16x16x32_bf16 v[72:75], v[164:167], v[224:227], 0
	v_mfma_f32_16x16x32_bf16 v[72:75], v[160:163], v[220:223], v[72:75]
	v_mfma_f32_16x16x32_bf16 v[68:71], v[176:179], v[220:223], 0
	v_mfma_f32_16x16x32_bf16 v[68:71], v[180:183], v[224:227], v[68:71]
	v_mfma_f32_16x16x32_bf16 v[84:87], v[180:183], v[216:219], 0
	v_mfma_f32_16x16x32_bf16 v[84:87], v[176:179], v[212:215], v[84:87]
	v_mfma_f32_16x16x32_bf16 v[100:103], v[176:179], v[204:207], 0
	v_mfma_f32_16x16x32_bf16 v[100:103], v[180:183], v[208:211], v[100:103]
	v_mfma_f32_16x16x32_bf16 v[124:127], v[180:183], v[188:191], 0
	v_mfma_f32_16x16x32_bf16 v[124:127], v[176:179], v[184:187], v[124:127]
	s_setprio 0
	s_barrier
	s_add_i32 s50, s56, s46
	v_lshl_add_u64 v[168:169], s[72:73], 0, v[2:3]
	s_mov_b32 m0, s50
	ds_read_b128 v[184:187], v173 offset:16384
	ds_read_b128 v[188:191], v173 offset:17408
	ds_read_b128 v[204:207], v173 offset:18432
	ds_read_b128 v[208:211], v173 offset:19456
	ds_read_b128 v[212:215], v173 offset:20480
	ds_read_b128 v[216:219], v173 offset:21504
	ds_read_b128 v[220:223], v173 offset:22528
	ds_read_b128 v[224:227], v173 offset:23552
	global_load_lds_dwordx4 v[168:169], off
	s_add_i32 m0, s50, 0x2000
	s_add_u32 s50, s72, 0x100000
	v_lshl_add_u64 v[228:229], s[72:73], 0, v[144:145]
	s_addc_u32 s51, s73, 0
	s_add_i32 s56, s57, s46
	global_load_lds_dwordx4 v[228:229], off
	v_lshl_add_u64 v[240:241], s[50:51], 0, v[2:3]
	s_mov_b32 m0, s56
	v_lshl_add_u64 v[242:243], s[76:77], 0, v[142:143]
	global_load_lds_dwordx4 v[240:241], off
	v_lshl_add_u64 v[240:241], s[50:51], 0, v[144:145]
	s_add_i32 m0, s56, 0x2000
	s_nop 0
	global_load_lds_dwordx4 v[240:241], off
	v_lshl_add_u64 v[240:241], s[76:77], 0, v[140:141]
	s_mov_b32 m0, s47
	s_nop 0
	global_load_lds_dwordx4 v[240:241], off
	s_mov_b32 m0, s52
	s_nop 0
	global_load_lds_dwordx4 v[242:243], off
	s_waitcnt vmcnt(8)
	s_waitcnt lgkmcnt(0)
	s_barrier
; #define PG8_STAGE(bufoff, gbase, voff) do { _Pragma("unroll") for (int _i = 0; _i < 2; ++_i) \
;         __builtin_amdgcn_global_load_lds((const unsigned*)((const char*)(gbase) + (voff)[_i]), (PG8_LAS unsigned*)(lds + (bufoff) + ldsw + _i * 8192), 16, 0, 0); } while (0)
; #define PG8_LDA(dst, b, h) do { _Pragma("unroll") for (int m = 0; m < 4; ++m) _Pragma("unroll") for (int k = 0; k < 2; ++k) dst[m][k] = *(const PG8_LAS bf16x8*)(lds + PG8_SA(b, h) + aoff + m * 2048 + k * 1024); } while (0)
; #define PG8_LDB(dst, b, h) do { _Pragma("unroll") for (int n = 0; n < 2; ++n) _Pragma("unroll") for (int k = 0; k < 2; ++k) dst[n][k] = *(const PG8_LAS bf16x8*)(lds + PG8_SB(b, h) + boff + n * 2048 + k * 1024); } while (0)
; #define PG8_WAIT_V(n) asm volatile("s_waitcnt vmcnt(" #n ")" ::: "memory")
; #define PG8_WAIT_L(n) asm volatile("s_waitcnt lgkmcnt(" #n ")" ::: "memory")
; #define PG8_BAR __builtin_amdgcn_s_barrier()
; #define PG8_SCHED __builtin_amdgcn_sched_barrier(0)
; template <class Epi, class Sched, bool ALIGN_EPI = false, bool SP2 = false, bool I8 = false>
; __device__ __forceinline__ void gemm_phase(PG8_LAS unsigned char* lds, const Gemm g, const Sched& S, const Epi& E) {
;     ...
;             PG8_WAIT_V(8); PG8_WAIT_L(0); PG8_BAR; PG8_MMA(1, 0, At, B0); PG8_MMA(1, 1, At, B1); PG8_BAR; PG8_SCHED;
;             PG8_LDB(B0, 1, 0); PG8_LDB(B1, 1, 1); PG8_SCHED; PG8_LDA(At, 1, 0); PG8_STAGE(PG8_SA(0, 1), a2 + hstep, voffA);
;             PG8_WAIT_V(8); PG8_WAIT_L(0); PG8_BAR; PG8_MMA(0, 0, At, B0); PG8_MMA(0, 1, At, B1); PG8_BAR; PG8_SCHED;
	s_setprio 1
	s_waitcnt lgkmcnt(0)
	v_mfma_f32_16x16x32_bf16 v[64:67], v[112:115], v[184:187], 0
	v_mfma_f32_16x16x32_bf16 v[64:67], v[120:123], v[188:191], v[64:67]
	v_mfma_f32_16x16x32_bf16 v[48:51], v[120:123], v[208:211], 0
	v_mfma_f32_16x16x32_bf16 v[48:51], v[112:115], v[204:207], v[48:51]
	v_mfma_f32_16x16x32_bf16 v[32:35], v[112:115], v[212:215], 0
	v_mfma_f32_16x16x32_bf16 v[32:35], v[120:123], v[216:219], v[32:35]
	v_mfma_f32_16x16x32_bf16 v[16:19], v[120:123], v[224:227], 0
	v_mfma_f32_16x16x32_bf16 v[16:19], v[112:115], v[220:223], v[16:19]
	v_mfma_f32_16x16x32_bf16 v[12:15], v[152:155], v[220:223], 0
	v_mfma_f32_16x16x32_bf16 v[12:15], v[156:159], v[224:227], v[12:15]
	v_mfma_f32_16x16x32_bf16 v[28:31], v[156:159], v[216:219], 0
	v_mfma_f32_16x16x32_bf16 v[28:31], v[152:155], v[212:215], v[28:31]
	v_mfma_f32_16x16x32_bf16 v[44:47], v[152:155], v[204:207], 0
	v_mfma_f32_16x16x32_bf16 v[44:47], v[156:159], v[208:211], v[44:47]
	v_mfma_f32_16x16x32_bf16 v[60:63], v[156:159], v[188:191], 0
	v_mfma_f32_16x16x32_bf16 v[60:63], v[152:155], v[184:187], v[60:63]
	v_mfma_f32_16x16x32_bf16 v[56:59], v[160:163], v[184:187], 0
	v_mfma_f32_16x16x32_bf16 v[56:59], v[164:167], v[188:191], v[56:59]
	v_mfma_f32_16x16x32_bf16 v[40:43], v[164:167], v[208:211], 0
	v_mfma_f32_16x16x32_bf16 v[40:43], v[160:163], v[204:207], v[40:43]
	v_mfma_f32_16x16x32_bf16 v[24:27], v[160:163], v[212:215], 0
	v_mfma_f32_16x16x32_bf16 v[24:27], v[164:167], v[216:219], v[24:27]
	v_mfma_f32_16x16x32_bf16 v[8:11], v[164:167], v[224:227], 0
	v_mfma_f32_16x16x32_bf16 v[8:11], v[160:163], v[220:223], v[8:11]
	v_mfma_f32_16x16x32_bf16 v[4:7], v[176:179], v[220:223], 0
	v_mfma_f32_16x16x32_bf16 v[4:7], v[180:183], v[224:227], v[4:7]
	v_mfma_f32_16x16x32_bf16 v[20:23], v[180:183], v[216:219], 0
	v_mfma_f32_16x16x32_bf16 v[20:23], v[176:179], v[212:215], v[20:23]
	v_mfma_f32_16x16x32_bf16 v[36:39], v[176:179], v[204:207], 0
	v_mfma_f32_16x16x32_bf16 v[36:39], v[180:183], v[208:211], v[36:39]
	v_mfma_f32_16x16x32_bf16 v[52:55], v[180:183], v[188:191], 0
	v_mfma_f32_16x16x32_bf16 v[52:55], v[176:179], v[184:187], v[52:55]
	s_setprio 0
	s_barrier
	s_add_i32 s56, 0, 0x18000
	s_add_i32 s57, 0, 0x1c000
	v_add_u32_e32 v156, s56, v171
	v_add_u32_e32 v175, s57, v171
	ds_read_b128 v[112:115], v156
	ds_read_b128 v[120:123], v156 offset:1024
	ds_read_b128 v[152:155], v156 offset:2048
	ds_read_b128 v[156:159], v156 offset:3072
	ds_read_b128 v[160:163], v175
	ds_read_b128 v[164:167], v175 offset:1024
	ds_read_b128 v[176:179], v175 offset:2048
	ds_read_b128 v[180:183], v175 offset:3072
	s_add_u32 s50, s76, 0x100000
	s_addc_u32 s51, s77, 0
	s_mov_b32 m0, s53
	v_lshl_add_u64 v[244:245], s[50:51], 0, v[140:141]
	ds_read_b128 v[184:187], v173 offset:32768
	ds_read_b128 v[188:191], v173 offset:33792
	ds_read_b128 v[204:207], v173 offset:34816
	ds_read_b128 v[208:211], v173 offset:35840
	ds_read_b128 v[212:215], v173 offset:36864
	ds_read_b128 v[216:219], v173 offset:37888
	ds_read_b128 v[220:223], v173 offset:38912
	ds_read_b128 v[224:227], v173 offset:39936
	global_load_lds_dwordx4 v[244:245], off
	v_lshl_add_u64 v[244:245], s[50:51], 0, v[142:143]
	s_mov_b32 m0, s64
	s_nop 0
	global_load_lds_dwordx4 v[244:245], off
	s_waitcnt vmcnt(8)
	s_waitcnt lgkmcnt(0)
	s_barrier
	s_setprio 1
	s_waitcnt lgkmcnt(0)
	v_mfma_f32_16x16x32_bf16 v[136:139], v[112:115], v[184:187], v[136:139]
	v_mfma_f32_16x16x32_bf16 v[136:139], v[120:123], v[188:191], v[136:139]
	v_mfma_f32_16x16x32_bf16 v[116:119], v[120:123], v[208:211], v[116:119]
	v_mfma_f32_16x16x32_bf16 v[116:119], v[112:115], v[204:207], v[116:119]
	v_mfma_f32_16x16x32_bf16 v[96:99], v[112:115], v[212:215], v[96:99]
	v_mfma_f32_16x16x32_bf16 v[96:99], v[120:123], v[216:219], v[96:99]
	v_mfma_f32_16x16x32_bf16 v[80:83], v[120:123], v[224:227], v[80:83]
	v_mfma_f32_16x16x32_bf16 v[80:83], v[112:115], v[220:223], v[80:83]
	v_mfma_f32_16x16x32_bf16 v[76:79], v[152:155], v[220:223], v[76:79]
	v_mfma_f32_16x16x32_bf16 v[76:79], v[156:159], v[224:227], v[76:79]
	v_mfma_f32_16x16x32_bf16 v[92:95], v[156:159], v[216:219], v[92:95]
	v_mfma_f32_16x16x32_bf16 v[92:95], v[152:155], v[212:215], v[92:95]
	v_mfma_f32_16x16x32_bf16 v[108:111], v[152:155], v[204:207], v[108:111]
	v_mfma_f32_16x16x32_bf16 v[108:111], v[156:159], v[208:211], v[108:111]
	v_mfma_f32_16x16x32_bf16 v[132:135], v[156:159], v[188:191], v[132:135]
	v_mfma_f32_16x16x32_bf16 v[132:135], v[152:155], v[184:187], v[132:135]
	v_mfma_f32_16x16x32_bf16 v[128:131], v[160:163], v[184:187], v[128:131]
	v_mfma_f32_16x16x32_bf16 v[128:131], v[164:167], v[188:191], v[128:131]
	v_mfma_f32_16x16x32_bf16 v[104:107], v[164:167], v[208:211], v[104:107]
	v_mfma_f32_16x16x32_bf16 v[104:107], v[160:163], v[204:207], v[104:107]
	v_mfma_f32_16x16x32_bf16 v[88:91], v[160:163], v[212:215], v[88:91]
	v_mfma_f32_16x16x32_bf16 v[88:91], v[164:167], v[216:219], v[88:91]
	v_mfma_f32_16x16x32_bf16 v[72:75], v[164:167], v[224:227], v[72:75]
	v_mfma_f32_16x16x32_bf16 v[72:75], v[160:163], v[220:223], v[72:75]
	v_mfma_f32_16x16x32_bf16 v[68:71], v[176:179], v[220:223], v[68:71]
	v_mfma_f32_16x16x32_bf16 v[68:71], v[180:183], v[224:227], v[68:71]
	v_mfma_f32_16x16x32_bf16 v[84:87], v[180:183], v[216:219], v[84:87]
	v_mfma_f32_16x16x32_bf16 v[84:87], v[176:179], v[212:215], v[84:87]
	v_mfma_f32_16x16x32_bf16 v[100:103], v[176:179], v[204:207], v[100:103]
	v_mfma_f32_16x16x32_bf16 v[100:103], v[180:183], v[208:211], v[100:103]
	v_mfma_f32_16x16x32_bf16 v[124:127], v[180:183], v[188:191], v[124:127]
	v_mfma_f32_16x16x32_bf16 v[124:127], v[176:179], v[184:187], v[124:127]
	s_setprio 0
	s_barrier
; #define PG8_STAGE(bufoff, gbase, voff) do { _Pragma("unroll") for (int _i = 0; _i < 2; ++_i) \
;         __builtin_amdgcn_global_load_lds((const unsigned*)((const char*)(gbase) + (voff)[_i]), (PG8_LAS unsigned*)(lds + (bufoff) + ldsw + _i * 8192), 16, 0, 0); } while (0)
; #define PG8_LDA(dst, b, h) do { _Pragma("unroll") for (int m = 0; m < 4; ++m) _Pragma("unroll") for (int k = 0; k < 2; ++k) dst[m][k] = *(const PG8_LAS bf16x8*)(lds + PG8_SA(b, h) + aoff + m * 2048 + k * 1024); } while (0)
; #define PG8_LDB(dst, b, h) do { _Pragma("unroll") for (int n = 0; n < 2; ++n) _Pragma("unroll") for (int k = 0; k < 2; ++k) dst[n][k] = *(const PG8_LAS bf16x8*)(lds + PG8_SB(b, h) + boff + n * 2048 + k * 1024); } while (0)
; #define PG8_WAIT_V(n) asm volatile("s_waitcnt vmcnt(" #n ")" ::: "memory")
; template <class Epi, class Sched, bool ALIGN_EPI = false, bool SP2 = false, bool I8 = false>
; __device__ __forceinline__ void gemm_phase(PG8_LAS unsigned char* lds, const Gemm g, const Sched& S, const Epi& E) {
;     ...
;             const char* a1 = cA + (size_t)(t + 1) * kstep;
;             const char* a2 = last ? nA : cA + (size_t)(t + 2) * kstep; const char* b2 = last ? nB : cB + (size_t)(t + 2) * kstep;
;             const char* a3 = a2 + kstep; const char* b3 = b2 + kstep;
;             if (last && has_next) S.a_ready(nxt);
;             if constexpr (SP2) {
;             PG8_LDB(B0, 0, 0); PG8_LDB(B1, 0, 1); PG8_SCHED; PG8_LDA(At, 0, 0); PG8_STAGE(PG8_SA(1, 1), a1 + hstep, voffA);
;             PG8_WAIT_V(8); PG8_WAIT_L(0); PG8_BAR; PG8_MMA(0, 0, At, B0); PG8_MMA(0, 1, At, B1); PG8_BAR; PG8_SCHED;
;             PG8_LDA(At, 0, 1); PG8_STAGE(PG8_SB(0, 0), b2, voffB); PG8_STAGE(PG8_SB(0, 1), b2 + hstep, voffB); PG8_STAGE(PG8_SA(0, 0), a2, voffA);
;             PG8_WAIT_V(8); PG8_WAIT_L(0); PG8_BAR; PG8_MMA(1, 0, At, B0); PG8_MMA(1, 1, At, B1); PG8_BAR; PG8_SCHED;
;             PG8_LDB(B0, 1, 0); PG8_LDB(B1, 1, 1); PG8_SCHED; PG8_LDA(At, 1, 0); PG8_STAGE(PG8_SA(0, 1), a2 + hstep, voffA);
;             PG8_WAIT_V(8); PG8_WAIT_L(0); PG8_BAR; PG8_MMA(0, 0, At, B0); PG8_MMA(0, 1, At, B1); PG8_BAR; PG8_SCHED;
;             PG8_LDA(At, 1, 1); PG8_STAGE(PG8_SB(1, 0), b3, voffB); PG8_STAGE(PG8_SB(1, 1), b3 + hstep, voffB); PG8_STAGE(PG8_SA(1, 0), a3, voffA);
;             PG8_WAIT_V(8); PG8_WAIT_L(0); PG8_BAR; PG8_MMA(1, 0, At, B0); PG8_MMA(1, 1, At, B1); PG8_BAR; PG8_SCHED;
	s_add_i32 s50, s56, s46
	v_lshl_add_u64 v[168:169], v[168:169], 0, s[84:85]
	s_mov_b32 m0, s50
	ds_read_b128 v[184:187], v173 offset:49152
	ds_read_b128 v[188:191], v173 offset:50176
	ds_read_b128 v[204:207], v173 offset:51200
	ds_read_b128 v[208:211], v173 offset:52224
	ds_read_b128 v[212:215], v173 offset:53248
	ds_read_b128 v[216:219], v173 offset:54272
	ds_read_b128 v[220:223], v173 offset:55296
	ds_read_b128 v[224:227], v173 offset:56320
	global_load_lds_dwordx4 v[168:169], off
	s_add_i32 m0, s50, 0x2000
	s_add_u32 s50, s72, 0x100080
	v_lshl_add_u64 v[168:169], v[228:229], 0, s[84:85]
	s_addc_u32 s51, s73, 0
	s_add_i32 s56, s57, s46
	global_load_lds_dwordx4 v[168:169], off
	v_lshl_add_u64 v[168:169], s[50:51], 0, v[2:3]
	s_mov_b32 m0, s56
	s_nop 0
	global_load_lds_dwordx4 v[168:169], off
	v_lshl_add_u64 v[168:169], s[50:51], 0, v[144:145]
	s_add_i32 m0, s56, 0x2000
	s_nop 0
	global_load_lds_dwordx4 v[168:169], off
	v_lshl_add_u64 v[168:169], v[240:241], 0, s[84:85]
	s_mov_b32 m0, s28
	s_nop 0
	global_load_lds_dwordx4 v[168:169], off
	v_lshl_add_u64 v[168:169], v[242:243], 0, s[84:85]
	s_mov_b32 m0, s65
	s_nop 0
	global_load_lds_dwordx4 v[168:169], off
	s_waitcnt vmcnt(8)
	s_waitcnt lgkmcnt(0)
	s_barrier
	s_setprio 1
	s_waitcnt lgkmcnt(0)
	v_mfma_f32_16x16x32_bf16 v[64:67], v[112:115], v[184:187], v[64:67]
	v_mfma_f32_16x16x32_bf16 v[64:67], v[120:123], v[188:191], v[64:67]
	v_mfma_f32_16x16x32_bf16 v[48:51], v[120:123], v[208:211], v[48:51]
	v_mfma_f32_16x16x32_bf16 v[48:51], v[112:115], v[204:207], v[48:51]
	v_mfma_f32_16x16x32_bf16 v[32:35], v[112:115], v[212:215], v[32:35]
	v_mfma_f32_16x16x32_bf16 v[32:35], v[120:123], v[216:219], v[32:35]
	v_mfma_f32_16x16x32_bf16 v[16:19], v[120:123], v[224:227], v[16:19]
	v_mfma_f32_16x16x32_bf16 v[16:19], v[112:115], v[220:223], v[16:19]
	v_mfma_f32_16x16x32_bf16 v[12:15], v[152:155], v[220:223], v[12:15]
	v_mfma_f32_16x16x32_bf16 v[12:15], v[156:159], v[224:227], v[12:15]
	v_mfma_f32_16x16x32_bf16 v[28:31], v[156:159], v[216:219], v[28:31]
	v_mfma_f32_16x16x32_bf16 v[28:31], v[152:155], v[212:215], v[28:31]
	v_mfma_f32_16x16x32_bf16 v[44:47], v[152:155], v[204:207], v[44:47]
	v_mfma_f32_16x16x32_bf16 v[44:47], v[156:159], v[208:211], v[44:47]
	v_mfma_f32_16x16x32_bf16 v[60:63], v[156:159], v[188:191], v[60:63]
	v_mfma_f32_16x16x32_bf16 v[60:63], v[152:155], v[184:187], v[60:63]
	v_mfma_f32_16x16x32_bf16 v[56:59], v[160:163], v[184:187], v[56:59]
	v_mfma_f32_16x16x32_bf16 v[56:59], v[164:167], v[188:191], v[56:59]
	v_mfma_f32_16x16x32_bf16 v[40:43], v[164:167], v[208:211], v[40:43]
	v_mfma_f32_16x16x32_bf16 v[40:43], v[160:163], v[204:207], v[40:43]
	v_mfma_f32_16x16x32_bf16 v[24:27], v[160:163], v[212:215], v[24:27]
	v_mfma_f32_16x16x32_bf16 v[24:27], v[164:167], v[216:219], v[24:27]
	v_mfma_f32_16x16x32_bf16 v[8:11], v[164:167], v[224:227], v[8:11]
	v_mfma_f32_16x16x32_bf16 v[8:11], v[160:163], v[220:223], v[8:11]
	v_mfma_f32_16x16x32_bf16 v[4:7], v[176:179], v[220:223], v[4:7]
	v_mfma_f32_16x16x32_bf16 v[4:7], v[180:183], v[224:227], v[4:7]
	v_mfma_f32_16x16x32_bf16 v[20:23], v[180:183], v[216:219], v[20:23]
	v_mfma_f32_16x16x32_bf16 v[20:23], v[176:179], v[212:215], v[20:23]
	v_mfma_f32_16x16x32_bf16 v[36:39], v[176:179], v[204:207], v[36:39]
	v_mfma_f32_16x16x32_bf16 v[36:39], v[180:183], v[208:211], v[36:39]
	v_mfma_f32_16x16x32_bf16 v[52:55], v[180:183], v[188:191], v[52:55]
	v_mfma_f32_16x16x32_bf16 v[52:55], v[176:179], v[184:187], v[52:55]
	s_setprio 0
	s_add_i32 s97, s97, 2
	s_add_u32 s12, s12, 0x100
	s_addc_u32 s13, s13, 0
	s_add_u32 s37, s37, 0x100
	s_addc_u32 s61, s61, 0
	s_cmp_gt_u32 s97, 61
	s_barrier
	s_cbranch_scc1 .Lkloop_exit_1
.LBB0_230:
	s_add_u32 s50, s12, 0xfff00080
	s_addc_u32 s51, s13, -1
	s_add_i32 s56, 0, 0x10000
	s_cmp_eq_u32 s97, 60
	s_cselect_b32 s77, s11, s51
	s_cselect_b32 s76, s34, s50
	s_cselect_b32 s73, s27, s61
	s_cselect_b32 s72, s35, s37
	s_add_i32 s57, 0, 0x14000
	v_add_u32_e32 v156, s56, v171
	v_add_u32_e32 v168, s57, v171
	s_waitcnt vmcnt(0)
	ds_read_b128 v[112:115], v156
	ds_read_b128 v[120:123], v156 offset:1024
	ds_read_b128 v[152:155], v156 offset:2048
	ds_read_b128 v[156:159], v156 offset:3072
	ds_read_b128 v[160:163], v168
	ds_read_b128 v[164:167], v168 offset:1024
	s_waitcnt lgkmcnt(0)
	ds_read_b128 v[176:179], v168 offset:2048
	ds_read_b128 v[180:183], v168 offset:3072
	v_lshl_add_u64 v[168:169], s[12:13], 0, v[148:149]
	s_add_i32 m0, s47, 0xc000
	ds_read_b128 v[184:187], v173
	ds_read_b128 v[188:191], v173 offset:1024
	ds_read_b128 v[204:207], v173 offset:2048
	ds_read_b128 v[208:211], v173 offset:3072
	ds_read_b128 v[212:215], v173 offset:4096
	ds_read_b128 v[216:219], v173 offset:5120
	ds_read_b128 v[220:223], v173 offset:6144
	ds_read_b128 v[224:227], v173 offset:7168
	global_load_lds_dwordx4 v[168:169], off
	v_lshl_add_u64 v[168:169], s[12:13], 0, v[150:151]
	s_add_i32 m0, s47, 0xe000
	s_nop 0
	global_load_lds_dwordx4 v[168:169], off
	s_waitcnt vmcnt(8)
	s_waitcnt lgkmcnt(0)
	s_barrier
; #define PG8_STAGE(bufoff, gbase, voff) do { _Pragma("unroll") for (int _i = 0; _i < 2; ++_i) \
;         __builtin_amdgcn_global_load_lds((const unsigned*)((const char*)(gbase) + (voff)[_i]), (PG8_LAS unsigned*)(lds + (bufoff) + ldsw + _i * 8192), 16, 0, 0); } while (0)
; #define PG8_LDA(dst, b, h) do { _Pragma("unroll") for (int m = 0; m < 4; ++m) _Pragma("unroll") for (int k = 0; k < 2; ++k) dst[m][k] = *(const PG8_LAS bf16x8*)(lds + PG8_SA(b, h) + aoff + m * 2048 + k * 1024); } while (0)
; #define PG8_WAIT_V(n) asm volatile("s_waitcnt vmcnt(" #n ")" ::: "memory")
; #define PG8_WAIT_L(n) asm volatile("s_waitcnt lgkmcnt(" #n ")" ::: "memory")
; #define PG8_BAR __builtin_amdgcn_s_barrier()
; #define PG8_SCHED __builtin_amdgcn_sched_barrier(0)
; template <class Epi, class Sched, bool ALIGN_EPI = false, bool SP2 = false, bool I8 = false>
; __device__ __forceinline__ void gemm_phase(PG8_LAS unsigned char* lds, const Gemm g, const Sched& S, const Epi& E) {
;     ...
;             PG8_WAIT_V(8); PG8_WAIT_L(0); PG8_BAR; PG8_MMA(0, 0, At, B0); PG8_MMA(0, 1, At, B1); PG8_BAR; PG8_SCHED;
;             PG8_LDA(At, 0, 1); PG8_STAGE(PG8_SB(0, 0), b2, voffB); PG8_STAGE(PG8_SB(0, 1), b2 + hstep, voffB); PG8_STAGE(PG8_SA(0, 0), a2, voffA);
;             PG8_WAIT_V(8); PG8_WAIT_L(0); PG8_BAR; PG8_MMA(1, 0, At, B0); PG8_MMA(1, 1, At, B1); PG8_BAR; PG8_SCHED;
	s_setprio 1
	s_waitcnt lgkmcnt(0)
	v_mfma_f32_16x16x32_bf16 v[136:139], v[112:115], v[184:187], v[136:139]
	v_mfma_f32_16x16x32_bf16 v[136:139], v[120:123], v[188:191], v[136:139]
	v_mfma_f32_16x16x32_bf16 v[116:119], v[120:123], v[208:211], v[116:119]
	v_mfma_f32_16x16x32_bf16 v[116:119], v[112:115], v[204:207], v[116:119]
	v_mfma_f32_16x16x32_bf16 v[96:99], v[112:115], v[212:215], v[96:99]
	v_mfma_f32_16x16x32_bf16 v[96:99], v[120:123], v[216:219], v[96:99]
	v_mfma_f32_16x16x32_bf16 v[80:83], v[120:123], v[224:227], v[80:83]
	v_mfma_f32_16x16x32_bf16 v[80:83], v[112:115], v[220:223], v[80:83]
	v_mfma_f32_16x16x32_bf16 v[76:79], v[152:155], v[220:223], v[76:79]
	v_mfma_f32_16x16x32_bf16 v[76:79], v[156:159], v[224:227], v[76:79]
	v_mfma_f32_16x16x32_bf16 v[92:95], v[156:159], v[216:219], v[92:95]
	v_mfma_f32_16x16x32_bf16 v[92:95], v[152:155], v[212:215], v[92:95]
	v_mfma_f32_16x16x32_bf16 v[108:111], v[152:155], v[204:207], v[108:111]
	v_mfma_f32_16x16x32_bf16 v[108:111], v[156:159], v[208:211], v[108:111]
	v_mfma_f32_16x16x32_bf16 v[132:135], v[156:159], v[188:191], v[132:135]
	v_mfma_f32_16x16x32_bf16 v[132:135], v[152:155], v[184:187], v[132:135]
	v_mfma_f32_16x16x32_bf16 v[128:131], v[160:163], v[184:187], v[128:131]
	v_mfma_f32_16x16x32_bf16 v[128:131], v[164:167], v[188:191], v[128:131]
	v_mfma_f32_16x16x32_bf16 v[104:107], v[164:167], v[208:211], v[104:107]
	v_mfma_f32_16x16x32_bf16 v[104:107], v[160:163], v[204:207], v[104:107]
	v_mfma_f32_16x16x32_bf16 v[88:91], v[160:163], v[212:215], v[88:91]
	v_mfma_f32_16x16x32_bf16 v[88:91], v[164:167], v[216:219], v[88:91]
	v_mfma_f32_16x16x32_bf16 v[72:75], v[164:167], v[224:227], v[72:75]
	v_mfma_f32_16x16x32_bf16 v[72:75], v[160:163], v[220:223], v[72:75]
	v_mfma_f32_16x16x32_bf16 v[68:71], v[176:179], v[220:223], v[68:71]
	v_mfma_f32_16x16x32_bf16 v[68:71], v[180:183], v[224:227], v[68:71]
	v_mfma_f32_16x16x32_bf16 v[84:87], v[180:183], v[216:219], v[84:87]
	v_mfma_f32_16x16x32_bf16 v[84:87], v[176:179], v[212:215], v[84:87]
	v_mfma_f32_16x16x32_bf16 v[100:103], v[176:179], v[204:207], v[100:103]
	v_mfma_f32_16x16x32_bf16 v[100:103], v[180:183], v[208:211], v[100:103]
	v_mfma_f32_16x16x32_bf16 v[124:127], v[180:183], v[188:191], v[124:127]
	v_mfma_f32_16x16x32_bf16 v[124:127], v[176:179], v[184:187], v[124:127]
	s_setprio 0
	s_barrier
	s_add_i32 s50, s56, s46
	v_lshl_add_u64 v[168:169], s[72:73], 0, v[2:3]
	s_mov_b32 m0, s50
	ds_read_b128 v[184:187], v173 offset:16384
	ds_read_b128 v[188:191], v173 offset:17408
	ds_read_b128 v[204:207], v173 offset:18432
	ds_read_b128 v[208:211], v173 offset:19456
	ds_read_b128 v[212:215], v173 offset:20480
	ds_read_b128 v[216:219], v173 offset:21504
	ds_read_b128 v[220:223], v173 offset:22528
	ds_read_b128 v[224:227], v173 offset:23552
	global_load_lds_dwordx4 v[168:169], off
	s_add_i32 m0, s50, 0x2000
	s_add_u32 s50, s72, 0x100000
	v_lshl_add_u64 v[228:229], s[72:73], 0, v[144:145]
	s_addc_u32 s51, s73, 0
	s_add_i32 s56, s57, s46
	global_load_lds_dwordx4 v[228:229], off
	v_lshl_add_u64 v[240:241], s[50:51], 0, v[2:3]
	s_mov_b32 m0, s56
	v_lshl_add_u64 v[242:243], s[76:77], 0, v[142:143]
	global_load_lds_dwordx4 v[240:241], off
	v_lshl_add_u64 v[240:241], s[50:51], 0, v[144:145]
	s_add_i32 m0, s56, 0x2000
	s_nop 0
	global_load_lds_dwordx4 v[240:241], off
	v_lshl_add_u64 v[240:241], s[76:77], 0, v[140:141]
	s_mov_b32 m0, s47
	s_nop 0
	global_load_lds_dwordx4 v[240:241], off
	s_mov_b32 m0, s52
	s_nop 0
	global_load_lds_dwordx4 v[242:243], off
	s_waitcnt vmcnt(8)
	s_waitcnt lgkmcnt(0)
	s_barrier
	s_setprio 1
	s_waitcnt lgkmcnt(0)
	v_mfma_f32_16x16x32_bf16 v[64:67], v[112:115], v[184:187], v[64:67]
	v_mfma_f32_16x16x32_bf16 v[64:67], v[120:123], v[188:191], v[64:67]
	v_mfma_f32_16x16x32_bf16 v[48:51], v[120:123], v[208:211], v[48:51]
	v_mfma_f32_16x16x32_bf16 v[48:51], v[112:115], v[204:207], v[48:51]
	v_mfma_f32_16x16x32_bf16 v[32:35], v[112:115], v[212:215], v[32:35]
	v_mfma_f32_16x16x32_bf16 v[32:35], v[120:123], v[216:219], v[32:35]
	v_mfma_f32_16x16x32_bf16 v[16:19], v[120:123], v[224:227], v[16:19]
	v_mfma_f32_16x16x32_bf16 v[16:19], v[112:115], v[220:223], v[16:19]
	v_mfma_f32_16x16x32_bf16 v[12:15], v[152:155], v[220:223], v[12:15]
	v_mfma_f32_16x16x32_bf16 v[12:15], v[156:159], v[224:227], v[12:15]
	v_mfma_f32_16x16x32_bf16 v[28:31], v[156:159], v[216:219], v[28:31]
	v_mfma_f32_16x16x32_bf16 v[28:31], v[152:155], v[212:215], v[28:31]
	v_mfma_f32_16x16x32_bf16 v[44:47], v[152:155], v[204:207], v[44:47]
	v_mfma_f32_16x16x32_bf16 v[44:47], v[156:159], v[208:211], v[44:47]
	v_mfma_f32_16x16x32_bf16 v[60:63], v[156:159], v[188:191], v[60:63]
	v_mfma_f32_16x16x32_bf16 v[60:63], v[152:155], v[184:187], v[60:63]
	v_mfma_f32_16x16x32_bf16 v[56:59], v[160:163], v[184:187], v[56:59]
	v_mfma_f32_16x16x32_bf16 v[56:59], v[164:167], v[188:191], v[56:59]
	v_mfma_f32_16x16x32_bf16 v[40:43], v[164:167], v[208:211], v[40:43]
	v_mfma_f32_16x16x32_bf16 v[40:43], v[160:163], v[204:207], v[40:43]
	v_mfma_f32_16x16x32_bf16 v[24:27], v[160:163], v[212:215], v[24:27]
	v_mfma_f32_16x16x32_bf16 v[24:27], v[164:167], v[216:219], v[24:27]
	v_mfma_f32_16x16x32_bf16 v[8:11], v[164:167], v[224:227], v[8:11]
	v_mfma_f32_16x16x32_bf16 v[8:11], v[160:163], v[220:223], v[8:11]
	v_mfma_f32_16x16x32_bf16 v[4:7], v[176:179], v[220:223], v[4:7]
	v_mfma_f32_16x16x32_bf16 v[4:7], v[180:183], v[224:227], v[4:7]
	v_mfma_f32_16x16x32_bf16 v[20:23], v[180:183], v[216:219], v[20:23]
	v_mfma_f32_16x16x32_bf16 v[20:23], v[176:179], v[212:215], v[20:23]
	v_mfma_f32_16x16x32_bf16 v[36:39], v[176:179], v[204:207], v[36:39]
	v_mfma_f32_16x16x32_bf16 v[36:39], v[180:183], v[208:211], v[36:39]
	v_mfma_f32_16x16x32_bf16 v[52:55], v[180:183], v[188:191], v[52:55]
	v_mfma_f32_16x16x32_bf16 v[52:55], v[176:179], v[184:187], v[52:55]
	s_setprio 0
	s_barrier
; #define PG8_STAGE(bufoff, gbase, voff) do { _Pragma("unroll") for (int _i = 0; _i < 2; ++_i) \
;         __builtin_amdgcn_global_load_lds((const unsigned*)((const char*)(gbase) + (voff)[_i]), (PG8_LAS unsigned*)(lds + (bufoff) + ldsw + _i * 8192), 16, 0, 0); } while (0)
; #define PG8_LDA(dst, b, h) do { _Pragma("unroll") for (int m = 0; m < 4; ++m) _Pragma("unroll") for (int k = 0; k < 2; ++k) dst[m][k] = *(const PG8_LAS bf16x8*)(lds + PG8_SA(b, h) + aoff + m * 2048 + k * 1024); } while (0)
; #define PG8_LDB(dst, b, h) do { _Pragma("unroll") for (int n = 0; n < 2; ++n) _Pragma("unroll") for (int k = 0; k < 2; ++k) dst[n][k] = *(const PG8_LAS bf16x8*)(lds + PG8_SB(b, h) + boff + n * 2048 + k * 1024); } while (0)
; #define PG8_WAIT_V(n) asm volatile("s_waitcnt vmcnt(" #n ")" ::: "memory")
; #define PG8_WAIT_L(n) asm volatile("s_waitcnt lgkmcnt(" #n ")" ::: "memory")
; #define PG8_BAR __builtin_amdgcn_s_barrier()
; #define PG8_SCHED __builtin_amdgcn_sched_barrier(0)
; template <class Epi, class Sched, bool ALIGN_EPI = false, bool SP2 = false, bool I8 = false>
; __device__ __forceinline__ void gemm_phase(PG8_LAS unsigned char* lds, const Gemm g, const Sched& S, const Epi& E) {
;     ...
;             PG8_LDB(B0, 1, 0); PG8_LDB(B1, 1, 1); PG8_SCHED; PG8_LDA(At, 1, 0); PG8_STAGE(PG8_SA(0, 1), a2 + hstep, voffA);
;             PG8_WAIT_V(8); PG8_WAIT_L(0); PG8_BAR; PG8_MMA(0, 0, At, B0); PG8_MMA(0, 1, At, B1); PG8_BAR; PG8_SCHED;
	s_add_i32 s56, 0, 0x18000
	s_add_i32 s57, 0, 0x1c000
	v_add_u32_e32 v156, s56, v171
	v_add_u32_e32 v175, s57, v171
	ds_read_b128 v[112:115], v156
	ds_read_b128 v[120:123], v156 offset:1024
	ds_read_b128 v[152:155], v156 offset:2048
	ds_read_b128 v[156:159], v156 offset:3072
	ds_read_b128 v[160:163], v175
	ds_read_b128 v[164:167], v175 offset:1024
	ds_read_b128 v[176:179], v175 offset:2048
	ds_read_b128 v[180:183], v175 offset:3072
	s_add_u32 s50, s76, 0x100000
	s_addc_u32 s51, s77, 0
	s_mov_b32 m0, s53
	v_lshl_add_u64 v[244:245], s[50:51], 0, v[140:141]
	ds_read_b128 v[184:187], v173 offset:32768
	ds_read_b128 v[188:191], v173 offset:33792
	ds_read_b128 v[204:207], v173 offset:34816
	ds_read_b128 v[208:211], v173 offset:35840
	ds_read_b128 v[212:215], v173 offset:36864
	ds_read_b128 v[216:219], v173 offset:37888
	ds_read_b128 v[220:223], v173 offset:38912
	ds_read_b128 v[224:227], v173 offset:39936
	global_load_lds_dwordx4 v[244:245], off
	v_lshl_add_u64 v[244:245], s[50:51], 0, v[142:143]
	s_mov_b32 m0, s64
	s_nop 0
	global_load_lds_dwordx4 v[244:245], off
	s_waitcnt vmcnt(8)
	s_waitcnt lgkmcnt(0)
	s_barrier
	s_setprio 1
	s_waitcnt lgkmcnt(0)
	v_mfma_f32_16x16x32_bf16 v[136:139], v[112:115], v[184:187], v[136:139]
	v_mfma_f32_16x16x32_bf16 v[136:139], v[120:123], v[188:191], v[136:139]
	v_mfma_f32_16x16x32_bf16 v[116:119], v[120:123], v[208:211], v[116:119]
	v_mfma_f32_16x16x32_bf16 v[116:119], v[112:115], v[204:207], v[116:119]
	v_mfma_f32_16x16x32_bf16 v[96:99], v[112:115], v[212:215], v[96:99]
	v_mfma_f32_16x16x32_bf16 v[96:99], v[120:123], v[216:219], v[96:99]
	v_mfma_f32_16x16x32_bf16 v[80:83], v[120:123], v[224:227], v[80:83]
	v_mfma_f32_16x16x32_bf16 v[80:83], v[112:115], v[220:223], v[80:83]
	v_mfma_f32_16x16x32_bf16 v[76:79], v[152:155], v[220:223], v[76:79]
	v_mfma_f32_16x16x32_bf16 v[76:79], v[156:159], v[224:227], v[76:79]
	v_mfma_f32_16x16x32_bf16 v[92:95], v[156:159], v[216:219], v[92:95]
	v_mfma_f32_16x16x32_bf16 v[92:95], v[152:155], v[212:215], v[92:95]
	v_mfma_f32_16x16x32_bf16 v[108:111], v[152:155], v[204:207], v[108:111]
	v_mfma_f32_16x16x32_bf16 v[108:111], v[156:159], v[208:211], v[108:111]
	v_mfma_f32_16x16x32_bf16 v[132:135], v[156:159], v[188:191], v[132:135]
	v_mfma_f32_16x16x32_bf16 v[132:135], v[152:155], v[184:187], v[132:135]
	v_mfma_f32_16x16x32_bf16 v[128:131], v[160:163], v[184:187], v[128:131]
	v_mfma_f32_16x16x32_bf16 v[128:131], v[164:167], v[188:191], v[128:131]
	v_mfma_f32_16x16x32_bf16 v[104:107], v[164:167], v[208:211], v[104:107]
	v_mfma_f32_16x16x32_bf16 v[104:107], v[160:163], v[204:207], v[104:107]
	v_mfma_f32_16x16x32_bf16 v[88:91], v[160:163], v[212:215], v[88:91]
	v_mfma_f32_16x16x32_bf16 v[88:91], v[164:167], v[216:219], v[88:91]
	v_mfma_f32_16x16x32_bf16 v[72:75], v[164:167], v[224:227], v[72:75]
	v_mfma_f32_16x16x32_bf16 v[72:75], v[160:163], v[220:223], v[72:75]
	v_mfma_f32_16x16x32_bf16 v[68:71], v[176:179], v[220:223], v[68:71]
	v_mfma_f32_16x16x32_bf16 v[68:71], v[180:183], v[224:227], v[68:71]
	v_mfma_f32_16x16x32_bf16 v[84:87], v[180:183], v[216:219], v[84:87]
	v_mfma_f32_16x16x32_bf16 v[84:87], v[176:179], v[212:215], v[84:87]
	v_mfma_f32_16x16x32_bf16 v[100:103], v[176:179], v[204:207], v[100:103]
	v_mfma_f32_16x16x32_bf16 v[100:103], v[180:183], v[208:211], v[100:103]
	v_mfma_f32_16x16x32_bf16 v[124:127], v[180:183], v[188:191], v[124:127]
	v_mfma_f32_16x16x32_bf16 v[124:127], v[176:179], v[184:187], v[124:127]
	s_setprio 0
	s_barrier
; #define PG8_STAGE(bufoff, gbase, voff) do { _Pragma("unroll") for (int _i = 0; _i < 2; ++_i) \
;         __builtin_amdgcn_global_load_lds((const unsigned*)((const char*)(gbase) + (voff)[_i]), (PG8_LAS unsigned*)(lds + (bufoff) + ldsw + _i * 8192), 16, 0, 0); } while (0)
; #define PG8_LDA(dst, b, h) do { _Pragma("unroll") for (int m = 0; m < 4; ++m) _Pragma("unroll") for (int k = 0; k < 2; ++k) dst[m][k] = *(const PG8_LAS bf16x8*)(lds + PG8_SA(b, h) + aoff + m * 2048 + k * 1024); } while (0)
; #define PG8_WAIT_V(n) asm volatile("s_waitcnt vmcnt(" #n ")" ::: "memory")
; #define PG8_WAIT_L(n) asm volatile("s_waitcnt lgkmcnt(" #n ")" ::: "memory")
; #define PG8_BAR __builtin_amdgcn_s_barrier()
; #define PG8_SCHED __builtin_amdgcn_sched_barrier(0)
; template <class Epi, class Sched, bool ALIGN_EPI = false, bool SP2 = false, bool I8 = false>
; __device__ __forceinline__ void gemm_phase(PG8_LAS unsigned char* lds, const Gemm g, const Sched& S, const Epi& E) {
;     ...
;         for (int t = 0; t < nt; t += 2) {
;             const bool last = (t == nt - 2);
;             const char* a1 = cA + (size_t)(t + 1) * kstep;
;             const char* a2 = last ? nA : cA + (size_t)(t + 2) * kstep; const char* b2 = last ? nB : cB + (size_t)(t + 2) * kstep;
;     ...
;             PG8_LDA(At, 1, 1); PG8_STAGE(PG8_SB(1, 0), b3, voffB); PG8_STAGE(PG8_SB(1, 1), b3 + hstep, voffB); PG8_STAGE(PG8_SA(1, 0), a3, voffA);
;             PG8_WAIT_V(8); PG8_WAIT_L(0); PG8_BAR; PG8_MMA(1, 0, At, B0); PG8_MMA(1, 1, At, B1); PG8_BAR; PG8_SCHED;
	s_add_i32 s50, s56, s46
	v_lshl_add_u64 v[168:169], v[168:169], 0, s[84:85]
	s_mov_b32 m0, s50
	ds_read_b128 v[184:187], v173 offset:49152
	ds_read_b128 v[188:191], v173 offset:50176
	ds_read_b128 v[204:207], v173 offset:51200
	ds_read_b128 v[208:211], v173 offset:52224
	ds_read_b128 v[212:215], v173 offset:53248
	ds_read_b128 v[216:219], v173 offset:54272
	ds_read_b128 v[220:223], v173 offset:55296
	ds_read_b128 v[224:227], v173 offset:56320
	global_load_lds_dwordx4 v[168:169], off
	s_add_i32 m0, s50, 0x2000
	s_add_u32 s50, s72, 0x100080
	v_lshl_add_u64 v[168:169], v[228:229], 0, s[84:85]
	s_addc_u32 s51, s73, 0
	s_add_i32 s56, s57, s46
	global_load_lds_dwordx4 v[168:169], off
	v_lshl_add_u64 v[168:169], s[50:51], 0, v[2:3]
	s_mov_b32 m0, s56
	s_nop 0
	global_load_lds_dwordx4 v[168:169], off
	v_lshl_add_u64 v[168:169], s[50:51], 0, v[144:145]
	s_add_i32 m0, s56, 0x2000
	s_nop 0
	global_load_lds_dwordx4 v[168:169], off
	v_lshl_add_u64 v[168:169], v[240:241], 0, s[84:85]
	s_mov_b32 m0, s28
	s_nop 0
	global_load_lds_dwordx4 v[168:169], off
	v_lshl_add_u64 v[168:169], v[242:243], 0, s[84:85]
	s_mov_b32 m0, s65
	s_nop 0
	global_load_lds_dwordx4 v[168:169], off
	s_waitcnt vmcnt(8)
	s_waitcnt lgkmcnt(0)
	s_barrier
	s_setprio 1
	s_waitcnt lgkmcnt(0)
	v_mfma_f32_16x16x32_bf16 v[64:67], v[112:115], v[184:187], v[64:67]
	v_mfma_f32_16x16x32_bf16 v[64:67], v[120:123], v[188:191], v[64:67]
	v_mfma_f32_16x16x32_bf16 v[48:51], v[120:123], v[208:211], v[48:51]
	v_mfma_f32_16x16x32_bf16 v[48:51], v[112:115], v[204:207], v[48:51]
	v_mfma_f32_16x16x32_bf16 v[32:35], v[112:115], v[212:215], v[32:35]
	v_mfma_f32_16x16x32_bf16 v[32:35], v[120:123], v[216:219], v[32:35]
	v_mfma_f32_16x16x32_bf16 v[16:19], v[120:123], v[224:227], v[16:19]
	v_mfma_f32_16x16x32_bf16 v[16:19], v[112:115], v[220:223], v[16:19]
	v_mfma_f32_16x16x32_bf16 v[12:15], v[152:155], v[220:223], v[12:15]
	v_mfma_f32_16x16x32_bf16 v[12:15], v[156:159], v[224:227], v[12:15]
	v_mfma_f32_16x16x32_bf16 v[28:31], v[156:159], v[216:219], v[28:31]
	v_mfma_f32_16x16x32_bf16 v[28:31], v[152:155], v[212:215], v[28:31]
	v_mfma_f32_16x16x32_bf16 v[44:47], v[152:155], v[204:207], v[44:47]
	v_mfma_f32_16x16x32_bf16 v[44:47], v[156:159], v[208:211], v[44:47]
	v_mfma_f32_16x16x32_bf16 v[60:63], v[156:159], v[188:191], v[60:63]
	v_mfma_f32_16x16x32_bf16 v[60:63], v[152:155], v[184:187], v[60:63]
	v_mfma_f32_16x16x32_bf16 v[56:59], v[160:163], v[184:187], v[56:59]
	v_mfma_f32_16x16x32_bf16 v[56:59], v[164:167], v[188:191], v[56:59]
	v_mfma_f32_16x16x32_bf16 v[40:43], v[164:167], v[208:211], v[40:43]
	v_mfma_f32_16x16x32_bf16 v[40:43], v[160:163], v[204:207], v[40:43]
	v_mfma_f32_16x16x32_bf16 v[24:27], v[160:163], v[212:215], v[24:27]
	v_mfma_f32_16x16x32_bf16 v[24:27], v[164:167], v[216:219], v[24:27]
	v_mfma_f32_16x16x32_bf16 v[8:11], v[164:167], v[224:227], v[8:11]
	v_mfma_f32_16x16x32_bf16 v[8:11], v[160:163], v[220:223], v[8:11]
	v_mfma_f32_16x16x32_bf16 v[4:7], v[176:179], v[220:223], v[4:7]
	v_mfma_f32_16x16x32_bf16 v[4:7], v[180:183], v[224:227], v[4:7]
	v_mfma_f32_16x16x32_bf16 v[20:23], v[180:183], v[216:219], v[20:23]
	v_mfma_f32_16x16x32_bf16 v[20:23], v[176:179], v[212:215], v[20:23]
	v_mfma_f32_16x16x32_bf16 v[36:39], v[176:179], v[204:207], v[36:39]
	v_mfma_f32_16x16x32_bf16 v[36:39], v[180:183], v[208:211], v[36:39]
	v_mfma_f32_16x16x32_bf16 v[52:55], v[180:183], v[188:191], v[52:55]
	v_mfma_f32_16x16x32_bf16 v[52:55], v[176:179], v[184:187], v[52:55]
	s_setprio 0
	s_add_i32 s97, s97, 2
	s_add_u32 s12, s12, 0x100
	s_addc_u32 s13, s13, 0
	s_add_u32 s37, s37, 0x100
	s_addc_u32 s61, s61, 0
	s_cmp_gt_u32 s97, 61
	s_barrier
	s_cbranch_scc0 .LBB0_230

; #define PG8_STAGE(bufoff, gbase, voff) do { _Pragma("unroll") for (int _i = 0; _i < 2; ++_i) \
;         __builtin_amdgcn_global_load_lds((const unsigned*)((const char*)(gbase) + (voff)[_i]), (PG8_LAS unsigned*)(lds + (bufoff) + ldsw + _i * 8192), 16, 0, 0); } while (0)
; #define PG8_LDA(dst, b, h) do { _Pragma("unroll") for (int m = 0; m < 4; ++m) _Pragma("unroll") for (int k = 0; k < 2; ++k) dst[m][k] = *(const PG8_LAS bf16x8*)(lds + PG8_SA(b, h) + aoff + m * 2048 + k * 1024); } while (0)
; #define PG8_LDB(dst, b, h) do { _Pragma("unroll") for (int n = 0; n < 2; ++n) _Pragma("unroll") for (int k = 0; k < 2; ++k) dst[n][k] = *(const PG8_LAS bf16x8*)(lds + PG8_SB(b, h) + boff + n * 2048 + k * 1024); } while (0)
; #define PG8_WAIT_V(n) asm volatile("s_waitcnt vmcnt(" #n ")" ::: "memory")
; #define PG8_WAIT_L(n) asm volatile("s_waitcnt lgkmcnt(" #n ")" ::: "memory")
; #define PG8_BAR __builtin_amdgcn_s_barrier()
; #define PG8_SCHED __builtin_amdgcn_sched_barrier(0)
; template <class Epi, class Sched, bool ALIGN_EPI = false, bool SP2 = false, bool I8 = false>
; __device__ __forceinline__ void gemm_phase(PG8_LAS unsigned char* lds, const Gemm g, const Sched& S, const Epi& E) {
;     ...
;         const bool has_next = S.next(ui + 1, nxt);
;         const char* nA = has_next ? (const char*)g.A + (size_t)nxt.pm * tstep : cA; const char* nB = has_next ? (const char*)g.Bt + (size_t)nxt.pn * tstep : cB;
;         for (int t = 0; t < nt; t += 2) {
;             const bool last = (t == nt - 2);
;             const char* a1 = cA + (size_t)(t + 1) * kstep;
;             const char* a2 = last ? nA : cA + (size_t)(t + 2) * kstep; const char* b2 = last ? nB : cB + (size_t)(t + 2) * kstep;
;             const char* a3 = a2 + kstep; const char* b3 = b2 + kstep;
;             if (last && has_next) S.a_ready(nxt);
;             if constexpr (SP2) {
;             PG8_LDB(B0, 0, 0); PG8_LDB(B1, 0, 1); PG8_SCHED; PG8_LDA(At, 0, 0); PG8_STAGE(PG8_SA(1, 1), a1 + hstep, voffA);
;             PG8_WAIT_V(8); PG8_WAIT_L(0); PG8_BAR; PG8_MMA(0, 0, At, B0); PG8_MMA(0, 1, At, B1); PG8_BAR; PG8_SCHED;
;             PG8_LDA(At, 0, 1); PG8_STAGE(PG8_SB(0, 0), b2, voffB); PG8_STAGE(PG8_SB(0, 1), b2 + hstep, voffB); PG8_STAGE(PG8_SA(0, 0), a2, voffA);
;             PG8_WAIT_V(8); PG8_WAIT_L(0); PG8_BAR; PG8_MMA(1, 0, At, B0); PG8_MMA(1, 1, At, B1); PG8_BAR; PG8_SCHED;
.LBB0_1455:
	s_ashr_i32 s17, s16, 31
	s_lshl_b64 s[20:21], s[16:17], 21
	s_add_u32 s20, s28, s20
	s_addc_u32 s21, s34, s21
	s_and_b64 s[22:23], s[8:9], exec
	s_cselect_b32 s17, s21, s25
	s_cselect_b32 s51, s20, s24
	s_ashr_i32 s19, s18, 31
	s_lshl_b64 s[22:23], s[18:19], 21
	s_add_u32 s22, s35, s22
	s_addc_u32 s23, s39, s23
	s_and_b64 s[36:37], s[8:9], exec
	s_cselect_b32 s19, s23, s27
	s_cselect_b32 s52, s22, s26
	s_add_u32 s24, s24, 0x100080
	s_addc_u32 s25, s25, 0
	s_add_u32 s53, s26, 0x100
	s_addc_u32 s54, s27, 0
	s_mov_b32 s55, -2
	s_waitcnt vmcnt(0)
	s_add_u32 s26, s24, 0xfff00080
	s_addc_u32 s27, s25, -1
	s_add_i32 s56, 0, 0x10000
	s_cmp_eq_u32 s55, 60
	s_cselect_b32 s37, s17, s27
	s_cselect_b32 s36, s51, s26
	s_cselect_b32 s27, s19, s54
	s_cselect_b32 s26, s52, s53
	s_add_i32 s58, 0, 0x14000
	v_add_u32_e32 v144, s56, v240
	v_add_u32_e32 v160, s58, v240
	ds_read_b128 v[124:127], v144
	ds_read_b128 v[128:131], v144 offset:1024
	ds_read_b128 v[132:135], v144 offset:2048
	ds_read_b128 v[144:147], v144 offset:3072
	ds_read_b128 v[148:151], v160
	ds_read_b128 v[152:155], v160 offset:1024
	ds_read_b128 v[156:159], v160 offset:2048
	ds_read_b128 v[160:163], v160 offset:3072
	v_lshl_add_u64 v[218:219], s[24:25], 0, v[210:211]
	s_add_i32 m0, s41, 0xc000
	ds_read_b128 v[164:167], v242
	ds_read_b128 v[168:171], v242 offset:1024
	ds_read_b128 v[172:175], v242 offset:2048
	ds_read_b128 v[176:179], v242 offset:3072
	ds_read_b128 v[180:183], v242 offset:4096
	ds_read_b128 v[184:187], v242 offset:5120
	ds_read_b128 v[188:191], v242 offset:6144
	ds_read_b128 v[214:217], v242 offset:7168
	global_load_lds_dwordx4 v[218:219], off
	v_lshl_add_u64 v[218:219], s[24:25], 0, v[212:213]
	s_add_i32 m0, s41, 0xe000
	s_nop 0
	global_load_lds_dwordx4 v[218:219], off
	s_waitcnt vmcnt(8)
	s_waitcnt lgkmcnt(0)
	s_barrier
	s_setprio 1
	s_waitcnt lgkmcnt(0)
	v_mfma_f32_16x16x32_bf16 v[140:143], v[124:127], v[164:167], 0
	v_mfma_f32_16x16x32_bf16 v[140:143], v[128:131], v[168:171], v[140:143]
	v_mfma_f32_16x16x32_bf16 v[112:115], v[128:131], v[176:179], 0
	v_mfma_f32_16x16x32_bf16 v[112:115], v[124:127], v[172:175], v[112:115]
	v_mfma_f32_16x16x32_bf16 v[96:99], v[124:127], v[180:183], 0
	v_mfma_f32_16x16x32_bf16 v[96:99], v[128:131], v[184:187], v[96:99]
	v_mfma_f32_16x16x32_bf16 v[80:83], v[128:131], v[214:217], 0
	v_mfma_f32_16x16x32_bf16 v[80:83], v[124:127], v[188:191], v[80:83]
	v_mfma_f32_16x16x32_bf16 v[76:79], v[132:135], v[188:191], 0
	v_mfma_f32_16x16x32_bf16 v[76:79], v[144:147], v[214:217], v[76:79]
	v_mfma_f32_16x16x32_bf16 v[92:95], v[144:147], v[184:187], 0
	v_mfma_f32_16x16x32_bf16 v[92:95], v[132:135], v[180:183], v[92:95]
	v_mfma_f32_16x16x32_bf16 v[108:111], v[132:135], v[172:175], 0
	v_mfma_f32_16x16x32_bf16 v[108:111], v[144:147], v[176:179], v[108:111]
	v_mfma_f32_16x16x32_bf16 v[136:139], v[144:147], v[168:171], 0
	v_mfma_f32_16x16x32_bf16 v[136:139], v[132:135], v[164:167], v[136:139]
	v_mfma_f32_16x16x32_bf16 v[120:123], v[148:151], v[164:167], 0
	v_mfma_f32_16x16x32_bf16 v[120:123], v[152:155], v[168:171], v[120:123]
	v_mfma_f32_16x16x32_bf16 v[104:107], v[152:155], v[176:179], 0
	v_mfma_f32_16x16x32_bf16 v[104:107], v[148:151], v[172:175], v[104:107]
	v_mfma_f32_16x16x32_bf16 v[88:91], v[148:151], v[180:183], 0
	v_mfma_f32_16x16x32_bf16 v[88:91], v[152:155], v[184:187], v[88:91]
	v_mfma_f32_16x16x32_bf16 v[72:75], v[152:155], v[214:217], 0
	v_mfma_f32_16x16x32_bf16 v[72:75], v[148:151], v[188:191], v[72:75]
	v_mfma_f32_16x16x32_bf16 v[68:71], v[156:159], v[188:191], 0
	v_mfma_f32_16x16x32_bf16 v[68:71], v[160:163], v[214:217], v[68:71]
	v_mfma_f32_16x16x32_bf16 v[84:87], v[160:163], v[184:187], 0
	v_mfma_f32_16x16x32_bf16 v[84:87], v[156:159], v[180:183], v[84:87]
	v_mfma_f32_16x16x32_bf16 v[100:103], v[156:159], v[172:175], 0
	v_mfma_f32_16x16x32_bf16 v[100:103], v[160:163], v[176:179], v[100:103]
	v_mfma_f32_16x16x32_bf16 v[116:119], v[160:163], v[168:171], 0
	v_mfma_f32_16x16x32_bf16 v[116:119], v[156:159], v[164:167], v[116:119]
	s_setprio 0
	s_barrier
	s_add_i32 s56, s56, s40
	v_lshl_add_u64 v[218:219], s[26:27], 0, v[2:3]
	s_mov_b32 m0, s56
	ds_read_b128 v[164:167], v242 offset:16384
	ds_read_b128 v[168:171], v242 offset:17408
	ds_read_b128 v[172:175], v242 offset:18432
	ds_read_b128 v[176:179], v242 offset:19456
	ds_read_b128 v[180:183], v242 offset:20480
	ds_read_b128 v[184:187], v242 offset:21504
	ds_read_b128 v[188:191], v242 offset:22528
	ds_read_b128 v[214:217], v242 offset:23552
	global_load_lds_dwordx4 v[218:219], off
	s_add_i32 m0, s56, 0x2000
	s_add_u32 s56, s26, 0x100000
	v_lshl_add_u64 v[220:221], s[26:27], 0, v[204:205]
	s_addc_u32 s57, s27, 0
	s_add_i32 s58, s58, s40
	global_load_lds_dwordx4 v[220:221], off
	v_lshl_add_u64 v[222:223], s[56:57], 0, v[2:3]
	s_mov_b32 m0, s58
	v_lshl_add_u64 v[224:225], s[36:37], 0, v[206:207]
	global_load_lds_dwordx4 v[222:223], off
	v_lshl_add_u64 v[222:223], s[56:57], 0, v[204:205]
	s_add_i32 m0, s58, 0x2000
	s_nop 0
	global_load_lds_dwordx4 v[222:223], off
	v_lshl_add_u64 v[222:223], s[36:37], 0, v[208:209]
	s_mov_b32 m0, s41
	s_nop 0
	global_load_lds_dwordx4 v[222:223], off
	s_mov_b32 m0, s42
	s_nop 0
	global_load_lds_dwordx4 v[224:225], off
	s_waitcnt vmcnt(8)
	s_waitcnt lgkmcnt(0)
	s_barrier
; #define PG8_STAGE(bufoff, gbase, voff) do { _Pragma("unroll") for (int _i = 0; _i < 2; ++_i) \
;         __builtin_amdgcn_global_load_lds((const unsigned*)((const char*)(gbase) + (voff)[_i]), (PG8_LAS unsigned*)(lds + (bufoff) + ldsw + _i * 8192), 16, 0, 0); } while (0)
; #define PG8_LDA(dst, b, h) do { _Pragma("unroll") for (int m = 0; m < 4; ++m) _Pragma("unroll") for (int k = 0; k < 2; ++k) dst[m][k] = *(const PG8_LAS bf16x8*)(lds + PG8_SA(b, h) + aoff + m * 2048 + k * 1024); } while (0)
; #define PG8_LDB(dst, b, h) do { _Pragma("unroll") for (int n = 0; n < 2; ++n) _Pragma("unroll") for (int k = 0; k < 2; ++k) dst[n][k] = *(const PG8_LAS bf16x8*)(lds + PG8_SB(b, h) + boff + n * 2048 + k * 1024); } while (0)
; #define PG8_WAIT_V(n) asm volatile("s_waitcnt vmcnt(" #n ")" ::: "memory")
; #define PG8_WAIT_L(n) asm volatile("s_waitcnt lgkmcnt(" #n ")" ::: "memory")
; #define PG8_BAR __builtin_amdgcn_s_barrier()
; #define PG8_SCHED __builtin_amdgcn_sched_barrier(0)
; template <class Epi, class Sched, bool ALIGN_EPI = false, bool SP2 = false, bool I8 = false>
; __device__ __forceinline__ void gemm_phase(PG8_LAS unsigned char* lds, const Gemm g, const Sched& S, const Epi& E) {
;     ...
;             PG8_WAIT_V(8); PG8_WAIT_L(0); PG8_BAR; PG8_MMA(1, 0, At, B0); PG8_MMA(1, 1, At, B1); PG8_BAR; PG8_SCHED;
;             PG8_LDB(B0, 1, 0); PG8_LDB(B1, 1, 1); PG8_SCHED; PG8_LDA(At, 1, 0); PG8_STAGE(PG8_SA(0, 1), a2 + hstep, voffA);
;             PG8_WAIT_V(8); PG8_WAIT_L(0); PG8_BAR; PG8_MMA(0, 0, At, B0); PG8_MMA(0, 1, At, B1); PG8_BAR; PG8_SCHED;
	s_setprio 1
	s_waitcnt lgkmcnt(0)
	v_mfma_f32_16x16x32_bf16 v[64:67], v[124:127], v[164:167], 0
	v_mfma_f32_16x16x32_bf16 v[64:67], v[128:131], v[168:171], v[64:67]
	v_mfma_f32_16x16x32_bf16 v[48:51], v[128:131], v[176:179], 0
	v_mfma_f32_16x16x32_bf16 v[48:51], v[124:127], v[172:175], v[48:51]
	v_mfma_f32_16x16x32_bf16 v[32:35], v[124:127], v[180:183], 0
	v_mfma_f32_16x16x32_bf16 v[32:35], v[128:131], v[184:187], v[32:35]
	v_mfma_f32_16x16x32_bf16 v[16:19], v[128:131], v[214:217], 0
	v_mfma_f32_16x16x32_bf16 v[16:19], v[124:127], v[188:191], v[16:19]
	v_mfma_f32_16x16x32_bf16 v[12:15], v[132:135], v[188:191], 0
	v_mfma_f32_16x16x32_bf16 v[12:15], v[144:147], v[214:217], v[12:15]
	v_mfma_f32_16x16x32_bf16 v[28:31], v[144:147], v[184:187], 0
	v_mfma_f32_16x16x32_bf16 v[28:31], v[132:135], v[180:183], v[28:31]
	v_mfma_f32_16x16x32_bf16 v[44:47], v[132:135], v[172:175], 0
	v_mfma_f32_16x16x32_bf16 v[44:47], v[144:147], v[176:179], v[44:47]
	v_mfma_f32_16x16x32_bf16 v[60:63], v[144:147], v[168:171], 0
	v_mfma_f32_16x16x32_bf16 v[60:63], v[132:135], v[164:167], v[60:63]
	v_mfma_f32_16x16x32_bf16 v[56:59], v[148:151], v[164:167], 0
	v_mfma_f32_16x16x32_bf16 v[56:59], v[152:155], v[168:171], v[56:59]
	v_mfma_f32_16x16x32_bf16 v[40:43], v[152:155], v[176:179], 0
	v_mfma_f32_16x16x32_bf16 v[40:43], v[148:151], v[172:175], v[40:43]
	v_mfma_f32_16x16x32_bf16 v[24:27], v[148:151], v[180:183], 0
	v_mfma_f32_16x16x32_bf16 v[24:27], v[152:155], v[184:187], v[24:27]
	v_mfma_f32_16x16x32_bf16 v[8:11], v[152:155], v[214:217], 0
	v_mfma_f32_16x16x32_bf16 v[8:11], v[148:151], v[188:191], v[8:11]
	v_mfma_f32_16x16x32_bf16 v[4:7], v[156:159], v[188:191], 0
	v_mfma_f32_16x16x32_bf16 v[4:7], v[160:163], v[214:217], v[4:7]
	v_mfma_f32_16x16x32_bf16 v[20:23], v[160:163], v[184:187], 0
	v_mfma_f32_16x16x32_bf16 v[20:23], v[156:159], v[180:183], v[20:23]
	v_mfma_f32_16x16x32_bf16 v[36:39], v[156:159], v[172:175], 0
	v_mfma_f32_16x16x32_bf16 v[36:39], v[160:163], v[176:179], v[36:39]
	v_mfma_f32_16x16x32_bf16 v[52:55], v[160:163], v[168:171], 0
	v_mfma_f32_16x16x32_bf16 v[52:55], v[156:159], v[164:167], v[52:55]
	s_setprio 0
	s_barrier
	s_add_i32 s56, 0, 0x18000
	s_add_i32 s57, 0, 0x1c000
	v_add_u32_e32 v144, s56, v240
	v_add_u32_e32 v160, s57, v240
	ds_read_b128 v[124:127], v144
	ds_read_b128 v[128:131], v144 offset:1024
	ds_read_b128 v[132:135], v144 offset:2048
	ds_read_b128 v[144:147], v144 offset:3072
	ds_read_b128 v[148:151], v160
	ds_read_b128 v[152:155], v160 offset:1024
	ds_read_b128 v[156:159], v160 offset:2048
	ds_read_b128 v[160:163], v160 offset:3072
	s_add_u32 s36, s36, 0x100000
	s_addc_u32 s37, s37, 0
	s_mov_b32 m0, s43
	v_lshl_add_u64 v[226:227], s[36:37], 0, v[208:209]
	ds_read_b128 v[164:167], v242 offset:32768
	ds_read_b128 v[168:171], v242 offset:33792
	ds_read_b128 v[172:175], v242 offset:34816
	ds_read_b128 v[176:179], v242 offset:35840
	ds_read_b128 v[180:183], v242 offset:36864
	ds_read_b128 v[184:187], v242 offset:37888
	ds_read_b128 v[188:191], v242 offset:38912
	ds_read_b128 v[214:217], v242 offset:39936
	global_load_lds_dwordx4 v[226:227], off
	v_lshl_add_u64 v[226:227], s[36:37], 0, v[206:207]
	s_mov_b32 m0, s44
	s_nop 0
	global_load_lds_dwordx4 v[226:227], off
	s_waitcnt vmcnt(8)
	s_waitcnt lgkmcnt(0)
	s_barrier
	s_setprio 1
	s_waitcnt lgkmcnt(0)
	v_mfma_f32_16x16x32_bf16 v[140:143], v[124:127], v[164:167], v[140:143]
	v_mfma_f32_16x16x32_bf16 v[140:143], v[128:131], v[168:171], v[140:143]
	v_mfma_f32_16x16x32_bf16 v[112:115], v[128:131], v[176:179], v[112:115]
	v_mfma_f32_16x16x32_bf16 v[112:115], v[124:127], v[172:175], v[112:115]
	v_mfma_f32_16x16x32_bf16 v[96:99], v[124:127], v[180:183], v[96:99]
	v_mfma_f32_16x16x32_bf16 v[96:99], v[128:131], v[184:187], v[96:99]
	v_mfma_f32_16x16x32_bf16 v[80:83], v[128:131], v[214:217], v[80:83]
	v_mfma_f32_16x16x32_bf16 v[80:83], v[124:127], v[188:191], v[80:83]
	v_mfma_f32_16x16x32_bf16 v[76:79], v[132:135], v[188:191], v[76:79]
	v_mfma_f32_16x16x32_bf16 v[76:79], v[144:147], v[214:217], v[76:79]
	v_mfma_f32_16x16x32_bf16 v[92:95], v[144:147], v[184:187], v[92:95]
	v_mfma_f32_16x16x32_bf16 v[92:95], v[132:135], v[180:183], v[92:95]
	v_mfma_f32_16x16x32_bf16 v[108:111], v[132:135], v[172:175], v[108:111]
	v_mfma_f32_16x16x32_bf16 v[108:111], v[144:147], v[176:179], v[108:111]
	v_mfma_f32_16x16x32_bf16 v[136:139], v[144:147], v[168:171], v[136:139]
	v_mfma_f32_16x16x32_bf16 v[136:139], v[132:135], v[164:167], v[136:139]
	v_mfma_f32_16x16x32_bf16 v[120:123], v[148:151], v[164:167], v[120:123]
	v_mfma_f32_16x16x32_bf16 v[120:123], v[152:155], v[168:171], v[120:123]
	v_mfma_f32_16x16x32_bf16 v[104:107], v[152:155], v[176:179], v[104:107]
	v_mfma_f32_16x16x32_bf16 v[104:107], v[148:151], v[172:175], v[104:107]
	v_mfma_f32_16x16x32_bf16 v[88:91], v[148:151], v[180:183], v[88:91]
	v_mfma_f32_16x16x32_bf16 v[88:91], v[152:155], v[184:187], v[88:91]
	v_mfma_f32_16x16x32_bf16 v[72:75], v[152:155], v[214:217], v[72:75]
	v_mfma_f32_16x16x32_bf16 v[72:75], v[148:151], v[188:191], v[72:75]
	v_mfma_f32_16x16x32_bf16 v[68:71], v[156:159], v[188:191], v[68:71]
	v_mfma_f32_16x16x32_bf16 v[68:71], v[160:163], v[214:217], v[68:71]
	v_mfma_f32_16x16x32_bf16 v[84:87], v[160:163], v[184:187], v[84:87]
	v_mfma_f32_16x16x32_bf16 v[84:87], v[156:159], v[180:183], v[84:87]
	v_mfma_f32_16x16x32_bf16 v[100:103], v[156:159], v[172:175], v[100:103]
	v_mfma_f32_16x16x32_bf16 v[100:103], v[160:163], v[176:179], v[100:103]
	v_mfma_f32_16x16x32_bf16 v[116:119], v[160:163], v[168:171], v[116:119]
	v_mfma_f32_16x16x32_bf16 v[116:119], v[156:159], v[164:167], v[116:119]
	s_setprio 0
	s_barrier
; #define PG8_STAGE(bufoff, gbase, voff) do { _Pragma("unroll") for (int _i = 0; _i < 2; ++_i) \
;         __builtin_amdgcn_global_load_lds((const unsigned*)((const char*)(gbase) + (voff)[_i]), (PG8_LAS unsigned*)(lds + (bufoff) + ldsw + _i * 8192), 16, 0, 0); } while (0)
; #define PG8_LDA(dst, b, h) do { _Pragma("unroll") for (int m = 0; m < 4; ++m) _Pragma("unroll") for (int k = 0; k < 2; ++k) dst[m][k] = *(const PG8_LAS bf16x8*)(lds + PG8_SA(b, h) + aoff + m * 2048 + k * 1024); } while (0)
; #define PG8_LDB(dst, b, h) do { _Pragma("unroll") for (int n = 0; n < 2; ++n) _Pragma("unroll") for (int k = 0; k < 2; ++k) dst[n][k] = *(const PG8_LAS bf16x8*)(lds + PG8_SB(b, h) + boff + n * 2048 + k * 1024); } while (0)
; #define PG8_WAIT_V(n) asm volatile("s_waitcnt vmcnt(" #n ")" ::: "memory")
; #define PG8_WAIT_L(n) asm volatile("s_waitcnt lgkmcnt(" #n ")" ::: "memory")
; #define PG8_BAR __builtin_amdgcn_s_barrier()
; #define PG8_SCHED __builtin_amdgcn_sched_barrier(0)
; template <class Epi, class Sched, bool ALIGN_EPI = false, bool SP2 = false, bool I8 = false>
; __device__ __forceinline__ void gemm_phase(PG8_LAS unsigned char* lds, const Gemm g, const Sched& S, const Epi& E) {
;     ...
;         for (int t = 0; t < nt; t += 2) {
;             const bool last = (t == nt - 2);
;             const char* a1 = cA + (size_t)(t + 1) * kstep;
;             const char* a2 = last ? nA : cA + (size_t)(t + 2) * kstep; const char* b2 = last ? nB : cB + (size_t)(t + 2) * kstep;
;             const char* a3 = a2 + kstep; const char* b3 = b2 + kstep;
;             if (last && has_next) S.a_ready(nxt);
;             if constexpr (SP2) {
;             PG8_LDB(B0, 0, 0); PG8_LDB(B1, 0, 1); PG8_SCHED; PG8_LDA(At, 0, 0); PG8_STAGE(PG8_SA(1, 1), a1 + hstep, voffA);
;     ...
;             PG8_LDA(At, 1, 1); PG8_STAGE(PG8_SB(1, 0), b3, voffB); PG8_STAGE(PG8_SB(1, 1), b3 + hstep, voffB); PG8_STAGE(PG8_SA(1, 0), a3, voffA);
;             PG8_WAIT_V(8); PG8_WAIT_L(0); PG8_BAR; PG8_MMA(1, 0, At, B0); PG8_MMA(1, 1, At, B1); PG8_BAR; PG8_SCHED;
	s_add_i32 s36, s56, s40
	v_lshl_add_u64 v[218:219], v[218:219], 0, s[84:85]
	s_mov_b32 m0, s36
	ds_read_b128 v[164:167], v242 offset:49152
	ds_read_b128 v[168:171], v242 offset:50176
	ds_read_b128 v[172:175], v242 offset:51200
	ds_read_b128 v[176:179], v242 offset:52224
	ds_read_b128 v[180:183], v242 offset:53248
	ds_read_b128 v[184:187], v242 offset:54272
	ds_read_b128 v[188:191], v242 offset:55296
	ds_read_b128 v[214:217], v242 offset:56320
	global_load_lds_dwordx4 v[218:219], off
	s_add_i32 m0, s36, 0x2000
	s_add_u32 s26, s26, 0x100080
	v_lshl_add_u64 v[218:219], v[220:221], 0, s[84:85]
	s_addc_u32 s27, s27, 0
	s_add_i32 s36, s57, s40
	global_load_lds_dwordx4 v[218:219], off
	v_lshl_add_u64 v[218:219], s[26:27], 0, v[2:3]
	s_mov_b32 m0, s36
	s_nop 0
	global_load_lds_dwordx4 v[218:219], off
	v_lshl_add_u64 v[218:219], s[26:27], 0, v[204:205]
	s_add_i32 m0, s36, 0x2000
	s_nop 0
	global_load_lds_dwordx4 v[218:219], off
	v_lshl_add_u64 v[218:219], v[222:223], 0, s[84:85]
	s_mov_b32 m0, s45
	s_nop 0
	global_load_lds_dwordx4 v[218:219], off
	v_lshl_add_u64 v[218:219], v[224:225], 0, s[84:85]
	s_mov_b32 m0, s46
	s_nop 0
	global_load_lds_dwordx4 v[218:219], off
	s_waitcnt vmcnt(8)
	s_waitcnt lgkmcnt(0)
	s_barrier
	s_setprio 1
	s_waitcnt lgkmcnt(0)
	v_mfma_f32_16x16x32_bf16 v[64:67], v[124:127], v[164:167], v[64:67]
	v_mfma_f32_16x16x32_bf16 v[64:67], v[128:131], v[168:171], v[64:67]
	v_mfma_f32_16x16x32_bf16 v[48:51], v[128:131], v[176:179], v[48:51]
	v_mfma_f32_16x16x32_bf16 v[48:51], v[124:127], v[172:175], v[48:51]
	v_mfma_f32_16x16x32_bf16 v[32:35], v[124:127], v[180:183], v[32:35]
	v_mfma_f32_16x16x32_bf16 v[32:35], v[128:131], v[184:187], v[32:35]
	v_mfma_f32_16x16x32_bf16 v[16:19], v[128:131], v[214:217], v[16:19]
	v_mfma_f32_16x16x32_bf16 v[16:19], v[124:127], v[188:191], v[16:19]
	v_mfma_f32_16x16x32_bf16 v[12:15], v[132:135], v[188:191], v[12:15]
	v_mfma_f32_16x16x32_bf16 v[12:15], v[144:147], v[214:217], v[12:15]
	v_mfma_f32_16x16x32_bf16 v[28:31], v[144:147], v[184:187], v[28:31]
	v_mfma_f32_16x16x32_bf16 v[28:31], v[132:135], v[180:183], v[28:31]
	v_mfma_f32_16x16x32_bf16 v[44:47], v[132:135], v[172:175], v[44:47]
	v_mfma_f32_16x16x32_bf16 v[44:47], v[144:147], v[176:179], v[44:47]
	v_mfma_f32_16x16x32_bf16 v[60:63], v[144:147], v[168:171], v[60:63]
	v_mfma_f32_16x16x32_bf16 v[60:63], v[132:135], v[164:167], v[60:63]
	v_mfma_f32_16x16x32_bf16 v[56:59], v[148:151], v[164:167], v[56:59]
	v_mfma_f32_16x16x32_bf16 v[56:59], v[152:155], v[168:171], v[56:59]
	v_mfma_f32_16x16x32_bf16 v[40:43], v[152:155], v[176:179], v[40:43]
	v_mfma_f32_16x16x32_bf16 v[40:43], v[148:151], v[172:175], v[40:43]
	v_mfma_f32_16x16x32_bf16 v[24:27], v[148:151], v[180:183], v[24:27]
	v_mfma_f32_16x16x32_bf16 v[24:27], v[152:155], v[184:187], v[24:27]
	v_mfma_f32_16x16x32_bf16 v[8:11], v[152:155], v[214:217], v[8:11]
	v_mfma_f32_16x16x32_bf16 v[8:11], v[148:151], v[188:191], v[8:11]
	v_mfma_f32_16x16x32_bf16 v[4:7], v[156:159], v[188:191], v[4:7]
	v_mfma_f32_16x16x32_bf16 v[4:7], v[160:163], v[214:217], v[4:7]
	v_mfma_f32_16x16x32_bf16 v[20:23], v[160:163], v[184:187], v[20:23]
	v_mfma_f32_16x16x32_bf16 v[20:23], v[156:159], v[180:183], v[20:23]
	v_mfma_f32_16x16x32_bf16 v[36:39], v[156:159], v[172:175], v[36:39]
	v_mfma_f32_16x16x32_bf16 v[36:39], v[160:163], v[176:179], v[36:39]
	v_mfma_f32_16x16x32_bf16 v[52:55], v[160:163], v[168:171], v[52:55]
	v_mfma_f32_16x16x32_bf16 v[52:55], v[156:159], v[164:167], v[52:55]
	s_setprio 0
	s_add_i32 s55, s55, 2
	s_add_u32 s24, s24, 0x100
	s_addc_u32 s25, s25, 0
	s_add_u32 s53, s53, 0x100
	s_addc_u32 s54, s54, 0
	s_cmp_gt_u32 s55, 61
	s_barrier
	s_cbranch_scc1 .Lkloop_exit_2
.LBB0_1456:
	s_add_u32 s26, s24, 0xfff00080
	s_addc_u32 s27, s25, -1
	s_add_i32 s56, 0, 0x10000
	s_cmp_eq_u32 s55, 60
	s_cselect_b32 s37, s17, s27
	s_cselect_b32 s36, s51, s26
	s_cselect_b32 s27, s19, s54
	s_cselect_b32 s26, s52, s53
	s_add_i32 s58, 0, 0x14000
	v_add_u32_e32 v144, s56, v240
	v_add_u32_e32 v160, s58, v240
	ds_read_b128 v[124:127], v144
	ds_read_b128 v[128:131], v144 offset:1024
	ds_read_b128 v[132:135], v144 offset:2048
	ds_read_b128 v[144:147], v144 offset:3072
	ds_read_b128 v[148:151], v160
	ds_read_b128 v[152:155], v160 offset:1024
	ds_read_b128 v[156:159], v160 offset:2048
	ds_read_b128 v[160:163], v160 offset:3072
	v_lshl_add_u64 v[218:219], s[24:25], 0, v[210:211]
	s_add_i32 m0, s41, 0xc000
	ds_read_b128 v[164:167], v242
	ds_read_b128 v[168:171], v242 offset:1024
	ds_read_b128 v[172:175], v242 offset:2048
	ds_read_b128 v[176:179], v242 offset:3072
	ds_read_b128 v[180:183], v242 offset:4096
	ds_read_b128 v[184:187], v242 offset:5120
	ds_read_b128 v[188:191], v242 offset:6144
	ds_read_b128 v[214:217], v242 offset:7168
	global_load_lds_dwordx4 v[218:219], off
	v_lshl_add_u64 v[218:219], s[24:25], 0, v[212:213]
	s_add_i32 m0, s41, 0xe000
	s_nop 0
	global_load_lds_dwordx4 v[218:219], off
	s_waitcnt vmcnt(8)
	s_waitcnt lgkmcnt(0)
	s_barrier
; #define PG8_STAGE(bufoff, gbase, voff) do { _Pragma("unroll") for (int _i = 0; _i < 2; ++_i) \
;         __builtin_amdgcn_global_load_lds((const unsigned*)((const char*)(gbase) + (voff)[_i]), (PG8_LAS unsigned*)(lds + (bufoff) + ldsw + _i * 8192), 16, 0, 0); } while (0)
; #define PG8_LDA(dst, b, h) do { _Pragma("unroll") for (int m = 0; m < 4; ++m) _Pragma("unroll") for (int k = 0; k < 2; ++k) dst[m][k] = *(const PG8_LAS bf16x8*)(lds + PG8_SA(b, h) + aoff + m * 2048 + k * 1024); } while (0)
; #define PG8_WAIT_V(n) asm volatile("s_waitcnt vmcnt(" #n ")" ::: "memory")
; #define PG8_WAIT_L(n) asm volatile("s_waitcnt lgkmcnt(" #n ")" ::: "memory")
; #define PG8_BAR __builtin_amdgcn_s_barrier()
; #define PG8_SCHED __builtin_amdgcn_sched_barrier(0)
; template <class Epi, class Sched, bool ALIGN_EPI = false, bool SP2 = false, bool I8 = false>
; __device__ __forceinline__ void gemm_phase(PG8_LAS unsigned char* lds, const Gemm g, const Sched& S, const Epi& E) {
;     ...
;             PG8_WAIT_V(8); PG8_WAIT_L(0); PG8_BAR; PG8_MMA(0, 0, At, B0); PG8_MMA(0, 1, At, B1); PG8_BAR; PG8_SCHED;
;             PG8_LDA(At, 0, 1); PG8_STAGE(PG8_SB(0, 0), b2, voffB); PG8_STAGE(PG8_SB(0, 1), b2 + hstep, voffB); PG8_STAGE(PG8_SA(0, 0), a2, voffA);
;             PG8_WAIT_V(8); PG8_WAIT_L(0); PG8_BAR; PG8_MMA(1, 0, At, B0); PG8_MMA(1, 1, At, B1); PG8_BAR; PG8_SCHED;
	s_setprio 1
	s_waitcnt lgkmcnt(0)
	v_mfma_f32_16x16x32_bf16 v[140:143], v[124:127], v[164:167], v[140:143]
	v_mfma_f32_16x16x32_bf16 v[140:143], v[128:131], v[168:171], v[140:143]
	v_mfma_f32_16x16x32_bf16 v[112:115], v[128:131], v[176:179], v[112:115]
	v_mfma_f32_16x16x32_bf16 v[112:115], v[124:127], v[172:175], v[112:115]
	v_mfma_f32_16x16x32_bf16 v[96:99], v[124:127], v[180:183], v[96:99]
	v_mfma_f32_16x16x32_bf16 v[96:99], v[128:131], v[184:187], v[96:99]
	v_mfma_f32_16x16x32_bf16 v[80:83], v[128:131], v[214:217], v[80:83]
	v_mfma_f32_16x16x32_bf16 v[80:83], v[124:127], v[188:191], v[80:83]
	v_mfma_f32_16x16x32_bf16 v[76:79], v[132:135], v[188:191], v[76:79]
	v_mfma_f32_16x16x32_bf16 v[76:79], v[144:147], v[214:217], v[76:79]
	v_mfma_f32_16x16x32_bf16 v[92:95], v[144:147], v[184:187], v[92:95]
	v_mfma_f32_16x16x32_bf16 v[92:95], v[132:135], v[180:183], v[92:95]
	v_mfma_f32_16x16x32_bf16 v[108:111], v[132:135], v[172:175], v[108:111]
	v_mfma_f32_16x16x32_bf16 v[108:111], v[144:147], v[176:179], v[108:111]
	v_mfma_f32_16x16x32_bf16 v[136:139], v[144:147], v[168:171], v[136:139]
	v_mfma_f32_16x16x32_bf16 v[136:139], v[132:135], v[164:167], v[136:139]
	v_mfma_f32_16x16x32_bf16 v[120:123], v[148:151], v[164:167], v[120:123]
	v_mfma_f32_16x16x32_bf16 v[120:123], v[152:155], v[168:171], v[120:123]
	v_mfma_f32_16x16x32_bf16 v[104:107], v[152:155], v[176:179], v[104:107]
	v_mfma_f32_16x16x32_bf16 v[104:107], v[148:151], v[172:175], v[104:107]
	v_mfma_f32_16x16x32_bf16 v[88:91], v[148:151], v[180:183], v[88:91]
	v_mfma_f32_16x16x32_bf16 v[88:91], v[152:155], v[184:187], v[88:91]
	v_mfma_f32_16x16x32_bf16 v[72:75], v[152:155], v[214:217], v[72:75]
	v_mfma_f32_16x16x32_bf16 v[72:75], v[148:151], v[188:191], v[72:75]
	v_mfma_f32_16x16x32_bf16 v[68:71], v[156:159], v[188:191], v[68:71]
	v_mfma_f32_16x16x32_bf16 v[68:71], v[160:163], v[214:217], v[68:71]
	v_mfma_f32_16x16x32_bf16 v[84:87], v[160:163], v[184:187], v[84:87]
	v_mfma_f32_16x16x32_bf16 v[84:87], v[156:159], v[180:183], v[84:87]
	v_mfma_f32_16x16x32_bf16 v[100:103], v[156:159], v[172:175], v[100:103]
	v_mfma_f32_16x16x32_bf16 v[100:103], v[160:163], v[176:179], v[100:103]
	v_mfma_f32_16x16x32_bf16 v[116:119], v[160:163], v[168:171], v[116:119]
	v_mfma_f32_16x16x32_bf16 v[116:119], v[156:159], v[164:167], v[116:119]
	s_setprio 0
	s_barrier
	s_add_i32 s56, s56, s40
	v_lshl_add_u64 v[218:219], s[26:27], 0, v[2:3]
	s_mov_b32 m0, s56
	ds_read_b128 v[164:167], v242 offset:16384
	ds_read_b128 v[168:171], v242 offset:17408
	ds_read_b128 v[172:175], v242 offset:18432
	ds_read_b128 v[176:179], v242 offset:19456
	ds_read_b128 v[180:183], v242 offset:20480
	ds_read_b128 v[184:187], v242 offset:21504
	ds_read_b128 v[188:191], v242 offset:22528
	ds_read_b128 v[214:217], v242 offset:23552
	global_load_lds_dwordx4 v[218:219], off
	s_add_i32 m0, s56, 0x2000
	s_add_u32 s56, s26, 0x100000
	v_lshl_add_u64 v[220:221], s[26:27], 0, v[204:205]
	s_addc_u32 s57, s27, 0
	s_add_i32 s58, s58, s40
	global_load_lds_dwordx4 v[220:221], off
	v_lshl_add_u64 v[222:223], s[56:57], 0, v[2:3]
	s_mov_b32 m0, s58
	v_lshl_add_u64 v[224:225], s[36:37], 0, v[206:207]
	global_load_lds_dwordx4 v[222:223], off
	v_lshl_add_u64 v[222:223], s[56:57], 0, v[204:205]
	s_add_i32 m0, s58, 0x2000
	s_nop 0
	global_load_lds_dwordx4 v[222:223], off
	v_lshl_add_u64 v[222:223], s[36:37], 0, v[208:209]
	s_mov_b32 m0, s41
	s_nop 0
	global_load_lds_dwordx4 v[222:223], off
	s_mov_b32 m0, s42
	s_nop 0
	global_load_lds_dwordx4 v[224:225], off
	s_waitcnt vmcnt(8)
	s_waitcnt lgkmcnt(0)
	s_barrier
	s_setprio 1
	s_waitcnt lgkmcnt(0)
	v_mfma_f32_16x16x32_bf16 v[64:67], v[124:127], v[164:167], v[64:67]
	v_mfma_f32_16x16x32_bf16 v[64:67], v[128:131], v[168:171], v[64:67]
	v_mfma_f32_16x16x32_bf16 v[48:51], v[128:131], v[176:179], v[48:51]
	v_mfma_f32_16x16x32_bf16 v[48:51], v[124:127], v[172:175], v[48:51]
	v_mfma_f32_16x16x32_bf16 v[32:35], v[124:127], v[180:183], v[32:35]
	v_mfma_f32_16x16x32_bf16 v[32:35], v[128:131], v[184:187], v[32:35]
	v_mfma_f32_16x16x32_bf16 v[16:19], v[128:131], v[214:217], v[16:19]
	v_mfma_f32_16x16x32_bf16 v[16:19], v[124:127], v[188:191], v[16:19]
	v_mfma_f32_16x16x32_bf16 v[12:15], v[132:135], v[188:191], v[12:15]
	v_mfma_f32_16x16x32_bf16 v[12:15], v[144:147], v[214:217], v[12:15]
	v_mfma_f32_16x16x32_bf16 v[28:31], v[144:147], v[184:187], v[28:31]
	v_mfma_f32_16x16x32_bf16 v[28:31], v[132:135], v[180:183], v[28:31]
	v_mfma_f32_16x16x32_bf16 v[44:47], v[132:135], v[172:175], v[44:47]
	v_mfma_f32_16x16x32_bf16 v[44:47], v[144:147], v[176:179], v[44:47]
	v_mfma_f32_16x16x32_bf16 v[60:63], v[144:147], v[168:171], v[60:63]
	v_mfma_f32_16x16x32_bf16 v[60:63], v[132:135], v[164:167], v[60:63]
	v_mfma_f32_16x16x32_bf16 v[56:59], v[148:151], v[164:167], v[56:59]
	v_mfma_f32_16x16x32_bf16 v[56:59], v[152:155], v[168:171], v[56:59]
	v_mfma_f32_16x16x32_bf16 v[40:43], v[152:155], v[176:179], v[40:43]
	v_mfma_f32_16x16x32_bf16 v[40:43], v[148:151], v[172:175], v[40:43]
	v_mfma_f32_16x16x32_bf16 v[24:27], v[148:151], v[180:183], v[24:27]
	v_mfma_f32_16x16x32_bf16 v[24:27], v[152:155], v[184:187], v[24:27]
	v_mfma_f32_16x16x32_bf16 v[8:11], v[152:155], v[214:217], v[8:11]
	v_mfma_f32_16x16x32_bf16 v[8:11], v[148:151], v[188:191], v[8:11]
	v_mfma_f32_16x16x32_bf16 v[4:7], v[156:159], v[188:191], v[4:7]
	v_mfma_f32_16x16x32_bf16 v[4:7], v[160:163], v[214:217], v[4:7]
	v_mfma_f32_16x16x32_bf16 v[20:23], v[160:163], v[184:187], v[20:23]
	v_mfma_f32_16x16x32_bf16 v[20:23], v[156:159], v[180:183], v[20:23]
	v_mfma_f32_16x16x32_bf16 v[36:39], v[156:159], v[172:175], v[36:39]
	v_mfma_f32_16x16x32_bf16 v[36:39], v[160:163], v[176:179], v[36:39]
	v_mfma_f32_16x16x32_bf16 v[52:55], v[160:163], v[168:171], v[52:55]
	v_mfma_f32_16x16x32_bf16 v[52:55], v[156:159], v[164:167], v[52:55]
	s_setprio 0
	s_barrier
; #define PG8_STAGE(bufoff, gbase, voff) do { _Pragma("unroll") for (int _i = 0; _i < 2; ++_i) \
;         __builtin_amdgcn_global_load_lds((const unsigned*)((const char*)(gbase) + (voff)[_i]), (PG8_LAS unsigned*)(lds + (bufoff) + ldsw + _i * 8192), 16, 0, 0); } while (0)
; #define PG8_LDA(dst, b, h) do { _Pragma("unroll") for (int m = 0; m < 4; ++m) _Pragma("unroll") for (int k = 0; k < 2; ++k) dst[m][k] = *(const PG8_LAS bf16x8*)(lds + PG8_SA(b, h) + aoff + m * 2048 + k * 1024); } while (0)
; #define PG8_LDB(dst, b, h) do { _Pragma("unroll") for (int n = 0; n < 2; ++n) _Pragma("unroll") for (int k = 0; k < 2; ++k) dst[n][k] = *(const PG8_LAS bf16x8*)(lds + PG8_SB(b, h) + boff + n * 2048 + k * 1024); } while (0)
; #define PG8_WAIT_V(n) asm volatile("s_waitcnt vmcnt(" #n ")" ::: "memory")
; #define PG8_WAIT_L(n) asm volatile("s_waitcnt lgkmcnt(" #n ")" ::: "memory")
; #define PG8_BAR __builtin_amdgcn_s_barrier()
; #define PG8_SCHED __builtin_amdgcn_sched_barrier(0)
; template <class Epi, class Sched, bool ALIGN_EPI = false, bool SP2 = false, bool I8 = false>
; __device__ __forceinline__ void gemm_phase(PG8_LAS unsigned char* lds, const Gemm g, const Sched& S, const Epi& E) {
;     ...
;             PG8_LDB(B0, 1, 0); PG8_LDB(B1, 1, 1); PG8_SCHED; PG8_LDA(At, 1, 0); PG8_STAGE(PG8_SA(0, 1), a2 + hstep, voffA);
;             PG8_WAIT_V(8); PG8_WAIT_L(0); PG8_BAR; PG8_MMA(0, 0, At, B0); PG8_MMA(0, 1, At, B1); PG8_BAR; PG8_SCHED;
	s_add_i32 s56, 0, 0x18000
	s_add_i32 s57, 0, 0x1c000
	v_add_u32_e32 v144, s56, v240
	v_add_u32_e32 v160, s57, v240
	ds_read_b128 v[124:127], v144
	ds_read_b128 v[128:131], v144 offset:1024
	ds_read_b128 v[132:135], v144 offset:2048
	ds_read_b128 v[144:147], v144 offset:3072
	ds_read_b128 v[148:151], v160
	ds_read_b128 v[152:155], v160 offset:1024
	ds_read_b128 v[156:159], v160 offset:2048
	ds_read_b128 v[160:163], v160 offset:3072
	s_add_u32 s36, s36, 0x100000
	s_addc_u32 s37, s37, 0
	s_mov_b32 m0, s43
	v_lshl_add_u64 v[226:227], s[36:37], 0, v[208:209]
	ds_read_b128 v[164:167], v242 offset:32768
	ds_read_b128 v[168:171], v242 offset:33792
	ds_read_b128 v[172:175], v242 offset:34816
	ds_read_b128 v[176:179], v242 offset:35840
	ds_read_b128 v[180:183], v242 offset:36864
	ds_read_b128 v[184:187], v242 offset:37888
	ds_read_b128 v[188:191], v242 offset:38912
	ds_read_b128 v[214:217], v242 offset:39936
	global_load_lds_dwordx4 v[226:227], off
	v_lshl_add_u64 v[226:227], s[36:37], 0, v[206:207]
	s_mov_b32 m0, s44
	s_nop 0
	global_load_lds_dwordx4 v[226:227], off
	s_waitcnt vmcnt(8)
	s_waitcnt lgkmcnt(0)
	s_barrier
	s_setprio 1
	s_waitcnt lgkmcnt(0)
	v_mfma_f32_16x16x32_bf16 v[140:143], v[124:127], v[164:167], v[140:143]
	v_mfma_f32_16x16x32_bf16 v[140:143], v[128:131], v[168:171], v[140:143]
	v_mfma_f32_16x16x32_bf16 v[112:115], v[128:131], v[176:179], v[112:115]
	v_mfma_f32_16x16x32_bf16 v[112:115], v[124:127], v[172:175], v[112:115]
	v_mfma_f32_16x16x32_bf16 v[96:99], v[124:127], v[180:183], v[96:99]
	v_mfma_f32_16x16x32_bf16 v[96:99], v[128:131], v[184:187], v[96:99]
	v_mfma_f32_16x16x32_bf16 v[80:83], v[128:131], v[214:217], v[80:83]
	v_mfma_f32_16x16x32_bf16 v[80:83], v[124:127], v[188:191], v[80:83]
	v_mfma_f32_16x16x32_bf16 v[76:79], v[132:135], v[188:191], v[76:79]
	v_mfma_f32_16x16x32_bf16 v[76:79], v[144:147], v[214:217], v[76:79]
	v_mfma_f32_16x16x32_bf16 v[92:95], v[144:147], v[184:187], v[92:95]
	v_mfma_f32_16x16x32_bf16 v[92:95], v[132:135], v[180:183], v[92:95]
	v_mfma_f32_16x16x32_bf16 v[108:111], v[132:135], v[172:175], v[108:111]
	v_mfma_f32_16x16x32_bf16 v[108:111], v[144:147], v[176:179], v[108:111]
	v_mfma_f32_16x16x32_bf16 v[136:139], v[144:147], v[168:171], v[136:139]
	v_mfma_f32_16x16x32_bf16 v[136:139], v[132:135], v[164:167], v[136:139]
	v_mfma_f32_16x16x32_bf16 v[120:123], v[148:151], v[164:167], v[120:123]
	v_mfma_f32_16x16x32_bf16 v[120:123], v[152:155], v[168:171], v[120:123]
	v_mfma_f32_16x16x32_bf16 v[104:107], v[152:155], v[176:179], v[104:107]
	v_mfma_f32_16x16x32_bf16 v[104:107], v[148:151], v[172:175], v[104:107]
	v_mfma_f32_16x16x32_bf16 v[88:91], v[148:151], v[180:183], v[88:91]
	v_mfma_f32_16x16x32_bf16 v[88:91], v[152:155], v[184:187], v[88:91]
	v_mfma_f32_16x16x32_bf16 v[72:75], v[152:155], v[214:217], v[72:75]
	v_mfma_f32_16x16x32_bf16 v[72:75], v[148:151], v[188:191], v[72:75]
	v_mfma_f32_16x16x32_bf16 v[68:71], v[156:159], v[188:191], v[68:71]
	v_mfma_f32_16x16x32_bf16 v[68:71], v[160:163], v[214:217], v[68:71]
	v_mfma_f32_16x16x32_bf16 v[84:87], v[160:163], v[184:187], v[84:87]
	v_mfma_f32_16x16x32_bf16 v[84:87], v[156:159], v[180:183], v[84:87]
	v_mfma_f32_16x16x32_bf16 v[100:103], v[156:159], v[172:175], v[100:103]
	v_mfma_f32_16x16x32_bf16 v[100:103], v[160:163], v[176:179], v[100:103]
	v_mfma_f32_16x16x32_bf16 v[116:119], v[160:163], v[168:171], v[116:119]
	v_mfma_f32_16x16x32_bf16 v[116:119], v[156:159], v[164:167], v[116:119]
	s_setprio 0
	s_barrier
; #define PG8_STAGE(bufoff, gbase, voff) do { _Pragma("unroll") for (int _i = 0; _i < 2; ++_i) \
;         __builtin_amdgcn_global_load_lds((const unsigned*)((const char*)(gbase) + (voff)[_i]), (PG8_LAS unsigned*)(lds + (bufoff) + ldsw + _i * 8192), 16, 0, 0); } while (0)
; #define PG8_LDA(dst, b, h) do { _Pragma("unroll") for (int m = 0; m < 4; ++m) _Pragma("unroll") for (int k = 0; k < 2; ++k) dst[m][k] = *(const PG8_LAS bf16x8*)(lds + PG8_SA(b, h) + aoff + m * 2048 + k * 1024); } while (0)
; #define PG8_WAIT_V(n) asm volatile("s_waitcnt vmcnt(" #n ")" ::: "memory")
; #define PG8_WAIT_L(n) asm volatile("s_waitcnt lgkmcnt(" #n ")" ::: "memory")
; #define PG8_BAR __builtin_amdgcn_s_barrier()
; #define PG8_SCHED __builtin_amdgcn_sched_barrier(0)
; template <class Epi, class Sched, bool ALIGN_EPI = false, bool SP2 = false, bool I8 = false>
; __device__ __forceinline__ void gemm_phase(PG8_LAS unsigned char* lds, const Gemm g, const Sched& S, const Epi& E) {
;     ...
;         for (int t = 0; t < nt; t += 2) {
;             const bool last = (t == nt - 2);
;             const char* a1 = cA + (size_t)(t + 1) * kstep;
;             const char* a2 = last ? nA : cA + (size_t)(t + 2) * kstep; const char* b2 = last ? nB : cB + (size_t)(t + 2) * kstep;
;     ...
;             PG8_LDA(At, 1, 1); PG8_STAGE(PG8_SB(1, 0), b3, voffB); PG8_STAGE(PG8_SB(1, 1), b3 + hstep, voffB); PG8_STAGE(PG8_SA(1, 0), a3, voffA);
;             PG8_WAIT_V(8); PG8_WAIT_L(0); PG8_BAR; PG8_MMA(1, 0, At, B0); PG8_MMA(1, 1, At, B1); PG8_BAR; PG8_SCHED;
	s_add_i32 s36, s56, s40
	v_lshl_add_u64 v[218:219], v[218:219], 0, s[84:85]
	s_mov_b32 m0, s36
	ds_read_b128 v[164:167], v242 offset:49152
	ds_read_b128 v[168:171], v242 offset:50176
	ds_read_b128 v[172:175], v242 offset:51200
	ds_read_b128 v[176:179], v242 offset:52224
	ds_read_b128 v[180:183], v242 offset:53248
	ds_read_b128 v[184:187], v242 offset:54272
	ds_read_b128 v[188:191], v242 offset:55296
	ds_read_b128 v[214:217], v242 offset:56320
	global_load_lds_dwordx4 v[218:219], off
	s_add_i32 m0, s36, 0x2000
	s_add_u32 s26, s26, 0x100080
	v_lshl_add_u64 v[218:219], v[220:221], 0, s[84:85]
	s_addc_u32 s27, s27, 0
	s_add_i32 s36, s57, s40
	global_load_lds_dwordx4 v[218:219], off
	v_lshl_add_u64 v[218:219], s[26:27], 0, v[2:3]
	s_mov_b32 m0, s36
	s_nop 0
	global_load_lds_dwordx4 v[218:219], off
	v_lshl_add_u64 v[218:219], s[26:27], 0, v[204:205]
	s_add_i32 m0, s36, 0x2000
	s_nop 0
	global_load_lds_dwordx4 v[218:219], off
	v_lshl_add_u64 v[218:219], v[222:223], 0, s[84:85]
	s_mov_b32 m0, s45
	s_nop 0
	global_load_lds_dwordx4 v[218:219], off
	v_lshl_add_u64 v[218:219], v[224:225], 0, s[84:85]
	s_mov_b32 m0, s46
	s_nop 0
	global_load_lds_dwordx4 v[218:219], off
	s_waitcnt vmcnt(8)
	s_waitcnt lgkmcnt(0)
	s_barrier
	s_setprio 1
	s_waitcnt lgkmcnt(0)
	v_mfma_f32_16x16x32_bf16 v[64:67], v[124:127], v[164:167], v[64:67]
	v_mfma_f32_16x16x32_bf16 v[64:67], v[128:131], v[168:171], v[64:67]
	v_mfma_f32_16x16x32_bf16 v[48:51], v[128:131], v[176:179], v[48:51]
	v_mfma_f32_16x16x32_bf16 v[48:51], v[124:127], v[172:175], v[48:51]
	v_mfma_f32_16x16x32_bf16 v[32:35], v[124:127], v[180:183], v[32:35]
	v_mfma_f32_16x16x32_bf16 v[32:35], v[128:131], v[184:187], v[32:35]
	v_mfma_f32_16x16x32_bf16 v[16:19], v[128:131], v[214:217], v[16:19]
	v_mfma_f32_16x16x32_bf16 v[16:19], v[124:127], v[188:191], v[16:19]
	v_mfma_f32_16x16x32_bf16 v[12:15], v[132:135], v[188:191], v[12:15]
	v_mfma_f32_16x16x32_bf16 v[12:15], v[144:147], v[214:217], v[12:15]
	v_mfma_f32_16x16x32_bf16 v[28:31], v[144:147], v[184:187], v[28:31]
	v_mfma_f32_16x16x32_bf16 v[28:31], v[132:135], v[180:183], v[28:31]
	v_mfma_f32_16x16x32_bf16 v[44:47], v[132:135], v[172:175], v[44:47]
	v_mfma_f32_16x16x32_bf16 v[44:47], v[144:147], v[176:179], v[44:47]
	v_mfma_f32_16x16x32_bf16 v[60:63], v[144:147], v[168:171], v[60:63]
	v_mfma_f32_16x16x32_bf16 v[60:63], v[132:135], v[164:167], v[60:63]
	v_mfma_f32_16x16x32_bf16 v[56:59], v[148:151], v[164:167], v[56:59]
	v_mfma_f32_16x16x32_bf16 v[56:59], v[152:155], v[168:171], v[56:59]
	v_mfma_f32_16x16x32_bf16 v[40:43], v[152:155], v[176:179], v[40:43]
	v_mfma_f32_16x16x32_bf16 v[40:43], v[148:151], v[172:175], v[40:43]
	v_mfma_f32_16x16x32_bf16 v[24:27], v[148:151], v[180:183], v[24:27]
	v_mfma_f32_16x16x32_bf16 v[24:27], v[152:155], v[184:187], v[24:27]
	v_mfma_f32_16x16x32_bf16 v[8:11], v[152:155], v[214:217], v[8:11]
	v_mfma_f32_16x16x32_bf16 v[8:11], v[148:151], v[188:191], v[8:11]
	v_mfma_f32_16x16x32_bf16 v[4:7], v[156:159], v[188:191], v[4:7]
	v_mfma_f32_16x16x32_bf16 v[4:7], v[160:163], v[214:217], v[4:7]
	v_mfma_f32_16x16x32_bf16 v[20:23], v[160:163], v[184:187], v[20:23]
	v_mfma_f32_16x16x32_bf16 v[20:23], v[156:159], v[180:183], v[20:23]
	v_mfma_f32_16x16x32_bf16 v[36:39], v[156:159], v[172:175], v[36:39]
	v_mfma_f32_16x16x32_bf16 v[36:39], v[160:163], v[176:179], v[36:39]
	v_mfma_f32_16x16x32_bf16 v[52:55], v[160:163], v[168:171], v[52:55]
	v_mfma_f32_16x16x32_bf16 v[52:55], v[156:159], v[164:167], v[52:55]
	s_setprio 0
	s_add_i32 s55, s55, 2
	s_add_u32 s24, s24, 0x100
	s_addc_u32 s25, s25, 0
	s_add_u32 s53, s53, 0x100
	s_addc_u32 s54, s54, 0
	s_cmp_gt_u32 s55, 61
	s_barrier
	s_cbranch_scc0 .LBB0_1456

; #define PG8_STAGE(bufoff, gbase, voff) do { _Pragma("unroll") for (int _i = 0; _i < 2; ++_i) \
;         __builtin_amdgcn_global_load_lds((const unsigned*)((const char*)(gbase) + (voff)[_i]), (PG8_LAS unsigned*)(lds + (bufoff) + ldsw + _i * 8192), 16, 0, 0); } while (0)
; #define PG8_LDA(dst, b, h) do { _Pragma("unroll") for (int m = 0; m < 4; ++m) _Pragma("unroll") for (int k = 0; k < 2; ++k) dst[m][k] = *(const PG8_LAS bf16x8*)(lds + PG8_SA(b, h) + aoff + m * 2048 + k * 1024); } while (0)
; #define PG8_LDB(dst, b, h) do { _Pragma("unroll") for (int n = 0; n < 2; ++n) _Pragma("unroll") for (int k = 0; k < 2; ++k) dst[n][k] = *(const PG8_LAS bf16x8*)(lds + PG8_SB(b, h) + boff + n * 2048 + k * 1024); } while (0)
; #define PG8_WAIT_V(n) asm volatile("s_waitcnt vmcnt(" #n ")" ::: "memory")
; #define PG8_WAIT_L(n) asm volatile("s_waitcnt lgkmcnt(" #n ")" ::: "memory")
; #define PG8_BAR __builtin_amdgcn_s_barrier()
; #define PG8_SCHED __builtin_amdgcn_sched_barrier(0)
; template <class Epi, class Sched, bool ALIGN_EPI = false, bool SP2 = false, bool I8 = false>
; __device__ __forceinline__ void gemm_phase(PG8_LAS unsigned char* lds, const Gemm g, const Sched& S, const Epi& E) {
;     ...
;         const bool has_next = S.next(ui + 1, nxt);
;         const char* nA = has_next ? (const char*)g.A + (size_t)nxt.pm * tstep : cA; const char* nB = has_next ? (const char*)g.Bt + (size_t)nxt.pn * tstep : cB;
;         for (int t = 0; t < nt; t += 2) {
;             const bool last = (t == nt - 2);
;             const char* a1 = cA + (size_t)(t + 1) * kstep;
;             const char* a2 = last ? nA : cA + (size_t)(t + 2) * kstep; const char* b2 = last ? nB : cB + (size_t)(t + 2) * kstep;
;             const char* a3 = a2 + kstep; const char* b3 = b2 + kstep;
;             if (last && has_next) S.a_ready(nxt);
;             if constexpr (SP2) {
;             PG8_LDB(B0, 0, 0); PG8_LDB(B1, 0, 1); PG8_SCHED; PG8_LDA(At, 0, 0); PG8_STAGE(PG8_SA(1, 1), a1 + hstep, voffA);
;             PG8_WAIT_V(8); PG8_WAIT_L(0); PG8_BAR; PG8_MMA(0, 0, At, B0); PG8_MMA(0, 1, At, B1); PG8_BAR; PG8_SCHED;
;             PG8_LDA(At, 0, 1); PG8_STAGE(PG8_SB(0, 0), b2, voffB); PG8_STAGE(PG8_SB(0, 1), b2 + hstep, voffB); PG8_STAGE(PG8_SA(0, 0), a2, voffA);
;             PG8_WAIT_V(8); PG8_WAIT_L(0); PG8_BAR; PG8_MMA(1, 0, At, B0); PG8_MMA(1, 1, At, B1); PG8_BAR; PG8_SCHED;
.LBB0_1590:
	s_ashr_i32 s25, s24, 31
	s_lshl_b64 s[26:27], s[24:25], 20
	s_add_u32 s26, s28, s26
	s_addc_u32 s27, s42, s27
	s_and_b64 s[36:37], s[10:11], exec
	s_cselect_b32 s25, s27, s41
	s_cselect_b32 s57, s26, s40
	s_ashr_i32 s23, s22, 31
	s_lshl_b64 s[36:37], s[22:23], 20
	s_add_u32 s36, s43, s36
	s_addc_u32 s37, s46, s37
	s_and_b64 s[48:49], s[10:11], exec
	s_cselect_b32 s23, s37, s45
	s_cselect_b32 s58, s36, s44
	s_add_u32 s40, s40, 0x80080
	s_addc_u32 s41, s41, 0
	s_add_u32 s59, s44, 0x100
	s_addc_u32 s60, s45, 0
	s_mov_b32 s61, -2
	s_add_u32 s44, s40, 0xfff80080
	s_addc_u32 s45, s41, -1
	s_add_i32 s64, 0, 0x10000
	s_cmp_eq_u32 s61, 28
	s_cselect_b32 s49, s25, s45
	s_cselect_b32 s48, s57, s44
	s_cselect_b32 s45, s23, s60
	s_cselect_b32 s44, s58, s59
	s_add_i32 s67, 0, 0x14000
	v_add_u32_e32 v144, s64, v167
	v_add_u32_e32 v158, s67, v167
	ds_read_b128 v[36:39], v144
	ds_read_b128 v[44:47], v144 offset:1024
	ds_read_b128 v[140:143], v144 offset:2048
	ds_read_b128 v[144:147], v144 offset:3072
	ds_read_b128 v[160:163], v158
	ds_read_b128 v[172:175], v158 offset:1024
	ds_read_b128 v[176:179], v158 offset:2048
	ds_read_b128 v[180:183], v158 offset:3072
	v_lshl_add_u64 v[164:165], s[40:41], 0, v[154:155]
	s_add_i32 m0, s50, 0xc000
	ds_read_b128 v[184:187], v171
	ds_read_b128 v[188:191], v171 offset:1024
	ds_read_b128 v[204:207], v171 offset:2048
	ds_read_b128 v[208:211], v171 offset:3072
	ds_read_b128 v[212:215], v171 offset:4096
	ds_read_b128 v[216:219], v171 offset:5120
	ds_read_b128 v[220:223], v171 offset:6144
	ds_read_b128 v[224:227], v171 offset:7168
	global_load_lds_dwordx4 v[164:165], off
	v_lshl_add_u64 v[164:165], s[40:41], 0, v[156:157]
	s_add_i32 m0, s50, 0xe000
	s_nop 0
	global_load_lds_dwordx4 v[164:165], off
	s_waitcnt vmcnt(8)
	s_waitcnt lgkmcnt(0)
	s_barrier
	s_setprio 1
	s_waitcnt lgkmcnt(0)
	v_mfma_i32_16x16x64_i8 v[136:139], v[36:39], v[184:187], 0
	v_mfma_i32_16x16x64_i8 v[136:139], v[44:47], v[188:191], v[136:139]
	v_mfma_i32_16x16x64_i8 v[120:123], v[44:47], v[208:211], 0
	v_mfma_i32_16x16x64_i8 v[120:123], v[36:39], v[204:207], v[120:123]
	v_mfma_i32_16x16x64_i8 v[104:107], v[36:39], v[212:215], 0
	v_mfma_i32_16x16x64_i8 v[104:107], v[44:47], v[216:219], v[104:107]
	v_mfma_i32_16x16x64_i8 v[88:91], v[44:47], v[224:227], 0
	v_mfma_i32_16x16x64_i8 v[88:91], v[36:39], v[220:223], v[88:91]
	v_mfma_i32_16x16x64_i8 v[80:83], v[140:143], v[220:223], 0
	v_mfma_i32_16x16x64_i8 v[80:83], v[144:147], v[224:227], v[80:83]
	v_mfma_i32_16x16x64_i8 v[96:99], v[144:147], v[216:219], 0
	v_mfma_i32_16x16x64_i8 v[96:99], v[140:143], v[212:215], v[96:99]
	v_mfma_i32_16x16x64_i8 v[112:115], v[140:143], v[204:207], 0
	v_mfma_i32_16x16x64_i8 v[112:115], v[144:147], v[208:211], v[112:115]
	v_mfma_i32_16x16x64_i8 v[128:131], v[144:147], v[188:191], 0
	v_mfma_i32_16x16x64_i8 v[128:131], v[140:143], v[184:187], v[128:131]
	v_mfma_i32_16x16x64_i8 v[132:135], v[160:163], v[184:187], 0
	v_mfma_i32_16x16x64_i8 v[132:135], v[172:175], v[188:191], v[132:135]
	v_mfma_i32_16x16x64_i8 v[116:119], v[172:175], v[208:211], 0
	v_mfma_i32_16x16x64_i8 v[116:119], v[160:163], v[204:207], v[116:119]
	v_mfma_i32_16x16x64_i8 v[100:103], v[160:163], v[212:215], 0
	v_mfma_i32_16x16x64_i8 v[100:103], v[172:175], v[216:219], v[100:103]
	v_mfma_i32_16x16x64_i8 v[84:87], v[172:175], v[224:227], 0
	v_mfma_i32_16x16x64_i8 v[84:87], v[160:163], v[220:223], v[84:87]
	v_mfma_i32_16x16x64_i8 v[76:79], v[176:179], v[220:223], 0
	v_mfma_i32_16x16x64_i8 v[76:79], v[180:183], v[224:227], v[76:79]
	v_mfma_i32_16x16x64_i8 v[92:95], v[180:183], v[216:219], 0
	v_mfma_i32_16x16x64_i8 v[92:95], v[176:179], v[212:215], v[92:95]
	v_mfma_i32_16x16x64_i8 v[108:111], v[176:179], v[204:207], 0
	v_mfma_i32_16x16x64_i8 v[108:111], v[180:183], v[208:211], v[108:111]
	v_mfma_i32_16x16x64_i8 v[124:127], v[180:183], v[188:191], 0
	v_mfma_i32_16x16x64_i8 v[124:127], v[176:179], v[184:187], v[124:127]
	s_setprio 0
	s_barrier
	s_add_i32 s64, s64, s47
	v_lshl_add_u64 v[164:165], s[44:45], 0, v[2:3]
	s_mov_b32 m0, s64
	ds_read_b128 v[184:187], v171 offset:16384
	ds_read_b128 v[188:191], v171 offset:17408
	ds_read_b128 v[204:207], v171 offset:18432
	ds_read_b128 v[208:211], v171 offset:19456
	ds_read_b128 v[212:215], v171 offset:20480
	ds_read_b128 v[216:219], v171 offset:21504
	ds_read_b128 v[220:223], v171 offset:22528
	ds_read_b128 v[224:227], v171 offset:23552
	global_load_lds_dwordx4 v[164:165], off
	s_add_i32 m0, s64, 0x2000
	s_add_u32 s64, s44, 0x80000
	v_lshl_add_u64 v[228:229], s[44:45], 0, v[148:149]
	s_addc_u32 s65, s45, 0
	s_add_i32 s67, s67, s47
	global_load_lds_dwordx4 v[228:229], off
	v_lshl_add_u64 v[240:241], s[64:65], 0, v[2:3]
	s_mov_b32 m0, s67
	v_lshl_add_u64 v[242:243], s[48:49], 0, v[150:151]
	global_load_lds_dwordx4 v[240:241], off
	v_lshl_add_u64 v[240:241], s[64:65], 0, v[148:149]
	s_add_i32 m0, s67, 0x2000
	s_nop 0
	global_load_lds_dwordx4 v[240:241], off
	v_lshl_add_u64 v[240:241], s[48:49], 0, v[152:153]
	s_mov_b32 m0, s50
	s_nop 0
	global_load_lds_dwordx4 v[240:241], off
	s_mov_b32 m0, s51
	s_nop 0
	global_load_lds_dwordx4 v[242:243], off
	s_waitcnt vmcnt(8)
	s_waitcnt lgkmcnt(0)
	s_barrier
; #define PG8_STAGE(bufoff, gbase, voff) do { _Pragma("unroll") for (int _i = 0; _i < 2; ++_i) \
;         __builtin_amdgcn_global_load_lds((const unsigned*)((const char*)(gbase) + (voff)[_i]), (PG8_LAS unsigned*)(lds + (bufoff) + ldsw + _i * 8192), 16, 0, 0); } while (0)
; #define PG8_LDA(dst, b, h) do { _Pragma("unroll") for (int m = 0; m < 4; ++m) _Pragma("unroll") for (int k = 0; k < 2; ++k) dst[m][k] = *(const PG8_LAS bf16x8*)(lds + PG8_SA(b, h) + aoff + m * 2048 + k * 1024); } while (0)
; #define PG8_LDB(dst, b, h) do { _Pragma("unroll") for (int n = 0; n < 2; ++n) _Pragma("unroll") for (int k = 0; k < 2; ++k) dst[n][k] = *(const PG8_LAS bf16x8*)(lds + PG8_SB(b, h) + boff + n * 2048 + k * 1024); } while (0)
; #define PG8_WAIT_V(n) asm volatile("s_waitcnt vmcnt(" #n ")" ::: "memory")
; #define PG8_WAIT_L(n) asm volatile("s_waitcnt lgkmcnt(" #n ")" ::: "memory")
; #define PG8_BAR __builtin_amdgcn_s_barrier()
; #define PG8_SCHED __builtin_amdgcn_sched_barrier(0)
; template <class Epi, class Sched, bool ALIGN_EPI = false, bool SP2 = false, bool I8 = false>
; __device__ __forceinline__ void gemm_phase(PG8_LAS unsigned char* lds, const Gemm g, const Sched& S, const Epi& E) {
;     ...
;             PG8_WAIT_V(8); PG8_WAIT_L(0); PG8_BAR; PG8_MMA(1, 0, At, B0); PG8_MMA(1, 1, At, B1); PG8_BAR; PG8_SCHED;
;             PG8_LDB(B0, 1, 0); PG8_LDB(B1, 1, 1); PG8_SCHED; PG8_LDA(At, 1, 0); PG8_STAGE(PG8_SA(0, 1), a2 + hstep, voffA);
;             PG8_WAIT_V(8); PG8_WAIT_L(0); PG8_BAR; PG8_MMA(0, 0, At, B0); PG8_MMA(0, 1, At, B1); PG8_BAR; PG8_SCHED;
	s_setprio 1
	s_waitcnt lgkmcnt(0)
	v_mfma_i32_16x16x64_i8 v[72:75], v[36:39], v[184:187], 0
	v_mfma_i32_16x16x64_i8 v[72:75], v[44:47], v[188:191], v[72:75]
	v_mfma_i32_16x16x64_i8 v[56:59], v[44:47], v[208:211], 0
	v_mfma_i32_16x16x64_i8 v[56:59], v[36:39], v[204:207], v[56:59]
	v_mfma_i32_16x16x64_i8 v[32:35], v[36:39], v[212:215], 0
	v_mfma_i32_16x16x64_i8 v[32:35], v[44:47], v[216:219], v[32:35]
	v_mfma_i32_16x16x64_i8 v[16:19], v[44:47], v[224:227], 0
	v_mfma_i32_16x16x64_i8 v[16:19], v[36:39], v[220:223], v[16:19]
	v_mfma_i32_16x16x64_i8 v[8:11], v[140:143], v[220:223], 0
	v_mfma_i32_16x16x64_i8 v[8:11], v[144:147], v[224:227], v[8:11]
	v_mfma_i32_16x16x64_i8 v[24:27], v[144:147], v[216:219], 0
	v_mfma_i32_16x16x64_i8 v[24:27], v[140:143], v[212:215], v[24:27]
	v_mfma_i32_16x16x64_i8 v[48:51], v[140:143], v[204:207], 0
	v_mfma_i32_16x16x64_i8 v[48:51], v[144:147], v[208:211], v[48:51]
	v_mfma_i32_16x16x64_i8 v[64:67], v[144:147], v[188:191], 0
	v_mfma_i32_16x16x64_i8 v[64:67], v[140:143], v[184:187], v[64:67]
	v_mfma_i32_16x16x64_i8 v[36:39], v[160:163], v[184:187], 0
	v_mfma_i32_16x16x64_i8 v[36:39], v[172:175], v[188:191], v[36:39]
	v_mfma_i32_16x16x64_i8 v[52:55], v[172:175], v[208:211], 0
	v_mfma_i32_16x16x64_i8 v[52:55], v[160:163], v[204:207], v[52:55]
	v_mfma_i32_16x16x64_i8 v[28:31], v[160:163], v[212:215], 0
	v_mfma_i32_16x16x64_i8 v[28:31], v[172:175], v[216:219], v[28:31]
	v_mfma_i32_16x16x64_i8 v[12:15], v[172:175], v[224:227], 0
	v_mfma_i32_16x16x64_i8 v[12:15], v[160:163], v[220:223], v[12:15]
	v_mfma_i32_16x16x64_i8 v[4:7], v[176:179], v[220:223], 0
	v_mfma_i32_16x16x64_i8 v[4:7], v[180:183], v[224:227], v[4:7]
	v_mfma_i32_16x16x64_i8 v[20:23], v[180:183], v[216:219], 0
	v_mfma_i32_16x16x64_i8 v[20:23], v[176:179], v[212:215], v[20:23]
	v_mfma_i32_16x16x64_i8 v[40:43], v[176:179], v[204:207], 0
	v_mfma_i32_16x16x64_i8 v[40:43], v[180:183], v[208:211], v[40:43]
	v_mfma_i32_16x16x64_i8 v[44:47], v[180:183], v[188:191], 0
	v_mfma_i32_16x16x64_i8 v[44:47], v[176:179], v[184:187], v[44:47]
	s_setprio 0
	s_barrier
	s_add_i32 s64, 0, 0x18000
	s_add_i32 s65, 0, 0x1c000
	v_add_u32_e32 v144, s64, v167
	v_add_u32_e32 v158, s65, v167
	ds_read_b128 v[60:63], v144
	ds_read_b128 v[68:71], v144 offset:1024
	ds_read_b128 v[140:143], v144 offset:2048
	ds_read_b128 v[144:147], v144 offset:3072
	ds_read_b128 v[160:163], v158
	ds_read_b128 v[172:175], v158 offset:1024
	ds_read_b128 v[176:179], v158 offset:2048
	ds_read_b128 v[180:183], v158 offset:3072
	s_add_u32 s48, s48, 0x80000
	s_addc_u32 s49, s49, 0
	s_mov_b32 m0, s52
	v_lshl_add_u64 v[244:245], s[48:49], 0, v[152:153]
	ds_read_b128 v[184:187], v171 offset:32768
	ds_read_b128 v[188:191], v171 offset:33792
	ds_read_b128 v[204:207], v171 offset:34816
	ds_read_b128 v[208:211], v171 offset:35840
	ds_read_b128 v[212:215], v171 offset:36864
	ds_read_b128 v[216:219], v171 offset:37888
	ds_read_b128 v[220:223], v171 offset:38912
	ds_read_b128 v[224:227], v171 offset:39936
	global_load_lds_dwordx4 v[244:245], off
	v_lshl_add_u64 v[244:245], s[48:49], 0, v[150:151]
	s_mov_b32 m0, s53
	s_nop 0
	global_load_lds_dwordx4 v[244:245], off
	s_waitcnt vmcnt(8)
	s_waitcnt lgkmcnt(0)
	s_barrier
	s_setprio 1
	s_waitcnt lgkmcnt(0)
	v_mfma_i32_16x16x64_i8 v[136:139], v[60:63], v[184:187], v[136:139]
	v_mfma_i32_16x16x64_i8 v[136:139], v[68:71], v[188:191], v[136:139]
	v_mfma_i32_16x16x64_i8 v[120:123], v[68:71], v[208:211], v[120:123]
	v_mfma_i32_16x16x64_i8 v[120:123], v[60:63], v[204:207], v[120:123]
	v_mfma_i32_16x16x64_i8 v[104:107], v[60:63], v[212:215], v[104:107]
	v_mfma_i32_16x16x64_i8 v[104:107], v[68:71], v[216:219], v[104:107]
	v_mfma_i32_16x16x64_i8 v[88:91], v[68:71], v[224:227], v[88:91]
	v_mfma_i32_16x16x64_i8 v[88:91], v[60:63], v[220:223], v[88:91]
	v_mfma_i32_16x16x64_i8 v[80:83], v[140:143], v[220:223], v[80:83]
	v_mfma_i32_16x16x64_i8 v[80:83], v[144:147], v[224:227], v[80:83]
	v_mfma_i32_16x16x64_i8 v[96:99], v[144:147], v[216:219], v[96:99]
	v_mfma_i32_16x16x64_i8 v[96:99], v[140:143], v[212:215], v[96:99]
	v_mfma_i32_16x16x64_i8 v[112:115], v[140:143], v[204:207], v[112:115]
	v_mfma_i32_16x16x64_i8 v[112:115], v[144:147], v[208:211], v[112:115]
	v_mfma_i32_16x16x64_i8 v[128:131], v[144:147], v[188:191], v[128:131]
	v_mfma_i32_16x16x64_i8 v[128:131], v[140:143], v[184:187], v[128:131]
	v_mfma_i32_16x16x64_i8 v[132:135], v[160:163], v[184:187], v[132:135]
	v_mfma_i32_16x16x64_i8 v[132:135], v[172:175], v[188:191], v[132:135]
	v_mfma_i32_16x16x64_i8 v[116:119], v[172:175], v[208:211], v[116:119]
	v_mfma_i32_16x16x64_i8 v[116:119], v[160:163], v[204:207], v[116:119]
	v_mfma_i32_16x16x64_i8 v[100:103], v[160:163], v[212:215], v[100:103]
	v_mfma_i32_16x16x64_i8 v[100:103], v[172:175], v[216:219], v[100:103]
	v_mfma_i32_16x16x64_i8 v[84:87], v[172:175], v[224:227], v[84:87]
	v_mfma_i32_16x16x64_i8 v[84:87], v[160:163], v[220:223], v[84:87]
	v_mfma_i32_16x16x64_i8 v[76:79], v[176:179], v[220:223], v[76:79]
	v_mfma_i32_16x16x64_i8 v[76:79], v[180:183], v[224:227], v[76:79]
	v_mfma_i32_16x16x64_i8 v[92:95], v[180:183], v[216:219], v[92:95]
	v_mfma_i32_16x16x64_i8 v[92:95], v[176:179], v[212:215], v[92:95]
	v_mfma_i32_16x16x64_i8 v[108:111], v[176:179], v[204:207], v[108:111]
	v_mfma_i32_16x16x64_i8 v[108:111], v[180:183], v[208:211], v[108:111]
	v_mfma_i32_16x16x64_i8 v[124:127], v[180:183], v[188:191], v[124:127]
	v_mfma_i32_16x16x64_i8 v[124:127], v[176:179], v[184:187], v[124:127]
	s_setprio 0
	s_barrier
; #define PG8_STAGE(bufoff, gbase, voff) do { _Pragma("unroll") for (int _i = 0; _i < 2; ++_i) \
;         __builtin_amdgcn_global_load_lds((const unsigned*)((const char*)(gbase) + (voff)[_i]), (PG8_LAS unsigned*)(lds + (bufoff) + ldsw + _i * 8192), 16, 0, 0); } while (0)
; #define PG8_LDA(dst, b, h) do { _Pragma("unroll") for (int m = 0; m < 4; ++m) _Pragma("unroll") for (int k = 0; k < 2; ++k) dst[m][k] = *(const PG8_LAS bf16x8*)(lds + PG8_SA(b, h) + aoff + m * 2048 + k * 1024); } while (0)
; #define PG8_LDB(dst, b, h) do { _Pragma("unroll") for (int n = 0; n < 2; ++n) _Pragma("unroll") for (int k = 0; k < 2; ++k) dst[n][k] = *(const PG8_LAS bf16x8*)(lds + PG8_SB(b, h) + boff + n * 2048 + k * 1024); } while (0)
; #define PG8_WAIT_V(n) asm volatile("s_waitcnt vmcnt(" #n ")" ::: "memory")
; #define PG8_WAIT_L(n) asm volatile("s_waitcnt lgkmcnt(" #n ")" ::: "memory")
; #define PG8_BAR __builtin_amdgcn_s_barrier()
; #define PG8_SCHED __builtin_amdgcn_sched_barrier(0)
; template <class Epi, class Sched, bool ALIGN_EPI = false, bool SP2 = false, bool I8 = false>
; __device__ __forceinline__ void gemm_phase(PG8_LAS unsigned char* lds, const Gemm g, const Sched& S, const Epi& E) {
;     ...
;         for (int t = 0; t < nt; t += 2) {
;             const bool last = (t == nt - 2);
;             const char* a1 = cA + (size_t)(t + 1) * kstep;
;             const char* a2 = last ? nA : cA + (size_t)(t + 2) * kstep; const char* b2 = last ? nB : cB + (size_t)(t + 2) * kstep;
;             const char* a3 = a2 + kstep; const char* b3 = b2 + kstep;
;             if (last && has_next) S.a_ready(nxt);
;             if constexpr (SP2) {
;             PG8_LDB(B0, 0, 0); PG8_LDB(B1, 0, 1); PG8_SCHED; PG8_LDA(At, 0, 0); PG8_STAGE(PG8_SA(1, 1), a1 + hstep, voffA);
;     ...
;             PG8_LDA(At, 1, 1); PG8_STAGE(PG8_SB(1, 0), b3, voffB); PG8_STAGE(PG8_SB(1, 1), b3 + hstep, voffB); PG8_STAGE(PG8_SA(1, 0), a3, voffA);
;             PG8_WAIT_V(8); PG8_WAIT_L(0); PG8_BAR; PG8_MMA(1, 0, At, B0); PG8_MMA(1, 1, At, B1); PG8_BAR; PG8_SCHED;
	s_add_i32 s48, s64, s47
	v_lshl_add_u64 v[164:165], v[164:165], 0, s[84:85]
	s_mov_b32 m0, s48
	ds_read_b128 v[184:187], v171 offset:49152
	ds_read_b128 v[188:191], v171 offset:50176
	ds_read_b128 v[204:207], v171 offset:51200
	ds_read_b128 v[208:211], v171 offset:52224
	ds_read_b128 v[212:215], v171 offset:53248
	ds_read_b128 v[216:219], v171 offset:54272
	ds_read_b128 v[220:223], v171 offset:55296
	ds_read_b128 v[224:227], v171 offset:56320
	global_load_lds_dwordx4 v[164:165], off
	s_add_i32 m0, s48, 0x2000
	s_add_u32 s44, s44, 0x80080
	v_lshl_add_u64 v[164:165], v[228:229], 0, s[84:85]
	s_addc_u32 s45, s45, 0
	s_add_i32 s48, s65, s47
	global_load_lds_dwordx4 v[164:165], off
	v_lshl_add_u64 v[164:165], s[44:45], 0, v[2:3]
	s_mov_b32 m0, s48
	s_nop 0
	global_load_lds_dwordx4 v[164:165], off
	v_lshl_add_u64 v[164:165], s[44:45], 0, v[148:149]
	s_add_i32 m0, s48, 0x2000
	s_nop 0
	global_load_lds_dwordx4 v[164:165], off
	v_lshl_add_u64 v[164:165], v[240:241], 0, s[84:85]
	s_mov_b32 m0, s54
	s_nop 0
	global_load_lds_dwordx4 v[164:165], off
	v_lshl_add_u64 v[164:165], v[242:243], 0, s[84:85]
	s_mov_b32 m0, s55
	s_nop 0
	global_load_lds_dwordx4 v[164:165], off
	s_waitcnt vmcnt(8)
	s_waitcnt lgkmcnt(0)
	s_barrier
	s_setprio 1
	s_waitcnt lgkmcnt(0)
	v_mfma_i32_16x16x64_i8 v[72:75], v[60:63], v[184:187], v[72:75]
	v_mfma_i32_16x16x64_i8 v[72:75], v[68:71], v[188:191], v[72:75]
	v_mfma_i32_16x16x64_i8 v[56:59], v[68:71], v[208:211], v[56:59]
	v_mfma_i32_16x16x64_i8 v[56:59], v[60:63], v[204:207], v[56:59]
	v_mfma_i32_16x16x64_i8 v[32:35], v[60:63], v[212:215], v[32:35]
	v_mfma_i32_16x16x64_i8 v[32:35], v[68:71], v[216:219], v[32:35]
	v_mfma_i32_16x16x64_i8 v[16:19], v[68:71], v[224:227], v[16:19]
	v_mfma_i32_16x16x64_i8 v[16:19], v[60:63], v[220:223], v[16:19]
	v_mfma_i32_16x16x64_i8 v[8:11], v[140:143], v[220:223], v[8:11]
	v_mfma_i32_16x16x64_i8 v[8:11], v[144:147], v[224:227], v[8:11]
	v_mfma_i32_16x16x64_i8 v[24:27], v[144:147], v[216:219], v[24:27]
	v_mfma_i32_16x16x64_i8 v[24:27], v[140:143], v[212:215], v[24:27]
	v_mfma_i32_16x16x64_i8 v[48:51], v[140:143], v[204:207], v[48:51]
	v_mfma_i32_16x16x64_i8 v[48:51], v[144:147], v[208:211], v[48:51]
	v_mfma_i32_16x16x64_i8 v[64:67], v[144:147], v[188:191], v[64:67]
	v_mfma_i32_16x16x64_i8 v[64:67], v[140:143], v[184:187], v[64:67]
	v_mfma_i32_16x16x64_i8 v[36:39], v[160:163], v[184:187], v[36:39]
	v_mfma_i32_16x16x64_i8 v[68:71], v[172:175], v[188:191], v[36:39]
	v_mfma_i32_16x16x64_i8 v[36:39], v[172:175], v[208:211], v[52:55]
	v_mfma_i32_16x16x64_i8 v[52:55], v[160:163], v[204:207], v[36:39]
	v_mfma_i32_16x16x64_i8 v[28:31], v[160:163], v[212:215], v[28:31]
	v_mfma_i32_16x16x64_i8 v[28:31], v[172:175], v[216:219], v[28:31]
	v_mfma_i32_16x16x64_i8 v[12:15], v[172:175], v[224:227], v[12:15]
	v_mfma_i32_16x16x64_i8 v[12:15], v[160:163], v[220:223], v[12:15]
	v_mfma_i32_16x16x64_i8 v[4:7], v[176:179], v[220:223], v[4:7]
	v_mfma_i32_16x16x64_i8 v[4:7], v[180:183], v[224:227], v[4:7]
	v_mfma_i32_16x16x64_i8 v[20:23], v[180:183], v[216:219], v[20:23]
	v_mfma_i32_16x16x64_i8 v[20:23], v[176:179], v[212:215], v[20:23]
	v_mfma_i32_16x16x64_i8 v[36:39], v[176:179], v[204:207], v[40:43]
	v_mfma_i32_16x16x64_i8 v[40:43], v[180:183], v[208:211], v[36:39]
	v_mfma_i32_16x16x64_i8 v[36:39], v[180:183], v[188:191], v[44:47]
	v_mfma_i32_16x16x64_i8 v[60:63], v[176:179], v[184:187], v[36:39]
	s_setprio 0
	s_add_i32 s61, s61, 2
	s_add_u32 s40, s40, 0x100
	s_addc_u32 s41, s41, 0
	s_add_u32 s59, s59, 0x100
	s_addc_u32 s60, s60, 0
	s_cmp_gt_u32 s61, 29
	s_barrier
	s_cbranch_scc1 .Lkloop_exit_3
.LBB0_1591:
	s_add_u32 s44, s40, 0xfff80080
	s_addc_u32 s45, s41, -1
	s_add_i32 s64, 0, 0x10000
	s_cmp_eq_u32 s61, 28
	s_cselect_b32 s49, s25, s45
	s_cselect_b32 s48, s57, s44
	s_cselect_b32 s45, s23, s60
	s_cselect_b32 s44, s58, s59
	s_add_i32 s67, 0, 0x14000
	v_add_u32_e32 v144, s64, v167
	v_add_u32_e32 v158, s67, v167
	ds_read_b128 v[36:39], v144
	ds_read_b128 v[44:47], v144 offset:1024
	ds_read_b128 v[140:143], v144 offset:2048
	ds_read_b128 v[144:147], v144 offset:3072
	ds_read_b128 v[160:163], v158
	ds_read_b128 v[172:175], v158 offset:1024
	ds_read_b128 v[176:179], v158 offset:2048
	ds_read_b128 v[180:183], v158 offset:3072
	v_lshl_add_u64 v[164:165], s[40:41], 0, v[154:155]
	s_add_i32 m0, s50, 0xc000
	ds_read_b128 v[184:187], v171
	ds_read_b128 v[188:191], v171 offset:1024
	ds_read_b128 v[204:207], v171 offset:2048
	ds_read_b128 v[208:211], v171 offset:3072
	ds_read_b128 v[212:215], v171 offset:4096
	ds_read_b128 v[216:219], v171 offset:5120
	ds_read_b128 v[220:223], v171 offset:6144
	ds_read_b128 v[224:227], v171 offset:7168
	global_load_lds_dwordx4 v[164:165], off
	v_lshl_add_u64 v[164:165], s[40:41], 0, v[156:157]
	s_add_i32 m0, s50, 0xe000
	s_nop 0
	global_load_lds_dwordx4 v[164:165], off
	s_waitcnt vmcnt(8)
	s_waitcnt lgkmcnt(0)
	s_barrier
; #define PG8_STAGE(bufoff, gbase, voff) do { _Pragma("unroll") for (int _i = 0; _i < 2; ++_i) \
;         __builtin_amdgcn_global_load_lds((const unsigned*)((const char*)(gbase) + (voff)[_i]), (PG8_LAS unsigned*)(lds + (bufoff) + ldsw + _i * 8192), 16, 0, 0); } while (0)
; #define PG8_LDA(dst, b, h) do { _Pragma("unroll") for (int m = 0; m < 4; ++m) _Pragma("unroll") for (int k = 0; k < 2; ++k) dst[m][k] = *(const PG8_LAS bf16x8*)(lds + PG8_SA(b, h) + aoff + m * 2048 + k * 1024); } while (0)
; #define PG8_WAIT_V(n) asm volatile("s_waitcnt vmcnt(" #n ")" ::: "memory")
; #define PG8_WAIT_L(n) asm volatile("s_waitcnt lgkmcnt(" #n ")" ::: "memory")
; #define PG8_BAR __builtin_amdgcn_s_barrier()
; #define PG8_SCHED __builtin_amdgcn_sched_barrier(0)
; template <class Epi, class Sched, bool ALIGN_EPI = false, bool SP2 = false, bool I8 = false>
; __device__ __forceinline__ void gemm_phase(PG8_LAS unsigned char* lds, const Gemm g, const Sched& S, const Epi& E) {
;     ...
;             PG8_WAIT_V(8); PG8_WAIT_L(0); PG8_BAR; PG8_MMA(0, 0, At, B0); PG8_MMA(0, 1, At, B1); PG8_BAR; PG8_SCHED;
;             PG8_LDA(At, 0, 1); PG8_STAGE(PG8_SB(0, 0), b2, voffB); PG8_STAGE(PG8_SB(0, 1), b2 + hstep, voffB); PG8_STAGE(PG8_SA(0, 0), a2, voffA);
;             PG8_WAIT_V(8); PG8_WAIT_L(0); PG8_BAR; PG8_MMA(1, 0, At, B0); PG8_MMA(1, 1, At, B1); PG8_BAR; PG8_SCHED;
	s_setprio 1
	s_waitcnt lgkmcnt(0)
	v_mfma_i32_16x16x64_i8 v[136:139], v[36:39], v[184:187], v[136:139]
	v_mfma_i32_16x16x64_i8 v[136:139], v[44:47], v[188:191], v[136:139]
	v_mfma_i32_16x16x64_i8 v[120:123], v[44:47], v[208:211], v[120:123]
	v_mfma_i32_16x16x64_i8 v[120:123], v[36:39], v[204:207], v[120:123]
	v_mfma_i32_16x16x64_i8 v[104:107], v[36:39], v[212:215], v[104:107]
	v_mfma_i32_16x16x64_i8 v[104:107], v[44:47], v[216:219], v[104:107]
	v_mfma_i32_16x16x64_i8 v[88:91], v[44:47], v[224:227], v[88:91]
	v_mfma_i32_16x16x64_i8 v[88:91], v[36:39], v[220:223], v[88:91]
	v_mfma_i32_16x16x64_i8 v[80:83], v[140:143], v[220:223], v[80:83]
	v_mfma_i32_16x16x64_i8 v[80:83], v[144:147], v[224:227], v[80:83]
	v_mfma_i32_16x16x64_i8 v[96:99], v[144:147], v[216:219], v[96:99]
	v_mfma_i32_16x16x64_i8 v[96:99], v[140:143], v[212:215], v[96:99]
	v_mfma_i32_16x16x64_i8 v[112:115], v[140:143], v[204:207], v[112:115]
	v_mfma_i32_16x16x64_i8 v[112:115], v[144:147], v[208:211], v[112:115]
	v_mfma_i32_16x16x64_i8 v[128:131], v[144:147], v[188:191], v[128:131]
	v_mfma_i32_16x16x64_i8 v[128:131], v[140:143], v[184:187], v[128:131]
	v_mfma_i32_16x16x64_i8 v[132:135], v[160:163], v[184:187], v[132:135]
	v_mfma_i32_16x16x64_i8 v[132:135], v[172:175], v[188:191], v[132:135]
	v_mfma_i32_16x16x64_i8 v[116:119], v[172:175], v[208:211], v[116:119]
	v_mfma_i32_16x16x64_i8 v[116:119], v[160:163], v[204:207], v[116:119]
	v_mfma_i32_16x16x64_i8 v[100:103], v[160:163], v[212:215], v[100:103]
	v_mfma_i32_16x16x64_i8 v[100:103], v[172:175], v[216:219], v[100:103]
	v_mfma_i32_16x16x64_i8 v[84:87], v[172:175], v[224:227], v[84:87]
	v_mfma_i32_16x16x64_i8 v[84:87], v[160:163], v[220:223], v[84:87]
	v_mfma_i32_16x16x64_i8 v[76:79], v[176:179], v[220:223], v[76:79]
	v_mfma_i32_16x16x64_i8 v[76:79], v[180:183], v[224:227], v[76:79]
	v_mfma_i32_16x16x64_i8 v[92:95], v[180:183], v[216:219], v[92:95]
	v_mfma_i32_16x16x64_i8 v[92:95], v[176:179], v[212:215], v[92:95]
	v_mfma_i32_16x16x64_i8 v[108:111], v[176:179], v[204:207], v[108:111]
	v_mfma_i32_16x16x64_i8 v[108:111], v[180:183], v[208:211], v[108:111]
	v_mfma_i32_16x16x64_i8 v[124:127], v[180:183], v[188:191], v[124:127]
	v_mfma_i32_16x16x64_i8 v[124:127], v[176:179], v[184:187], v[124:127]
	s_setprio 0
	s_barrier
	s_add_i32 s64, s64, s47
	v_lshl_add_u64 v[164:165], s[44:45], 0, v[2:3]
	s_mov_b32 m0, s64
	ds_read_b128 v[184:187], v171 offset:16384
	ds_read_b128 v[188:191], v171 offset:17408
	ds_read_b128 v[204:207], v171 offset:18432
	ds_read_b128 v[208:211], v171 offset:19456
	ds_read_b128 v[212:215], v171 offset:20480
	ds_read_b128 v[216:219], v171 offset:21504
	ds_read_b128 v[220:223], v171 offset:22528
	ds_read_b128 v[224:227], v171 offset:23552
	global_load_lds_dwordx4 v[164:165], off
	s_add_i32 m0, s64, 0x2000
	s_add_u32 s64, s44, 0x80000
	v_lshl_add_u64 v[228:229], s[44:45], 0, v[148:149]
	s_addc_u32 s65, s45, 0
	s_add_i32 s67, s67, s47
	global_load_lds_dwordx4 v[228:229], off
	v_lshl_add_u64 v[240:241], s[64:65], 0, v[2:3]
	s_mov_b32 m0, s67
	v_lshl_add_u64 v[242:243], s[48:49], 0, v[150:151]
	global_load_lds_dwordx4 v[240:241], off
	v_lshl_add_u64 v[240:241], s[64:65], 0, v[148:149]
	s_add_i32 m0, s67, 0x2000
	s_nop 0
	global_load_lds_dwordx4 v[240:241], off
	v_lshl_add_u64 v[240:241], s[48:49], 0, v[152:153]
	s_mov_b32 m0, s50
	s_nop 0
	global_load_lds_dwordx4 v[240:241], off
	s_mov_b32 m0, s51
	s_nop 0
	global_load_lds_dwordx4 v[242:243], off
	s_waitcnt vmcnt(8)
	s_waitcnt lgkmcnt(0)
	s_barrier
	s_setprio 1
	s_waitcnt lgkmcnt(0)
	v_mfma_i32_16x16x64_i8 v[72:75], v[36:39], v[184:187], v[72:75]
	v_mfma_i32_16x16x64_i8 v[72:75], v[44:47], v[188:191], v[72:75]
	v_mfma_i32_16x16x64_i8 v[56:59], v[44:47], v[208:211], v[56:59]
	v_mfma_i32_16x16x64_i8 v[56:59], v[36:39], v[204:207], v[56:59]
	v_mfma_i32_16x16x64_i8 v[32:35], v[36:39], v[212:215], v[32:35]
	v_mfma_i32_16x16x64_i8 v[32:35], v[44:47], v[216:219], v[32:35]
	v_mfma_i32_16x16x64_i8 v[16:19], v[44:47], v[224:227], v[16:19]
	v_mfma_i32_16x16x64_i8 v[16:19], v[36:39], v[220:223], v[16:19]
	v_mfma_i32_16x16x64_i8 v[8:11], v[140:143], v[220:223], v[8:11]
	v_mfma_i32_16x16x64_i8 v[8:11], v[144:147], v[224:227], v[8:11]
	v_mfma_i32_16x16x64_i8 v[24:27], v[144:147], v[216:219], v[24:27]
	v_mfma_i32_16x16x64_i8 v[24:27], v[140:143], v[212:215], v[24:27]
	v_mfma_i32_16x16x64_i8 v[48:51], v[140:143], v[204:207], v[48:51]
	v_mfma_i32_16x16x64_i8 v[48:51], v[144:147], v[208:211], v[48:51]
	v_mfma_i32_16x16x64_i8 v[64:67], v[144:147], v[188:191], v[64:67]
	v_mfma_i32_16x16x64_i8 v[64:67], v[140:143], v[184:187], v[64:67]
	v_mfma_i32_16x16x64_i8 v[36:39], v[160:163], v[184:187], v[68:71]
	v_mfma_i32_16x16x64_i8 v[36:39], v[172:175], v[188:191], v[36:39]
	v_mfma_i32_16x16x64_i8 v[52:55], v[172:175], v[208:211], v[52:55]
	v_mfma_i32_16x16x64_i8 v[52:55], v[160:163], v[204:207], v[52:55]
	v_mfma_i32_16x16x64_i8 v[28:31], v[160:163], v[212:215], v[28:31]
	v_mfma_i32_16x16x64_i8 v[28:31], v[172:175], v[216:219], v[28:31]
	v_mfma_i32_16x16x64_i8 v[12:15], v[172:175], v[224:227], v[12:15]
	v_mfma_i32_16x16x64_i8 v[12:15], v[160:163], v[220:223], v[12:15]
	v_mfma_i32_16x16x64_i8 v[4:7], v[176:179], v[220:223], v[4:7]
	v_mfma_i32_16x16x64_i8 v[4:7], v[180:183], v[224:227], v[4:7]
	v_mfma_i32_16x16x64_i8 v[20:23], v[180:183], v[216:219], v[20:23]
	v_mfma_i32_16x16x64_i8 v[20:23], v[176:179], v[212:215], v[20:23]
	v_mfma_i32_16x16x64_i8 v[40:43], v[176:179], v[204:207], v[40:43]
	v_mfma_i32_16x16x64_i8 v[40:43], v[180:183], v[208:211], v[40:43]
	v_mfma_i32_16x16x64_i8 v[44:47], v[180:183], v[188:191], v[60:63]
	v_mfma_i32_16x16x64_i8 v[44:47], v[176:179], v[184:187], v[44:47]
	s_setprio 0
	s_barrier
; #define PG8_STAGE(bufoff, gbase, voff) do { _Pragma("unroll") for (int _i = 0; _i < 2; ++_i) \
;         __builtin_amdgcn_global_load_lds((const unsigned*)((const char*)(gbase) + (voff)[_i]), (PG8_LAS unsigned*)(lds + (bufoff) + ldsw + _i * 8192), 16, 0, 0); } while (0)
; #define PG8_LDA(dst, b, h) do { _Pragma("unroll") for (int m = 0; m < 4; ++m) _Pragma("unroll") for (int k = 0; k < 2; ++k) dst[m][k] = *(const PG8_LAS bf16x8*)(lds + PG8_SA(b, h) + aoff + m * 2048 + k * 1024); } while (0)
; #define PG8_LDB(dst, b, h) do { _Pragma("unroll") for (int n = 0; n < 2; ++n) _Pragma("unroll") for (int k = 0; k < 2; ++k) dst[n][k] = *(const PG8_LAS bf16x8*)(lds + PG8_SB(b, h) + boff + n * 2048 + k * 1024); } while (0)
; #define PG8_WAIT_V(n) asm volatile("s_waitcnt vmcnt(" #n ")" ::: "memory")
; #define PG8_WAIT_L(n) asm volatile("s_waitcnt lgkmcnt(" #n ")" ::: "memory")
; #define PG8_BAR __builtin_amdgcn_s_barrier()
; #define PG8_SCHED __builtin_amdgcn_sched_barrier(0)
; template <class Epi, class Sched, bool ALIGN_EPI = false, bool SP2 = false, bool I8 = false>
; __device__ __forceinline__ void gemm_phase(PG8_LAS unsigned char* lds, const Gemm g, const Sched& S, const Epi& E) {
;     ...
;             PG8_LDB(B0, 1, 0); PG8_LDB(B1, 1, 1); PG8_SCHED; PG8_LDA(At, 1, 0); PG8_STAGE(PG8_SA(0, 1), a2 + hstep, voffA);
;             PG8_WAIT_V(8); PG8_WAIT_L(0); PG8_BAR; PG8_MMA(0, 0, At, B0); PG8_MMA(0, 1, At, B1); PG8_BAR; PG8_SCHED;
;             PG8_LDA(At, 1, 1); PG8_STAGE(PG8_SB(1, 0), b3, voffB); PG8_STAGE(PG8_SB(1, 1), b3 + hstep, voffB); PG8_STAGE(PG8_SA(1, 0), a3, voffA);
;             PG8_WAIT_V(8); PG8_WAIT_L(0); PG8_BAR; PG8_MMA(1, 0, At, B0); PG8_MMA(1, 1, At, B1); PG8_BAR; PG8_SCHED;
	s_add_i32 s64, 0, 0x18000
	s_add_i32 s65, 0, 0x1c000
	v_add_u32_e32 v144, s64, v167
	v_add_u32_e32 v158, s65, v167
	ds_read_b128 v[60:63], v144
	ds_read_b128 v[68:71], v144 offset:1024
	ds_read_b128 v[140:143], v144 offset:2048
	ds_read_b128 v[144:147], v144 offset:3072
	ds_read_b128 v[160:163], v158
	ds_read_b128 v[172:175], v158 offset:1024
	ds_read_b128 v[176:179], v158 offset:2048
	ds_read_b128 v[180:183], v158 offset:3072
	s_add_u32 s48, s48, 0x80000
	s_addc_u32 s49, s49, 0
	s_mov_b32 m0, s52
	v_lshl_add_u64 v[244:245], s[48:49], 0, v[152:153]
	ds_read_b128 v[184:187], v171 offset:32768
	ds_read_b128 v[188:191], v171 offset:33792
	ds_read_b128 v[204:207], v171 offset:34816
	ds_read_b128 v[208:211], v171 offset:35840
	ds_read_b128 v[212:215], v171 offset:36864
	ds_read_b128 v[216:219], v171 offset:37888
	ds_read_b128 v[220:223], v171 offset:38912
	ds_read_b128 v[224:227], v171 offset:39936
	global_load_lds_dwordx4 v[244:245], off
	v_lshl_add_u64 v[244:245], s[48:49], 0, v[150:151]
	s_mov_b32 m0, s53
	s_nop 0
	global_load_lds_dwordx4 v[244:245], off
	s_waitcnt vmcnt(8)
	s_waitcnt lgkmcnt(0)
	s_barrier
	s_setprio 1
	s_waitcnt lgkmcnt(0)
	v_mfma_i32_16x16x64_i8 v[136:139], v[60:63], v[184:187], v[136:139]
	v_mfma_i32_16x16x64_i8 v[136:139], v[68:71], v[188:191], v[136:139]
	v_mfma_i32_16x16x64_i8 v[120:123], v[68:71], v[208:211], v[120:123]
	v_mfma_i32_16x16x64_i8 v[120:123], v[60:63], v[204:207], v[120:123]
	v_mfma_i32_16x16x64_i8 v[104:107], v[60:63], v[212:215], v[104:107]
	v_mfma_i32_16x16x64_i8 v[104:107], v[68:71], v[216:219], v[104:107]
	v_mfma_i32_16x16x64_i8 v[88:91], v[68:71], v[224:227], v[88:91]
	v_mfma_i32_16x16x64_i8 v[88:91], v[60:63], v[220:223], v[88:91]
	v_mfma_i32_16x16x64_i8 v[80:83], v[140:143], v[220:223], v[80:83]
	v_mfma_i32_16x16x64_i8 v[80:83], v[144:147], v[224:227], v[80:83]
	v_mfma_i32_16x16x64_i8 v[96:99], v[144:147], v[216:219], v[96:99]
	v_mfma_i32_16x16x64_i8 v[96:99], v[140:143], v[212:215], v[96:99]
	v_mfma_i32_16x16x64_i8 v[112:115], v[140:143], v[204:207], v[112:115]
	v_mfma_i32_16x16x64_i8 v[112:115], v[144:147], v[208:211], v[112:115]
	v_mfma_i32_16x16x64_i8 v[128:131], v[144:147], v[188:191], v[128:131]
	v_mfma_i32_16x16x64_i8 v[128:131], v[140:143], v[184:187], v[128:131]
	v_mfma_i32_16x16x64_i8 v[132:135], v[160:163], v[184:187], v[132:135]
	v_mfma_i32_16x16x64_i8 v[132:135], v[172:175], v[188:191], v[132:135]
	v_mfma_i32_16x16x64_i8 v[116:119], v[172:175], v[208:211], v[116:119]
	v_mfma_i32_16x16x64_i8 v[116:119], v[160:163], v[204:207], v[116:119]
	v_mfma_i32_16x16x64_i8 v[100:103], v[160:163], v[212:215], v[100:103]
	v_mfma_i32_16x16x64_i8 v[100:103], v[172:175], v[216:219], v[100:103]
	v_mfma_i32_16x16x64_i8 v[84:87], v[172:175], v[224:227], v[84:87]
	v_mfma_i32_16x16x64_i8 v[84:87], v[160:163], v[220:223], v[84:87]
	v_mfma_i32_16x16x64_i8 v[76:79], v[176:179], v[220:223], v[76:79]
	v_mfma_i32_16x16x64_i8 v[76:79], v[180:183], v[224:227], v[76:79]
	v_mfma_i32_16x16x64_i8 v[92:95], v[180:183], v[216:219], v[92:95]
	v_mfma_i32_16x16x64_i8 v[92:95], v[176:179], v[212:215], v[92:95]
	v_mfma_i32_16x16x64_i8 v[108:111], v[176:179], v[204:207], v[108:111]
	v_mfma_i32_16x16x64_i8 v[108:111], v[180:183], v[208:211], v[108:111]
	v_mfma_i32_16x16x64_i8 v[124:127], v[180:183], v[188:191], v[124:127]
	v_mfma_i32_16x16x64_i8 v[124:127], v[176:179], v[184:187], v[124:127]
	s_setprio 0
	s_barrier
	s_add_i32 s48, s64, s47
	v_lshl_add_u64 v[164:165], v[164:165], 0, s[84:85]
	s_mov_b32 m0, s48
	ds_read_b128 v[184:187], v171 offset:49152
	ds_read_b128 v[188:191], v171 offset:50176
	ds_read_b128 v[204:207], v171 offset:51200
	ds_read_b128 v[208:211], v171 offset:52224
	ds_read_b128 v[212:215], v171 offset:53248
	ds_read_b128 v[216:219], v171 offset:54272
	ds_read_b128 v[220:223], v171 offset:55296
	ds_read_b128 v[224:227], v171 offset:56320
	global_load_lds_dwordx4 v[164:165], off
	s_add_i32 m0, s48, 0x2000
	s_add_u32 s44, s44, 0x80080
	v_lshl_add_u64 v[164:165], v[228:229], 0, s[84:85]
	s_addc_u32 s45, s45, 0
	s_add_i32 s48, s65, s47
	global_load_lds_dwordx4 v[164:165], off
	v_lshl_add_u64 v[164:165], s[44:45], 0, v[2:3]
	s_mov_b32 m0, s48
	s_nop 0
	global_load_lds_dwordx4 v[164:165], off
	v_lshl_add_u64 v[164:165], s[44:45], 0, v[148:149]
	s_add_i32 m0, s48, 0x2000
	s_nop 0
	global_load_lds_dwordx4 v[164:165], off
	v_lshl_add_u64 v[164:165], v[240:241], 0, s[84:85]
	s_mov_b32 m0, s54
	s_nop 0
	global_load_lds_dwordx4 v[164:165], off
	v_lshl_add_u64 v[164:165], v[242:243], 0, s[84:85]
	s_mov_b32 m0, s55
	s_nop 0
	global_load_lds_dwordx4 v[164:165], off
	s_waitcnt vmcnt(8)
	s_waitcnt lgkmcnt(0)
	s_barrier
	s_setprio 1
	s_waitcnt lgkmcnt(0)
	v_mfma_i32_16x16x64_i8 v[72:75], v[60:63], v[184:187], v[72:75]
	v_mfma_i32_16x16x64_i8 v[72:75], v[68:71], v[188:191], v[72:75]
	v_mfma_i32_16x16x64_i8 v[56:59], v[68:71], v[208:211], v[56:59]
	v_mfma_i32_16x16x64_i8 v[56:59], v[60:63], v[204:207], v[56:59]
	v_mfma_i32_16x16x64_i8 v[32:35], v[60:63], v[212:215], v[32:35]
	v_mfma_i32_16x16x64_i8 v[32:35], v[68:71], v[216:219], v[32:35]
	v_mfma_i32_16x16x64_i8 v[16:19], v[68:71], v[224:227], v[16:19]
	v_mfma_i32_16x16x64_i8 v[16:19], v[60:63], v[220:223], v[16:19]
	v_mfma_i32_16x16x64_i8 v[8:11], v[140:143], v[220:223], v[8:11]
	v_mfma_i32_16x16x64_i8 v[8:11], v[144:147], v[224:227], v[8:11]
	v_mfma_i32_16x16x64_i8 v[24:27], v[144:147], v[216:219], v[24:27]
	v_mfma_i32_16x16x64_i8 v[24:27], v[140:143], v[212:215], v[24:27]
	v_mfma_i32_16x16x64_i8 v[48:51], v[140:143], v[204:207], v[48:51]
	v_mfma_i32_16x16x64_i8 v[48:51], v[144:147], v[208:211], v[48:51]
	v_mfma_i32_16x16x64_i8 v[64:67], v[144:147], v[188:191], v[64:67]
	v_mfma_i32_16x16x64_i8 v[64:67], v[140:143], v[184:187], v[64:67]
	v_mfma_i32_16x16x64_i8 v[36:39], v[160:163], v[184:187], v[36:39]
	v_mfma_i32_16x16x64_i8 v[68:71], v[172:175], v[188:191], v[36:39]
	v_mfma_i32_16x16x64_i8 v[36:39], v[172:175], v[208:211], v[52:55]
	v_mfma_i32_16x16x64_i8 v[52:55], v[160:163], v[204:207], v[36:39]
	v_mfma_i32_16x16x64_i8 v[28:31], v[160:163], v[212:215], v[28:31]
	v_mfma_i32_16x16x64_i8 v[28:31], v[172:175], v[216:219], v[28:31]
	v_mfma_i32_16x16x64_i8 v[12:15], v[172:175], v[224:227], v[12:15]
	v_mfma_i32_16x16x64_i8 v[12:15], v[160:163], v[220:223], v[12:15]
	v_mfma_i32_16x16x64_i8 v[4:7], v[176:179], v[220:223], v[4:7]
	v_mfma_i32_16x16x64_i8 v[4:7], v[180:183], v[224:227], v[4:7]
	v_mfma_i32_16x16x64_i8 v[20:23], v[180:183], v[216:219], v[20:23]
	v_mfma_i32_16x16x64_i8 v[20:23], v[176:179], v[212:215], v[20:23]
	v_mfma_i32_16x16x64_i8 v[36:39], v[176:179], v[204:207], v[40:43]
	v_mfma_i32_16x16x64_i8 v[40:43], v[180:183], v[208:211], v[36:39]
	v_mfma_i32_16x16x64_i8 v[36:39], v[180:183], v[188:191], v[44:47]
	v_mfma_i32_16x16x64_i8 v[60:63], v[176:179], v[184:187], v[36:39]
	s_setprio 0
	s_add_i32 s61, s61, 2
	s_add_u32 s40, s40, 0x100
	s_addc_u32 s41, s41, 0
	s_add_u32 s59, s59, 0x100
	s_addc_u32 s60, s60, 0
	s_cmp_gt_u32 s61, 29
	s_barrier
	s_cbranch_scc0 .LBB0_1591

; #define PG8_STAGE(bufoff, gbase, voff) do { _Pragma("unroll") for (int _i = 0; _i < 2; ++_i) \
;         __builtin_amdgcn_global_load_lds((const unsigned*)((const char*)(gbase) + (voff)[_i]), (PG8_LAS unsigned*)(lds + (bufoff) + ldsw + _i * 8192), 16, 0, 0); } while (0)
; #define PG8_LDA(dst, b, h) do { _Pragma("unroll") for (int m = 0; m < 4; ++m) _Pragma("unroll") for (int k = 0; k < 2; ++k) dst[m][k] = *(const PG8_LAS bf16x8*)(lds + PG8_SA(b, h) + aoff + m * 2048 + k * 1024); } while (0)
; #define PG8_LDB(dst, b, h) do { _Pragma("unroll") for (int n = 0; n < 2; ++n) _Pragma("unroll") for (int k = 0; k < 2; ++k) dst[n][k] = *(const PG8_LAS bf16x8*)(lds + PG8_SB(b, h) + boff + n * 2048 + k * 1024); } while (0)
; #define PG8_SCHED __builtin_amdgcn_sched_barrier(0)
; template <class Epi, class Sched, bool ALIGN_EPI = false, bool SP2 = false, bool I8 = false>
; __device__ __forceinline__ void gemm_phase(PG8_LAS unsigned char* lds, const Gemm g, const Sched& S, const Epi& E) {
;     ...
;         for (int t = 0; t < nt; t += 2) {
;             const bool last = (t == nt - 2);
;             const char* a1 = cA + (size_t)(t + 1) * kstep;
;             const char* a2 = last ? nA : cA + (size_t)(t + 2) * kstep; const char* b2 = last ? nB : cB + (size_t)(t + 2) * kstep;
;             const char* a3 = a2 + kstep; const char* b3 = b2 + kstep;
;             if (last && has_next) S.a_ready(nxt);
;             if constexpr (SP2) {
;             PG8_LDB(B0, 0, 0); PG8_LDB(B1, 0, 1); PG8_SCHED; PG8_LDA(At, 0, 0); PG8_STAGE(PG8_SA(1, 1), a1 + hstep, voffA);
;     ...
;         for (int a = 0; a < 2; ++a)
; #pragma unroll
;             for (int b = 0; b < 2; ++b)
; #pragma unroll
;                 for (int m = 0; m < 4; ++m)
; #pragma unroll
;                     for (int n = 0; n < 2; ++n) acc[a][b][m][n] = (acc_t){0, 0, 0, 0};
.LBB0_1621:
	v_mov_b32_e32 v127, 0
	s_andn2_b64 vcc, exec, s[26:27]
	v_mov_b32_e32 v126, v127
	v_mov_b32_e32 v125, v127
	v_mov_b32_e32 v124, v127
	v_mov_b32_e32 v131, v127
	v_mov_b32_e32 v130, v127
	v_mov_b32_e32 v129, v127
	v_mov_b32_e32 v128, v127
	v_mov_b32_e32 v115, v127
	v_mov_b32_e32 v114, v127
	v_mov_b32_e32 v113, v127
	v_mov_b32_e32 v112, v127
	v_mov_b32_e32 v111, v127
	v_mov_b32_e32 v110, v127
	v_mov_b32_e32 v109, v127
	v_mov_b32_e32 v108, v127
	v_mov_b32_e32 v99, v127
	v_mov_b32_e32 v98, v127
	v_mov_b32_e32 v97, v127
	v_mov_b32_e32 v96, v127
	v_mov_b32_e32 v95, v127
	v_mov_b32_e32 v94, v127
	v_mov_b32_e32 v93, v127
	v_mov_b32_e32 v92, v127
	v_mov_b32_e32 v83, v127
	v_mov_b32_e32 v82, v127
	v_mov_b32_e32 v81, v127
	v_mov_b32_e32 v80, v127
	v_mov_b32_e32 v79, v127
	v_mov_b32_e32 v78, v127
	v_mov_b32_e32 v77, v127
	v_mov_b32_e32 v76, v127
	v_mov_b32_e32 v123, v127
	v_mov_b32_e32 v122, v127
	v_mov_b32_e32 v121, v127
	v_mov_b32_e32 v120, v127
	v_mov_b32_e32 v119, v127
	v_mov_b32_e32 v118, v127
	v_mov_b32_e32 v117, v127
	v_mov_b32_e32 v116, v127
	v_mov_b32_e32 v107, v127
	v_mov_b32_e32 v106, v127
	v_mov_b32_e32 v105, v127
	v_mov_b32_e32 v104, v127
	v_mov_b32_e32 v103, v127
	v_mov_b32_e32 v102, v127
	v_mov_b32_e32 v101, v127
	v_mov_b32_e32 v100, v127
	v_mov_b32_e32 v91, v127
	v_mov_b32_e32 v90, v127
	v_mov_b32_e32 v89, v127
	v_mov_b32_e32 v88, v127
	v_mov_b32_e32 v87, v127
	v_mov_b32_e32 v86, v127
	v_mov_b32_e32 v85, v127
	v_mov_b32_e32 v84, v127
	v_mov_b32_e32 v75, v127
	v_mov_b32_e32 v74, v127
	v_mov_b32_e32 v73, v127
	v_mov_b32_e32 v72, v127
	v_mov_b32_e32 v71, v127
	v_mov_b32_e32 v70, v127
	v_mov_b32_e32 v69, v127
	v_mov_b32_e32 v68, v127
	v_mov_b32_e32 v67, v127
	v_mov_b32_e32 v66, v127
	v_mov_b32_e32 v65, v127
	v_mov_b32_e32 v64, v127
	v_mov_b32_e32 v63, v127
	v_mov_b32_e32 v62, v127
	v_mov_b32_e32 v61, v127
	v_mov_b32_e32 v60, v127
	v_mov_b32_e32 v51, v127
	v_mov_b32_e32 v50, v127
	v_mov_b32_e32 v49, v127
	v_mov_b32_e32 v48, v127
	v_mov_b32_e32 v47, v127
	v_mov_b32_e32 v46, v127
	v_mov_b32_e32 v45, v127
	v_mov_b32_e32 v44, v127
	v_mov_b32_e32 v35, v127
	v_mov_b32_e32 v34, v127
	v_mov_b32_e32 v33, v127
	v_mov_b32_e32 v32, v127
	v_mov_b32_e32 v31, v127
	v_mov_b32_e32 v30, v127
	v_mov_b32_e32 v29, v127
	v_mov_b32_e32 v28, v127
	v_mov_b32_e32 v19, v127
	v_mov_b32_e32 v18, v127
	v_mov_b32_e32 v17, v127
	v_mov_b32_e32 v16, v127
	v_mov_b32_e32 v15, v127
	v_mov_b32_e32 v14, v127
	v_mov_b32_e32 v13, v127
	v_mov_b32_e32 v12, v127
	v_mov_b32_e32 v59, v127
	v_mov_b32_e32 v58, v127
	v_mov_b32_e32 v57, v127
	v_mov_b32_e32 v56, v127
	v_mov_b32_e32 v55, v127
	v_mov_b32_e32 v54, v127
	v_mov_b32_e32 v53, v127
	v_mov_b32_e32 v52, v127
	v_mov_b32_e32 v43, v127
	v_mov_b32_e32 v42, v127
	v_mov_b32_e32 v41, v127
	v_mov_b32_e32 v40, v127
	v_mov_b32_e32 v39, v127
	v_mov_b32_e32 v38, v127
	v_mov_b32_e32 v37, v127
	v_mov_b32_e32 v36, v127
	v_mov_b32_e32 v27, v127
	v_mov_b32_e32 v26, v127
	v_mov_b32_e32 v25, v127
	v_mov_b32_e32 v24, v127
	v_mov_b32_e32 v23, v127
	v_mov_b32_e32 v22, v127
	v_mov_b32_e32 v21, v127
	v_mov_b32_e32 v20, v127
	v_mov_b32_e32 v11, v127
	v_mov_b32_e32 v10, v127
	v_mov_b32_e32 v9, v127
	v_mov_b32_e32 v8, v127
	v_mov_b32_e32 v7, v127
	v_mov_b32_e32 v6, v127
	v_mov_b32_e32 v5, v127
	v_mov_b32_e32 v4, v127
	s_cbranch_vccnz .LBB0_1625
	s_add_u32 s44, s44, 0x80
	s_addc_u32 s45, s45, 0
	s_add_u32 s65, s48, 0x100
	s_addc_u32 s67, s49, 0
	s_mov_b32 s48, 0
	s_add_i32 s72, s48, 2
	s_add_u32 s73, s44, 0x80
	s_addc_u32 s49, s45, 0
	s_add_i32 s86, 0, 0x10000
	s_cmp_eq_u32 s57, s48
	s_cselect_b32 s49, s13, s49
	s_cselect_b32 s48, s12, s73
	s_cselect_b32 s77, s41, s67
	s_cselect_b32 s76, s40, s65
	s_add_i32 s73, 0, 0x14000
	v_add_u32_e32 v158, s86, v143
	v_add_u32_e32 v174, s73, v143
	ds_read_b128 v[146:149], v158
	ds_read_b128 v[150:153], v158 offset:1024
	ds_read_b128 v[154:157], v158 offset:2048
	ds_read_b128 v[158:161], v158 offset:3072
	ds_read_b128 v[162:165], v174
	ds_read_b128 v[166:169], v174 offset:1024
	ds_read_b128 v[170:173], v174 offset:2048
	ds_read_b128 v[174:177], v174 offset:3072
	v_lshl_add_u64 v[190:191], s[44:45], 0, v[138:139]
	s_add_i32 m0, s47, 0xc000
	ds_read_b128 v[178:181], v145
	ds_read_b128 v[182:185], v145 offset:1024
	ds_read_b128 v[186:189], v145 offset:2048
	ds_read_b128 v[204:207], v145 offset:3072
	ds_read_b128 v[208:211], v145 offset:4096
	ds_read_b128 v[212:215], v145 offset:5120
	ds_read_b128 v[216:219], v145 offset:6144
	ds_read_b128 v[220:223], v145 offset:7168
	global_load_lds_dwordx4 v[190:191], off
	v_lshl_add_u64 v[190:191], s[44:45], 0, v[140:141]
	s_add_i32 m0, s47, 0xe000
	s_nop 0
	global_load_lds_dwordx4 v[190:191], off
	s_waitcnt vmcnt(8)
	s_waitcnt lgkmcnt(0)
	s_barrier
; #define PG8_STAGE(bufoff, gbase, voff) do { _Pragma("unroll") for (int _i = 0; _i < 2; ++_i) \
;         __builtin_amdgcn_global_load_lds((const unsigned*)((const char*)(gbase) + (voff)[_i]), (PG8_LAS unsigned*)(lds + (bufoff) + ldsw + _i * 8192), 16, 0, 0); } while (0)
; #define PG8_LDA(dst, b, h) do { _Pragma("unroll") for (int m = 0; m < 4; ++m) _Pragma("unroll") for (int k = 0; k < 2; ++k) dst[m][k] = *(const PG8_LAS bf16x8*)(lds + PG8_SA(b, h) + aoff + m * 2048 + k * 1024); } while (0)
; #define PG8_WAIT_V(n) asm volatile("s_waitcnt vmcnt(" #n ")" ::: "memory")
; #define PG8_WAIT_L(n) asm volatile("s_waitcnt lgkmcnt(" #n ")" ::: "memory")
; #define PG8_BAR __builtin_amdgcn_s_barrier()
; #define PG8_SCHED __builtin_amdgcn_sched_barrier(0)
; template <class Epi, class Sched, bool ALIGN_EPI = false, bool SP2 = false, bool I8 = false>
; __device__ __forceinline__ void gemm_phase(PG8_LAS unsigned char* lds, const Gemm g, const Sched& S, const Epi& E) {
;     ...
;             PG8_WAIT_V(8); PG8_WAIT_L(0); PG8_BAR; PG8_MMA(0, 0, At, B0); PG8_MMA(0, 1, At, B1); PG8_BAR; PG8_SCHED;
;             PG8_LDA(At, 0, 1); PG8_STAGE(PG8_SB(0, 0), b2, voffB); PG8_STAGE(PG8_SB(0, 1), b2 + hstep, voffB); PG8_STAGE(PG8_SA(0, 0), a2, voffA);
;             PG8_WAIT_V(8); PG8_WAIT_L(0); PG8_BAR; PG8_MMA(1, 0, At, B0); PG8_MMA(1, 1, At, B1); PG8_BAR; PG8_SCHED;
	s_setprio 1
	s_waitcnt lgkmcnt(0)
	v_mfma_f32_16x16x32_bf16 v[124:127], v[146:149], v[178:181], 0
	v_mfma_f32_16x16x32_bf16 v[124:127], v[150:153], v[182:185], v[124:127]
	v_mfma_f32_16x16x32_bf16 v[112:115], v[150:153], v[204:207], 0
	v_mfma_f32_16x16x32_bf16 v[112:115], v[146:149], v[186:189], v[112:115]
	v_mfma_f32_16x16x32_bf16 v[96:99], v[146:149], v[208:211], 0
	v_mfma_f32_16x16x32_bf16 v[96:99], v[150:153], v[212:215], v[96:99]
	v_mfma_f32_16x16x32_bf16 v[80:83], v[150:153], v[220:223], 0
	v_mfma_f32_16x16x32_bf16 v[80:83], v[146:149], v[216:219], v[80:83]
	v_mfma_f32_16x16x32_bf16 v[76:79], v[154:157], v[216:219], 0
	v_mfma_f32_16x16x32_bf16 v[76:79], v[158:161], v[220:223], v[76:79]
	v_mfma_f32_16x16x32_bf16 v[92:95], v[158:161], v[212:215], 0
	v_mfma_f32_16x16x32_bf16 v[92:95], v[154:157], v[208:211], v[92:95]
	v_mfma_f32_16x16x32_bf16 v[108:111], v[154:157], v[186:189], 0
	v_mfma_f32_16x16x32_bf16 v[108:111], v[158:161], v[204:207], v[108:111]
	v_mfma_f32_16x16x32_bf16 v[128:131], v[158:161], v[182:185], 0
	v_mfma_f32_16x16x32_bf16 v[128:131], v[154:157], v[178:181], v[128:131]
	v_mfma_f32_16x16x32_bf16 v[120:123], v[162:165], v[178:181], 0
	v_mfma_f32_16x16x32_bf16 v[120:123], v[166:169], v[182:185], v[120:123]
	v_mfma_f32_16x16x32_bf16 v[104:107], v[166:169], v[204:207], 0
	v_mfma_f32_16x16x32_bf16 v[104:107], v[162:165], v[186:189], v[104:107]
	v_mfma_f32_16x16x32_bf16 v[88:91], v[162:165], v[208:211], 0
	v_mfma_f32_16x16x32_bf16 v[88:91], v[166:169], v[212:215], v[88:91]
	v_mfma_f32_16x16x32_bf16 v[72:75], v[166:169], v[220:223], 0
	v_mfma_f32_16x16x32_bf16 v[72:75], v[162:165], v[216:219], v[72:75]
	v_mfma_f32_16x16x32_bf16 v[68:71], v[170:173], v[216:219], 0
	v_mfma_f32_16x16x32_bf16 v[68:71], v[174:177], v[220:223], v[68:71]
	v_mfma_f32_16x16x32_bf16 v[84:87], v[174:177], v[212:215], 0
	v_mfma_f32_16x16x32_bf16 v[84:87], v[170:173], v[208:211], v[84:87]
	v_mfma_f32_16x16x32_bf16 v[100:103], v[170:173], v[186:189], 0
	v_mfma_f32_16x16x32_bf16 v[100:103], v[174:177], v[204:207], v[100:103]
	v_mfma_f32_16x16x32_bf16 v[116:119], v[174:177], v[182:185], 0
	v_mfma_f32_16x16x32_bf16 v[116:119], v[170:173], v[178:181], v[116:119]
	s_setprio 0
	s_barrier
	s_add_i32 s86, s86, s28
	v_lshl_add_u64 v[190:191], s[76:77], 0, v[2:3]
	s_mov_b32 m0, s86
	ds_read_b128 v[178:181], v145 offset:16384
	ds_read_b128 v[182:185], v145 offset:17408
	ds_read_b128 v[186:189], v145 offset:18432
	ds_read_b128 v[204:207], v145 offset:19456
	ds_read_b128 v[208:211], v145 offset:20480
	ds_read_b128 v[212:215], v145 offset:21504
	ds_read_b128 v[216:219], v145 offset:22528
	ds_read_b128 v[220:223], v145 offset:23552
	global_load_lds_dwordx4 v[190:191], off
	s_add_i32 m0, s86, 0x2000
	v_lshl_add_u64 v[224:225], s[76:77], 0, v[136:137]
	s_add_u32 s76, s76, s18
	s_addc_u32 s77, s77, s19
	s_add_i32 s73, s73, s28
	global_load_lds_dwordx4 v[224:225], off
	v_lshl_add_u64 v[226:227], s[76:77], 0, v[2:3]
	s_mov_b32 m0, s73
	v_lshl_add_u64 v[228:229], s[76:77], 0, v[136:137]
	global_load_lds_dwordx4 v[226:227], off
	s_add_i32 m0, s73, 0x2000
	v_lshl_add_u64 v[240:241], s[48:49], 0, v[132:133]
	global_load_lds_dwordx4 v[228:229], off
	s_mov_b32 m0, s47
	v_lshl_add_u64 v[242:243], s[48:49], 0, v[134:135]
	global_load_lds_dwordx4 v[240:241], off
	s_mov_b32 m0, s50
	s_nop 0
	global_load_lds_dwordx4 v[242:243], off
	s_waitcnt vmcnt(8)
	s_waitcnt lgkmcnt(0)
	s_barrier
	s_setprio 1
	s_waitcnt lgkmcnt(0)
	v_mfma_f32_16x16x32_bf16 v[64:67], v[146:149], v[178:181], 0
	v_mfma_f32_16x16x32_bf16 v[64:67], v[150:153], v[182:185], v[64:67]
	v_mfma_f32_16x16x32_bf16 v[48:51], v[150:153], v[204:207], 0
	v_mfma_f32_16x16x32_bf16 v[48:51], v[146:149], v[186:189], v[48:51]
	v_mfma_f32_16x16x32_bf16 v[32:35], v[146:149], v[208:211], 0
	v_mfma_f32_16x16x32_bf16 v[32:35], v[150:153], v[212:215], v[32:35]
	v_mfma_f32_16x16x32_bf16 v[16:19], v[150:153], v[220:223], 0
	v_mfma_f32_16x16x32_bf16 v[16:19], v[146:149], v[216:219], v[16:19]
	v_mfma_f32_16x16x32_bf16 v[12:15], v[154:157], v[216:219], 0
	v_mfma_f32_16x16x32_bf16 v[12:15], v[158:161], v[220:223], v[12:15]
	v_mfma_f32_16x16x32_bf16 v[28:31], v[158:161], v[212:215], 0
	v_mfma_f32_16x16x32_bf16 v[28:31], v[154:157], v[208:211], v[28:31]
	v_mfma_f32_16x16x32_bf16 v[44:47], v[154:157], v[186:189], 0
	v_mfma_f32_16x16x32_bf16 v[44:47], v[158:161], v[204:207], v[44:47]
	v_mfma_f32_16x16x32_bf16 v[60:63], v[158:161], v[182:185], 0
	v_mfma_f32_16x16x32_bf16 v[60:63], v[154:157], v[178:181], v[60:63]
	v_mfma_f32_16x16x32_bf16 v[56:59], v[162:165], v[178:181], 0
	v_mfma_f32_16x16x32_bf16 v[56:59], v[166:169], v[182:185], v[56:59]
	v_mfma_f32_16x16x32_bf16 v[40:43], v[166:169], v[204:207], 0
	v_mfma_f32_16x16x32_bf16 v[40:43], v[162:165], v[186:189], v[40:43]
	v_mfma_f32_16x16x32_bf16 v[24:27], v[162:165], v[208:211], 0
	v_mfma_f32_16x16x32_bf16 v[24:27], v[166:169], v[212:215], v[24:27]
	v_mfma_f32_16x16x32_bf16 v[8:11], v[166:169], v[220:223], 0
	v_mfma_f32_16x16x32_bf16 v[8:11], v[162:165], v[216:219], v[8:11]
	v_mfma_f32_16x16x32_bf16 v[4:7], v[170:173], v[216:219], 0
	v_mfma_f32_16x16x32_bf16 v[4:7], v[174:177], v[220:223], v[4:7]
	v_mfma_f32_16x16x32_bf16 v[20:23], v[174:177], v[212:215], 0
	v_mfma_f32_16x16x32_bf16 v[20:23], v[170:173], v[208:211], v[20:23]
	v_mfma_f32_16x16x32_bf16 v[36:39], v[170:173], v[186:189], 0
	v_mfma_f32_16x16x32_bf16 v[36:39], v[174:177], v[204:207], v[36:39]
	v_mfma_f32_16x16x32_bf16 v[52:55], v[174:177], v[182:185], 0
	v_mfma_f32_16x16x32_bf16 v[52:55], v[170:173], v[178:181], v[52:55]
	s_setprio 0
	s_barrier
; #define PG8_STAGE(bufoff, gbase, voff) do { _Pragma("unroll") for (int _i = 0; _i < 2; ++_i) \
;         __builtin_amdgcn_global_load_lds((const unsigned*)((const char*)(gbase) + (voff)[_i]), (PG8_LAS unsigned*)(lds + (bufoff) + ldsw + _i * 8192), 16, 0, 0); } while (0)
; #define PG8_LDA(dst, b, h) do { _Pragma("unroll") for (int m = 0; m < 4; ++m) _Pragma("unroll") for (int k = 0; k < 2; ++k) dst[m][k] = *(const PG8_LAS bf16x8*)(lds + PG8_SA(b, h) + aoff + m * 2048 + k * 1024); } while (0)
; #define PG8_LDB(dst, b, h) do { _Pragma("unroll") for (int n = 0; n < 2; ++n) _Pragma("unroll") for (int k = 0; k < 2; ++k) dst[n][k] = *(const PG8_LAS bf16x8*)(lds + PG8_SB(b, h) + boff + n * 2048 + k * 1024); } while (0)
; #define PG8_WAIT_V(n) asm volatile("s_waitcnt vmcnt(" #n ")" ::: "memory")
; #define PG8_WAIT_L(n) asm volatile("s_waitcnt lgkmcnt(" #n ")" ::: "memory")
; #define PG8_BAR __builtin_amdgcn_s_barrier()
; #define PG8_SCHED __builtin_amdgcn_sched_barrier(0)
; template <class Epi, class Sched, bool ALIGN_EPI = false, bool SP2 = false, bool I8 = false>
; __device__ __forceinline__ void gemm_phase(PG8_LAS unsigned char* lds, const Gemm g, const Sched& S, const Epi& E) {
;     ...
;             PG8_LDB(B0, 1, 0); PG8_LDB(B1, 1, 1); PG8_SCHED; PG8_LDA(At, 1, 0); PG8_STAGE(PG8_SA(0, 1), a2 + hstep, voffA);
;             PG8_WAIT_V(8); PG8_WAIT_L(0); PG8_BAR; PG8_MMA(0, 0, At, B0); PG8_MMA(0, 1, At, B1); PG8_BAR; PG8_SCHED;
;             PG8_LDA(At, 1, 1); PG8_STAGE(PG8_SB(1, 0), b3, voffB); PG8_STAGE(PG8_SB(1, 1), b3 + hstep, voffB); PG8_STAGE(PG8_SA(1, 0), a3, voffA);
	s_add_i32 s73, 0, 0x18000
	s_add_i32 s76, 0, 0x1c000
	v_add_u32_e32 v158, s73, v143
	v_add_u32_e32 v174, s76, v143
	ds_read_b128 v[146:149], v158
	ds_read_b128 v[150:153], v158 offset:1024
	ds_read_b128 v[154:157], v158 offset:2048
	ds_read_b128 v[158:161], v158 offset:3072
	ds_read_b128 v[162:165], v174
	ds_read_b128 v[166:169], v174 offset:1024
	ds_read_b128 v[170:173], v174 offset:2048
	ds_read_b128 v[174:177], v174 offset:3072
	s_add_u32 s48, s48, s18
	s_addc_u32 s49, s49, s19
	s_mov_b32 m0, s51
	v_lshl_add_u64 v[244:245], s[48:49], 0, v[132:133]
	ds_read_b128 v[178:181], v145 offset:32768
	ds_read_b128 v[182:185], v145 offset:33792
	ds_read_b128 v[186:189], v145 offset:34816
	ds_read_b128 v[204:207], v145 offset:35840
	ds_read_b128 v[208:211], v145 offset:36864
	ds_read_b128 v[212:215], v145 offset:37888
	ds_read_b128 v[216:219], v145 offset:38912
	ds_read_b128 v[220:223], v145 offset:39936
	global_load_lds_dwordx4 v[244:245], off
	v_lshl_add_u64 v[244:245], s[48:49], 0, v[134:135]
	s_mov_b32 m0, s52
	s_nop 0
	global_load_lds_dwordx4 v[244:245], off
	s_waitcnt vmcnt(8)
	s_waitcnt lgkmcnt(0)
	s_barrier
	s_setprio 1
	s_waitcnt lgkmcnt(0)
	v_mfma_f32_16x16x32_bf16 v[124:127], v[146:149], v[178:181], v[124:127]
	v_mfma_f32_16x16x32_bf16 v[124:127], v[150:153], v[182:185], v[124:127]
	v_mfma_f32_16x16x32_bf16 v[112:115], v[150:153], v[204:207], v[112:115]
	v_mfma_f32_16x16x32_bf16 v[112:115], v[146:149], v[186:189], v[112:115]
	v_mfma_f32_16x16x32_bf16 v[96:99], v[146:149], v[208:211], v[96:99]
	v_mfma_f32_16x16x32_bf16 v[96:99], v[150:153], v[212:215], v[96:99]
	v_mfma_f32_16x16x32_bf16 v[80:83], v[150:153], v[220:223], v[80:83]
	v_mfma_f32_16x16x32_bf16 v[80:83], v[146:149], v[216:219], v[80:83]
	v_mfma_f32_16x16x32_bf16 v[76:79], v[154:157], v[216:219], v[76:79]
	v_mfma_f32_16x16x32_bf16 v[76:79], v[158:161], v[220:223], v[76:79]
	v_mfma_f32_16x16x32_bf16 v[92:95], v[158:161], v[212:215], v[92:95]
	v_mfma_f32_16x16x32_bf16 v[92:95], v[154:157], v[208:211], v[92:95]
	v_mfma_f32_16x16x32_bf16 v[108:111], v[154:157], v[186:189], v[108:111]
	v_mfma_f32_16x16x32_bf16 v[108:111], v[158:161], v[204:207], v[108:111]
	v_mfma_f32_16x16x32_bf16 v[128:131], v[158:161], v[182:185], v[128:131]
	v_mfma_f32_16x16x32_bf16 v[128:131], v[154:157], v[178:181], v[128:131]
	v_mfma_f32_16x16x32_bf16 v[120:123], v[162:165], v[178:181], v[120:123]
	v_mfma_f32_16x16x32_bf16 v[120:123], v[166:169], v[182:185], v[120:123]
	v_mfma_f32_16x16x32_bf16 v[104:107], v[166:169], v[204:207], v[104:107]
	v_mfma_f32_16x16x32_bf16 v[104:107], v[162:165], v[186:189], v[104:107]
	v_mfma_f32_16x16x32_bf16 v[88:91], v[162:165], v[208:211], v[88:91]
	v_mfma_f32_16x16x32_bf16 v[88:91], v[166:169], v[212:215], v[88:91]
	v_mfma_f32_16x16x32_bf16 v[72:75], v[166:169], v[220:223], v[72:75]
	v_mfma_f32_16x16x32_bf16 v[72:75], v[162:165], v[216:219], v[72:75]
	v_mfma_f32_16x16x32_bf16 v[68:71], v[170:173], v[216:219], v[68:71]
	v_mfma_f32_16x16x32_bf16 v[68:71], v[174:177], v[220:223], v[68:71]
	v_mfma_f32_16x16x32_bf16 v[84:87], v[174:177], v[212:215], v[84:87]
	v_mfma_f32_16x16x32_bf16 v[84:87], v[170:173], v[208:211], v[84:87]
	v_mfma_f32_16x16x32_bf16 v[100:103], v[170:173], v[186:189], v[100:103]
	v_mfma_f32_16x16x32_bf16 v[100:103], v[174:177], v[204:207], v[100:103]
	v_mfma_f32_16x16x32_bf16 v[116:119], v[174:177], v[182:185], v[116:119]
	v_mfma_f32_16x16x32_bf16 v[116:119], v[170:173], v[178:181], v[116:119]
	s_setprio 0
	s_barrier
	s_add_i32 s48, s73, s28
	v_lshl_add_u64 v[190:191], v[190:191], 0, s[84:85]
	s_mov_b32 m0, s48
	ds_read_b128 v[178:181], v145 offset:49152
	ds_read_b128 v[182:185], v145 offset:50176
	ds_read_b128 v[186:189], v145 offset:51200
	ds_read_b128 v[204:207], v145 offset:52224
	ds_read_b128 v[208:211], v145 offset:53248
	ds_read_b128 v[212:215], v145 offset:54272
	ds_read_b128 v[216:219], v145 offset:55296
	ds_read_b128 v[220:223], v145 offset:56320
	global_load_lds_dwordx4 v[190:191], off
	v_lshl_add_u64 v[190:191], v[224:225], 0, s[84:85]
	s_add_i32 m0, s48, 0x2000
	s_add_i32 s48, s76, s28
	global_load_lds_dwordx4 v[190:191], off
	v_lshl_add_u64 v[190:191], v[226:227], 0, s[84:85]
	s_mov_b32 m0, s48
	s_nop 0
	global_load_lds_dwordx4 v[190:191], off
	v_lshl_add_u64 v[190:191], v[228:229], 0, s[84:85]
	s_add_i32 m0, s48, 0x2000
	s_nop 0
	global_load_lds_dwordx4 v[190:191], off
	v_lshl_add_u64 v[190:191], v[240:241], 0, s[84:85]
	s_mov_b32 m0, s55
	s_nop 0
	global_load_lds_dwordx4 v[190:191], off
	v_lshl_add_u64 v[190:191], v[242:243], 0, s[84:85]
	s_mov_b32 m0, s56
	s_nop 0
	global_load_lds_dwordx4 v[190:191], off
	s_waitcnt vmcnt(8)
	s_waitcnt lgkmcnt(0)
	s_barrier
; #define PG8_STAGE(bufoff, gbase, voff) do { _Pragma("unroll") for (int _i = 0; _i < 2; ++_i) \
;         __builtin_amdgcn_global_load_lds((const unsigned*)((const char*)(gbase) + (voff)[_i]), (PG8_LAS unsigned*)(lds + (bufoff) + ldsw + _i * 8192), 16, 0, 0); } while (0)
; #define PG8_LDA(dst, b, h) do { _Pragma("unroll") for (int m = 0; m < 4; ++m) _Pragma("unroll") for (int k = 0; k < 2; ++k) dst[m][k] = *(const PG8_LAS bf16x8*)(lds + PG8_SA(b, h) + aoff + m * 2048 + k * 1024); } while (0)
; #define PG8_WAIT_V(n) asm volatile("s_waitcnt vmcnt(" #n ")" ::: "memory")
; #define PG8_WAIT_L(n) asm volatile("s_waitcnt lgkmcnt(" #n ")" ::: "memory")
; #define PG8_BAR __builtin_amdgcn_s_barrier()
; template <class Epi, class Sched, bool ALIGN_EPI = false, bool SP2 = false, bool I8 = false>
; __device__ __forceinline__ void gemm_phase(PG8_LAS unsigned char* lds, const Gemm g, const Sched& S, const Epi& E) {
;     ...
;         for (int t = 0; t < nt; t += 2) {
;             const bool last = (t == nt - 2);
;             const char* a1 = cA + (size_t)(t + 1) * kstep;
;             const char* a2 = last ? nA : cA + (size_t)(t + 2) * kstep; const char* b2 = last ? nB : cB + (size_t)(t + 2) * kstep;
;             const char* a3 = a2 + kstep; const char* b3 = b2 + kstep;
;             if (last && has_next) S.a_ready(nxt);
;             if constexpr (SP2) {
;             PG8_LDB(B0, 0, 0); PG8_LDB(B1, 0, 1); PG8_SCHED; PG8_LDA(At, 0, 0); PG8_STAGE(PG8_SA(1, 1), a1 + hstep, voffA);
;             PG8_WAIT_V(8); PG8_WAIT_L(0); PG8_BAR; PG8_MMA(0, 0, At, B0); PG8_MMA(0, 1, At, B1); PG8_BAR; PG8_SCHED;
;             PG8_LDA(At, 0, 1); PG8_STAGE(PG8_SB(0, 0), b2, voffB); PG8_STAGE(PG8_SB(0, 1), b2 + hstep, voffB); PG8_STAGE(PG8_SA(0, 0), a2, voffA);
;             PG8_WAIT_V(8); PG8_WAIT_L(0); PG8_BAR; PG8_MMA(1, 0, At, B0); PG8_MMA(1, 1, At, B1); PG8_BAR; PG8_SCHED;
;             PG8_LDB(B0, 1, 0); PG8_LDB(B1, 1, 1); PG8_SCHED; PG8_LDA(At, 1, 0); PG8_STAGE(PG8_SA(0, 1), a2 + hstep, voffA);
;             PG8_WAIT_V(8); PG8_WAIT_L(0); PG8_BAR; PG8_MMA(0, 0, At, B0); PG8_MMA(0, 1, At, B1); PG8_BAR; PG8_SCHED;
;             PG8_LDA(At, 1, 1); PG8_STAGE(PG8_SB(1, 0), b3, voffB); PG8_STAGE(PG8_SB(1, 1), b3 + hstep, voffB); PG8_STAGE(PG8_SA(1, 0), a3, voffA);
;             PG8_WAIT_V(8); PG8_WAIT_L(0); PG8_BAR; PG8_MMA(1, 0, At, B0); PG8_MMA(1, 1, At, B1); PG8_BAR; PG8_SCHED;
	s_setprio 1
	s_waitcnt lgkmcnt(0)
	v_mfma_f32_16x16x32_bf16 v[64:67], v[146:149], v[178:181], v[64:67]
	v_mfma_f32_16x16x32_bf16 v[64:67], v[150:153], v[182:185], v[64:67]
	v_mfma_f32_16x16x32_bf16 v[48:51], v[150:153], v[204:207], v[48:51]
	v_mfma_f32_16x16x32_bf16 v[48:51], v[146:149], v[186:189], v[48:51]
	v_mfma_f32_16x16x32_bf16 v[32:35], v[146:149], v[208:211], v[32:35]
	v_mfma_f32_16x16x32_bf16 v[32:35], v[150:153], v[212:215], v[32:35]
	v_mfma_f32_16x16x32_bf16 v[16:19], v[150:153], v[220:223], v[16:19]
	v_mfma_f32_16x16x32_bf16 v[16:19], v[146:149], v[216:219], v[16:19]
	v_mfma_f32_16x16x32_bf16 v[12:15], v[154:157], v[216:219], v[12:15]
	v_mfma_f32_16x16x32_bf16 v[12:15], v[158:161], v[220:223], v[12:15]
	v_mfma_f32_16x16x32_bf16 v[28:31], v[158:161], v[212:215], v[28:31]
	v_mfma_f32_16x16x32_bf16 v[28:31], v[154:157], v[208:211], v[28:31]
	v_mfma_f32_16x16x32_bf16 v[44:47], v[154:157], v[186:189], v[44:47]
	v_mfma_f32_16x16x32_bf16 v[44:47], v[158:161], v[204:207], v[44:47]
	v_mfma_f32_16x16x32_bf16 v[60:63], v[158:161], v[182:185], v[60:63]
	v_mfma_f32_16x16x32_bf16 v[60:63], v[154:157], v[178:181], v[60:63]
	v_mfma_f32_16x16x32_bf16 v[56:59], v[162:165], v[178:181], v[56:59]
	v_mfma_f32_16x16x32_bf16 v[56:59], v[166:169], v[182:185], v[56:59]
	v_mfma_f32_16x16x32_bf16 v[40:43], v[166:169], v[204:207], v[40:43]
	v_mfma_f32_16x16x32_bf16 v[40:43], v[162:165], v[186:189], v[40:43]
	v_mfma_f32_16x16x32_bf16 v[24:27], v[162:165], v[208:211], v[24:27]
	v_mfma_f32_16x16x32_bf16 v[24:27], v[166:169], v[212:215], v[24:27]
	v_mfma_f32_16x16x32_bf16 v[8:11], v[166:169], v[220:223], v[8:11]
	v_mfma_f32_16x16x32_bf16 v[8:11], v[162:165], v[216:219], v[8:11]
	v_mfma_f32_16x16x32_bf16 v[4:7], v[170:173], v[216:219], v[4:7]
	v_mfma_f32_16x16x32_bf16 v[4:7], v[174:177], v[220:223], v[4:7]
	v_mfma_f32_16x16x32_bf16 v[20:23], v[174:177], v[212:215], v[20:23]
	v_mfma_f32_16x16x32_bf16 v[20:23], v[170:173], v[208:211], v[20:23]
	v_mfma_f32_16x16x32_bf16 v[36:39], v[170:173], v[186:189], v[36:39]
	v_mfma_f32_16x16x32_bf16 v[36:39], v[174:177], v[204:207], v[36:39]
	v_mfma_f32_16x16x32_bf16 v[52:55], v[174:177], v[182:185], v[52:55]
	v_mfma_f32_16x16x32_bf16 v[52:55], v[170:173], v[178:181], v[52:55]
	s_setprio 0
	s_add_u32 s44, s44, 0x100
	s_addc_u32 s45, s45, 0
	s_add_u32 s65, s65, 0x100
	s_addc_u32 s67, s67, 0
	s_cmp_ge_i32 s72, s53
	s_mov_b32 s48, s72
	s_barrier
	s_cbranch_scc1 .Lkloop_exit_4
.LBB0_1623:
	s_add_i32 s72, s48, 2
	s_add_u32 s73, s44, 0x80
	s_addc_u32 s49, s45, 0
	s_add_i32 s86, 0, 0x10000
	s_cmp_eq_u32 s57, s48
	s_cselect_b32 s49, s13, s49
	s_cselect_b32 s48, s12, s73
	s_cselect_b32 s77, s41, s67
	s_cselect_b32 s76, s40, s65
	s_add_i32 s73, 0, 0x14000
	v_add_u32_e32 v158, s86, v143
	v_add_u32_e32 v174, s73, v143
	ds_read_b128 v[146:149], v158
	ds_read_b128 v[150:153], v158 offset:1024
	ds_read_b128 v[154:157], v158 offset:2048
	ds_read_b128 v[158:161], v158 offset:3072
	ds_read_b128 v[162:165], v174
	ds_read_b128 v[166:169], v174 offset:1024
	ds_read_b128 v[170:173], v174 offset:2048
	ds_read_b128 v[174:177], v174 offset:3072
	v_lshl_add_u64 v[190:191], s[44:45], 0, v[138:139]
	s_add_i32 m0, s47, 0xc000
	ds_read_b128 v[178:181], v145
	ds_read_b128 v[182:185], v145 offset:1024
	ds_read_b128 v[186:189], v145 offset:2048
	ds_read_b128 v[204:207], v145 offset:3072
	ds_read_b128 v[208:211], v145 offset:4096
	ds_read_b128 v[212:215], v145 offset:5120
	ds_read_b128 v[216:219], v145 offset:6144
	ds_read_b128 v[220:223], v145 offset:7168
	global_load_lds_dwordx4 v[190:191], off
	v_lshl_add_u64 v[190:191], s[44:45], 0, v[140:141]
	s_add_i32 m0, s47, 0xe000
	s_nop 0
	global_load_lds_dwordx4 v[190:191], off
	s_waitcnt vmcnt(8)
	s_waitcnt lgkmcnt(0)
	s_barrier
	s_setprio 1
	s_waitcnt lgkmcnt(0)
	v_mfma_f32_16x16x32_bf16 v[124:127], v[146:149], v[178:181], v[124:127]
	v_mfma_f32_16x16x32_bf16 v[124:127], v[150:153], v[182:185], v[124:127]
	v_mfma_f32_16x16x32_bf16 v[112:115], v[150:153], v[204:207], v[112:115]
	v_mfma_f32_16x16x32_bf16 v[112:115], v[146:149], v[186:189], v[112:115]
	v_mfma_f32_16x16x32_bf16 v[96:99], v[146:149], v[208:211], v[96:99]
	v_mfma_f32_16x16x32_bf16 v[96:99], v[150:153], v[212:215], v[96:99]
	v_mfma_f32_16x16x32_bf16 v[80:83], v[150:153], v[220:223], v[80:83]
	v_mfma_f32_16x16x32_bf16 v[80:83], v[146:149], v[216:219], v[80:83]
	v_mfma_f32_16x16x32_bf16 v[76:79], v[154:157], v[216:219], v[76:79]
	v_mfma_f32_16x16x32_bf16 v[76:79], v[158:161], v[220:223], v[76:79]
	v_mfma_f32_16x16x32_bf16 v[92:95], v[158:161], v[212:215], v[92:95]
	v_mfma_f32_16x16x32_bf16 v[92:95], v[154:157], v[208:211], v[92:95]
	v_mfma_f32_16x16x32_bf16 v[108:111], v[154:157], v[186:189], v[108:111]
	v_mfma_f32_16x16x32_bf16 v[108:111], v[158:161], v[204:207], v[108:111]
	v_mfma_f32_16x16x32_bf16 v[128:131], v[158:161], v[182:185], v[128:131]
	v_mfma_f32_16x16x32_bf16 v[128:131], v[154:157], v[178:181], v[128:131]
	v_mfma_f32_16x16x32_bf16 v[120:123], v[162:165], v[178:181], v[120:123]
	v_mfma_f32_16x16x32_bf16 v[120:123], v[166:169], v[182:185], v[120:123]
	v_mfma_f32_16x16x32_bf16 v[104:107], v[166:169], v[204:207], v[104:107]
	v_mfma_f32_16x16x32_bf16 v[104:107], v[162:165], v[186:189], v[104:107]
	v_mfma_f32_16x16x32_bf16 v[88:91], v[162:165], v[208:211], v[88:91]
	v_mfma_f32_16x16x32_bf16 v[88:91], v[166:169], v[212:215], v[88:91]
	v_mfma_f32_16x16x32_bf16 v[72:75], v[166:169], v[220:223], v[72:75]
	v_mfma_f32_16x16x32_bf16 v[72:75], v[162:165], v[216:219], v[72:75]
	v_mfma_f32_16x16x32_bf16 v[68:71], v[170:173], v[216:219], v[68:71]
	v_mfma_f32_16x16x32_bf16 v[68:71], v[174:177], v[220:223], v[68:71]
	v_mfma_f32_16x16x32_bf16 v[84:87], v[174:177], v[212:215], v[84:87]
	v_mfma_f32_16x16x32_bf16 v[84:87], v[170:173], v[208:211], v[84:87]
	v_mfma_f32_16x16x32_bf16 v[100:103], v[170:173], v[186:189], v[100:103]
	v_mfma_f32_16x16x32_bf16 v[100:103], v[174:177], v[204:207], v[100:103]
	v_mfma_f32_16x16x32_bf16 v[116:119], v[174:177], v[182:185], v[116:119]
	v_mfma_f32_16x16x32_bf16 v[116:119], v[170:173], v[178:181], v[116:119]
	s_setprio 0
	s_barrier
; #define PG8_STAGE(bufoff, gbase, voff) do { _Pragma("unroll") for (int _i = 0; _i < 2; ++_i) \
;         __builtin_amdgcn_global_load_lds((const unsigned*)((const char*)(gbase) + (voff)[_i]), (PG8_LAS unsigned*)(lds + (bufoff) + ldsw + _i * 8192), 16, 0, 0); } while (0)
; #define PG8_LDA(dst, b, h) do { _Pragma("unroll") for (int m = 0; m < 4; ++m) _Pragma("unroll") for (int k = 0; k < 2; ++k) dst[m][k] = *(const PG8_LAS bf16x8*)(lds + PG8_SA(b, h) + aoff + m * 2048 + k * 1024); } while (0)
; #define PG8_LDB(dst, b, h) do { _Pragma("unroll") for (int n = 0; n < 2; ++n) _Pragma("unroll") for (int k = 0; k < 2; ++k) dst[n][k] = *(const PG8_LAS bf16x8*)(lds + PG8_SB(b, h) + boff + n * 2048 + k * 1024); } while (0)
; #define PG8_WAIT_V(n) asm volatile("s_waitcnt vmcnt(" #n ")" ::: "memory")
; #define PG8_WAIT_L(n) asm volatile("s_waitcnt lgkmcnt(" #n ")" ::: "memory")
; #define PG8_BAR __builtin_amdgcn_s_barrier()
; #define PG8_SCHED __builtin_amdgcn_sched_barrier(0)
; template <class Epi, class Sched, bool ALIGN_EPI = false, bool SP2 = false, bool I8 = false>
; __device__ __forceinline__ void gemm_phase(PG8_LAS unsigned char* lds, const Gemm g, const Sched& S, const Epi& E) {
;     ...
;             PG8_WAIT_V(8); PG8_WAIT_L(0); PG8_BAR; PG8_MMA(1, 0, At, B0); PG8_MMA(1, 1, At, B1); PG8_BAR; PG8_SCHED;
;             PG8_LDB(B0, 1, 0); PG8_LDB(B1, 1, 1); PG8_SCHED; PG8_LDA(At, 1, 0); PG8_STAGE(PG8_SA(0, 1), a2 + hstep, voffA);
;             PG8_WAIT_V(8); PG8_WAIT_L(0); PG8_BAR; PG8_MMA(0, 0, At, B0); PG8_MMA(0, 1, At, B1); PG8_BAR; PG8_SCHED;
	s_add_i32 s86, s86, s28
	v_lshl_add_u64 v[190:191], s[76:77], 0, v[2:3]
	s_mov_b32 m0, s86
	ds_read_b128 v[178:181], v145 offset:16384
	ds_read_b128 v[182:185], v145 offset:17408
	ds_read_b128 v[186:189], v145 offset:18432
	ds_read_b128 v[204:207], v145 offset:19456
	ds_read_b128 v[208:211], v145 offset:20480
	ds_read_b128 v[212:215], v145 offset:21504
	ds_read_b128 v[216:219], v145 offset:22528
	ds_read_b128 v[220:223], v145 offset:23552
	global_load_lds_dwordx4 v[190:191], off
	s_add_i32 m0, s86, 0x2000
	v_lshl_add_u64 v[224:225], s[76:77], 0, v[136:137]
	s_add_u32 s76, s76, s18
	s_addc_u32 s77, s77, s19
	s_add_i32 s73, s73, s28
	global_load_lds_dwordx4 v[224:225], off
	v_lshl_add_u64 v[226:227], s[76:77], 0, v[2:3]
	s_mov_b32 m0, s73
	v_lshl_add_u64 v[228:229], s[76:77], 0, v[136:137]
	global_load_lds_dwordx4 v[226:227], off
	s_add_i32 m0, s73, 0x2000
	v_lshl_add_u64 v[240:241], s[48:49], 0, v[132:133]
	global_load_lds_dwordx4 v[228:229], off
	s_mov_b32 m0, s47
	v_lshl_add_u64 v[242:243], s[48:49], 0, v[134:135]
	global_load_lds_dwordx4 v[240:241], off
	s_mov_b32 m0, s50
	s_nop 0
	global_load_lds_dwordx4 v[242:243], off
	s_waitcnt vmcnt(8)
	s_waitcnt lgkmcnt(0)
	s_barrier
	s_setprio 1
	s_waitcnt lgkmcnt(0)
	v_mfma_f32_16x16x32_bf16 v[64:67], v[146:149], v[178:181], v[64:67]
	v_mfma_f32_16x16x32_bf16 v[64:67], v[150:153], v[182:185], v[64:67]
	v_mfma_f32_16x16x32_bf16 v[48:51], v[150:153], v[204:207], v[48:51]
	v_mfma_f32_16x16x32_bf16 v[48:51], v[146:149], v[186:189], v[48:51]
	v_mfma_f32_16x16x32_bf16 v[32:35], v[146:149], v[208:211], v[32:35]
	v_mfma_f32_16x16x32_bf16 v[32:35], v[150:153], v[212:215], v[32:35]
	v_mfma_f32_16x16x32_bf16 v[16:19], v[150:153], v[220:223], v[16:19]
	v_mfma_f32_16x16x32_bf16 v[16:19], v[146:149], v[216:219], v[16:19]
	v_mfma_f32_16x16x32_bf16 v[12:15], v[154:157], v[216:219], v[12:15]
	v_mfma_f32_16x16x32_bf16 v[12:15], v[158:161], v[220:223], v[12:15]
	v_mfma_f32_16x16x32_bf16 v[28:31], v[158:161], v[212:215], v[28:31]
	v_mfma_f32_16x16x32_bf16 v[28:31], v[154:157], v[208:211], v[28:31]
	v_mfma_f32_16x16x32_bf16 v[44:47], v[154:157], v[186:189], v[44:47]
	v_mfma_f32_16x16x32_bf16 v[44:47], v[158:161], v[204:207], v[44:47]
	v_mfma_f32_16x16x32_bf16 v[60:63], v[158:161], v[182:185], v[60:63]
	v_mfma_f32_16x16x32_bf16 v[60:63], v[154:157], v[178:181], v[60:63]
	v_mfma_f32_16x16x32_bf16 v[56:59], v[162:165], v[178:181], v[56:59]
	v_mfma_f32_16x16x32_bf16 v[56:59], v[166:169], v[182:185], v[56:59]
	v_mfma_f32_16x16x32_bf16 v[40:43], v[166:169], v[204:207], v[40:43]
	v_mfma_f32_16x16x32_bf16 v[40:43], v[162:165], v[186:189], v[40:43]
	v_mfma_f32_16x16x32_bf16 v[24:27], v[162:165], v[208:211], v[24:27]
	v_mfma_f32_16x16x32_bf16 v[24:27], v[166:169], v[212:215], v[24:27]
	v_mfma_f32_16x16x32_bf16 v[8:11], v[166:169], v[220:223], v[8:11]
	v_mfma_f32_16x16x32_bf16 v[8:11], v[162:165], v[216:219], v[8:11]
	v_mfma_f32_16x16x32_bf16 v[4:7], v[170:173], v[216:219], v[4:7]
	v_mfma_f32_16x16x32_bf16 v[4:7], v[174:177], v[220:223], v[4:7]
	v_mfma_f32_16x16x32_bf16 v[20:23], v[174:177], v[212:215], v[20:23]
	v_mfma_f32_16x16x32_bf16 v[20:23], v[170:173], v[208:211], v[20:23]
	v_mfma_f32_16x16x32_bf16 v[36:39], v[170:173], v[186:189], v[36:39]
	v_mfma_f32_16x16x32_bf16 v[36:39], v[174:177], v[204:207], v[36:39]
	v_mfma_f32_16x16x32_bf16 v[52:55], v[174:177], v[182:185], v[52:55]
	v_mfma_f32_16x16x32_bf16 v[52:55], v[170:173], v[178:181], v[52:55]
	s_setprio 0
	s_barrier
	s_add_i32 s73, 0, 0x18000
	s_add_i32 s76, 0, 0x1c000
	v_add_u32_e32 v158, s73, v143
	v_add_u32_e32 v174, s76, v143
	ds_read_b128 v[146:149], v158
	ds_read_b128 v[150:153], v158 offset:1024
	ds_read_b128 v[154:157], v158 offset:2048
	ds_read_b128 v[158:161], v158 offset:3072
	ds_read_b128 v[162:165], v174
	ds_read_b128 v[166:169], v174 offset:1024
	ds_read_b128 v[170:173], v174 offset:2048
	ds_read_b128 v[174:177], v174 offset:3072
	s_add_u32 s48, s48, s18
	s_addc_u32 s49, s49, s19
	s_mov_b32 m0, s51
	v_lshl_add_u64 v[244:245], s[48:49], 0, v[132:133]
	ds_read_b128 v[178:181], v145 offset:32768
	ds_read_b128 v[182:185], v145 offset:33792
	ds_read_b128 v[186:189], v145 offset:34816
	ds_read_b128 v[204:207], v145 offset:35840
	ds_read_b128 v[208:211], v145 offset:36864
	ds_read_b128 v[212:215], v145 offset:37888
	ds_read_b128 v[216:219], v145 offset:38912
	ds_read_b128 v[220:223], v145 offset:39936
	global_load_lds_dwordx4 v[244:245], off
	v_lshl_add_u64 v[244:245], s[48:49], 0, v[134:135]
	s_mov_b32 m0, s52
	s_nop 0
	global_load_lds_dwordx4 v[244:245], off
	s_waitcnt vmcnt(8)
	s_waitcnt lgkmcnt(0)
	s_barrier
; #define PG8_STAGE(bufoff, gbase, voff) do { _Pragma("unroll") for (int _i = 0; _i < 2; ++_i) \
;         __builtin_amdgcn_global_load_lds((const unsigned*)((const char*)(gbase) + (voff)[_i]), (PG8_LAS unsigned*)(lds + (bufoff) + ldsw + _i * 8192), 16, 0, 0); } while (0)
; #define PG8_LDA(dst, b, h) do { _Pragma("unroll") for (int m = 0; m < 4; ++m) _Pragma("unroll") for (int k = 0; k < 2; ++k) dst[m][k] = *(const PG8_LAS bf16x8*)(lds + PG8_SA(b, h) + aoff + m * 2048 + k * 1024); } while (0)
; #define PG8_WAIT_V(n) asm volatile("s_waitcnt vmcnt(" #n ")" ::: "memory")
; #define PG8_WAIT_L(n) asm volatile("s_waitcnt lgkmcnt(" #n ")" ::: "memory")
; #define PG8_BAR __builtin_amdgcn_s_barrier()
; #define PG8_SCHED __builtin_amdgcn_sched_barrier(0)
; template <class Epi, class Sched, bool ALIGN_EPI = false, bool SP2 = false, bool I8 = false>
; __device__ __forceinline__ void gemm_phase(PG8_LAS unsigned char* lds, const Gemm g, const Sched& S, const Epi& E) {
;     ...
;             PG8_WAIT_V(8); PG8_WAIT_L(0); PG8_BAR; PG8_MMA(0, 0, At, B0); PG8_MMA(0, 1, At, B1); PG8_BAR; PG8_SCHED;
;             PG8_LDA(At, 1, 1); PG8_STAGE(PG8_SB(1, 0), b3, voffB); PG8_STAGE(PG8_SB(1, 1), b3 + hstep, voffB); PG8_STAGE(PG8_SA(1, 0), a3, voffA);
;             PG8_WAIT_V(8); PG8_WAIT_L(0); PG8_BAR; PG8_MMA(1, 0, At, B0); PG8_MMA(1, 1, At, B1); PG8_BAR; PG8_SCHED;
	s_setprio 1
	s_waitcnt lgkmcnt(0)
	v_mfma_f32_16x16x32_bf16 v[124:127], v[146:149], v[178:181], v[124:127]
	v_mfma_f32_16x16x32_bf16 v[124:127], v[150:153], v[182:185], v[124:127]
	v_mfma_f32_16x16x32_bf16 v[112:115], v[150:153], v[204:207], v[112:115]
	v_mfma_f32_16x16x32_bf16 v[112:115], v[146:149], v[186:189], v[112:115]
	v_mfma_f32_16x16x32_bf16 v[96:99], v[146:149], v[208:211], v[96:99]
	v_mfma_f32_16x16x32_bf16 v[96:99], v[150:153], v[212:215], v[96:99]
	v_mfma_f32_16x16x32_bf16 v[80:83], v[150:153], v[220:223], v[80:83]
	v_mfma_f32_16x16x32_bf16 v[80:83], v[146:149], v[216:219], v[80:83]
	v_mfma_f32_16x16x32_bf16 v[76:79], v[154:157], v[216:219], v[76:79]
	v_mfma_f32_16x16x32_bf16 v[76:79], v[158:161], v[220:223], v[76:79]
	v_mfma_f32_16x16x32_bf16 v[92:95], v[158:161], v[212:215], v[92:95]
	v_mfma_f32_16x16x32_bf16 v[92:95], v[154:157], v[208:211], v[92:95]
	v_mfma_f32_16x16x32_bf16 v[108:111], v[154:157], v[186:189], v[108:111]
	v_mfma_f32_16x16x32_bf16 v[108:111], v[158:161], v[204:207], v[108:111]
	v_mfma_f32_16x16x32_bf16 v[128:131], v[158:161], v[182:185], v[128:131]
	v_mfma_f32_16x16x32_bf16 v[128:131], v[154:157], v[178:181], v[128:131]
	v_mfma_f32_16x16x32_bf16 v[120:123], v[162:165], v[178:181], v[120:123]
	v_mfma_f32_16x16x32_bf16 v[120:123], v[166:169], v[182:185], v[120:123]
	v_mfma_f32_16x16x32_bf16 v[104:107], v[166:169], v[204:207], v[104:107]
	v_mfma_f32_16x16x32_bf16 v[104:107], v[162:165], v[186:189], v[104:107]
	v_mfma_f32_16x16x32_bf16 v[88:91], v[162:165], v[208:211], v[88:91]
	v_mfma_f32_16x16x32_bf16 v[88:91], v[166:169], v[212:215], v[88:91]
	v_mfma_f32_16x16x32_bf16 v[72:75], v[166:169], v[220:223], v[72:75]
	v_mfma_f32_16x16x32_bf16 v[72:75], v[162:165], v[216:219], v[72:75]
	v_mfma_f32_16x16x32_bf16 v[68:71], v[170:173], v[216:219], v[68:71]
	v_mfma_f32_16x16x32_bf16 v[68:71], v[174:177], v[220:223], v[68:71]
	v_mfma_f32_16x16x32_bf16 v[84:87], v[174:177], v[212:215], v[84:87]
	v_mfma_f32_16x16x32_bf16 v[84:87], v[170:173], v[208:211], v[84:87]
	v_mfma_f32_16x16x32_bf16 v[100:103], v[170:173], v[186:189], v[100:103]
	v_mfma_f32_16x16x32_bf16 v[100:103], v[174:177], v[204:207], v[100:103]
	v_mfma_f32_16x16x32_bf16 v[116:119], v[174:177], v[182:185], v[116:119]
	v_mfma_f32_16x16x32_bf16 v[116:119], v[170:173], v[178:181], v[116:119]
	s_setprio 0
	s_barrier
	s_add_i32 s48, s73, s28
	v_lshl_add_u64 v[190:191], v[190:191], 0, s[84:85]
	s_mov_b32 m0, s48
	ds_read_b128 v[178:181], v145 offset:49152
	ds_read_b128 v[182:185], v145 offset:50176
	ds_read_b128 v[186:189], v145 offset:51200
	ds_read_b128 v[204:207], v145 offset:52224
	ds_read_b128 v[208:211], v145 offset:53248
	ds_read_b128 v[212:215], v145 offset:54272
	ds_read_b128 v[216:219], v145 offset:55296
	ds_read_b128 v[220:223], v145 offset:56320
	global_load_lds_dwordx4 v[190:191], off
	v_lshl_add_u64 v[190:191], v[224:225], 0, s[84:85]
	s_add_i32 m0, s48, 0x2000
	s_add_i32 s48, s76, s28
	global_load_lds_dwordx4 v[190:191], off
	v_lshl_add_u64 v[190:191], v[226:227], 0, s[84:85]
	s_mov_b32 m0, s48
	s_nop 0
	global_load_lds_dwordx4 v[190:191], off
	v_lshl_add_u64 v[190:191], v[228:229], 0, s[84:85]
	s_add_i32 m0, s48, 0x2000
	s_nop 0
	global_load_lds_dwordx4 v[190:191], off
	v_lshl_add_u64 v[190:191], v[240:241], 0, s[84:85]
	s_mov_b32 m0, s55
	s_nop 0
	global_load_lds_dwordx4 v[190:191], off
	v_lshl_add_u64 v[190:191], v[242:243], 0, s[84:85]
	s_mov_b32 m0, s56
	s_nop 0
	global_load_lds_dwordx4 v[190:191], off
	s_waitcnt vmcnt(8)
	s_waitcnt lgkmcnt(0)
	s_barrier
	s_setprio 1
	s_waitcnt lgkmcnt(0)
	v_mfma_f32_16x16x32_bf16 v[64:67], v[146:149], v[178:181], v[64:67]
	v_mfma_f32_16x16x32_bf16 v[64:67], v[150:153], v[182:185], v[64:67]
	v_mfma_f32_16x16x32_bf16 v[48:51], v[150:153], v[204:207], v[48:51]
	v_mfma_f32_16x16x32_bf16 v[48:51], v[146:149], v[186:189], v[48:51]
	v_mfma_f32_16x16x32_bf16 v[32:35], v[146:149], v[208:211], v[32:35]
	v_mfma_f32_16x16x32_bf16 v[32:35], v[150:153], v[212:215], v[32:35]
	v_mfma_f32_16x16x32_bf16 v[16:19], v[150:153], v[220:223], v[16:19]
	v_mfma_f32_16x16x32_bf16 v[16:19], v[146:149], v[216:219], v[16:19]
	v_mfma_f32_16x16x32_bf16 v[12:15], v[154:157], v[216:219], v[12:15]
	v_mfma_f32_16x16x32_bf16 v[12:15], v[158:161], v[220:223], v[12:15]
	v_mfma_f32_16x16x32_bf16 v[28:31], v[158:161], v[212:215], v[28:31]
	v_mfma_f32_16x16x32_bf16 v[28:31], v[154:157], v[208:211], v[28:31]
	v_mfma_f32_16x16x32_bf16 v[44:47], v[154:157], v[186:189], v[44:47]
	v_mfma_f32_16x16x32_bf16 v[44:47], v[158:161], v[204:207], v[44:47]
	v_mfma_f32_16x16x32_bf16 v[60:63], v[158:161], v[182:185], v[60:63]
	v_mfma_f32_16x16x32_bf16 v[60:63], v[154:157], v[178:181], v[60:63]
	v_mfma_f32_16x16x32_bf16 v[56:59], v[162:165], v[178:181], v[56:59]
	v_mfma_f32_16x16x32_bf16 v[56:59], v[166:169], v[182:185], v[56:59]
	v_mfma_f32_16x16x32_bf16 v[40:43], v[166:169], v[204:207], v[40:43]
	v_mfma_f32_16x16x32_bf16 v[40:43], v[162:165], v[186:189], v[40:43]
	v_mfma_f32_16x16x32_bf16 v[24:27], v[162:165], v[208:211], v[24:27]
	v_mfma_f32_16x16x32_bf16 v[24:27], v[166:169], v[212:215], v[24:27]
	v_mfma_f32_16x16x32_bf16 v[8:11], v[166:169], v[220:223], v[8:11]
	v_mfma_f32_16x16x32_bf16 v[8:11], v[162:165], v[216:219], v[8:11]
	v_mfma_f32_16x16x32_bf16 v[4:7], v[170:173], v[216:219], v[4:7]
	v_mfma_f32_16x16x32_bf16 v[4:7], v[174:177], v[220:223], v[4:7]
	v_mfma_f32_16x16x32_bf16 v[20:23], v[174:177], v[212:215], v[20:23]
	v_mfma_f32_16x16x32_bf16 v[20:23], v[170:173], v[208:211], v[20:23]
	v_mfma_f32_16x16x32_bf16 v[36:39], v[170:173], v[186:189], v[36:39]
	v_mfma_f32_16x16x32_bf16 v[36:39], v[174:177], v[204:207], v[36:39]
	v_mfma_f32_16x16x32_bf16 v[52:55], v[174:177], v[182:185], v[52:55]
	v_mfma_f32_16x16x32_bf16 v[52:55], v[170:173], v[178:181], v[52:55]
	s_setprio 0
	s_add_u32 s44, s44, 0x100
	s_addc_u32 s45, s45, 0
	s_add_u32 s65, s65, 0x100
	s_addc_u32 s67, s67, 0
	s_cmp_ge_i32 s72, s53
	s_mov_b32 s48, s72
	s_barrier
	s_cbranch_scc0 .LBB0_1623

; #define PG8_STAGE(bufoff, gbase, voff) do { _Pragma("unroll") for (int _i = 0; _i < 2; ++_i) \
;         __builtin_amdgcn_global_load_lds((const unsigned*)((const char*)(gbase) + (voff)[_i]), (PG8_LAS unsigned*)(lds + (bufoff) + ldsw + _i * 8192), 16, 0, 0); } while (0)
; #define PG8_LDA(dst, b, h) do { _Pragma("unroll") for (int m = 0; m < 4; ++m) _Pragma("unroll") for (int k = 0; k < 2; ++k) dst[m][k] = *(const PG8_LAS bf16x8*)(lds + PG8_SA(b, h) + aoff + m * 2048 + k * 1024); } while (0)
; #define PG8_LDB(dst, b, h) do { _Pragma("unroll") for (int n = 0; n < 2; ++n) _Pragma("unroll") for (int k = 0; k < 2; ++k) dst[n][k] = *(const PG8_LAS bf16x8*)(lds + PG8_SB(b, h) + boff + n * 2048 + k * 1024); } while (0)
; #define PG8_WAIT_V(n) asm volatile("s_waitcnt vmcnt(" #n ")" ::: "memory")
; #define PG8_WAIT_L(n) asm volatile("s_waitcnt lgkmcnt(" #n ")" ::: "memory")
; #define PG8_BAR __builtin_amdgcn_s_barrier()
; #define PG8_SCHED __builtin_amdgcn_sched_barrier(0)
; template <class Epi, class Sched, bool ALIGN_EPI = false, bool SP2 = false, bool I8 = false>
; __device__ __forceinline__ void gemm_phase(PG8_LAS unsigned char* lds, const Gemm g, const Sched& S, const Epi& E) {
;     ...
;         const char* nA = has_next ? (const char*)g.A + (size_t)nxt.pm * tstep : cA; const char* nB = has_next ? (const char*)g.Bt + (size_t)nxt.pn * tstep : cB;
;         for (int t = 0; t < nt; t += 2) {
;             const bool last = (t == nt - 2);
;             const char* a1 = cA + (size_t)(t + 1) * kstep;
;             const char* a2 = last ? nA : cA + (size_t)(t + 2) * kstep; const char* b2 = last ? nB : cB + (size_t)(t + 2) * kstep;
;             const char* a3 = a2 + kstep; const char* b3 = b2 + kstep;
;             if (last && has_next) S.a_ready(nxt);
;             if constexpr (SP2) {
;             PG8_LDB(B0, 0, 0); PG8_LDB(B1, 0, 1); PG8_SCHED; PG8_LDA(At, 0, 0); PG8_STAGE(PG8_SA(1, 1), a1 + hstep, voffA);
;             PG8_WAIT_V(8); PG8_WAIT_L(0); PG8_BAR; PG8_MMA(0, 0, At, B0); PG8_MMA(0, 1, At, B1); PG8_BAR; PG8_SCHED;
;             PG8_LDA(At, 0, 1); PG8_STAGE(PG8_SB(0, 0), b2, voffB); PG8_STAGE(PG8_SB(0, 1), b2 + hstep, voffB); PG8_STAGE(PG8_SA(0, 0), a2, voffA);
;             PG8_WAIT_V(8); PG8_WAIT_L(0); PG8_BAR; PG8_MMA(1, 0, At, B0); PG8_MMA(1, 1, At, B1); PG8_BAR; PG8_SCHED;
.LBB0_1699:
	s_add_u32 s53, s24, 0x100
	s_addc_u32 s54, s25, 0
	s_mov_b32 s55, -2
	s_add_u32 s24, s22, 0x100
	s_addc_u32 s25, s23, 0
	s_add_i32 s56, 0, 0x10000
	s_cmpk_eq_i32 s55, 0xa8
	s_cselect_b32 s37, s13, s25
	s_cselect_b32 s36, s12, s24
	s_cselect_b32 s27, s21, s54
	s_cselect_b32 s26, s20, s53
	s_add_i32 s57, 0, 0x14000
	v_add_u32_e32 v144, s56, v240
	v_add_u32_e32 v160, s57, v240
	ds_read_b128 v[124:127], v144
	ds_read_b128 v[128:131], v144 offset:1024
	ds_read_b128 v[132:135], v144 offset:2048
	ds_read_b128 v[144:147], v144 offset:3072
	ds_read_b128 v[148:151], v160
	ds_read_b128 v[152:155], v160 offset:1024
	ds_read_b128 v[156:159], v160 offset:2048
	ds_read_b128 v[160:163], v160 offset:3072
	v_lshl_add_u64 v[218:219], s[22:23], 0, v[210:211]
	s_add_i32 m0, s42, 0xc000
	ds_read_b128 v[164:167], v242
	ds_read_b128 v[168:171], v242 offset:1024
	ds_read_b128 v[172:175], v242 offset:2048
	ds_read_b128 v[176:179], v242 offset:3072
	ds_read_b128 v[180:183], v242 offset:4096
	ds_read_b128 v[184:187], v242 offset:5120
	ds_read_b128 v[188:191], v242 offset:6144
	ds_read_b128 v[214:217], v242 offset:7168
	global_load_lds_dwordx4 v[218:219], off
	v_lshl_add_u64 v[218:219], s[22:23], 0, v[212:213]
	s_add_i32 m0, s42, 0xe000
	s_nop 0
	global_load_lds_dwordx4 v[218:219], off
	s_waitcnt vmcnt(8)
	s_waitcnt lgkmcnt(0)
	s_barrier
	s_setprio 1
	s_waitcnt lgkmcnt(0)
	v_mfma_f32_16x16x32_bf16 v[140:143], v[124:127], v[164:167], 0
	v_mfma_f32_16x16x32_bf16 v[140:143], v[128:131], v[168:171], v[140:143]
	v_mfma_f32_16x16x32_bf16 v[112:115], v[128:131], v[176:179], 0
	v_mfma_f32_16x16x32_bf16 v[112:115], v[124:127], v[172:175], v[112:115]
	v_mfma_f32_16x16x32_bf16 v[96:99], v[124:127], v[180:183], 0
	v_mfma_f32_16x16x32_bf16 v[96:99], v[128:131], v[184:187], v[96:99]
	v_mfma_f32_16x16x32_bf16 v[80:83], v[128:131], v[214:217], 0
	v_mfma_f32_16x16x32_bf16 v[80:83], v[124:127], v[188:191], v[80:83]
	v_mfma_f32_16x16x32_bf16 v[76:79], v[132:135], v[188:191], 0
	v_mfma_f32_16x16x32_bf16 v[76:79], v[144:147], v[214:217], v[76:79]
	v_mfma_f32_16x16x32_bf16 v[92:95], v[144:147], v[184:187], 0
	v_mfma_f32_16x16x32_bf16 v[92:95], v[132:135], v[180:183], v[92:95]
	v_mfma_f32_16x16x32_bf16 v[108:111], v[132:135], v[172:175], 0
	v_mfma_f32_16x16x32_bf16 v[108:111], v[144:147], v[176:179], v[108:111]
	v_mfma_f32_16x16x32_bf16 v[136:139], v[144:147], v[168:171], 0
	v_mfma_f32_16x16x32_bf16 v[136:139], v[132:135], v[164:167], v[136:139]
	v_mfma_f32_16x16x32_bf16 v[120:123], v[148:151], v[164:167], 0
	v_mfma_f32_16x16x32_bf16 v[120:123], v[152:155], v[168:171], v[120:123]
	v_mfma_f32_16x16x32_bf16 v[104:107], v[152:155], v[176:179], 0
	v_mfma_f32_16x16x32_bf16 v[104:107], v[148:151], v[172:175], v[104:107]
	v_mfma_f32_16x16x32_bf16 v[88:91], v[148:151], v[180:183], 0
	v_mfma_f32_16x16x32_bf16 v[88:91], v[152:155], v[184:187], v[88:91]
	v_mfma_f32_16x16x32_bf16 v[72:75], v[152:155], v[214:217], 0
	v_mfma_f32_16x16x32_bf16 v[72:75], v[148:151], v[188:191], v[72:75]
	v_mfma_f32_16x16x32_bf16 v[68:71], v[156:159], v[188:191], 0
	v_mfma_f32_16x16x32_bf16 v[68:71], v[160:163], v[214:217], v[68:71]
	v_mfma_f32_16x16x32_bf16 v[84:87], v[160:163], v[184:187], 0
	v_mfma_f32_16x16x32_bf16 v[84:87], v[156:159], v[180:183], v[84:87]
	v_mfma_f32_16x16x32_bf16 v[100:103], v[156:159], v[172:175], 0
	v_mfma_f32_16x16x32_bf16 v[100:103], v[160:163], v[176:179], v[100:103]
	v_mfma_f32_16x16x32_bf16 v[116:119], v[160:163], v[168:171], 0
	v_mfma_f32_16x16x32_bf16 v[116:119], v[156:159], v[164:167], v[116:119]
	s_setprio 0
	s_barrier
	s_add_i32 s22, s56, s41
	v_lshl_add_u64 v[218:219], s[26:27], 0, v[2:3]
	s_mov_b32 m0, s22
	ds_read_b128 v[164:167], v242 offset:16384
	ds_read_b128 v[168:171], v242 offset:17408
	ds_read_b128 v[172:175], v242 offset:18432
	ds_read_b128 v[176:179], v242 offset:19456
	ds_read_b128 v[180:183], v242 offset:20480
	ds_read_b128 v[184:187], v242 offset:21504
	ds_read_b128 v[188:191], v242 offset:22528
	ds_read_b128 v[214:217], v242 offset:23552
	global_load_lds_dwordx4 v[218:219], off
	s_add_i32 m0, s22, 0x2000
	s_add_u32 s22, s26, 0x2b0000
	v_lshl_add_u64 v[220:221], s[26:27], 0, v[204:205]
	s_addc_u32 s23, s27, 0
	s_add_i32 s56, s57, s41
	global_load_lds_dwordx4 v[220:221], off
	v_lshl_add_u64 v[222:223], s[22:23], 0, v[2:3]
	s_mov_b32 m0, s56
	v_lshl_add_u64 v[224:225], s[36:37], 0, v[206:207]
	global_load_lds_dwordx4 v[222:223], off
	v_lshl_add_u64 v[222:223], s[22:23], 0, v[204:205]
	s_add_i32 m0, s56, 0x2000
	s_nop 0
	global_load_lds_dwordx4 v[222:223], off
	v_lshl_add_u64 v[222:223], s[36:37], 0, v[208:209]
	s_mov_b32 m0, s42
	s_nop 0
	global_load_lds_dwordx4 v[222:223], off
	s_mov_b32 m0, s43
	s_nop 0
	global_load_lds_dwordx4 v[224:225], off
	s_waitcnt vmcnt(8)
	s_waitcnt lgkmcnt(0)
	s_barrier
; #define PG8_STAGE(bufoff, gbase, voff) do { _Pragma("unroll") for (int _i = 0; _i < 2; ++_i) \
;         __builtin_amdgcn_global_load_lds((const unsigned*)((const char*)(gbase) + (voff)[_i]), (PG8_LAS unsigned*)(lds + (bufoff) + ldsw + _i * 8192), 16, 0, 0); } while (0)
; #define PG8_LDA(dst, b, h) do { _Pragma("unroll") for (int m = 0; m < 4; ++m) _Pragma("unroll") for (int k = 0; k < 2; ++k) dst[m][k] = *(const PG8_LAS bf16x8*)(lds + PG8_SA(b, h) + aoff + m * 2048 + k * 1024); } while (0)
; #define PG8_LDB(dst, b, h) do { _Pragma("unroll") for (int n = 0; n < 2; ++n) _Pragma("unroll") for (int k = 0; k < 2; ++k) dst[n][k] = *(const PG8_LAS bf16x8*)(lds + PG8_SB(b, h) + boff + n * 2048 + k * 1024); } while (0)
; #define PG8_WAIT_V(n) asm volatile("s_waitcnt vmcnt(" #n ")" ::: "memory")
; #define PG8_WAIT_L(n) asm volatile("s_waitcnt lgkmcnt(" #n ")" ::: "memory")
; #define PG8_BAR __builtin_amdgcn_s_barrier()
; #define PG8_SCHED __builtin_amdgcn_sched_barrier(0)
; template <class Epi, class Sched, bool ALIGN_EPI = false, bool SP2 = false, bool I8 = false>
; __device__ __forceinline__ void gemm_phase(PG8_LAS unsigned char* lds, const Gemm g, const Sched& S, const Epi& E) {
;     ...
;             PG8_WAIT_V(8); PG8_WAIT_L(0); PG8_BAR; PG8_MMA(1, 0, At, B0); PG8_MMA(1, 1, At, B1); PG8_BAR; PG8_SCHED;
;             PG8_LDB(B0, 1, 0); PG8_LDB(B1, 1, 1); PG8_SCHED; PG8_LDA(At, 1, 0); PG8_STAGE(PG8_SA(0, 1), a2 + hstep, voffA);
;             PG8_WAIT_V(8); PG8_WAIT_L(0); PG8_BAR; PG8_MMA(0, 0, At, B0); PG8_MMA(0, 1, At, B1); PG8_BAR; PG8_SCHED;
	s_setprio 1
	s_waitcnt lgkmcnt(0)
	v_mfma_f32_16x16x32_bf16 v[64:67], v[124:127], v[164:167], 0
	v_mfma_f32_16x16x32_bf16 v[64:67], v[128:131], v[168:171], v[64:67]
	v_mfma_f32_16x16x32_bf16 v[48:51], v[128:131], v[176:179], 0
	v_mfma_f32_16x16x32_bf16 v[48:51], v[124:127], v[172:175], v[48:51]
	v_mfma_f32_16x16x32_bf16 v[32:35], v[124:127], v[180:183], 0
	v_mfma_f32_16x16x32_bf16 v[32:35], v[128:131], v[184:187], v[32:35]
	v_mfma_f32_16x16x32_bf16 v[16:19], v[128:131], v[214:217], 0
	v_mfma_f32_16x16x32_bf16 v[16:19], v[124:127], v[188:191], v[16:19]
	v_mfma_f32_16x16x32_bf16 v[12:15], v[132:135], v[188:191], 0
	v_mfma_f32_16x16x32_bf16 v[12:15], v[144:147], v[214:217], v[12:15]
	v_mfma_f32_16x16x32_bf16 v[28:31], v[144:147], v[184:187], 0
	v_mfma_f32_16x16x32_bf16 v[28:31], v[132:135], v[180:183], v[28:31]
	v_mfma_f32_16x16x32_bf16 v[44:47], v[132:135], v[172:175], 0
	v_mfma_f32_16x16x32_bf16 v[44:47], v[144:147], v[176:179], v[44:47]
	v_mfma_f32_16x16x32_bf16 v[60:63], v[144:147], v[168:171], 0
	v_mfma_f32_16x16x32_bf16 v[60:63], v[132:135], v[164:167], v[60:63]
	v_mfma_f32_16x16x32_bf16 v[56:59], v[148:151], v[164:167], 0
	v_mfma_f32_16x16x32_bf16 v[56:59], v[152:155], v[168:171], v[56:59]
	v_mfma_f32_16x16x32_bf16 v[40:43], v[152:155], v[176:179], 0
	v_mfma_f32_16x16x32_bf16 v[40:43], v[148:151], v[172:175], v[40:43]
	v_mfma_f32_16x16x32_bf16 v[24:27], v[148:151], v[180:183], 0
	v_mfma_f32_16x16x32_bf16 v[24:27], v[152:155], v[184:187], v[24:27]
	v_mfma_f32_16x16x32_bf16 v[8:11], v[152:155], v[214:217], 0
	v_mfma_f32_16x16x32_bf16 v[8:11], v[148:151], v[188:191], v[8:11]
	v_mfma_f32_16x16x32_bf16 v[4:7], v[156:159], v[188:191], 0
	v_mfma_f32_16x16x32_bf16 v[4:7], v[160:163], v[214:217], v[4:7]
	v_mfma_f32_16x16x32_bf16 v[20:23], v[160:163], v[184:187], 0
	v_mfma_f32_16x16x32_bf16 v[20:23], v[156:159], v[180:183], v[20:23]
	v_mfma_f32_16x16x32_bf16 v[36:39], v[156:159], v[172:175], 0
	v_mfma_f32_16x16x32_bf16 v[36:39], v[160:163], v[176:179], v[36:39]
	v_mfma_f32_16x16x32_bf16 v[52:55], v[160:163], v[168:171], 0
	v_mfma_f32_16x16x32_bf16 v[52:55], v[156:159], v[164:167], v[52:55]
	s_setprio 0
	s_barrier
	s_add_i32 s56, 0, 0x18000
	s_add_i32 s57, 0, 0x1c000
	v_add_u32_e32 v144, s56, v240
	v_add_u32_e32 v160, s57, v240
	ds_read_b128 v[124:127], v144
	ds_read_b128 v[128:131], v144 offset:1024
	ds_read_b128 v[132:135], v144 offset:2048
	ds_read_b128 v[144:147], v144 offset:3072
	ds_read_b128 v[148:151], v160
	ds_read_b128 v[152:155], v160 offset:1024
	ds_read_b128 v[156:159], v160 offset:2048
	ds_read_b128 v[160:163], v160 offset:3072
	s_add_u32 s22, s36, 0x2b0000
	s_addc_u32 s23, s37, 0
	s_mov_b32 m0, s44
	v_lshl_add_u64 v[226:227], s[22:23], 0, v[208:209]
	ds_read_b128 v[164:167], v242 offset:32768
	ds_read_b128 v[168:171], v242 offset:33792
	ds_read_b128 v[172:175], v242 offset:34816
	ds_read_b128 v[176:179], v242 offset:35840
	ds_read_b128 v[180:183], v242 offset:36864
	ds_read_b128 v[184:187], v242 offset:37888
	ds_read_b128 v[188:191], v242 offset:38912
	ds_read_b128 v[214:217], v242 offset:39936
	global_load_lds_dwordx4 v[226:227], off
	v_lshl_add_u64 v[226:227], s[22:23], 0, v[206:207]
	s_mov_b32 m0, s45
	s_nop 0
	global_load_lds_dwordx4 v[226:227], off
	s_waitcnt vmcnt(8)
	s_waitcnt lgkmcnt(0)
	s_barrier
	s_setprio 1
	s_waitcnt lgkmcnt(0)
	v_mfma_f32_16x16x32_bf16 v[140:143], v[124:127], v[164:167], v[140:143]
	v_mfma_f32_16x16x32_bf16 v[140:143], v[128:131], v[168:171], v[140:143]
	v_mfma_f32_16x16x32_bf16 v[112:115], v[128:131], v[176:179], v[112:115]
	v_mfma_f32_16x16x32_bf16 v[112:115], v[124:127], v[172:175], v[112:115]
	v_mfma_f32_16x16x32_bf16 v[96:99], v[124:127], v[180:183], v[96:99]
	v_mfma_f32_16x16x32_bf16 v[96:99], v[128:131], v[184:187], v[96:99]
	v_mfma_f32_16x16x32_bf16 v[80:83], v[128:131], v[214:217], v[80:83]
	v_mfma_f32_16x16x32_bf16 v[80:83], v[124:127], v[188:191], v[80:83]
	v_mfma_f32_16x16x32_bf16 v[76:79], v[132:135], v[188:191], v[76:79]
	v_mfma_f32_16x16x32_bf16 v[76:79], v[144:147], v[214:217], v[76:79]
	v_mfma_f32_16x16x32_bf16 v[92:95], v[144:147], v[184:187], v[92:95]
	v_mfma_f32_16x16x32_bf16 v[92:95], v[132:135], v[180:183], v[92:95]
	v_mfma_f32_16x16x32_bf16 v[108:111], v[132:135], v[172:175], v[108:111]
	v_mfma_f32_16x16x32_bf16 v[108:111], v[144:147], v[176:179], v[108:111]
	v_mfma_f32_16x16x32_bf16 v[136:139], v[144:147], v[168:171], v[136:139]
	v_mfma_f32_16x16x32_bf16 v[136:139], v[132:135], v[164:167], v[136:139]
	v_mfma_f32_16x16x32_bf16 v[120:123], v[148:151], v[164:167], v[120:123]
	v_mfma_f32_16x16x32_bf16 v[120:123], v[152:155], v[168:171], v[120:123]
	v_mfma_f32_16x16x32_bf16 v[104:107], v[152:155], v[176:179], v[104:107]
	v_mfma_f32_16x16x32_bf16 v[104:107], v[148:151], v[172:175], v[104:107]
	v_mfma_f32_16x16x32_bf16 v[88:91], v[148:151], v[180:183], v[88:91]
	v_mfma_f32_16x16x32_bf16 v[88:91], v[152:155], v[184:187], v[88:91]
	v_mfma_f32_16x16x32_bf16 v[72:75], v[152:155], v[214:217], v[72:75]
	v_mfma_f32_16x16x32_bf16 v[72:75], v[148:151], v[188:191], v[72:75]
	v_mfma_f32_16x16x32_bf16 v[68:71], v[156:159], v[188:191], v[68:71]
	v_mfma_f32_16x16x32_bf16 v[68:71], v[160:163], v[214:217], v[68:71]
	v_mfma_f32_16x16x32_bf16 v[84:87], v[160:163], v[184:187], v[84:87]
	v_mfma_f32_16x16x32_bf16 v[84:87], v[156:159], v[180:183], v[84:87]
	v_mfma_f32_16x16x32_bf16 v[100:103], v[156:159], v[172:175], v[100:103]
	v_mfma_f32_16x16x32_bf16 v[100:103], v[160:163], v[176:179], v[100:103]
	v_mfma_f32_16x16x32_bf16 v[116:119], v[160:163], v[168:171], v[116:119]
	v_mfma_f32_16x16x32_bf16 v[116:119], v[156:159], v[164:167], v[116:119]
	s_setprio 0
	s_barrier
; #define PG8_STAGE(bufoff, gbase, voff) do { _Pragma("unroll") for (int _i = 0; _i < 2; ++_i) \
;         __builtin_amdgcn_global_load_lds((const unsigned*)((const char*)(gbase) + (voff)[_i]), (PG8_LAS unsigned*)(lds + (bufoff) + ldsw + _i * 8192), 16, 0, 0); } while (0)
; #define PG8_LDA(dst, b, h) do { _Pragma("unroll") for (int m = 0; m < 4; ++m) _Pragma("unroll") for (int k = 0; k < 2; ++k) dst[m][k] = *(const PG8_LAS bf16x8*)(lds + PG8_SA(b, h) + aoff + m * 2048 + k * 1024); } while (0)
; #define PG8_LDB(dst, b, h) do { _Pragma("unroll") for (int n = 0; n < 2; ++n) _Pragma("unroll") for (int k = 0; k < 2; ++k) dst[n][k] = *(const PG8_LAS bf16x8*)(lds + PG8_SB(b, h) + boff + n * 2048 + k * 1024); } while (0)
; #define PG8_WAIT_V(n) asm volatile("s_waitcnt vmcnt(" #n ")" ::: "memory")
; #define PG8_WAIT_L(n) asm volatile("s_waitcnt lgkmcnt(" #n ")" ::: "memory")
; #define PG8_BAR __builtin_amdgcn_s_barrier()
; #define PG8_SCHED __builtin_amdgcn_sched_barrier(0)
; template <class Epi, class Sched, bool ALIGN_EPI = false, bool SP2 = false, bool I8 = false>
; __device__ __forceinline__ void gemm_phase(PG8_LAS unsigned char* lds, const Gemm g, const Sched& S, const Epi& E) {
;     ...
;         for (int t = 0; t < nt; t += 2) {
;             const bool last = (t == nt - 2);
;             const char* a1 = cA + (size_t)(t + 1) * kstep;
;             const char* a2 = last ? nA : cA + (size_t)(t + 2) * kstep; const char* b2 = last ? nB : cB + (size_t)(t + 2) * kstep;
;             const char* a3 = a2 + kstep; const char* b3 = b2 + kstep;
;             if (last && has_next) S.a_ready(nxt);
;             if constexpr (SP2) {
;             PG8_LDB(B0, 0, 0); PG8_LDB(B1, 0, 1); PG8_SCHED; PG8_LDA(At, 0, 0); PG8_STAGE(PG8_SA(1, 1), a1 + hstep, voffA);
;     ...
;             PG8_LDA(At, 1, 1); PG8_STAGE(PG8_SB(1, 0), b3, voffB); PG8_STAGE(PG8_SB(1, 1), b3 + hstep, voffB); PG8_STAGE(PG8_SA(1, 0), a3, voffA);
;             PG8_WAIT_V(8); PG8_WAIT_L(0); PG8_BAR; PG8_MMA(1, 0, At, B0); PG8_MMA(1, 1, At, B1); PG8_BAR; PG8_SCHED;
	s_add_i32 s22, s56, s41
	v_lshl_add_u64 v[218:219], v[218:219], 0, s[84:85]
	s_mov_b32 m0, s22
	ds_read_b128 v[164:167], v242 offset:49152
	ds_read_b128 v[168:171], v242 offset:50176
	ds_read_b128 v[172:175], v242 offset:51200
	ds_read_b128 v[176:179], v242 offset:52224
	ds_read_b128 v[180:183], v242 offset:53248
	ds_read_b128 v[184:187], v242 offset:54272
	ds_read_b128 v[188:191], v242 offset:55296
	ds_read_b128 v[214:217], v242 offset:56320
	global_load_lds_dwordx4 v[218:219], off
	s_add_i32 m0, s22, 0x2000
	s_add_u32 s22, s26, 0x2b0080
	v_lshl_add_u64 v[218:219], v[220:221], 0, s[84:85]
	s_addc_u32 s23, s27, 0
	s_add_i32 s26, s57, s41
	global_load_lds_dwordx4 v[218:219], off
	v_lshl_add_u64 v[218:219], s[22:23], 0, v[2:3]
	s_mov_b32 m0, s26
	s_nop 0
	global_load_lds_dwordx4 v[218:219], off
	v_lshl_add_u64 v[218:219], s[22:23], 0, v[204:205]
	s_add_i32 m0, s26, 0x2000
	s_nop 0
	global_load_lds_dwordx4 v[218:219], off
	v_lshl_add_u64 v[218:219], v[222:223], 0, s[84:85]
	s_mov_b32 m0, s46
	s_nop 0
	global_load_lds_dwordx4 v[218:219], off
	v_lshl_add_u64 v[218:219], v[224:225], 0, s[84:85]
	s_mov_b32 m0, s47
	s_nop 0
	global_load_lds_dwordx4 v[218:219], off
	s_waitcnt vmcnt(8)
	s_waitcnt lgkmcnt(0)
	s_barrier
	s_setprio 1
	s_waitcnt lgkmcnt(0)
	v_mfma_f32_16x16x32_bf16 v[64:67], v[124:127], v[164:167], v[64:67]
	v_mfma_f32_16x16x32_bf16 v[64:67], v[128:131], v[168:171], v[64:67]
	v_mfma_f32_16x16x32_bf16 v[48:51], v[128:131], v[176:179], v[48:51]
	v_mfma_f32_16x16x32_bf16 v[48:51], v[124:127], v[172:175], v[48:51]
	v_mfma_f32_16x16x32_bf16 v[32:35], v[124:127], v[180:183], v[32:35]
	v_mfma_f32_16x16x32_bf16 v[32:35], v[128:131], v[184:187], v[32:35]
	v_mfma_f32_16x16x32_bf16 v[16:19], v[128:131], v[214:217], v[16:19]
	v_mfma_f32_16x16x32_bf16 v[16:19], v[124:127], v[188:191], v[16:19]
	v_mfma_f32_16x16x32_bf16 v[12:15], v[132:135], v[188:191], v[12:15]
	v_mfma_f32_16x16x32_bf16 v[12:15], v[144:147], v[214:217], v[12:15]
	v_mfma_f32_16x16x32_bf16 v[28:31], v[144:147], v[184:187], v[28:31]
	v_mfma_f32_16x16x32_bf16 v[28:31], v[132:135], v[180:183], v[28:31]
	v_mfma_f32_16x16x32_bf16 v[44:47], v[132:135], v[172:175], v[44:47]
	v_mfma_f32_16x16x32_bf16 v[44:47], v[144:147], v[176:179], v[44:47]
	v_mfma_f32_16x16x32_bf16 v[60:63], v[144:147], v[168:171], v[60:63]
	v_mfma_f32_16x16x32_bf16 v[60:63], v[132:135], v[164:167], v[60:63]
	v_mfma_f32_16x16x32_bf16 v[56:59], v[148:151], v[164:167], v[56:59]
	v_mfma_f32_16x16x32_bf16 v[56:59], v[152:155], v[168:171], v[56:59]
	v_mfma_f32_16x16x32_bf16 v[40:43], v[152:155], v[176:179], v[40:43]
	v_mfma_f32_16x16x32_bf16 v[40:43], v[148:151], v[172:175], v[40:43]
	v_mfma_f32_16x16x32_bf16 v[24:27], v[148:151], v[180:183], v[24:27]
	v_mfma_f32_16x16x32_bf16 v[24:27], v[152:155], v[184:187], v[24:27]
	v_mfma_f32_16x16x32_bf16 v[8:11], v[152:155], v[214:217], v[8:11]
	v_mfma_f32_16x16x32_bf16 v[8:11], v[148:151], v[188:191], v[8:11]
	v_mfma_f32_16x16x32_bf16 v[4:7], v[156:159], v[188:191], v[4:7]
	v_mfma_f32_16x16x32_bf16 v[4:7], v[160:163], v[214:217], v[4:7]
	v_mfma_f32_16x16x32_bf16 v[20:23], v[160:163], v[184:187], v[20:23]
	v_mfma_f32_16x16x32_bf16 v[20:23], v[156:159], v[180:183], v[20:23]
	v_mfma_f32_16x16x32_bf16 v[36:39], v[156:159], v[172:175], v[36:39]
	v_mfma_f32_16x16x32_bf16 v[36:39], v[160:163], v[176:179], v[36:39]
	v_mfma_f32_16x16x32_bf16 v[52:55], v[160:163], v[168:171], v[52:55]
	v_mfma_f32_16x16x32_bf16 v[52:55], v[156:159], v[164:167], v[52:55]
	s_setprio 0
	s_add_i32 s55, s55, 2
	s_add_u32 s53, s53, 0x100
	s_addc_u32 s54, s54, 0
	s_cmpk_gt_u32 s55, 0xa9
	s_mov_b64 s[22:23], s[24:25]
	s_barrier
	s_cbranch_scc1 .Lkloop_exit_5
.LBB0_1700:
	s_add_u32 s24, s22, 0x100
	s_addc_u32 s25, s23, 0
	s_add_i32 s56, 0, 0x10000
	s_cmpk_eq_i32 s55, 0xa8
	s_cselect_b32 s37, s13, s25
	s_cselect_b32 s36, s12, s24
	s_cselect_b32 s27, s21, s54
	s_cselect_b32 s26, s20, s53
	s_add_i32 s57, 0, 0x14000
	v_add_u32_e32 v144, s56, v240
	v_add_u32_e32 v160, s57, v240
	ds_read_b128 v[124:127], v144
	ds_read_b128 v[128:131], v144 offset:1024
	ds_read_b128 v[132:135], v144 offset:2048
	ds_read_b128 v[144:147], v144 offset:3072
	ds_read_b128 v[148:151], v160
	ds_read_b128 v[152:155], v160 offset:1024
	ds_read_b128 v[156:159], v160 offset:2048
	ds_read_b128 v[160:163], v160 offset:3072
	v_lshl_add_u64 v[218:219], s[22:23], 0, v[210:211]
	s_add_i32 m0, s42, 0xc000
	ds_read_b128 v[164:167], v242
	ds_read_b128 v[168:171], v242 offset:1024
	ds_read_b128 v[172:175], v242 offset:2048
	ds_read_b128 v[176:179], v242 offset:3072
	ds_read_b128 v[180:183], v242 offset:4096
	ds_read_b128 v[184:187], v242 offset:5120
	ds_read_b128 v[188:191], v242 offset:6144
	ds_read_b128 v[214:217], v242 offset:7168
	global_load_lds_dwordx4 v[218:219], off
	v_lshl_add_u64 v[218:219], s[22:23], 0, v[212:213]
	s_add_i32 m0, s42, 0xe000
	s_nop 0
	global_load_lds_dwordx4 v[218:219], off
	s_waitcnt vmcnt(8)
	s_waitcnt lgkmcnt(0)
	s_barrier
; #define PG8_STAGE(bufoff, gbase, voff) do { _Pragma("unroll") for (int _i = 0; _i < 2; ++_i) \
;         __builtin_amdgcn_global_load_lds((const unsigned*)((const char*)(gbase) + (voff)[_i]), (PG8_LAS unsigned*)(lds + (bufoff) + ldsw + _i * 8192), 16, 0, 0); } while (0)
; #define PG8_LDA(dst, b, h) do { _Pragma("unroll") for (int m = 0; m < 4; ++m) _Pragma("unroll") for (int k = 0; k < 2; ++k) dst[m][k] = *(const PG8_LAS bf16x8*)(lds + PG8_SA(b, h) + aoff + m * 2048 + k * 1024); } while (0)
; #define PG8_WAIT_V(n) asm volatile("s_waitcnt vmcnt(" #n ")" ::: "memory")
; #define PG8_WAIT_L(n) asm volatile("s_waitcnt lgkmcnt(" #n ")" ::: "memory")
; #define PG8_BAR __builtin_amdgcn_s_barrier()
; #define PG8_SCHED __builtin_amdgcn_sched_barrier(0)
; template <class Epi, class Sched, bool ALIGN_EPI = false, bool SP2 = false, bool I8 = false>
; __device__ __forceinline__ void gemm_phase(PG8_LAS unsigned char* lds, const Gemm g, const Sched& S, const Epi& E) {
;     ...
;             PG8_WAIT_V(8); PG8_WAIT_L(0); PG8_BAR; PG8_MMA(0, 0, At, B0); PG8_MMA(0, 1, At, B1); PG8_BAR; PG8_SCHED;
;             PG8_LDA(At, 0, 1); PG8_STAGE(PG8_SB(0, 0), b2, voffB); PG8_STAGE(PG8_SB(0, 1), b2 + hstep, voffB); PG8_STAGE(PG8_SA(0, 0), a2, voffA);
;             PG8_WAIT_V(8); PG8_WAIT_L(0); PG8_BAR; PG8_MMA(1, 0, At, B0); PG8_MMA(1, 1, At, B1); PG8_BAR; PG8_SCHED;
	s_setprio 1
	s_waitcnt lgkmcnt(0)
	v_mfma_f32_16x16x32_bf16 v[140:143], v[124:127], v[164:167], v[140:143]
	v_mfma_f32_16x16x32_bf16 v[140:143], v[128:131], v[168:171], v[140:143]
	v_mfma_f32_16x16x32_bf16 v[112:115], v[128:131], v[176:179], v[112:115]
	v_mfma_f32_16x16x32_bf16 v[112:115], v[124:127], v[172:175], v[112:115]
	v_mfma_f32_16x16x32_bf16 v[96:99], v[124:127], v[180:183], v[96:99]
	v_mfma_f32_16x16x32_bf16 v[96:99], v[128:131], v[184:187], v[96:99]
	v_mfma_f32_16x16x32_bf16 v[80:83], v[128:131], v[214:217], v[80:83]
	v_mfma_f32_16x16x32_bf16 v[80:83], v[124:127], v[188:191], v[80:83]
	v_mfma_f32_16x16x32_bf16 v[76:79], v[132:135], v[188:191], v[76:79]
	v_mfma_f32_16x16x32_bf16 v[76:79], v[144:147], v[214:217], v[76:79]
	v_mfma_f32_16x16x32_bf16 v[92:95], v[144:147], v[184:187], v[92:95]
	v_mfma_f32_16x16x32_bf16 v[92:95], v[132:135], v[180:183], v[92:95]
	v_mfma_f32_16x16x32_bf16 v[108:111], v[132:135], v[172:175], v[108:111]
	v_mfma_f32_16x16x32_bf16 v[108:111], v[144:147], v[176:179], v[108:111]
	v_mfma_f32_16x16x32_bf16 v[136:139], v[144:147], v[168:171], v[136:139]
	v_mfma_f32_16x16x32_bf16 v[136:139], v[132:135], v[164:167], v[136:139]
	v_mfma_f32_16x16x32_bf16 v[120:123], v[148:151], v[164:167], v[120:123]
	v_mfma_f32_16x16x32_bf16 v[120:123], v[152:155], v[168:171], v[120:123]
	v_mfma_f32_16x16x32_bf16 v[104:107], v[152:155], v[176:179], v[104:107]
	v_mfma_f32_16x16x32_bf16 v[104:107], v[148:151], v[172:175], v[104:107]
	v_mfma_f32_16x16x32_bf16 v[88:91], v[148:151], v[180:183], v[88:91]
	v_mfma_f32_16x16x32_bf16 v[88:91], v[152:155], v[184:187], v[88:91]
	v_mfma_f32_16x16x32_bf16 v[72:75], v[152:155], v[214:217], v[72:75]
	v_mfma_f32_16x16x32_bf16 v[72:75], v[148:151], v[188:191], v[72:75]
	v_mfma_f32_16x16x32_bf16 v[68:71], v[156:159], v[188:191], v[68:71]
	v_mfma_f32_16x16x32_bf16 v[68:71], v[160:163], v[214:217], v[68:71]
	v_mfma_f32_16x16x32_bf16 v[84:87], v[160:163], v[184:187], v[84:87]
	v_mfma_f32_16x16x32_bf16 v[84:87], v[156:159], v[180:183], v[84:87]
	v_mfma_f32_16x16x32_bf16 v[100:103], v[156:159], v[172:175], v[100:103]
	v_mfma_f32_16x16x32_bf16 v[100:103], v[160:163], v[176:179], v[100:103]
	v_mfma_f32_16x16x32_bf16 v[116:119], v[160:163], v[168:171], v[116:119]
	v_mfma_f32_16x16x32_bf16 v[116:119], v[156:159], v[164:167], v[116:119]
	s_setprio 0
	s_barrier
	s_add_i32 s22, s56, s41
	v_lshl_add_u64 v[218:219], s[26:27], 0, v[2:3]
	s_mov_b32 m0, s22
	ds_read_b128 v[164:167], v242 offset:16384
	ds_read_b128 v[168:171], v242 offset:17408
	ds_read_b128 v[172:175], v242 offset:18432
	ds_read_b128 v[176:179], v242 offset:19456
	ds_read_b128 v[180:183], v242 offset:20480
	ds_read_b128 v[184:187], v242 offset:21504
	ds_read_b128 v[188:191], v242 offset:22528
	ds_read_b128 v[214:217], v242 offset:23552
	global_load_lds_dwordx4 v[218:219], off
	s_add_i32 m0, s22, 0x2000
	s_add_u32 s22, s26, 0x2b0000
	v_lshl_add_u64 v[220:221], s[26:27], 0, v[204:205]
	s_addc_u32 s23, s27, 0
	s_add_i32 s56, s57, s41
	global_load_lds_dwordx4 v[220:221], off
	v_lshl_add_u64 v[222:223], s[22:23], 0, v[2:3]
	s_mov_b32 m0, s56
	v_lshl_add_u64 v[224:225], s[36:37], 0, v[206:207]
	global_load_lds_dwordx4 v[222:223], off
	v_lshl_add_u64 v[222:223], s[22:23], 0, v[204:205]
	s_add_i32 m0, s56, 0x2000
	s_nop 0
	global_load_lds_dwordx4 v[222:223], off
	v_lshl_add_u64 v[222:223], s[36:37], 0, v[208:209]
	s_mov_b32 m0, s42
	s_nop 0
	global_load_lds_dwordx4 v[222:223], off
	s_mov_b32 m0, s43
	s_nop 0
	global_load_lds_dwordx4 v[224:225], off
	s_waitcnt vmcnt(8)
	s_waitcnt lgkmcnt(0)
	s_barrier
	s_setprio 1
	s_waitcnt lgkmcnt(0)
	v_mfma_f32_16x16x32_bf16 v[64:67], v[124:127], v[164:167], v[64:67]
	v_mfma_f32_16x16x32_bf16 v[64:67], v[128:131], v[168:171], v[64:67]
	v_mfma_f32_16x16x32_bf16 v[48:51], v[128:131], v[176:179], v[48:51]
	v_mfma_f32_16x16x32_bf16 v[48:51], v[124:127], v[172:175], v[48:51]
	v_mfma_f32_16x16x32_bf16 v[32:35], v[124:127], v[180:183], v[32:35]
	v_mfma_f32_16x16x32_bf16 v[32:35], v[128:131], v[184:187], v[32:35]
	v_mfma_f32_16x16x32_bf16 v[16:19], v[128:131], v[214:217], v[16:19]
	v_mfma_f32_16x16x32_bf16 v[16:19], v[124:127], v[188:191], v[16:19]
	v_mfma_f32_16x16x32_bf16 v[12:15], v[132:135], v[188:191], v[12:15]
	v_mfma_f32_16x16x32_bf16 v[12:15], v[144:147], v[214:217], v[12:15]
	v_mfma_f32_16x16x32_bf16 v[28:31], v[144:147], v[184:187], v[28:31]
	v_mfma_f32_16x16x32_bf16 v[28:31], v[132:135], v[180:183], v[28:31]
	v_mfma_f32_16x16x32_bf16 v[44:47], v[132:135], v[172:175], v[44:47]
	v_mfma_f32_16x16x32_bf16 v[44:47], v[144:147], v[176:179], v[44:47]
	v_mfma_f32_16x16x32_bf16 v[60:63], v[144:147], v[168:171], v[60:63]
	v_mfma_f32_16x16x32_bf16 v[60:63], v[132:135], v[164:167], v[60:63]
	v_mfma_f32_16x16x32_bf16 v[56:59], v[148:151], v[164:167], v[56:59]
	v_mfma_f32_16x16x32_bf16 v[56:59], v[152:155], v[168:171], v[56:59]
	v_mfma_f32_16x16x32_bf16 v[40:43], v[152:155], v[176:179], v[40:43]
	v_mfma_f32_16x16x32_bf16 v[40:43], v[148:151], v[172:175], v[40:43]
	v_mfma_f32_16x16x32_bf16 v[24:27], v[148:151], v[180:183], v[24:27]
	v_mfma_f32_16x16x32_bf16 v[24:27], v[152:155], v[184:187], v[24:27]
	v_mfma_f32_16x16x32_bf16 v[8:11], v[152:155], v[214:217], v[8:11]
	v_mfma_f32_16x16x32_bf16 v[8:11], v[148:151], v[188:191], v[8:11]
	v_mfma_f32_16x16x32_bf16 v[4:7], v[156:159], v[188:191], v[4:7]
	v_mfma_f32_16x16x32_bf16 v[4:7], v[160:163], v[214:217], v[4:7]
	v_mfma_f32_16x16x32_bf16 v[20:23], v[160:163], v[184:187], v[20:23]
	v_mfma_f32_16x16x32_bf16 v[20:23], v[156:159], v[180:183], v[20:23]
	v_mfma_f32_16x16x32_bf16 v[36:39], v[156:159], v[172:175], v[36:39]
	v_mfma_f32_16x16x32_bf16 v[36:39], v[160:163], v[176:179], v[36:39]
	v_mfma_f32_16x16x32_bf16 v[52:55], v[160:163], v[168:171], v[52:55]
	v_mfma_f32_16x16x32_bf16 v[52:55], v[156:159], v[164:167], v[52:55]
	s_setprio 0
	s_barrier
; #define PG8_STAGE(bufoff, gbase, voff) do { _Pragma("unroll") for (int _i = 0; _i < 2; ++_i) \
;         __builtin_amdgcn_global_load_lds((const unsigned*)((const char*)(gbase) + (voff)[_i]), (PG8_LAS unsigned*)(lds + (bufoff) + ldsw + _i * 8192), 16, 0, 0); } while (0)
; #define PG8_LDA(dst, b, h) do { _Pragma("unroll") for (int m = 0; m < 4; ++m) _Pragma("unroll") for (int k = 0; k < 2; ++k) dst[m][k] = *(const PG8_LAS bf16x8*)(lds + PG8_SA(b, h) + aoff + m * 2048 + k * 1024); } while (0)
; #define PG8_LDB(dst, b, h) do { _Pragma("unroll") for (int n = 0; n < 2; ++n) _Pragma("unroll") for (int k = 0; k < 2; ++k) dst[n][k] = *(const PG8_LAS bf16x8*)(lds + PG8_SB(b, h) + boff + n * 2048 + k * 1024); } while (0)
; #define PG8_WAIT_V(n) asm volatile("s_waitcnt vmcnt(" #n ")" ::: "memory")
; #define PG8_WAIT_L(n) asm volatile("s_waitcnt lgkmcnt(" #n ")" ::: "memory")
; #define PG8_BAR __builtin_amdgcn_s_barrier()
; #define PG8_SCHED __builtin_amdgcn_sched_barrier(0)
; template <class Epi, class Sched, bool ALIGN_EPI = false, bool SP2 = false, bool I8 = false>
; __device__ __forceinline__ void gemm_phase(PG8_LAS unsigned char* lds, const Gemm g, const Sched& S, const Epi& E) {
;     ...
;             PG8_LDB(B0, 1, 0); PG8_LDB(B1, 1, 1); PG8_SCHED; PG8_LDA(At, 1, 0); PG8_STAGE(PG8_SA(0, 1), a2 + hstep, voffA);
;             PG8_WAIT_V(8); PG8_WAIT_L(0); PG8_BAR; PG8_MMA(0, 0, At, B0); PG8_MMA(0, 1, At, B1); PG8_BAR; PG8_SCHED;
	s_add_i32 s56, 0, 0x18000
	s_add_i32 s57, 0, 0x1c000
	v_add_u32_e32 v144, s56, v240
	v_add_u32_e32 v160, s57, v240
	ds_read_b128 v[124:127], v144
	ds_read_b128 v[128:131], v144 offset:1024
	ds_read_b128 v[132:135], v144 offset:2048
	ds_read_b128 v[144:147], v144 offset:3072
	ds_read_b128 v[148:151], v160
	ds_read_b128 v[152:155], v160 offset:1024
	ds_read_b128 v[156:159], v160 offset:2048
	ds_read_b128 v[160:163], v160 offset:3072
	s_add_u32 s22, s36, 0x2b0000
	s_addc_u32 s23, s37, 0
	s_mov_b32 m0, s44
	v_lshl_add_u64 v[226:227], s[22:23], 0, v[208:209]
	ds_read_b128 v[164:167], v242 offset:32768
	ds_read_b128 v[168:171], v242 offset:33792
	ds_read_b128 v[172:175], v242 offset:34816
	ds_read_b128 v[176:179], v242 offset:35840
	ds_read_b128 v[180:183], v242 offset:36864
	ds_read_b128 v[184:187], v242 offset:37888
	ds_read_b128 v[188:191], v242 offset:38912
	ds_read_b128 v[214:217], v242 offset:39936
	global_load_lds_dwordx4 v[226:227], off
	v_lshl_add_u64 v[226:227], s[22:23], 0, v[206:207]
	s_mov_b32 m0, s45
	s_nop 0
	global_load_lds_dwordx4 v[226:227], off
	s_waitcnt vmcnt(8)
	s_waitcnt lgkmcnt(0)
	s_barrier
	s_setprio 1
	s_waitcnt lgkmcnt(0)
	v_mfma_f32_16x16x32_bf16 v[140:143], v[124:127], v[164:167], v[140:143]
	v_mfma_f32_16x16x32_bf16 v[140:143], v[128:131], v[168:171], v[140:143]
	v_mfma_f32_16x16x32_bf16 v[112:115], v[128:131], v[176:179], v[112:115]
	v_mfma_f32_16x16x32_bf16 v[112:115], v[124:127], v[172:175], v[112:115]
	v_mfma_f32_16x16x32_bf16 v[96:99], v[124:127], v[180:183], v[96:99]
	v_mfma_f32_16x16x32_bf16 v[96:99], v[128:131], v[184:187], v[96:99]
	v_mfma_f32_16x16x32_bf16 v[80:83], v[128:131], v[214:217], v[80:83]
	v_mfma_f32_16x16x32_bf16 v[80:83], v[124:127], v[188:191], v[80:83]
	v_mfma_f32_16x16x32_bf16 v[76:79], v[132:135], v[188:191], v[76:79]
	v_mfma_f32_16x16x32_bf16 v[76:79], v[144:147], v[214:217], v[76:79]
	v_mfma_f32_16x16x32_bf16 v[92:95], v[144:147], v[184:187], v[92:95]
	v_mfma_f32_16x16x32_bf16 v[92:95], v[132:135], v[180:183], v[92:95]
	v_mfma_f32_16x16x32_bf16 v[108:111], v[132:135], v[172:175], v[108:111]
	v_mfma_f32_16x16x32_bf16 v[108:111], v[144:147], v[176:179], v[108:111]
	v_mfma_f32_16x16x32_bf16 v[136:139], v[144:147], v[168:171], v[136:139]
	v_mfma_f32_16x16x32_bf16 v[136:139], v[132:135], v[164:167], v[136:139]
	v_mfma_f32_16x16x32_bf16 v[120:123], v[148:151], v[164:167], v[120:123]
	v_mfma_f32_16x16x32_bf16 v[120:123], v[152:155], v[168:171], v[120:123]
	v_mfma_f32_16x16x32_bf16 v[104:107], v[152:155], v[176:179], v[104:107]
	v_mfma_f32_16x16x32_bf16 v[104:107], v[148:151], v[172:175], v[104:107]
	v_mfma_f32_16x16x32_bf16 v[88:91], v[148:151], v[180:183], v[88:91]
	v_mfma_f32_16x16x32_bf16 v[88:91], v[152:155], v[184:187], v[88:91]
	v_mfma_f32_16x16x32_bf16 v[72:75], v[152:155], v[214:217], v[72:75]
	v_mfma_f32_16x16x32_bf16 v[72:75], v[148:151], v[188:191], v[72:75]
	v_mfma_f32_16x16x32_bf16 v[68:71], v[156:159], v[188:191], v[68:71]
	v_mfma_f32_16x16x32_bf16 v[68:71], v[160:163], v[214:217], v[68:71]
	v_mfma_f32_16x16x32_bf16 v[84:87], v[160:163], v[184:187], v[84:87]
	v_mfma_f32_16x16x32_bf16 v[84:87], v[156:159], v[180:183], v[84:87]
	v_mfma_f32_16x16x32_bf16 v[100:103], v[156:159], v[172:175], v[100:103]
	v_mfma_f32_16x16x32_bf16 v[100:103], v[160:163], v[176:179], v[100:103]
	v_mfma_f32_16x16x32_bf16 v[116:119], v[160:163], v[168:171], v[116:119]
	v_mfma_f32_16x16x32_bf16 v[116:119], v[156:159], v[164:167], v[116:119]
	s_setprio 0
	s_barrier
; #define PG8_STAGE(bufoff, gbase, voff) do { _Pragma("unroll") for (int _i = 0; _i < 2; ++_i) \
;         __builtin_amdgcn_global_load_lds((const unsigned*)((const char*)(gbase) + (voff)[_i]), (PG8_LAS unsigned*)(lds + (bufoff) + ldsw + _i * 8192), 16, 0, 0); } while (0)
; #define PG8_LDA(dst, b, h) do { _Pragma("unroll") for (int m = 0; m < 4; ++m) _Pragma("unroll") for (int k = 0; k < 2; ++k) dst[m][k] = *(const PG8_LAS bf16x8*)(lds + PG8_SA(b, h) + aoff + m * 2048 + k * 1024); } while (0)
; #define PG8_WAIT_V(n) asm volatile("s_waitcnt vmcnt(" #n ")" ::: "memory")
; #define PG8_WAIT_L(n) asm volatile("s_waitcnt lgkmcnt(" #n ")" ::: "memory")
; #define PG8_BAR __builtin_amdgcn_s_barrier()
; #define PG8_SCHED __builtin_amdgcn_sched_barrier(0)
; template <class Epi, class Sched, bool ALIGN_EPI = false, bool SP2 = false, bool I8 = false>
; __device__ __forceinline__ void gemm_phase(PG8_LAS unsigned char* lds, const Gemm g, const Sched& S, const Epi& E) {
;     ...
;         for (int t = 0; t < nt; t += 2) {
;             const bool last = (t == nt - 2);
;             const char* a1 = cA + (size_t)(t + 1) * kstep;
;             const char* a2 = last ? nA : cA + (size_t)(t + 2) * kstep; const char* b2 = last ? nB : cB + (size_t)(t + 2) * kstep;
;     ...
;             PG8_LDA(At, 1, 1); PG8_STAGE(PG8_SB(1, 0), b3, voffB); PG8_STAGE(PG8_SB(1, 1), b3 + hstep, voffB); PG8_STAGE(PG8_SA(1, 0), a3, voffA);
;             PG8_WAIT_V(8); PG8_WAIT_L(0); PG8_BAR; PG8_MMA(1, 0, At, B0); PG8_MMA(1, 1, At, B1); PG8_BAR; PG8_SCHED;
	s_add_i32 s22, s56, s41
	v_lshl_add_u64 v[218:219], v[218:219], 0, s[84:85]
	s_mov_b32 m0, s22
	ds_read_b128 v[164:167], v242 offset:49152
	ds_read_b128 v[168:171], v242 offset:50176
	ds_read_b128 v[172:175], v242 offset:51200
	ds_read_b128 v[176:179], v242 offset:52224
	ds_read_b128 v[180:183], v242 offset:53248
	ds_read_b128 v[184:187], v242 offset:54272
	ds_read_b128 v[188:191], v242 offset:55296
	ds_read_b128 v[214:217], v242 offset:56320
	global_load_lds_dwordx4 v[218:219], off
	s_add_i32 m0, s22, 0x2000
	s_add_u32 s22, s26, 0x2b0080
	v_lshl_add_u64 v[218:219], v[220:221], 0, s[84:85]
	s_addc_u32 s23, s27, 0
	s_add_i32 s26, s57, s41
	global_load_lds_dwordx4 v[218:219], off
	v_lshl_add_u64 v[218:219], s[22:23], 0, v[2:3]
	s_mov_b32 m0, s26
	s_nop 0
	global_load_lds_dwordx4 v[218:219], off
	v_lshl_add_u64 v[218:219], s[22:23], 0, v[204:205]
	s_add_i32 m0, s26, 0x2000
	s_nop 0
	global_load_lds_dwordx4 v[218:219], off
	v_lshl_add_u64 v[218:219], v[222:223], 0, s[84:85]
	s_mov_b32 m0, s46
	s_nop 0
	global_load_lds_dwordx4 v[218:219], off
	v_lshl_add_u64 v[218:219], v[224:225], 0, s[84:85]
	s_mov_b32 m0, s47
	s_nop 0
	global_load_lds_dwordx4 v[218:219], off
	s_waitcnt vmcnt(8)
	s_waitcnt lgkmcnt(0)
	s_barrier
	s_setprio 1
	s_waitcnt lgkmcnt(0)
	v_mfma_f32_16x16x32_bf16 v[64:67], v[124:127], v[164:167], v[64:67]
	v_mfma_f32_16x16x32_bf16 v[64:67], v[128:131], v[168:171], v[64:67]
	v_mfma_f32_16x16x32_bf16 v[48:51], v[128:131], v[176:179], v[48:51]
	v_mfma_f32_16x16x32_bf16 v[48:51], v[124:127], v[172:175], v[48:51]
	v_mfma_f32_16x16x32_bf16 v[32:35], v[124:127], v[180:183], v[32:35]
	v_mfma_f32_16x16x32_bf16 v[32:35], v[128:131], v[184:187], v[32:35]
	v_mfma_f32_16x16x32_bf16 v[16:19], v[128:131], v[214:217], v[16:19]
	v_mfma_f32_16x16x32_bf16 v[16:19], v[124:127], v[188:191], v[16:19]
	v_mfma_f32_16x16x32_bf16 v[12:15], v[132:135], v[188:191], v[12:15]
	v_mfma_f32_16x16x32_bf16 v[12:15], v[144:147], v[214:217], v[12:15]
	v_mfma_f32_16x16x32_bf16 v[28:31], v[144:147], v[184:187], v[28:31]
	v_mfma_f32_16x16x32_bf16 v[28:31], v[132:135], v[180:183], v[28:31]
	v_mfma_f32_16x16x32_bf16 v[44:47], v[132:135], v[172:175], v[44:47]
	v_mfma_f32_16x16x32_bf16 v[44:47], v[144:147], v[176:179], v[44:47]
	v_mfma_f32_16x16x32_bf16 v[60:63], v[144:147], v[168:171], v[60:63]
	v_mfma_f32_16x16x32_bf16 v[60:63], v[132:135], v[164:167], v[60:63]
	v_mfma_f32_16x16x32_bf16 v[56:59], v[148:151], v[164:167], v[56:59]
	v_mfma_f32_16x16x32_bf16 v[56:59], v[152:155], v[168:171], v[56:59]
	v_mfma_f32_16x16x32_bf16 v[40:43], v[152:155], v[176:179], v[40:43]
	v_mfma_f32_16x16x32_bf16 v[40:43], v[148:151], v[172:175], v[40:43]
	v_mfma_f32_16x16x32_bf16 v[24:27], v[148:151], v[180:183], v[24:27]
	v_mfma_f32_16x16x32_bf16 v[24:27], v[152:155], v[184:187], v[24:27]
	v_mfma_f32_16x16x32_bf16 v[8:11], v[152:155], v[214:217], v[8:11]
	v_mfma_f32_16x16x32_bf16 v[8:11], v[148:151], v[188:191], v[8:11]
	v_mfma_f32_16x16x32_bf16 v[4:7], v[156:159], v[188:191], v[4:7]
	v_mfma_f32_16x16x32_bf16 v[4:7], v[160:163], v[214:217], v[4:7]
	v_mfma_f32_16x16x32_bf16 v[20:23], v[160:163], v[184:187], v[20:23]
	v_mfma_f32_16x16x32_bf16 v[20:23], v[156:159], v[180:183], v[20:23]
	v_mfma_f32_16x16x32_bf16 v[36:39], v[156:159], v[172:175], v[36:39]
	v_mfma_f32_16x16x32_bf16 v[36:39], v[160:163], v[176:179], v[36:39]
	v_mfma_f32_16x16x32_bf16 v[52:55], v[160:163], v[168:171], v[52:55]
	v_mfma_f32_16x16x32_bf16 v[52:55], v[156:159], v[164:167], v[52:55]
	s_setprio 0
	s_add_i32 s55, s55, 2
	s_add_u32 s53, s53, 0x100
	s_addc_u32 s54, s54, 0
	s_cmpk_gt_u32 s55, 0xa9
	s_mov_b64 s[22:23], s[24:25]
	s_barrier
	s_cbranch_scc0 .LBB0_1700

; #define PG8_STAGE(bufoff, gbase, voff) do { _Pragma("unroll") for (int _i = 0; _i < 2; ++_i) \
;         __builtin_amdgcn_global_load_lds((const unsigned*)((const char*)(gbase) + (voff)[_i]), (PG8_LAS unsigned*)(lds + (bufoff) + ldsw + _i * 8192), 16, 0, 0); } while (0)
; #define PG8_LDA(dst, b, h) do { _Pragma("unroll") for (int m = 0; m < 4; ++m) _Pragma("unroll") for (int k = 0; k < 2; ++k) dst[m][k] = *(const PG8_LAS bf16x8*)(lds + PG8_SA(b, h) + aoff + m * 2048 + k * 1024); } while (0)
; #define PG8_LDB(dst, b, h) do { _Pragma("unroll") for (int n = 0; n < 2; ++n) _Pragma("unroll") for (int k = 0; k < 2; ++k) dst[n][k] = *(const PG8_LAS bf16x8*)(lds + PG8_SB(b, h) + boff + n * 2048 + k * 1024); } while (0)
; #define PG8_WAIT_V(n) asm volatile("s_waitcnt vmcnt(" #n ")" ::: "memory")
; #define PG8_WAIT_L(n) asm volatile("s_waitcnt lgkmcnt(" #n ")" ::: "memory")
; #define PG8_BAR __builtin_amdgcn_s_barrier()
; #define PG8_SCHED __builtin_amdgcn_sched_barrier(0)
; template <class Epi, class Sched, bool ALIGN_EPI = false, bool SP2 = false, bool I8 = false>
; __device__ __forceinline__ void gemm_phase(PG8_LAS unsigned char* lds, const Gemm g, const Sched& S, const Epi& E) {
;     ...
;         const bool has_next = S.next(ui + 1, nxt);
;         const char* nA = has_next ? (const char*)g.A + (size_t)nxt.pm * tstep : cA; const char* nB = has_next ? (const char*)g.Bt + (size_t)nxt.pn * tstep : cB;
;         for (int t = 0; t < nt; t += 2) {
;             const bool last = (t == nt - 2);
;             const char* a1 = cA + (size_t)(t + 1) * kstep;
;             const char* a2 = last ? nA : cA + (size_t)(t + 2) * kstep; const char* b2 = last ? nB : cB + (size_t)(t + 2) * kstep;
;             const char* a3 = a2 + kstep; const char* b3 = b2 + kstep;
;             if (last && has_next) S.a_ready(nxt);
;             if constexpr (SP2) {
;             PG8_LDB(B0, 0, 0); PG8_LDB(B1, 0, 1); PG8_SCHED; PG8_LDA(At, 0, 0); PG8_STAGE(PG8_SA(1, 1), a1 + hstep, voffA);
;             PG8_WAIT_V(8); PG8_WAIT_L(0); PG8_BAR; PG8_MMA(0, 0, At, B0); PG8_MMA(0, 1, At, B1); PG8_BAR; PG8_SCHED;
;             PG8_LDA(At, 0, 1); PG8_STAGE(PG8_SB(0, 0), b2, voffB); PG8_STAGE(PG8_SB(0, 1), b2 + hstep, voffB); PG8_STAGE(PG8_SA(0, 0), a2, voffA);
;             PG8_WAIT_V(8); PG8_WAIT_L(0); PG8_BAR; PG8_MMA(1, 0, At, B0); PG8_MMA(1, 1, At, B1); PG8_BAR; PG8_SCHED;
.LBB0_1842:
	s_ashr_i32 s45, s44, 31
	s_lshl_b64 s[34:35], s[44:45], 20
	s_add_u32 s50, s47, s34
	s_addc_u32 s51, s52, s35
	s_and_b64 s[34:35], s[8:9], exec
	s_cselect_b32 s11, s51, s55
	s_cselect_b32 s13, s50, s54
	s_ashr_i32 s49, s48, 31
	s_lshl_b64 s[34:35], s[48:49], 20
	s_add_u32 s56, s53, s34
	s_addc_u32 s57, s64, s35
	s_and_b64 s[34:35], s[8:9], exec
	s_cselect_b32 s34, s57, s59
	s_cselect_b32 s35, s56, s58
	s_add_u32 s54, s54, 0x80080
	s_addc_u32 s55, s55, 0
	s_add_u32 s45, s58, 0x100
	s_addc_u32 s49, s59, 0
	s_mov_b32 s86, -2
	s_waitcnt lgkmcnt(0)
	s_add_u32 s58, s54, 0xfff80080
	s_addc_u32 s59, s55, -1
	s_add_i32 s87, 0, 0x10000
	s_cmp_eq_u32 s86, 28
	s_cselect_b32 s61, s11, s59
	s_cselect_b32 s60, s13, s58
	s_cselect_b32 s59, s34, s49
	s_cselect_b32 s58, s35, s45
	s_add_i32 vcc_lo, 0, 0x14000
	v_add_u32_e32 v40, s87, v217
	v_add_u32_e32 v160, vcc_lo, v217
	ds_read_b128 v[28:31], v40
	ds_read_b128 v[32:35], v40 offset:1024
	ds_read_b128 v[36:39], v40 offset:2048
	ds_read_b128 v[40:43], v40 offset:3072
	ds_read_b128 v[140:143], v160
	ds_read_b128 v[144:147], v160 offset:1024
	ds_read_b128 v[156:159], v160 offset:2048
	ds_read_b128 v[160:163], v160 offset:3072
	v_lshl_add_u64 v[190:191], s[54:55], 0, v[186:187]
	s_add_i32 m0, s65, 0xc000
	ds_read_b128 v[164:167], v219
	ds_read_b128 v[168:171], v219 offset:1024
	ds_read_b128 v[172:175], v219 offset:2048
	ds_read_b128 v[176:179], v219 offset:3072
	ds_read_b128 v[204:207], v219 offset:4096
	ds_read_b128 v[208:211], v219 offset:5120
	ds_read_b128 v[212:215], v219 offset:6144
	ds_read_b128 v[220:223], v219 offset:7168
	global_load_lds_dwordx4 v[190:191], off
	v_lshl_add_u64 v[190:191], s[54:55], 0, v[188:189]
	s_add_i32 m0, s65, 0xe000
	s_nop 0
	global_load_lds_dwordx4 v[190:191], off
	s_waitcnt vmcnt(8)
	s_waitcnt lgkmcnt(0)
	s_barrier
	s_setprio 1
	s_waitcnt lgkmcnt(0)
	v_mfma_i32_16x16x64_i8 v[152:155], v[28:31], v[164:167], 0
	v_mfma_i32_16x16x64_i8 v[152:155], v[32:35], v[168:171], v[152:155]
	v_mfma_i32_16x16x64_i8 v[128:131], v[32:35], v[176:179], 0
	v_mfma_i32_16x16x64_i8 v[128:131], v[28:31], v[172:175], v[128:131]
	v_mfma_i32_16x16x64_i8 v[112:115], v[28:31], v[204:207], 0
	v_mfma_i32_16x16x64_i8 v[112:115], v[32:35], v[208:211], v[112:115]
	v_mfma_i32_16x16x64_i8 v[96:99], v[32:35], v[220:223], 0
	v_mfma_i32_16x16x64_i8 v[96:99], v[28:31], v[212:215], v[96:99]
	v_mfma_i32_16x16x64_i8 v[92:95], v[36:39], v[212:215], 0
	v_mfma_i32_16x16x64_i8 v[92:95], v[40:43], v[220:223], v[92:95]
	v_mfma_i32_16x16x64_i8 v[108:111], v[40:43], v[208:211], 0
	v_mfma_i32_16x16x64_i8 v[108:111], v[36:39], v[204:207], v[108:111]
	v_mfma_i32_16x16x64_i8 v[124:127], v[36:39], v[172:175], 0
	v_mfma_i32_16x16x64_i8 v[124:127], v[40:43], v[176:179], v[124:127]
	v_mfma_i32_16x16x64_i8 v[148:151], v[40:43], v[168:171], 0
	v_mfma_i32_16x16x64_i8 v[148:151], v[36:39], v[164:167], v[148:151]
	v_mfma_i32_16x16x64_i8 v[136:139], v[140:143], v[164:167], 0
	v_mfma_i32_16x16x64_i8 v[136:139], v[144:147], v[168:171], v[136:139]
	v_mfma_i32_16x16x64_i8 v[120:123], v[144:147], v[176:179], 0
	v_mfma_i32_16x16x64_i8 v[120:123], v[140:143], v[172:175], v[120:123]
	v_mfma_i32_16x16x64_i8 v[104:107], v[140:143], v[204:207], 0
	v_mfma_i32_16x16x64_i8 v[104:107], v[144:147], v[208:211], v[104:107]
	v_mfma_i32_16x16x64_i8 v[88:91], v[144:147], v[220:223], 0
	v_mfma_i32_16x16x64_i8 v[88:91], v[140:143], v[212:215], v[88:91]
	v_mfma_i32_16x16x64_i8 v[84:87], v[156:159], v[212:215], 0
	v_mfma_i32_16x16x64_i8 v[84:87], v[160:163], v[220:223], v[84:87]
	v_mfma_i32_16x16x64_i8 v[100:103], v[160:163], v[208:211], 0
	v_mfma_i32_16x16x64_i8 v[100:103], v[156:159], v[204:207], v[100:103]
	v_mfma_i32_16x16x64_i8 v[116:119], v[156:159], v[172:175], 0
	v_mfma_i32_16x16x64_i8 v[116:119], v[160:163], v[176:179], v[116:119]
	v_mfma_i32_16x16x64_i8 v[132:135], v[160:163], v[168:171], 0
	v_mfma_i32_16x16x64_i8 v[132:135], v[156:159], v[164:167], v[132:135]
	s_setprio 0
	s_barrier
	s_add_i32 s87, s87, s46
	v_lshl_add_u64 v[190:191], s[58:59], 0, v[2:3]
	s_mov_b32 m0, s87
	ds_read_b128 v[164:167], v219 offset:16384
	ds_read_b128 v[168:171], v219 offset:17408
	ds_read_b128 v[172:175], v219 offset:18432
	ds_read_b128 v[176:179], v219 offset:19456
	ds_read_b128 v[204:207], v219 offset:20480
	ds_read_b128 v[208:211], v219 offset:21504
	ds_read_b128 v[212:215], v219 offset:22528
	ds_read_b128 v[220:223], v219 offset:23552
	global_load_lds_dwordx4 v[190:191], off
	s_add_i32 m0, s87, 0x2000
	s_add_u32 s96, s58, 0x80000
	v_lshl_add_u64 v[224:225], s[58:59], 0, v[184:185]
	s_addc_u32 s97, s59, 0
	s_add_i32 s87, vcc_lo, s46
	global_load_lds_dwordx4 v[224:225], off
	v_lshl_add_u64 v[226:227], s[96:97], 0, v[2:3]
	s_mov_b32 m0, s87
	v_lshl_add_u64 v[228:229], s[60:61], 0, v[182:183]
	global_load_lds_dwordx4 v[226:227], off
	v_lshl_add_u64 v[226:227], s[96:97], 0, v[184:185]
	s_add_i32 m0, s87, 0x2000
	s_nop 0
	global_load_lds_dwordx4 v[226:227], off
	v_lshl_add_u64 v[226:227], s[60:61], 0, v[180:181]
	s_mov_b32 m0, s65
	s_nop 0
	global_load_lds_dwordx4 v[226:227], off
	s_mov_b32 m0, s67
	s_nop 0
	global_load_lds_dwordx4 v[228:229], off
	s_waitcnt vmcnt(8)
	s_waitcnt lgkmcnt(0)
	s_barrier
; #define PG8_STAGE(bufoff, gbase, voff) do { _Pragma("unroll") for (int _i = 0; _i < 2; ++_i) \
;         __builtin_amdgcn_global_load_lds((const unsigned*)((const char*)(gbase) + (voff)[_i]), (PG8_LAS unsigned*)(lds + (bufoff) + ldsw + _i * 8192), 16, 0, 0); } while (0)
; #define PG8_LDA(dst, b, h) do { _Pragma("unroll") for (int m = 0; m < 4; ++m) _Pragma("unroll") for (int k = 0; k < 2; ++k) dst[m][k] = *(const PG8_LAS bf16x8*)(lds + PG8_SA(b, h) + aoff + m * 2048 + k * 1024); } while (0)
; #define PG8_LDB(dst, b, h) do { _Pragma("unroll") for (int n = 0; n < 2; ++n) _Pragma("unroll") for (int k = 0; k < 2; ++k) dst[n][k] = *(const PG8_LAS bf16x8*)(lds + PG8_SB(b, h) + boff + n * 2048 + k * 1024); } while (0)
; #define PG8_WAIT_V(n) asm volatile("s_waitcnt vmcnt(" #n ")" ::: "memory")
; #define PG8_WAIT_L(n) asm volatile("s_waitcnt lgkmcnt(" #n ")" ::: "memory")
; #define PG8_BAR __builtin_amdgcn_s_barrier()
; #define PG8_SCHED __builtin_amdgcn_sched_barrier(0)
; template <class Epi, class Sched, bool ALIGN_EPI = false, bool SP2 = false, bool I8 = false>
; __device__ __forceinline__ void gemm_phase(PG8_LAS unsigned char* lds, const Gemm g, const Sched& S, const Epi& E) {
;     ...
;             PG8_WAIT_V(8); PG8_WAIT_L(0); PG8_BAR; PG8_MMA(1, 0, At, B0); PG8_MMA(1, 1, At, B1); PG8_BAR; PG8_SCHED;
;             PG8_LDB(B0, 1, 0); PG8_LDB(B1, 1, 1); PG8_SCHED; PG8_LDA(At, 1, 0); PG8_STAGE(PG8_SA(0, 1), a2 + hstep, voffA);
;             PG8_WAIT_V(8); PG8_WAIT_L(0); PG8_BAR; PG8_MMA(0, 0, At, B0); PG8_MMA(0, 1, At, B1); PG8_BAR; PG8_SCHED;
	s_setprio 1
	s_waitcnt lgkmcnt(0)
	v_mfma_i32_16x16x64_i8 v[80:83], v[28:31], v[164:167], 0
	v_mfma_i32_16x16x64_i8 v[80:83], v[32:35], v[168:171], v[80:83]
	v_mfma_i32_16x16x64_i8 v[64:67], v[32:35], v[176:179], 0
	v_mfma_i32_16x16x64_i8 v[64:67], v[28:31], v[172:175], v[64:67]
	v_mfma_i32_16x16x64_i8 v[48:51], v[28:31], v[204:207], 0
	v_mfma_i32_16x16x64_i8 v[48:51], v[32:35], v[208:211], v[48:51]
	v_mfma_i32_16x16x64_i8 v[16:19], v[32:35], v[220:223], 0
	v_mfma_i32_16x16x64_i8 v[16:19], v[28:31], v[212:215], v[16:19]
	v_mfma_i32_16x16x64_i8 v[12:15], v[36:39], v[212:215], 0
	v_mfma_i32_16x16x64_i8 v[12:15], v[40:43], v[220:223], v[12:15]
	v_mfma_i32_16x16x64_i8 v[44:47], v[40:43], v[208:211], 0
	v_mfma_i32_16x16x64_i8 v[44:47], v[36:39], v[204:207], v[44:47]
	v_mfma_i32_16x16x64_i8 v[60:63], v[36:39], v[172:175], 0
	v_mfma_i32_16x16x64_i8 v[60:63], v[40:43], v[176:179], v[60:63]
	v_mfma_i32_16x16x64_i8 v[76:79], v[40:43], v[168:171], 0
	v_mfma_i32_16x16x64_i8 v[76:79], v[36:39], v[164:167], v[76:79]
	v_mfma_i32_16x16x64_i8 v[28:31], v[140:143], v[164:167], 0
	v_mfma_i32_16x16x64_i8 v[28:31], v[144:147], v[168:171], v[28:31]
	v_mfma_i32_16x16x64_i8 v[36:39], v[144:147], v[176:179], 0
	v_mfma_i32_16x16x64_i8 v[36:39], v[140:143], v[172:175], v[36:39]
	v_mfma_i32_16x16x64_i8 v[24:27], v[140:143], v[204:207], 0
	v_mfma_i32_16x16x64_i8 v[24:27], v[144:147], v[208:211], v[24:27]
	v_mfma_i32_16x16x64_i8 v[8:11], v[144:147], v[220:223], 0
	v_mfma_i32_16x16x64_i8 v[8:11], v[140:143], v[212:215], v[8:11]
	v_mfma_i32_16x16x64_i8 v[4:7], v[156:159], v[212:215], 0
	v_mfma_i32_16x16x64_i8 v[4:7], v[160:163], v[220:223], v[4:7]
	v_mfma_i32_16x16x64_i8 v[20:23], v[160:163], v[208:211], 0
	v_mfma_i32_16x16x64_i8 v[20:23], v[156:159], v[204:207], v[20:23]
	v_mfma_i32_16x16x64_i8 v[40:43], v[156:159], v[172:175], 0
	v_mfma_i32_16x16x64_i8 v[40:43], v[160:163], v[176:179], v[40:43]
	v_mfma_i32_16x16x64_i8 v[32:35], v[160:163], v[168:171], 0
	v_mfma_i32_16x16x64_i8 v[32:35], v[156:159], v[164:167], v[32:35]
	s_setprio 0
	s_barrier
	s_add_i32 s87, 0, 0x18000
	s_add_i32 s96, 0, 0x1c000
	v_add_u32_e32 v72, s87, v217
	v_add_u32_e32 v160, s96, v217
	ds_read_b128 v[52:55], v72
	ds_read_b128 v[56:59], v72 offset:1024
	ds_read_b128 v[68:71], v72 offset:2048
	ds_read_b128 v[72:75], v72 offset:3072
	ds_read_b128 v[140:143], v160
	ds_read_b128 v[144:147], v160 offset:1024
	ds_read_b128 v[156:159], v160 offset:2048
	ds_read_b128 v[160:163], v160 offset:3072
	s_add_u32 s60, s60, 0x80000
	s_addc_u32 s61, s61, 0
	s_mov_b32 m0, s72
	v_lshl_add_u64 v[240:241], s[60:61], 0, v[180:181]
	ds_read_b128 v[164:167], v219 offset:32768
	ds_read_b128 v[168:171], v219 offset:33792
	ds_read_b128 v[172:175], v219 offset:34816
	ds_read_b128 v[176:179], v219 offset:35840
	ds_read_b128 v[204:207], v219 offset:36864
	ds_read_b128 v[208:211], v219 offset:37888
	ds_read_b128 v[212:215], v219 offset:38912
	ds_read_b128 v[220:223], v219 offset:39936
	global_load_lds_dwordx4 v[240:241], off
	v_lshl_add_u64 v[240:241], s[60:61], 0, v[182:183]
	s_mov_b32 m0, s73
	s_nop 0
	global_load_lds_dwordx4 v[240:241], off
	s_waitcnt vmcnt(8)
	s_waitcnt lgkmcnt(0)
	s_barrier
	s_setprio 1
	s_waitcnt lgkmcnt(0)
	v_mfma_i32_16x16x64_i8 v[152:155], v[52:55], v[164:167], v[152:155]
	v_mfma_i32_16x16x64_i8 v[152:155], v[56:59], v[168:171], v[152:155]
	v_mfma_i32_16x16x64_i8 v[128:131], v[56:59], v[176:179], v[128:131]
	v_mfma_i32_16x16x64_i8 v[128:131], v[52:55], v[172:175], v[128:131]
	v_mfma_i32_16x16x64_i8 v[112:115], v[52:55], v[204:207], v[112:115]
	v_mfma_i32_16x16x64_i8 v[112:115], v[56:59], v[208:211], v[112:115]
	v_mfma_i32_16x16x64_i8 v[96:99], v[56:59], v[220:223], v[96:99]
	v_mfma_i32_16x16x64_i8 v[96:99], v[52:55], v[212:215], v[96:99]
	v_mfma_i32_16x16x64_i8 v[92:95], v[68:71], v[212:215], v[92:95]
	v_mfma_i32_16x16x64_i8 v[92:95], v[72:75], v[220:223], v[92:95]
	v_mfma_i32_16x16x64_i8 v[108:111], v[72:75], v[208:211], v[108:111]
	v_mfma_i32_16x16x64_i8 v[108:111], v[68:71], v[204:207], v[108:111]
	v_mfma_i32_16x16x64_i8 v[124:127], v[68:71], v[172:175], v[124:127]
	v_mfma_i32_16x16x64_i8 v[124:127], v[72:75], v[176:179], v[124:127]
	v_mfma_i32_16x16x64_i8 v[148:151], v[72:75], v[168:171], v[148:151]
	v_mfma_i32_16x16x64_i8 v[148:151], v[68:71], v[164:167], v[148:151]
	v_mfma_i32_16x16x64_i8 v[136:139], v[140:143], v[164:167], v[136:139]
	v_mfma_i32_16x16x64_i8 v[136:139], v[144:147], v[168:171], v[136:139]
	v_mfma_i32_16x16x64_i8 v[120:123], v[144:147], v[176:179], v[120:123]
	v_mfma_i32_16x16x64_i8 v[120:123], v[140:143], v[172:175], v[120:123]
	v_mfma_i32_16x16x64_i8 v[104:107], v[140:143], v[204:207], v[104:107]
	v_mfma_i32_16x16x64_i8 v[104:107], v[144:147], v[208:211], v[104:107]
	v_mfma_i32_16x16x64_i8 v[88:91], v[144:147], v[220:223], v[88:91]
	v_mfma_i32_16x16x64_i8 v[88:91], v[140:143], v[212:215], v[88:91]
	v_mfma_i32_16x16x64_i8 v[84:87], v[156:159], v[212:215], v[84:87]
	v_mfma_i32_16x16x64_i8 v[84:87], v[160:163], v[220:223], v[84:87]
	v_mfma_i32_16x16x64_i8 v[100:103], v[160:163], v[208:211], v[100:103]
	v_mfma_i32_16x16x64_i8 v[100:103], v[156:159], v[204:207], v[100:103]
	v_mfma_i32_16x16x64_i8 v[116:119], v[156:159], v[172:175], v[116:119]
	v_mfma_i32_16x16x64_i8 v[116:119], v[160:163], v[176:179], v[116:119]
	v_mfma_i32_16x16x64_i8 v[132:135], v[160:163], v[168:171], v[132:135]
	v_mfma_i32_16x16x64_i8 v[132:135], v[156:159], v[164:167], v[132:135]
	s_setprio 0
	s_barrier
; #define PG8_STAGE(bufoff, gbase, voff) do { _Pragma("unroll") for (int _i = 0; _i < 2; ++_i) \
;         __builtin_amdgcn_global_load_lds((const unsigned*)((const char*)(gbase) + (voff)[_i]), (PG8_LAS unsigned*)(lds + (bufoff) + ldsw + _i * 8192), 16, 0, 0); } while (0)
; #define PG8_LDA(dst, b, h) do { _Pragma("unroll") for (int m = 0; m < 4; ++m) _Pragma("unroll") for (int k = 0; k < 2; ++k) dst[m][k] = *(const PG8_LAS bf16x8*)(lds + PG8_SA(b, h) + aoff + m * 2048 + k * 1024); } while (0)
; #define PG8_LDB(dst, b, h) do { _Pragma("unroll") for (int n = 0; n < 2; ++n) _Pragma("unroll") for (int k = 0; k < 2; ++k) dst[n][k] = *(const PG8_LAS bf16x8*)(lds + PG8_SB(b, h) + boff + n * 2048 + k * 1024); } while (0)
; #define PG8_WAIT_V(n) asm volatile("s_waitcnt vmcnt(" #n ")" ::: "memory")
; #define PG8_WAIT_L(n) asm volatile("s_waitcnt lgkmcnt(" #n ")" ::: "memory")
; #define PG8_BAR __builtin_amdgcn_s_barrier()
; #define PG8_SCHED __builtin_amdgcn_sched_barrier(0)
; template <class Epi, class Sched, bool ALIGN_EPI = false, bool SP2 = false, bool I8 = false>
; __device__ __forceinline__ void gemm_phase(PG8_LAS unsigned char* lds, const Gemm g, const Sched& S, const Epi& E) {
;     ...
;             PG8_LDB(B0, 0, 0); PG8_LDB(B1, 0, 1); PG8_SCHED; PG8_LDA(At, 0, 0); PG8_STAGE(PG8_SA(1, 1), a1 + hstep, voffA);
;             PG8_WAIT_V(8); PG8_WAIT_L(0); PG8_BAR; PG8_MMA(0, 0, At, B0); PG8_MMA(0, 1, At, B1); PG8_BAR; PG8_SCHED;
;     ...
;             PG8_LDA(At, 1, 1); PG8_STAGE(PG8_SB(1, 0), b3, voffB); PG8_STAGE(PG8_SB(1, 1), b3 + hstep, voffB); PG8_STAGE(PG8_SA(1, 0), a3, voffA);
;             PG8_WAIT_V(8); PG8_WAIT_L(0); PG8_BAR; PG8_MMA(1, 0, At, B0); PG8_MMA(1, 1, At, B1); PG8_BAR; PG8_SCHED;
	s_add_i32 s60, s87, s46
	v_lshl_add_u64 v[190:191], v[190:191], 0, s[84:85]
	s_mov_b32 m0, s60
	ds_read_b128 v[164:167], v219 offset:49152
	ds_read_b128 v[168:171], v219 offset:50176
	ds_read_b128 v[172:175], v219 offset:51200
	ds_read_b128 v[176:179], v219 offset:52224
	ds_read_b128 v[204:207], v219 offset:53248
	ds_read_b128 v[208:211], v219 offset:54272
	ds_read_b128 v[212:215], v219 offset:55296
	ds_read_b128 v[220:223], v219 offset:56320
	global_load_lds_dwordx4 v[190:191], off
	s_add_i32 m0, s60, 0x2000
	s_add_u32 s58, s58, 0x80080
	v_lshl_add_u64 v[190:191], v[224:225], 0, s[84:85]
	s_addc_u32 s59, s59, 0
	s_add_i32 s60, s96, s46
	global_load_lds_dwordx4 v[190:191], off
	v_lshl_add_u64 v[190:191], s[58:59], 0, v[2:3]
	s_mov_b32 m0, s60
	s_nop 0
	global_load_lds_dwordx4 v[190:191], off
	v_lshl_add_u64 v[190:191], s[58:59], 0, v[184:185]
	s_add_i32 m0, s60, 0x2000
	s_nop 0
	global_load_lds_dwordx4 v[190:191], off
	v_lshl_add_u64 v[190:191], v[226:227], 0, s[84:85]
	s_mov_b32 m0, s28
	s_nop 0
	global_load_lds_dwordx4 v[190:191], off
	v_lshl_add_u64 v[190:191], v[228:229], 0, s[84:85]
	s_mov_b32 m0, s77
	s_nop 0
	global_load_lds_dwordx4 v[190:191], off
	s_waitcnt vmcnt(8)
	s_waitcnt lgkmcnt(0)
	s_barrier
	s_setprio 1
	s_waitcnt lgkmcnt(0)
	v_mfma_i32_16x16x64_i8 v[80:83], v[52:55], v[164:167], v[80:83]
	v_mfma_i32_16x16x64_i8 v[80:83], v[56:59], v[168:171], v[80:83]
	v_mfma_i32_16x16x64_i8 v[64:67], v[56:59], v[176:179], v[64:67]
	v_mfma_i32_16x16x64_i8 v[64:67], v[52:55], v[172:175], v[64:67]
	v_mfma_i32_16x16x64_i8 v[48:51], v[52:55], v[204:207], v[48:51]
	v_mfma_i32_16x16x64_i8 v[48:51], v[56:59], v[208:211], v[48:51]
	v_mfma_i32_16x16x64_i8 v[16:19], v[56:59], v[220:223], v[16:19]
	v_mfma_i32_16x16x64_i8 v[16:19], v[52:55], v[212:215], v[16:19]
	v_mfma_i32_16x16x64_i8 v[12:15], v[68:71], v[212:215], v[12:15]
	v_mfma_i32_16x16x64_i8 v[12:15], v[72:75], v[220:223], v[12:15]
	v_mfma_i32_16x16x64_i8 v[44:47], v[72:75], v[208:211], v[44:47]
	v_mfma_i32_16x16x64_i8 v[44:47], v[68:71], v[204:207], v[44:47]
	v_mfma_i32_16x16x64_i8 v[60:63], v[68:71], v[172:175], v[60:63]
	v_mfma_i32_16x16x64_i8 v[60:63], v[72:75], v[176:179], v[60:63]
	v_mfma_i32_16x16x64_i8 v[76:79], v[72:75], v[168:171], v[76:79]
	v_mfma_i32_16x16x64_i8 v[76:79], v[68:71], v[164:167], v[76:79]
	v_mfma_i32_16x16x64_i8 v[28:31], v[140:143], v[164:167], v[28:31]
	v_mfma_i32_16x16x64_i8 v[72:75], v[144:147], v[168:171], v[28:31]
	v_mfma_i32_16x16x64_i8 v[28:31], v[144:147], v[176:179], v[36:39]
	v_mfma_i32_16x16x64_i8 v[56:59], v[140:143], v[172:175], v[28:31]
	v_mfma_i32_16x16x64_i8 v[24:27], v[140:143], v[204:207], v[24:27]
	v_mfma_i32_16x16x64_i8 v[24:27], v[144:147], v[208:211], v[24:27]
	v_mfma_i32_16x16x64_i8 v[8:11], v[144:147], v[220:223], v[8:11]
	v_mfma_i32_16x16x64_i8 v[8:11], v[140:143], v[212:215], v[8:11]
	v_mfma_i32_16x16x64_i8 v[4:7], v[156:159], v[212:215], v[4:7]
	v_mfma_i32_16x16x64_i8 v[4:7], v[160:163], v[220:223], v[4:7]
	v_mfma_i32_16x16x64_i8 v[20:23], v[160:163], v[208:211], v[20:23]
	v_mfma_i32_16x16x64_i8 v[20:23], v[156:159], v[204:207], v[20:23]
	v_mfma_i32_16x16x64_i8 v[28:31], v[156:159], v[172:175], v[40:43]
	v_mfma_i32_16x16x64_i8 v[52:55], v[160:163], v[176:179], v[28:31]
	v_mfma_i32_16x16x64_i8 v[28:31], v[160:163], v[168:171], v[32:35]
	v_mfma_i32_16x16x64_i8 v[68:71], v[156:159], v[164:167], v[28:31]
	s_setprio 0
	s_add_i32 s86, s86, 2
	s_add_u32 s54, s54, 0x100
	s_addc_u32 s55, s55, 0
	s_add_u32 s45, s45, 0x100
	s_addc_u32 s49, s49, 0
	s_cmp_gt_u32 s86, 29
	s_barrier
	s_cbranch_scc1 .Lkloop_exit_6
.LBB0_1843:
	s_add_u32 s58, s54, 0xfff80080
	s_addc_u32 s59, s55, -1
	s_add_i32 s87, 0, 0x10000
	s_cmp_eq_u32 s86, 28
	s_cselect_b32 s61, s11, s59
	s_cselect_b32 s60, s13, s58
	s_cselect_b32 s59, s34, s49
	s_cselect_b32 s58, s35, s45
	s_add_i32 vcc_lo, 0, 0x14000
	v_add_u32_e32 v40, s87, v217
	v_add_u32_e32 v160, vcc_lo, v217
	ds_read_b128 v[28:31], v40
	ds_read_b128 v[32:35], v40 offset:1024
	ds_read_b128 v[36:39], v40 offset:2048
	ds_read_b128 v[40:43], v40 offset:3072
	ds_read_b128 v[140:143], v160
	ds_read_b128 v[144:147], v160 offset:1024
	ds_read_b128 v[156:159], v160 offset:2048
	ds_read_b128 v[160:163], v160 offset:3072
	v_lshl_add_u64 v[190:191], s[54:55], 0, v[186:187]
	s_add_i32 m0, s65, 0xc000
	ds_read_b128 v[164:167], v219
	ds_read_b128 v[168:171], v219 offset:1024
	ds_read_b128 v[172:175], v219 offset:2048
	ds_read_b128 v[176:179], v219 offset:3072
	ds_read_b128 v[204:207], v219 offset:4096
	ds_read_b128 v[208:211], v219 offset:5120
	ds_read_b128 v[212:215], v219 offset:6144
	ds_read_b128 v[220:223], v219 offset:7168
	global_load_lds_dwordx4 v[190:191], off
	v_lshl_add_u64 v[190:191], s[54:55], 0, v[188:189]
	s_add_i32 m0, s65, 0xe000
	s_nop 0
	global_load_lds_dwordx4 v[190:191], off
	s_waitcnt vmcnt(8)
	s_waitcnt lgkmcnt(0)
	s_barrier
; #define PG8_STAGE(bufoff, gbase, voff) do { _Pragma("unroll") for (int _i = 0; _i < 2; ++_i) \
;         __builtin_amdgcn_global_load_lds((const unsigned*)((const char*)(gbase) + (voff)[_i]), (PG8_LAS unsigned*)(lds + (bufoff) + ldsw + _i * 8192), 16, 0, 0); } while (0)
; #define PG8_LDA(dst, b, h) do { _Pragma("unroll") for (int m = 0; m < 4; ++m) _Pragma("unroll") for (int k = 0; k < 2; ++k) dst[m][k] = *(const PG8_LAS bf16x8*)(lds + PG8_SA(b, h) + aoff + m * 2048 + k * 1024); } while (0)
; #define PG8_WAIT_V(n) asm volatile("s_waitcnt vmcnt(" #n ")" ::: "memory")
; #define PG8_WAIT_L(n) asm volatile("s_waitcnt lgkmcnt(" #n ")" ::: "memory")
; #define PG8_BAR __builtin_amdgcn_s_barrier()
; #define PG8_SCHED __builtin_amdgcn_sched_barrier(0)
; template <class Epi, class Sched, bool ALIGN_EPI = false, bool SP2 = false, bool I8 = false>
; __device__ __forceinline__ void gemm_phase(PG8_LAS unsigned char* lds, const Gemm g, const Sched& S, const Epi& E) {
;     ...
;             PG8_WAIT_V(8); PG8_WAIT_L(0); PG8_BAR; PG8_MMA(0, 0, At, B0); PG8_MMA(0, 1, At, B1); PG8_BAR; PG8_SCHED;
;             PG8_LDA(At, 0, 1); PG8_STAGE(PG8_SB(0, 0), b2, voffB); PG8_STAGE(PG8_SB(0, 1), b2 + hstep, voffB); PG8_STAGE(PG8_SA(0, 0), a2, voffA);
;             PG8_WAIT_V(8); PG8_WAIT_L(0); PG8_BAR; PG8_MMA(1, 0, At, B0); PG8_MMA(1, 1, At, B1); PG8_BAR; PG8_SCHED;
	s_setprio 1
	s_waitcnt lgkmcnt(0)
	v_mfma_i32_16x16x64_i8 v[152:155], v[28:31], v[164:167], v[152:155]
	v_mfma_i32_16x16x64_i8 v[152:155], v[32:35], v[168:171], v[152:155]
	v_mfma_i32_16x16x64_i8 v[128:131], v[32:35], v[176:179], v[128:131]
	v_mfma_i32_16x16x64_i8 v[128:131], v[28:31], v[172:175], v[128:131]
	v_mfma_i32_16x16x64_i8 v[112:115], v[28:31], v[204:207], v[112:115]
	v_mfma_i32_16x16x64_i8 v[112:115], v[32:35], v[208:211], v[112:115]
	v_mfma_i32_16x16x64_i8 v[96:99], v[32:35], v[220:223], v[96:99]
	v_mfma_i32_16x16x64_i8 v[96:99], v[28:31], v[212:215], v[96:99]
	v_mfma_i32_16x16x64_i8 v[92:95], v[36:39], v[212:215], v[92:95]
	v_mfma_i32_16x16x64_i8 v[92:95], v[40:43], v[220:223], v[92:95]
	v_mfma_i32_16x16x64_i8 v[108:111], v[40:43], v[208:211], v[108:111]
	v_mfma_i32_16x16x64_i8 v[108:111], v[36:39], v[204:207], v[108:111]
	v_mfma_i32_16x16x64_i8 v[124:127], v[36:39], v[172:175], v[124:127]
	v_mfma_i32_16x16x64_i8 v[124:127], v[40:43], v[176:179], v[124:127]
	v_mfma_i32_16x16x64_i8 v[148:151], v[40:43], v[168:171], v[148:151]
	v_mfma_i32_16x16x64_i8 v[148:151], v[36:39], v[164:167], v[148:151]
	v_mfma_i32_16x16x64_i8 v[136:139], v[140:143], v[164:167], v[136:139]
	v_mfma_i32_16x16x64_i8 v[136:139], v[144:147], v[168:171], v[136:139]
	v_mfma_i32_16x16x64_i8 v[120:123], v[144:147], v[176:179], v[120:123]
	v_mfma_i32_16x16x64_i8 v[120:123], v[140:143], v[172:175], v[120:123]
	v_mfma_i32_16x16x64_i8 v[104:107], v[140:143], v[204:207], v[104:107]
	v_mfma_i32_16x16x64_i8 v[104:107], v[144:147], v[208:211], v[104:107]
	v_mfma_i32_16x16x64_i8 v[88:91], v[144:147], v[220:223], v[88:91]
	v_mfma_i32_16x16x64_i8 v[88:91], v[140:143], v[212:215], v[88:91]
	v_mfma_i32_16x16x64_i8 v[84:87], v[156:159], v[212:215], v[84:87]
	v_mfma_i32_16x16x64_i8 v[84:87], v[160:163], v[220:223], v[84:87]
	v_mfma_i32_16x16x64_i8 v[100:103], v[160:163], v[208:211], v[100:103]
	v_mfma_i32_16x16x64_i8 v[100:103], v[156:159], v[204:207], v[100:103]
	v_mfma_i32_16x16x64_i8 v[116:119], v[156:159], v[172:175], v[116:119]
	v_mfma_i32_16x16x64_i8 v[116:119], v[160:163], v[176:179], v[116:119]
	v_mfma_i32_16x16x64_i8 v[132:135], v[160:163], v[168:171], v[132:135]
	v_mfma_i32_16x16x64_i8 v[132:135], v[156:159], v[164:167], v[132:135]
	s_setprio 0
	s_barrier
	s_add_i32 s87, s87, s46
	v_lshl_add_u64 v[190:191], s[58:59], 0, v[2:3]
	s_mov_b32 m0, s87
	ds_read_b128 v[164:167], v219 offset:16384
	ds_read_b128 v[168:171], v219 offset:17408
	ds_read_b128 v[172:175], v219 offset:18432
	ds_read_b128 v[176:179], v219 offset:19456
	ds_read_b128 v[204:207], v219 offset:20480
	ds_read_b128 v[208:211], v219 offset:21504
	ds_read_b128 v[212:215], v219 offset:22528
	ds_read_b128 v[220:223], v219 offset:23552
	global_load_lds_dwordx4 v[190:191], off
	s_add_i32 m0, s87, 0x2000
	s_add_u32 s96, s58, 0x80000
	v_lshl_add_u64 v[224:225], s[58:59], 0, v[184:185]
	s_addc_u32 s97, s59, 0
	s_add_i32 s87, vcc_lo, s46
	global_load_lds_dwordx4 v[224:225], off
	v_lshl_add_u64 v[226:227], s[96:97], 0, v[2:3]
	s_mov_b32 m0, s87
	v_lshl_add_u64 v[228:229], s[60:61], 0, v[182:183]
	global_load_lds_dwordx4 v[226:227], off
	v_lshl_add_u64 v[226:227], s[96:97], 0, v[184:185]
	s_add_i32 m0, s87, 0x2000
	s_nop 0
	global_load_lds_dwordx4 v[226:227], off
	v_lshl_add_u64 v[226:227], s[60:61], 0, v[180:181]
	s_mov_b32 m0, s65
	s_nop 0
	global_load_lds_dwordx4 v[226:227], off
	s_mov_b32 m0, s67
	s_nop 0
	global_load_lds_dwordx4 v[228:229], off
	s_waitcnt vmcnt(8)
	s_waitcnt lgkmcnt(0)
	s_barrier
	s_setprio 1
	s_waitcnt lgkmcnt(0)
	v_mfma_i32_16x16x64_i8 v[80:83], v[28:31], v[164:167], v[80:83]
	v_mfma_i32_16x16x64_i8 v[80:83], v[32:35], v[168:171], v[80:83]
	v_mfma_i32_16x16x64_i8 v[64:67], v[32:35], v[176:179], v[64:67]
	v_mfma_i32_16x16x64_i8 v[64:67], v[28:31], v[172:175], v[64:67]
	v_mfma_i32_16x16x64_i8 v[48:51], v[28:31], v[204:207], v[48:51]
	v_mfma_i32_16x16x64_i8 v[48:51], v[32:35], v[208:211], v[48:51]
	v_mfma_i32_16x16x64_i8 v[16:19], v[32:35], v[220:223], v[16:19]
	v_mfma_i32_16x16x64_i8 v[16:19], v[28:31], v[212:215], v[16:19]
	v_mfma_i32_16x16x64_i8 v[12:15], v[36:39], v[212:215], v[12:15]
	v_mfma_i32_16x16x64_i8 v[12:15], v[40:43], v[220:223], v[12:15]
	v_mfma_i32_16x16x64_i8 v[44:47], v[40:43], v[208:211], v[44:47]
	v_mfma_i32_16x16x64_i8 v[44:47], v[36:39], v[204:207], v[44:47]
	v_mfma_i32_16x16x64_i8 v[60:63], v[36:39], v[172:175], v[60:63]
	v_mfma_i32_16x16x64_i8 v[60:63], v[40:43], v[176:179], v[60:63]
	v_mfma_i32_16x16x64_i8 v[76:79], v[40:43], v[168:171], v[76:79]
	v_mfma_i32_16x16x64_i8 v[76:79], v[36:39], v[164:167], v[76:79]
	v_mfma_i32_16x16x64_i8 v[28:31], v[140:143], v[164:167], v[72:75]
	v_mfma_i32_16x16x64_i8 v[28:31], v[144:147], v[168:171], v[28:31]
	v_mfma_i32_16x16x64_i8 v[36:39], v[144:147], v[176:179], v[56:59]
	v_mfma_i32_16x16x64_i8 v[36:39], v[140:143], v[172:175], v[36:39]
	v_mfma_i32_16x16x64_i8 v[24:27], v[140:143], v[204:207], v[24:27]
	v_mfma_i32_16x16x64_i8 v[24:27], v[144:147], v[208:211], v[24:27]
	v_mfma_i32_16x16x64_i8 v[8:11], v[144:147], v[220:223], v[8:11]
	v_mfma_i32_16x16x64_i8 v[8:11], v[140:143], v[212:215], v[8:11]
	v_mfma_i32_16x16x64_i8 v[4:7], v[156:159], v[212:215], v[4:7]
	v_mfma_i32_16x16x64_i8 v[4:7], v[160:163], v[220:223], v[4:7]
	v_mfma_i32_16x16x64_i8 v[20:23], v[160:163], v[208:211], v[20:23]
	v_mfma_i32_16x16x64_i8 v[20:23], v[156:159], v[204:207], v[20:23]
	v_mfma_i32_16x16x64_i8 v[40:43], v[156:159], v[172:175], v[52:55]
	v_mfma_i32_16x16x64_i8 v[40:43], v[160:163], v[176:179], v[40:43]
	v_mfma_i32_16x16x64_i8 v[32:35], v[160:163], v[168:171], v[68:71]
	v_mfma_i32_16x16x64_i8 v[32:35], v[156:159], v[164:167], v[32:35]
	s_setprio 0
	s_barrier
; #define PG8_STAGE(bufoff, gbase, voff) do { _Pragma("unroll") for (int _i = 0; _i < 2; ++_i) \
;         __builtin_amdgcn_global_load_lds((const unsigned*)((const char*)(gbase) + (voff)[_i]), (PG8_LAS unsigned*)(lds + (bufoff) + ldsw + _i * 8192), 16, 0, 0); } while (0)
; #define PG8_LDA(dst, b, h) do { _Pragma("unroll") for (int m = 0; m < 4; ++m) _Pragma("unroll") for (int k = 0; k < 2; ++k) dst[m][k] = *(const PG8_LAS bf16x8*)(lds + PG8_SA(b, h) + aoff + m * 2048 + k * 1024); } while (0)
; #define PG8_LDB(dst, b, h) do { _Pragma("unroll") for (int n = 0; n < 2; ++n) _Pragma("unroll") for (int k = 0; k < 2; ++k) dst[n][k] = *(const PG8_LAS bf16x8*)(lds + PG8_SB(b, h) + boff + n * 2048 + k * 1024); } while (0)
; #define PG8_WAIT_V(n) asm volatile("s_waitcnt vmcnt(" #n ")" ::: "memory")
; #define PG8_WAIT_L(n) asm volatile("s_waitcnt lgkmcnt(" #n ")" ::: "memory")
; #define PG8_BAR __builtin_amdgcn_s_barrier()
; #define PG8_SCHED __builtin_amdgcn_sched_barrier(0)
; template <class Epi, class Sched, bool ALIGN_EPI = false, bool SP2 = false, bool I8 = false>
; __device__ __forceinline__ void gemm_phase(PG8_LAS unsigned char* lds, const Gemm g, const Sched& S, const Epi& E) {
;     ...
;             PG8_LDB(B0, 1, 0); PG8_LDB(B1, 1, 1); PG8_SCHED; PG8_LDA(At, 1, 0); PG8_STAGE(PG8_SA(0, 1), a2 + hstep, voffA);
;             PG8_WAIT_V(8); PG8_WAIT_L(0); PG8_BAR; PG8_MMA(0, 0, At, B0); PG8_MMA(0, 1, At, B1); PG8_BAR; PG8_SCHED;
;             PG8_LDA(At, 1, 1); PG8_STAGE(PG8_SB(1, 0), b3, voffB); PG8_STAGE(PG8_SB(1, 1), b3 + hstep, voffB); PG8_STAGE(PG8_SA(1, 0), a3, voffA);
;             PG8_WAIT_V(8); PG8_WAIT_L(0); PG8_BAR; PG8_MMA(1, 0, At, B0); PG8_MMA(1, 1, At, B1); PG8_BAR; PG8_SCHED;
	s_add_i32 s87, 0, 0x18000
	s_add_i32 s96, 0, 0x1c000
	v_add_u32_e32 v72, s87, v217
	v_add_u32_e32 v160, s96, v217
	ds_read_b128 v[52:55], v72
	ds_read_b128 v[56:59], v72 offset:1024
	ds_read_b128 v[68:71], v72 offset:2048
	ds_read_b128 v[72:75], v72 offset:3072
	ds_read_b128 v[140:143], v160
	ds_read_b128 v[144:147], v160 offset:1024
	ds_read_b128 v[156:159], v160 offset:2048
	ds_read_b128 v[160:163], v160 offset:3072
	s_add_u32 s60, s60, 0x80000
	s_addc_u32 s61, s61, 0
	s_mov_b32 m0, s72
	v_lshl_add_u64 v[240:241], s[60:61], 0, v[180:181]
	ds_read_b128 v[164:167], v219 offset:32768
	ds_read_b128 v[168:171], v219 offset:33792
	ds_read_b128 v[172:175], v219 offset:34816
	ds_read_b128 v[176:179], v219 offset:35840
	ds_read_b128 v[204:207], v219 offset:36864
	ds_read_b128 v[208:211], v219 offset:37888
	ds_read_b128 v[212:215], v219 offset:38912
	ds_read_b128 v[220:223], v219 offset:39936
	global_load_lds_dwordx4 v[240:241], off
	v_lshl_add_u64 v[240:241], s[60:61], 0, v[182:183]
	s_mov_b32 m0, s73
	s_nop 0
	global_load_lds_dwordx4 v[240:241], off
	s_waitcnt vmcnt(8)
	s_waitcnt lgkmcnt(0)
	s_barrier
	s_setprio 1
	s_waitcnt lgkmcnt(0)
	v_mfma_i32_16x16x64_i8 v[152:155], v[52:55], v[164:167], v[152:155]
	v_mfma_i32_16x16x64_i8 v[152:155], v[56:59], v[168:171], v[152:155]
	v_mfma_i32_16x16x64_i8 v[128:131], v[56:59], v[176:179], v[128:131]
	v_mfma_i32_16x16x64_i8 v[128:131], v[52:55], v[172:175], v[128:131]
	v_mfma_i32_16x16x64_i8 v[112:115], v[52:55], v[204:207], v[112:115]
	v_mfma_i32_16x16x64_i8 v[112:115], v[56:59], v[208:211], v[112:115]
	v_mfma_i32_16x16x64_i8 v[96:99], v[56:59], v[220:223], v[96:99]
	v_mfma_i32_16x16x64_i8 v[96:99], v[52:55], v[212:215], v[96:99]
	v_mfma_i32_16x16x64_i8 v[92:95], v[68:71], v[212:215], v[92:95]
	v_mfma_i32_16x16x64_i8 v[92:95], v[72:75], v[220:223], v[92:95]
	v_mfma_i32_16x16x64_i8 v[108:111], v[72:75], v[208:211], v[108:111]
	v_mfma_i32_16x16x64_i8 v[108:111], v[68:71], v[204:207], v[108:111]
	v_mfma_i32_16x16x64_i8 v[124:127], v[68:71], v[172:175], v[124:127]
	v_mfma_i32_16x16x64_i8 v[124:127], v[72:75], v[176:179], v[124:127]
	v_mfma_i32_16x16x64_i8 v[148:151], v[72:75], v[168:171], v[148:151]
	v_mfma_i32_16x16x64_i8 v[148:151], v[68:71], v[164:167], v[148:151]
	v_mfma_i32_16x16x64_i8 v[136:139], v[140:143], v[164:167], v[136:139]
	v_mfma_i32_16x16x64_i8 v[136:139], v[144:147], v[168:171], v[136:139]
	v_mfma_i32_16x16x64_i8 v[120:123], v[144:147], v[176:179], v[120:123]
	v_mfma_i32_16x16x64_i8 v[120:123], v[140:143], v[172:175], v[120:123]
	v_mfma_i32_16x16x64_i8 v[104:107], v[140:143], v[204:207], v[104:107]
	v_mfma_i32_16x16x64_i8 v[104:107], v[144:147], v[208:211], v[104:107]
	v_mfma_i32_16x16x64_i8 v[88:91], v[144:147], v[220:223], v[88:91]
	v_mfma_i32_16x16x64_i8 v[88:91], v[140:143], v[212:215], v[88:91]
	v_mfma_i32_16x16x64_i8 v[84:87], v[156:159], v[212:215], v[84:87]
	v_mfma_i32_16x16x64_i8 v[84:87], v[160:163], v[220:223], v[84:87]
	v_mfma_i32_16x16x64_i8 v[100:103], v[160:163], v[208:211], v[100:103]
	v_mfma_i32_16x16x64_i8 v[100:103], v[156:159], v[204:207], v[100:103]
	v_mfma_i32_16x16x64_i8 v[116:119], v[156:159], v[172:175], v[116:119]
	v_mfma_i32_16x16x64_i8 v[116:119], v[160:163], v[176:179], v[116:119]
	v_mfma_i32_16x16x64_i8 v[132:135], v[160:163], v[168:171], v[132:135]
	v_mfma_i32_16x16x64_i8 v[132:135], v[156:159], v[164:167], v[132:135]
	s_setprio 0
	s_barrier
	s_add_i32 s60, s87, s46
	v_lshl_add_u64 v[190:191], v[190:191], 0, s[84:85]
	s_mov_b32 m0, s60
	ds_read_b128 v[164:167], v219 offset:49152
	ds_read_b128 v[168:171], v219 offset:50176
	ds_read_b128 v[172:175], v219 offset:51200
	ds_read_b128 v[176:179], v219 offset:52224
	ds_read_b128 v[204:207], v219 offset:53248
	ds_read_b128 v[208:211], v219 offset:54272
	ds_read_b128 v[212:215], v219 offset:55296
	ds_read_b128 v[220:223], v219 offset:56320
	global_load_lds_dwordx4 v[190:191], off
	s_add_i32 m0, s60, 0x2000
	s_add_u32 s58, s58, 0x80080
	v_lshl_add_u64 v[190:191], v[224:225], 0, s[84:85]
	s_addc_u32 s59, s59, 0
	s_add_i32 s60, s96, s46
	global_load_lds_dwordx4 v[190:191], off
	v_lshl_add_u64 v[190:191], s[58:59], 0, v[2:3]
	s_mov_b32 m0, s60
	s_nop 0
	global_load_lds_dwordx4 v[190:191], off
	v_lshl_add_u64 v[190:191], s[58:59], 0, v[184:185]
	s_add_i32 m0, s60, 0x2000
	s_nop 0
	global_load_lds_dwordx4 v[190:191], off
	v_lshl_add_u64 v[190:191], v[226:227], 0, s[84:85]
	s_mov_b32 m0, s28
	s_nop 0
	global_load_lds_dwordx4 v[190:191], off
	v_lshl_add_u64 v[190:191], v[228:229], 0, s[84:85]
	s_mov_b32 m0, s77
	s_nop 0
	global_load_lds_dwordx4 v[190:191], off
	s_waitcnt vmcnt(8)
	s_waitcnt lgkmcnt(0)
	s_barrier
	s_setprio 1
	s_waitcnt lgkmcnt(0)
	v_mfma_i32_16x16x64_i8 v[80:83], v[52:55], v[164:167], v[80:83]
	v_mfma_i32_16x16x64_i8 v[80:83], v[56:59], v[168:171], v[80:83]
	v_mfma_i32_16x16x64_i8 v[64:67], v[56:59], v[176:179], v[64:67]
	v_mfma_i32_16x16x64_i8 v[64:67], v[52:55], v[172:175], v[64:67]
	v_mfma_i32_16x16x64_i8 v[48:51], v[52:55], v[204:207], v[48:51]
	v_mfma_i32_16x16x64_i8 v[48:51], v[56:59], v[208:211], v[48:51]
	v_mfma_i32_16x16x64_i8 v[16:19], v[56:59], v[220:223], v[16:19]
	v_mfma_i32_16x16x64_i8 v[16:19], v[52:55], v[212:215], v[16:19]
	v_mfma_i32_16x16x64_i8 v[12:15], v[68:71], v[212:215], v[12:15]
	v_mfma_i32_16x16x64_i8 v[12:15], v[72:75], v[220:223], v[12:15]
	v_mfma_i32_16x16x64_i8 v[44:47], v[72:75], v[208:211], v[44:47]
	v_mfma_i32_16x16x64_i8 v[44:47], v[68:71], v[204:207], v[44:47]
	v_mfma_i32_16x16x64_i8 v[60:63], v[68:71], v[172:175], v[60:63]
	v_mfma_i32_16x16x64_i8 v[60:63], v[72:75], v[176:179], v[60:63]
	v_mfma_i32_16x16x64_i8 v[76:79], v[72:75], v[168:171], v[76:79]
	v_mfma_i32_16x16x64_i8 v[76:79], v[68:71], v[164:167], v[76:79]
	v_mfma_i32_16x16x64_i8 v[28:31], v[140:143], v[164:167], v[28:31]
	v_mfma_i32_16x16x64_i8 v[72:75], v[144:147], v[168:171], v[28:31]
	v_mfma_i32_16x16x64_i8 v[28:31], v[144:147], v[176:179], v[36:39]
	v_mfma_i32_16x16x64_i8 v[56:59], v[140:143], v[172:175], v[28:31]
	v_mfma_i32_16x16x64_i8 v[24:27], v[140:143], v[204:207], v[24:27]
	v_mfma_i32_16x16x64_i8 v[24:27], v[144:147], v[208:211], v[24:27]
	v_mfma_i32_16x16x64_i8 v[8:11], v[144:147], v[220:223], v[8:11]
	v_mfma_i32_16x16x64_i8 v[8:11], v[140:143], v[212:215], v[8:11]
	v_mfma_i32_16x16x64_i8 v[4:7], v[156:159], v[212:215], v[4:7]
	v_mfma_i32_16x16x64_i8 v[4:7], v[160:163], v[220:223], v[4:7]
	v_mfma_i32_16x16x64_i8 v[20:23], v[160:163], v[208:211], v[20:23]
	v_mfma_i32_16x16x64_i8 v[20:23], v[156:159], v[204:207], v[20:23]
	v_mfma_i32_16x16x64_i8 v[28:31], v[156:159], v[172:175], v[40:43]
	v_mfma_i32_16x16x64_i8 v[52:55], v[160:163], v[176:179], v[28:31]
	v_mfma_i32_16x16x64_i8 v[28:31], v[160:163], v[168:171], v[32:35]
	v_mfma_i32_16x16x64_i8 v[68:71], v[156:159], v[164:167], v[28:31]
	s_setprio 0
	s_add_i32 s86, s86, 2
	s_add_u32 s54, s54, 0x100
	s_addc_u32 s55, s55, 0
	s_add_u32 s45, s45, 0x100
	s_addc_u32 s49, s49, 0
	s_cmp_gt_u32 s86, 29
	s_barrier
	s_cbranch_scc0 .LBB0_1843
